# all compiler-packed f32 VALU ops (v_pk_fma/mul/add_f32) outside the attention rescale path split into scalar pairs, since packed f32 measured slower than two scalar ops on this chip
# baseline (speedup 1.0000x reference)
; __device__ __forceinline__ void phase0a(const Params& p, const Ctx& c, float* lds) {
;     ...
;     for (long it = c.gtid; it < 16 * 6144; it += c.nthr) {
;       const int cq = (int)(it % 6144), ks = (int)(it / 6144); const int gc = cq * 4, l = gc / NMODC, col = gc % NMODC;
;       const float* wp = p.w_mod + ((size_t)l * DM + (size_t)ks * 128) * NMODC + col;
;       f32x4 a[5] = {};
; #pragma unroll 8
;       for (int k = 0; k < 128; ++k) { const f32x4 w = *(const f32x4*)(wp + (size_t)k * NMODC);
; #pragma unroll
;         for (int v = 0; v < 5; ++v) a[v] += w * lds[v * DM + ks * 128 + k]; }
; #pragma unroll
;       for (int v = 0; v < 5; ++v) *(f32x4*)(MP + ((size_t)ks * 5 + v) * 24576 + gc) = a[v];
;     }
.LBB0_23:
	v_lshl_add_u64 v[66:67], v[64:65], 0, s[16:17]
	v_add_co_u32_e32 v108, vcc, s18, v66
	ds_read_b128 v[24:27], v63
	ds_read_b128 v[20:23], v63 offset:16
	ds_read_b128 v[28:31], v63 offset:8192
	ds_read_b128 v[32:35], v63 offset:8208
	ds_read_b128 v[48:51], v63 offset:16384
	ds_read_b128 v[36:39], v63 offset:16400
	ds_read_b128 v[68:71], v63 offset:24576
	ds_read_b128 v[40:43], v63 offset:24592
	ds_read_b128 v[72:75], v63 offset:32768
	ds_read_b128 v[44:47], v63 offset:32784
	v_addc_co_u32_e32 v109, vcc, 0, v67, vcc
	v_add_co_u32_e32 v110, vcc, s19, v66
	global_load_dwordx4 v[76:79], v[66:67], off
	s_nop 0
	v_addc_co_u32_e32 v111, vcc, 0, v67, vcc
	v_add_co_u32_e32 v112, vcc, s20, v66
	s_add_u32 s16, s16, 0x60000
	s_nop 0
	v_addc_co_u32_e32 v113, vcc, 0, v67, vcc
	v_add_co_u32_e32 v114, vcc, s21, v66
	s_addc_u32 s17, s17, 0
	s_nop 0
	v_addc_co_u32_e32 v115, vcc, 0, v67, vcc
	v_add_co_u32_e32 v116, vcc, s22, v66
	s_waitcnt lgkmcnt(4)
	v_mov_b32_e32 v120, v39
	v_addc_co_u32_e32 v117, vcc, 0, v67, vcc
	v_add_co_u32_e32 v118, vcc, s23, v66
	s_waitcnt lgkmcnt(2)
	v_mov_b32_e32 v122, v43
	v_addc_co_u32_e32 v119, vcc, 0, v67, vcc
	v_add_co_u32_e32 v66, vcc, s24, v66
	s_waitcnt lgkmcnt(0)
	v_mov_b32_e32 v124, v47
	v_addc_co_u32_e32 v67, vcc, 0, v67, vcc
	global_load_dwordx4 v[80:83], v[108:109], off
	global_load_dwordx4 v[84:87], v[110:111], off
	global_load_dwordx4 v[88:91], v[112:113], off
	global_load_dwordx4 v[92:95], v[114:115], off
	global_load_dwordx4 v[96:99], v[116:117], off
	global_load_dwordx4 v[100:103], v[118:119], off
	global_load_dwordx4 v[104:107], v[66:67], off
	v_mov_b32_e32 v66, v27
	v_mov_b32_e32 v108, v31
	v_mov_b32_e32 v110, v51
	v_mov_b32_e32 v112, v71
	v_mov_b32_e32 v114, v75
	v_mov_b32_e32 v116, v23
	v_mov_b32_e32 v118, v35
	v_add_u32_e32 v63, 32, v63
	s_cmp_eq_u32 s16, 0x600000
	s_waitcnt vmcnt(7)
	v_fma_f32 v18, v78, v24, v18
	v_fma_f32 v19, v79, v24, v19
	v_fma_f32 v16, v76, v24, v16
	v_fma_f32 v17, v77, v24, v17
	v_fma_f32 v14, v78, v28, v14
	v_fma_f32 v15, v79, v28, v15
	v_fma_f32 v12, v76, v28, v12
	v_fma_f32 v13, v77, v28, v13
	v_fma_f32 v10, v78, v48, v10
	v_fma_f32 v11, v79, v48, v11
	v_fma_f32 v8, v76, v48, v8
	v_fma_f32 v9, v77, v48, v9
	v_fma_f32 v6, v78, v68, v6
	v_fma_f32 v7, v79, v68, v7
	v_fma_f32 v4, v76, v68, v4
	v_fma_f32 v5, v77, v68, v5
	v_fma_f32 v2, v78, v72, v2
	v_fma_f32 v3, v79, v72, v3
	v_fma_f32 v0, v76, v72, v0
	v_fma_f32 v1, v77, v72, v1
	s_waitcnt vmcnt(6)
	v_fma_f32 v16, v80, v25, v16
	v_fma_f32 v17, v81, v25, v17
	v_fma_f32 v18, v82, v25, v18
	v_fma_f32 v19, v83, v25, v19
	v_fma_f32 v12, v80, v29, v12
	v_fma_f32 v13, v81, v29, v13
	v_fma_f32 v14, v82, v29, v14
	v_fma_f32 v15, v83, v29, v15
	v_fma_f32 v8, v80, v49, v8
	v_fma_f32 v9, v81, v49, v9
	v_fma_f32 v10, v82, v49, v10
	v_fma_f32 v11, v83, v49, v11
	v_fma_f32 v4, v80, v69, v4
	v_fma_f32 v5, v81, v69, v5
	v_fma_f32 v6, v82, v69, v6
	v_fma_f32 v7, v83, v69, v7
	v_fma_f32 v0, v80, v73, v0
	v_fma_f32 v1, v81, v73, v1
	v_fma_f32 v2, v82, v73, v2
	v_fma_f32 v3, v83, v73, v3
	s_waitcnt vmcnt(5)
	v_fma_f32 v18, v86, v26, v18
	v_fma_f32 v19, v87, v26, v19
	v_fma_f32 v16, v84, v26, v16
	v_fma_f32 v17, v85, v26, v17
	v_fma_f32 v14, v86, v30, v14
	v_fma_f32 v15, v87, v30, v15
	v_fma_f32 v12, v84, v30, v12
	v_fma_f32 v13, v85, v30, v13
	v_fma_f32 v10, v86, v50, v10
	v_fma_f32 v11, v87, v50, v11
	v_fma_f32 v8, v84, v50, v8
	v_fma_f32 v9, v85, v50, v9
	v_fma_f32 v6, v86, v70, v6
	v_fma_f32 v7, v87, v70, v7
	v_fma_f32 v4, v84, v70, v4
	v_fma_f32 v5, v85, v70, v5
	v_fma_f32 v2, v86, v74, v2
	v_fma_f32 v3, v87, v74, v3
	v_fma_f32 v0, v84, v74, v0
	v_fma_f32 v1, v85, v74, v1
	s_waitcnt vmcnt(4)
	v_fma_f32 v18, v90, v66, v18
	v_fma_f32 v19, v91, v66, v19
	v_fma_f32 v16, v88, v66, v16
	v_fma_f32 v17, v89, v66, v17
	v_fma_f32 v14, v90, v108, v14
	v_fma_f32 v15, v91, v108, v15
	v_fma_f32 v12, v88, v108, v12
	v_fma_f32 v13, v89, v108, v13
	v_fma_f32 v10, v90, v110, v10
	v_fma_f32 v11, v91, v110, v11
	v_fma_f32 v8, v88, v110, v8
	v_fma_f32 v9, v89, v110, v9
	v_fma_f32 v6, v90, v112, v6
	v_fma_f32 v7, v91, v112, v7
	v_fma_f32 v4, v88, v112, v4
	v_fma_f32 v5, v89, v112, v5
	v_fma_f32 v2, v90, v114, v2
	v_fma_f32 v3, v91, v114, v3
	v_fma_f32 v0, v88, v114, v0
	v_fma_f32 v1, v89, v114, v1
	s_waitcnt vmcnt(3)
	v_fma_f32 v18, v94, v20, v18
	v_fma_f32 v19, v95, v20, v19
	v_fma_f32 v16, v92, v20, v16
	v_fma_f32 v17, v93, v20, v17
	v_fma_f32 v14, v94, v32, v14
	v_fma_f32 v15, v95, v32, v15
	v_fma_f32 v12, v92, v32, v12
	v_fma_f32 v13, v93, v32, v13
	v_fma_f32 v10, v94, v36, v10
	v_fma_f32 v11, v95, v36, v11
	v_fma_f32 v8, v92, v36, v8
	v_fma_f32 v9, v93, v36, v9
	v_fma_f32 v6, v94, v40, v6
	v_fma_f32 v7, v95, v40, v7
	v_fma_f32 v4, v92, v40, v4
	v_fma_f32 v5, v93, v40, v5
	v_fma_f32 v2, v94, v44, v2
	v_fma_f32 v3, v95, v44, v3
	v_fma_f32 v0, v92, v44, v0
	v_fma_f32 v1, v93, v44, v1
	s_waitcnt vmcnt(2)
	v_fma_f32 v18, v98, v21, v18
	v_fma_f32 v19, v99, v21, v19
	v_fma_f32 v16, v96, v21, v16
	v_fma_f32 v17, v97, v21, v17
	v_fma_f32 v14, v98, v33, v14
	v_fma_f32 v15, v99, v33, v15
	v_fma_f32 v12, v96, v33, v12
	v_fma_f32 v13, v97, v33, v13
	v_fma_f32 v10, v98, v37, v10
	v_fma_f32 v11, v99, v37, v11
	v_fma_f32 v8, v96, v37, v8
	v_fma_f32 v9, v97, v37, v9
	v_fma_f32 v6, v98, v41, v6
	v_fma_f32 v7, v99, v41, v7
	v_fma_f32 v4, v96, v41, v4
	v_fma_f32 v5, v97, v41, v5
	v_fma_f32 v2, v98, v45, v2
	v_fma_f32 v3, v99, v45, v3
	v_fma_f32 v0, v96, v45, v0
	v_fma_f32 v1, v97, v45, v1
	s_waitcnt vmcnt(1)
	v_fma_f32 v18, v102, v22, v18
	v_fma_f32 v19, v103, v22, v19
	v_fma_f32 v16, v100, v22, v16
	v_fma_f32 v17, v101, v22, v17
	v_fma_f32 v14, v102, v34, v14
	v_fma_f32 v15, v103, v34, v15
	v_fma_f32 v12, v100, v34, v12
	v_fma_f32 v13, v101, v34, v13
	v_fma_f32 v10, v102, v38, v10
	v_fma_f32 v11, v103, v38, v11
	v_fma_f32 v8, v100, v38, v8
	v_fma_f32 v9, v101, v38, v9
	v_fma_f32 v6, v102, v42, v6
	v_fma_f32 v7, v103, v42, v7
	v_fma_f32 v4, v100, v42, v4
	v_fma_f32 v5, v101, v42, v5
	v_fma_f32 v2, v102, v46, v2
	v_fma_f32 v3, v103, v46, v3
	v_fma_f32 v0, v100, v46, v0
	v_fma_f32 v1, v101, v46, v1
	s_waitcnt vmcnt(0)
	v_fma_f32 v18, v106, v116, v18
	v_fma_f32 v19, v107, v116, v19
	v_fma_f32 v16, v104, v116, v16
	v_fma_f32 v17, v105, v116, v17
	v_fma_f32 v14, v106, v118, v14
	v_fma_f32 v15, v107, v118, v15
	v_fma_f32 v12, v104, v118, v12
	v_fma_f32 v13, v105, v118, v13
	v_fma_f32 v10, v106, v120, v10
	v_fma_f32 v11, v107, v120, v11
	v_fma_f32 v8, v104, v120, v8
	v_fma_f32 v9, v105, v120, v9
	v_fma_f32 v6, v106, v122, v6
	v_fma_f32 v7, v107, v122, v7
	v_fma_f32 v4, v104, v122, v4
	v_fma_f32 v5, v105, v122, v5
	v_fma_f32 v2, v106, v124, v2
	v_fma_f32 v3, v107, v124, v3
	v_fma_f32 v0, v104, v124, v0
	v_fma_f32 v1, v105, v124, v1
	s_cbranch_scc0 .LBB0_23
; __device__ __forceinline__ void phase0a(const Params& p, const Ctx& c, float* lds) {
;     ...
; #pragma unroll
;       for (int v = 0; v < 5; ++v) *(f32x4*)(MP + ((size_t)ks * 5 + v) * 24576 + gc) = a[v];
;     }
	v_ashrrev_i32_e32 v63, 31, v62
	v_lshl_add_u64 v[20:21], v[62:63], 2, s[6:7]
	v_mad_i64_i32 v[20:21], s[16:17], v57, s25, v[20:21]
	global_store_dwordx4 v[20:21], v[16:19], off
	v_readlane_b32 s16, v250, 2
	v_readlane_b32 s17, v250, 3
	v_add_co_u32_e32 v16, vcc, 0x18000, v20
	s_nop 0
	v_lshl_add_u64 v[60:61], v[60:61], 0, s[16:17]
	v_addc_co_u32_e32 v17, vcc, 0, v21, vcc
	global_store_dwordx4 v[16:17], v[12:15], off
	s_nop 1
	v_add_co_u32_e32 v12, vcc, 0x30000, v20
	s_nop 1
	v_addc_co_u32_e32 v13, vcc, 0, v21, vcc
	global_store_dwordx4 v[12:13], v[8:11], off
	s_nop 1
	v_add_co_u32_e32 v8, vcc, 0x48000, v20
	s_nop 1
	v_addc_co_u32_e32 v9, vcc, 0, v21, vcc
	global_store_dwordx4 v[8:9], v[4:7], off
	s_nop 1
	v_add_co_u32_e32 v4, vcc, 0x60000, v20
	s_nop 1
	v_addc_co_u32_e32 v5, vcc, 0, v21, vcc
	v_cmp_lt_i64_e32 vcc, s[14:15], v[60:61]
	s_or_b64 s[12:13], vcc, s[12:13]
	global_store_dwordx4 v[4:5], v[0:3], off
	s_andn2_b64 exec, exec, s[12:13]
	s_cbranch_execnz .LBB0_22

; __device__ __forceinline__ void ssm_tables(const Params& p, const Ctx& c) {
;     ...
;   for (long i = c.gtid; i < 2L * 32 * 2 * 33 * 64; i += c.nthr) { const int pp = (int)(i & 63), j = (int)((i >> 6) % 33), idx = (int)((i >> 6) / 33);
;     const int d = idx & 1, g = (idx >> 1) & 31, l = idx >> 6, iidx = (l * 2 + d) * 32 + g;
;     const float lre = p.ssm_a_re[iidx * 64 + pp], lim = p.ssm_a_im[iidx * 64 + pp], dt = expf(p.ssm_log_dt[iidx]);
;     const float mag = expf(lre * dt * (float)j); float sn, cs; my_sincos(lim * dt * (float)j, sn, cs);
;     PW[i] = make_float2(mag * cs, mag * sn); }
.LBB0_43:
	s_or_b64 exec, exec, s[58:59]
	s_waitcnt vmcnt(0)
	v_mul_f32_e32 v4, v12, v17
	v_mul_f32_e32 v4, v4, v16
	v_mul_f32_e32 v5, 0x3fb8aa3b, v4
	v_fma_f32 v12, v4, s2, -v5
	v_rndne_f32_e32 v16, v5
	v_fmac_f32_e32 v12, 0x32a5705f, v4
	v_sub_f32_e32 v5, v5, v16
	v_add_f32_e32 v5, v5, v12
	v_cvt_i32_f32_e32 v12, v16
	v_exp_f32_e32 v5, v5
	v_cmp_ngt_f32_e32 vcc, s22, v4
	v_readlane_b32 s4, v250, 2
	v_readlane_b32 s5, v250, 3
	v_ldexp_f32 v5, v5, v12
	v_cndmask_b32_e32 v5, 0, v5, vcc
	v_cmp_nlt_f32_e32 vcc, s23, v4
	v_cvt_f32_f64_e32 v3, v[2:3]
	v_cvt_f32_f64_e32 v2, v[0:1]
	v_cndmask_b32_e32 v4, v9, v5, vcc
	v_lshl_add_u64 v[14:15], v[14:15], 0, s[4:5]
	v_mul_f32_e64 v0, v4, v2
	v_mul_f32_e64 v1, v4, v3
	v_cmp_lt_i64_e32 vcc, s[56:57], v[14:15]
	global_store_dwordx2 v[10:11], v[0:1], off
	s_or_b64 s[18:19], vcc, s[18:19]
	v_lshl_add_u64 v[10:11], v[10:11], 0, s[16:17]
	s_andn2_b64 exec, exec, s[18:19]
	s_cbranch_execz .LBB0_49

; __device__ __forceinline__ void ssm_tables(const Params& p, const Ctx& c) {
;     ...
;   for (long i = c.gtid; i < 2L * 32 * 2 * 64; i += c.nthr) { const int pp = (int)(i & 63), idx = (int)(i >> 6);
;     const int d = idx & 1, g = (idx >> 1) & 31, l = idx >> 6, iidx = (l * 2 + d) * 32 + g;
;     const float lre = p.ssm_a_re[iidx * 64 + pp], lim = p.ssm_a_im[iidx * 64 + pp], dt = expf(p.ssm_log_dt[iidx]);
;     const float mag = expf(lre * dt); float sn, cs; my_sincos(lim * dt, sn, cs); const float ar = mag * cs, ai = mag * sn;
;     const float nr = ar - 1.f, ni = ai, den = 1.f / (lre * lre + lim * lim), cr = (nr * lre + ni * lim) * den, ci = (ni * lre - nr * lim) * den;
;     const float* br = p.ssm_b_re + ((size_t)iidx * 64 + pp) * 16; const float* bi = p.ssm_b_im + ((size_t)iidx * 64 + pp) * 16;
;     for (int h = 0; h < 16; ++h) BB[((size_t)idx * 64 + pp) * 16 + h] = make_float2(cr * br[h] - ci * bi[h], cr * bi[h] + ci * br[h]); }
.LBB0_52:
	s_or_b64 exec, exec, s[62:63]
	v_lshlrev_b64 v[10:11], 12, v[10:11]
	v_lshl_or_b32 v10, v2, 2, v10
	v_lshl_add_u64 v[16:17], s[14:15], 0, v[10:11]
	v_lshl_add_u64 v[10:11], s[20:21], 0, v[10:11]
	global_load_dword v126, v[10:11], off
	global_load_dword v127, v[10:11], off offset:4
	global_load_dword v128, v[10:11], off offset:8
	global_load_dword v129, v[10:11], off offset:12
	global_load_dword v130, v[10:11], off offset:16
	global_load_dword v131, v[10:11], off offset:20
	global_load_dword v132, v[10:11], off offset:24
	global_load_dword v133, v[10:11], off offset:28
	global_load_dword v134, v[10:11], off offset:32
	global_load_dword v135, v[10:11], off offset:36
	global_load_dword v136, v[10:11], off offset:40
	global_load_dword v137, v[10:11], off offset:44
	global_load_dword v138, v[10:11], off offset:48
	global_load_dword v139, v[10:11], off offset:52
	global_load_dword v140, v[10:11], off offset:56
	global_load_dword v141, v[10:11], off offset:60
	s_waitcnt vmcnt(15)
	v_mov_b32_e32 v18, v126
	global_load_dword v142, v[16:17], off
	global_load_dword v143, v[16:17], off offset:4
	global_load_dword v144, v[16:17], off offset:8
	global_load_dword v145, v[16:17], off offset:12
	global_load_dword v146, v[16:17], off offset:16
	global_load_dword v147, v[16:17], off offset:20
	global_load_dword v148, v[16:17], off offset:24
	global_load_dword v149, v[16:17], off offset:28
	global_load_dword v150, v[16:17], off offset:32
	global_load_dword v151, v[16:17], off offset:36
	global_load_dword v152, v[16:17], off offset:40
	global_load_dword v153, v[16:17], off offset:44
	global_load_dword v154, v[16:17], off offset:48
	global_load_dword v155, v[16:17], off offset:52
	global_load_dword v156, v[16:17], off offset:56
	global_load_dword v157, v[16:17], off offset:60
	s_waitcnt vmcnt(32)
	s_waitcnt vmcnt(15)
	v_mov_b32_e32 v20, v142
	v_mul_f32_e32 v9, v4, v1
	v_lshrrev_b64 v[22:23], 6, v[6:7]
	v_cvt_f32_f64_e32 v19, v[12:13]
	v_cvt_f32_f64_e32 v15, v[14:15]
	v_mul_f32_e64 v12, v4, v4
	v_mul_f32_e64 v13, v5, v5
	v_mov_b32_e32 v14, v5
	v_mul_f32_e32 v5, 0x3fb8aa3b, v9
	v_add_f32_e32 v21, v12, v13
	v_mov_b32_e32 v1, v22
	v_fma_f32 v22, v9, s0, -v5
	v_rndne_f32_e32 v23, v5
	v_div_scale_f32 v24, s[4:5], v21, v21, 1.0
	v_ashrrev_i64 v[12:13], 26, v[0:1]
	v_fmac_f32_e32 v22, 0x32a5705f, v9
	v_sub_f32_e32 v1, v5, v23
	v_rcp_f32_e32 v26, v24
	v_add_f32_e32 v1, v1, v22
	v_cvt_i32_f32_e32 v5, v23
	v_exp_f32_e32 v1, v1
	v_fma_f32 v22, -v24, v26, 1.0
	v_div_scale_f32 v25, vcc, 1.0, v21, 1.0
	v_fmac_f32_e32 v26, v22, v26
	v_ldexp_f32 v1, v1, v5
	v_cmp_ngt_f32_e64 s[4:5], s1, v9
	v_mul_f32_e32 v5, v25, v26
	v_fma_f32 v22, -v24, v5, v25
	v_cndmask_b32_e64 v1, 0, v1, s[4:5]
	v_cmp_nlt_f32_e64 s[4:5], s2, v9
	v_fmac_f32_e32 v5, v22, v26
	v_or_b32_e32 v12, v12, v8
	v_cndmask_b32_e64 v1, v3, v1, s[4:5]
	v_mul_f32_e32 v23, v1, v19
	v_fma_f32 v22, v1, v15, -1.0
	v_fma_f32 v1, -v24, v5, v25
	v_mul_f32_e64 v15, v14, v22
	v_mul_f32_e64 v14, v14, v23
	v_div_fmas_f32 v1, v1, v26, v5
	v_fma_f32 v26, v4, v22, v14
	v_fma_f32 v27, v5, v23, v15
	v_fma_f32 v5, v4, v23, -v15
	v_fma_f32 v4, v4, v22, -v14
	v_div_fixup_f32 v24, v1, v21, 1.0
	v_mov_b32_e32 v27, v5
	v_mul_f32_e64 v4, v24, v26
	v_mul_f32_e64 v5, v24, v27
	v_lshlrev_b64 v[12:13], 7, v[12:13]
	v_lshl_add_u64 v[12:13], s[18:19], 0, v[12:13]
	v_lshl_add_u64 v[6:7], v[6:7], 0, s[22:23]
	v_cmp_lt_i64_e32 vcc, s[60:61], v[6:7]
	s_or_b64 s[24:25], vcc, s[24:25]
	v_mul_f32_e64 v14, v18, v5
	v_mul_f32_e64 v15, v18, v4
	v_fma_f32 v18, v20, v4, -v14
	v_fma_f32 v19, v21, v5, -v15
	v_fma_f32 v14, v20, v4, v14
	v_fma_f32 v15, v20, v5, v15
	v_mov_b32_e32 v19, v15
	global_store_dwordx2 v[12:13], v[18:19], off
	s_waitcnt vmcnt(31)
	v_mov_b32_e32 v14, v127
	s_nop 0
	s_waitcnt vmcnt(15)
	v_mov_b32_e32 v18, v143
	v_mul_f32_e64 v15, v4, v14
	v_mul_f32_e64 v14, v5, v14
	v_fma_f32 v20, v4, v18, -v14
	v_fma_f32 v21, v5, v19, -v15
	v_fma_f32 v14, v4, v18, v14
	v_fma_f32 v15, v5, v18, v15
	s_nop 0
	v_mov_b32_e32 v21, v15
	global_store_dwordx2 v[12:13], v[20:21], off offset:8
	s_waitcnt vmcnt(31)
	v_mov_b32_e32 v14, v128
	s_waitcnt vmcnt(15)
	v_mov_b32_e32 v18, v144
	v_mul_f32_e64 v15, v4, v14
	v_mul_f32_e64 v14, v5, v14
	v_fma_f32 v20, v4, v18, -v14
	v_fma_f32 v21, v5, v19, -v15
	v_fma_f32 v14, v4, v18, v14
	v_fma_f32 v15, v5, v18, v15
	s_nop 0
	v_mov_b32_e32 v21, v15
	global_store_dwordx2 v[12:13], v[20:21], off offset:16
	s_waitcnt vmcnt(31)
	v_mov_b32_e32 v14, v129
	s_waitcnt vmcnt(15)
; __device__ __forceinline__ void ssm_tables(const Params& p, const Ctx& c) {
;     ...
;     const float nr = ar - 1.f, ni = ai, den = 1.f / (lre * lre + lim * lim), cr = (nr * lre + ni * lim) * den, ci = (ni * lre - nr * lim) * den;
;     const float* br = p.ssm_b_re + ((size_t)iidx * 64 + pp) * 16; const float* bi = p.ssm_b_im + ((size_t)iidx * 64 + pp) * 16;
;     for (int h = 0; h < 16; ++h) BB[((size_t)idx * 64 + pp) * 16 + h] = make_float2(cr * br[h] - ci * bi[h], cr * bi[h] + ci * br[h]); }
	v_mov_b32_e32 v18, v145
	v_mul_f32_e64 v15, v4, v14
	v_mul_f32_e64 v14, v5, v14
	v_fma_f32 v20, v4, v18, -v14
	v_fma_f32 v21, v5, v19, -v15
	v_fma_f32 v14, v4, v18, v14
	v_fma_f32 v15, v5, v18, v15
	s_nop 0
	v_mov_b32_e32 v21, v15
	global_store_dwordx2 v[12:13], v[20:21], off offset:24
	s_waitcnt vmcnt(31)
	v_mov_b32_e32 v14, v130
	s_waitcnt vmcnt(15)
	v_mov_b32_e32 v18, v146
	v_mul_f32_e64 v15, v4, v14
	v_mul_f32_e64 v14, v5, v14
	v_fma_f32 v20, v4, v18, -v14
	v_fma_f32 v21, v5, v19, -v15
	v_fma_f32 v14, v4, v18, v14
	v_fma_f32 v15, v5, v18, v15
	s_nop 0
	v_mov_b32_e32 v21, v15
	global_store_dwordx2 v[12:13], v[20:21], off offset:32
	s_waitcnt vmcnt(31)
	v_mov_b32_e32 v14, v131
	s_waitcnt vmcnt(15)
	v_mov_b32_e32 v18, v147
	v_mul_f32_e64 v15, v4, v14
	v_mul_f32_e64 v14, v5, v14
	v_fma_f32 v20, v4, v18, -v14
	v_fma_f32 v21, v5, v19, -v15
	v_fma_f32 v14, v4, v18, v14
	v_fma_f32 v15, v5, v18, v15
	s_nop 0
	v_mov_b32_e32 v21, v15
	global_store_dwordx2 v[12:13], v[20:21], off offset:40
	s_waitcnt vmcnt(31)
	v_mov_b32_e32 v14, v132
	s_waitcnt vmcnt(15)
	v_mov_b32_e32 v18, v148
	v_mul_f32_e64 v15, v4, v14
	v_mul_f32_e64 v14, v5, v14
	v_fma_f32 v20, v4, v18, -v14
	v_fma_f32 v21, v5, v19, -v15
	v_fma_f32 v14, v4, v18, v14
	v_fma_f32 v15, v5, v18, v15
	s_nop 0
	v_mov_b32_e32 v21, v15
	global_store_dwordx2 v[12:13], v[20:21], off offset:48
	s_waitcnt vmcnt(31)
	v_mov_b32_e32 v14, v133
	s_waitcnt vmcnt(15)
	v_mov_b32_e32 v18, v149
	v_mul_f32_e64 v15, v4, v14
	v_mul_f32_e64 v14, v5, v14
	v_fma_f32 v20, v4, v18, -v14
	v_fma_f32 v21, v5, v19, -v15
	v_fma_f32 v14, v4, v18, v14
	v_fma_f32 v15, v5, v18, v15
	s_nop 0
	v_mov_b32_e32 v21, v15
	global_store_dwordx2 v[12:13], v[20:21], off offset:56
	s_waitcnt vmcnt(31)
	v_mov_b32_e32 v14, v134
	s_waitcnt vmcnt(15)
	v_mov_b32_e32 v18, v150
	v_mul_f32_e64 v15, v4, v14
	v_mul_f32_e64 v14, v5, v14
	v_fma_f32 v20, v4, v18, -v14
	v_fma_f32 v21, v5, v19, -v15
	v_fma_f32 v14, v4, v18, v14
	v_fma_f32 v15, v5, v18, v15
	s_nop 0
	v_mov_b32_e32 v21, v15
	global_store_dwordx2 v[12:13], v[20:21], off offset:64
	s_waitcnt vmcnt(31)
	v_mov_b32_e32 v14, v135
	s_waitcnt vmcnt(15)
	v_mov_b32_e32 v18, v151
	v_mul_f32_e64 v15, v4, v14
	v_mul_f32_e64 v14, v5, v14
	v_fma_f32 v20, v4, v18, -v14
	v_fma_f32 v21, v5, v19, -v15
	v_fma_f32 v14, v4, v18, v14
	v_fma_f32 v15, v5, v18, v15
	s_nop 0
	v_mov_b32_e32 v21, v15
	global_store_dwordx2 v[12:13], v[20:21], off offset:72
	s_waitcnt vmcnt(31)
	v_mov_b32_e32 v14, v136
	s_waitcnt vmcnt(15)
	v_mov_b32_e32 v18, v152
	v_mul_f32_e64 v15, v4, v14
	v_mul_f32_e64 v14, v5, v14
	v_fma_f32 v20, v4, v18, -v14
	v_fma_f32 v21, v5, v19, -v15
	v_fma_f32 v14, v4, v18, v14
	v_fma_f32 v15, v5, v18, v15
	s_nop 0
	v_mov_b32_e32 v21, v15
	global_store_dwordx2 v[12:13], v[20:21], off offset:80
	s_waitcnt vmcnt(31)
	v_mov_b32_e32 v14, v137
	s_waitcnt vmcnt(15)
	v_mov_b32_e32 v18, v153
	v_mul_f32_e64 v15, v4, v14
	v_mul_f32_e64 v14, v5, v14
	v_fma_f32 v20, v4, v18, -v14
	v_fma_f32 v21, v5, v19, -v15
	v_fma_f32 v14, v4, v18, v14
	v_fma_f32 v15, v5, v18, v15
	s_nop 0
	v_mov_b32_e32 v21, v15
	global_store_dwordx2 v[12:13], v[20:21], off offset:88
	s_waitcnt vmcnt(31)
	v_mov_b32_e32 v14, v138
	s_waitcnt vmcnt(15)
	v_mov_b32_e32 v18, v154
	v_mul_f32_e64 v15, v4, v14
	v_mul_f32_e64 v14, v5, v14
	v_fma_f32 v20, v4, v18, -v14
	v_fma_f32 v21, v5, v19, -v15
	v_fma_f32 v14, v4, v18, v14
	v_fma_f32 v15, v5, v18, v15
	s_nop 0
	v_mov_b32_e32 v21, v15
	global_store_dwordx2 v[12:13], v[20:21], off offset:96
	s_waitcnt vmcnt(31)
	v_mov_b32_e32 v14, v139
	s_waitcnt vmcnt(15)
	v_mov_b32_e32 v18, v155
	v_mul_f32_e64 v15, v4, v14
	v_mul_f32_e64 v14, v5, v14
	v_fma_f32 v20, v4, v18, -v14
	v_fma_f32 v21, v5, v19, -v15
	v_fma_f32 v14, v4, v18, v14
	v_fma_f32 v15, v5, v18, v15
	s_nop 0
	v_mov_b32_e32 v21, v15
	global_store_dwordx2 v[12:13], v[20:21], off offset:104
	s_waitcnt vmcnt(31)
	v_mov_b32_e32 v14, v140
	s_waitcnt vmcnt(15)
	v_mov_b32_e32 v18, v156
	v_mul_f32_e64 v15, v4, v14
	v_mul_f32_e64 v14, v5, v14
	v_fma_f32 v20, v4, v18, -v14
	v_fma_f32 v21, v5, v19, -v15
	v_fma_f32 v14, v4, v18, v14
	v_fma_f32 v15, v5, v18, v15
	s_nop 0
	v_mov_b32_e32 v21, v15
	global_store_dwordx2 v[12:13], v[20:21], off offset:112
	s_waitcnt vmcnt(31)
	v_mov_b32_e32 v10, v141
	s_nop 0
	s_waitcnt vmcnt(15)
	v_mov_b32_e32 v14, v157
	v_mul_f32_e64 v11, v4, v10
	v_mul_f32_e64 v10, v5, v10
	v_fma_f32 v16, v4, v14, -v10
	v_fma_f32 v17, v5, v15, -v11
	v_fma_f32 v4, v4, v14, v10
	v_fma_f32 v5, v5, v14, v11
	s_nop 0
	v_mov_b32_e32 v17, v5
	global_store_dwordx2 v[12:13], v[16:17], off offset:120
	s_andn2_b64 exec, exec, s[24:25]
	s_cbranch_execz .LBB0_56

; __device__ __forceinline__ unsigned cvtpk(float lo, float hi) { unsigned r; asm volatile("v_cvt_pk_bf16_f32 %0, %1, %2" : "=v"(r) : "v"(lo), "v"(hi)); return r; }
; __device__ __forceinline__ void fold_four(const Params& p, const Ctx& c, int l, float* lds) {
;     ...
;     const int kq = c.tid & 15, dq = c.tid >> 4;
;     f32x4 acc[4] = {};
;     for (int cc = 0; cc < 128; ++cc) {
;       const f32x4 a = *(const f32x4*)(WlT + cc * 68 + kq * 4), w = *(const f32x4*)(Wc + cc * 128 + dq * 4);
; #pragma unroll
;       for (int di = 0; di < 4; ++di) acc[di] += a * w[di];
;     }
; #pragma unroll
;     for (int di = 0; di < 4; ++di) { u32x2 o = {cvtpk(acc[di][0], acc[di][1]), cvtpk(acc[di][2], acc[di][3])};
;       *(u32x2*)(dstb + (size_t)(3584 + cs * 512 + g * 128 + dq * 4 + di) * DM + k0 + kq * 4) = o; }
.LBB0_173:
	v_add_u32_e32 v35, s24, v22
	ds_read_b128 v[36:39], v34
	ds_read_b128 v[40:43], v34 offset:512
	ds_read_b128 v[44:47], v34 offset:1024
	ds_read_b128 v[48:51], v34 offset:1536
	ds_read_b128 v[52:55], v34 offset:2048
	ds_read_b128 v[56:59], v34 offset:2560
	ds_read_b128 v[60:63], v34 offset:3072
	ds_read_b128 v[64:67], v34 offset:3584
	s_waitcnt lgkmcnt(7)
	v_mov_b32_e32 v100, v39
	ds_read_b128 v[68:71], v35
	ds_read_b128 v[72:75], v35 offset:272
	ds_read_b128 v[76:79], v35 offset:544
	ds_read_b128 v[80:83], v35 offset:816
	ds_read_b128 v[84:87], v35 offset:1088
	ds_read_b128 v[88:91], v35 offset:1360
	ds_read_b128 v[92:95], v35 offset:1632
	ds_read_b128 v[96:99], v35 offset:1904
	s_waitcnt lgkmcnt(14)
	v_mov_b32_e32 v102, v43
	s_waitcnt lgkmcnt(7)
	v_fma_f32 v20, v68, v36, v20
	v_fma_f32 v21, v69, v36, v21
	v_fma_f32 v18, v70, v36, v18
	v_fma_f32 v19, v71, v36, v19
	v_fma_f32 v16, v68, v37, v16
	v_fma_f32 v17, v69, v37, v17
	v_fma_f32 v14, v70, v37, v14
	v_fma_f32 v15, v71, v37, v15
	v_fma_f32 v12, v68, v38, v12
	v_fma_f32 v13, v69, v38, v13
	v_fma_f32 v10, v70, v38, v10
	v_fma_f32 v11, v71, v38, v11
	v_fma_f32 v6, v68, v100, v6
	v_fma_f32 v7, v69, v100, v7
	v_fma_f32 v8, v70, v100, v8
	v_fma_f32 v9, v71, v100, v9
	v_mov_b32_e32 v104, v47
	s_waitcnt lgkmcnt(6)
	v_fma_f32 v18, v74, v40, v18
	v_fma_f32 v19, v75, v40, v19
	v_fma_f32 v20, v72, v40, v20
	v_fma_f32 v21, v73, v40, v21
	v_fma_f32 v14, v74, v41, v14
	v_fma_f32 v15, v75, v41, v15
	v_fma_f32 v16, v72, v41, v16
	v_fma_f32 v17, v73, v41, v17
	v_fma_f32 v10, v74, v42, v10
	v_fma_f32 v11, v75, v42, v11
	v_fma_f32 v12, v72, v42, v12
	v_fma_f32 v13, v73, v42, v13
	v_fma_f32 v8, v74, v102, v8
	v_fma_f32 v9, v75, v102, v9
	v_fma_f32 v6, v72, v102, v6
	v_fma_f32 v7, v73, v102, v7
	v_mov_b32_e32 v106, v51
	s_waitcnt lgkmcnt(5)
	v_fma_f32 v18, v78, v44, v18
	v_fma_f32 v19, v79, v44, v19
	v_fma_f32 v20, v76, v44, v20
	v_fma_f32 v21, v77, v44, v21
	v_fma_f32 v14, v78, v45, v14
	v_fma_f32 v15, v79, v45, v15
	v_fma_f32 v16, v76, v45, v16
	v_fma_f32 v17, v77, v45, v17
	v_fma_f32 v12, v76, v46, v12
	v_fma_f32 v13, v77, v46, v13
	v_fma_f32 v10, v78, v46, v10
	v_fma_f32 v11, v79, v46, v11
	v_fma_f32 v6, v76, v104, v6
	v_fma_f32 v7, v77, v104, v7
	v_fma_f32 v8, v78, v104, v8
	v_fma_f32 v9, v79, v104, v9
	v_mov_b32_e32 v108, v55
	s_waitcnt lgkmcnt(4)
	v_fma_f32 v18, v82, v48, v18
	v_fma_f32 v19, v83, v48, v19
	v_fma_f32 v20, v80, v48, v20
	v_fma_f32 v21, v81, v48, v21
	v_fma_f32 v14, v82, v49, v14
	v_fma_f32 v15, v83, v49, v15
	v_fma_f32 v16, v80, v49, v16
	v_fma_f32 v17, v81, v49, v17
	v_fma_f32 v10, v82, v50, v10
	v_fma_f32 v11, v83, v50, v11
	v_fma_f32 v12, v80, v50, v12
	v_fma_f32 v13, v81, v50, v13
	v_fma_f32 v8, v82, v106, v8
	v_fma_f32 v9, v83, v106, v9
	v_fma_f32 v6, v80, v106, v6
	v_fma_f32 v7, v81, v106, v7
	v_mov_b32_e32 v110, v59
	s_waitcnt lgkmcnt(3)
	v_fma_f32 v18, v86, v52, v18
	v_fma_f32 v19, v87, v52, v19
	v_fma_f32 v20, v84, v52, v20
	v_fma_f32 v21, v85, v52, v21
	v_fma_f32 v14, v86, v53, v14
	v_fma_f32 v15, v87, v53, v15
	v_fma_f32 v16, v84, v53, v16
	v_fma_f32 v17, v85, v53, v17
	v_fma_f32 v12, v84, v54, v12
	v_fma_f32 v13, v85, v54, v13
	v_fma_f32 v10, v86, v54, v10
	v_fma_f32 v11, v87, v54, v11
	v_fma_f32 v6, v84, v108, v6
	v_fma_f32 v7, v85, v108, v7
	v_fma_f32 v8, v86, v108, v8
	v_fma_f32 v9, v87, v108, v9
	v_mov_b32_e32 v112, v63
	s_waitcnt lgkmcnt(2)
	v_fma_f32 v18, v90, v56, v18
	v_fma_f32 v19, v91, v56, v19
	v_fma_f32 v20, v88, v56, v20
	v_fma_f32 v21, v89, v56, v21
	v_fma_f32 v14, v90, v57, v14
	v_fma_f32 v15, v91, v57, v15
	v_fma_f32 v16, v88, v57, v16
	v_fma_f32 v17, v89, v57, v17
	v_fma_f32 v10, v90, v58, v10
	v_fma_f32 v11, v91, v58, v11
	v_fma_f32 v12, v88, v58, v12
	v_fma_f32 v13, v89, v58, v13
	v_fma_f32 v8, v90, v110, v8
	v_fma_f32 v9, v91, v110, v9
	v_fma_f32 v6, v88, v110, v6
	v_fma_f32 v7, v89, v110, v7
	s_addk_i32 s24, 0x880
	v_mov_b32_e32 v114, v67
	s_waitcnt lgkmcnt(1)
	v_fma_f32 v18, v94, v60, v18
	v_fma_f32 v19, v95, v60, v19
	v_fma_f32 v20, v92, v60, v20
	v_fma_f32 v21, v93, v60, v21
	v_fma_f32 v14, v94, v61, v14
	v_fma_f32 v15, v95, v61, v15
	v_fma_f32 v16, v92, v61, v16
	v_fma_f32 v17, v93, v61, v17
	v_fma_f32 v12, v92, v62, v12
	v_fma_f32 v13, v93, v62, v13
	v_fma_f32 v10, v94, v62, v10
	v_fma_f32 v11, v95, v62, v11
	v_fma_f32 v6, v92, v112, v6
	v_fma_f32 v7, v93, v112, v7
	v_fma_f32 v8, v94, v112, v8
	v_fma_f32 v9, v95, v112, v9
	v_add_u32_e32 v34, 0x1000, v34
	s_cmpk_eq_u32 s24, 0x8800
	s_waitcnt lgkmcnt(0)
	v_fma_f32 v18, v98, v64, v18
	v_fma_f32 v19, v99, v64, v19
	v_fma_f32 v20, v96, v64, v20
	v_fma_f32 v21, v97, v64, v21
	v_fma_f32 v14, v98, v65, v14
	v_fma_f32 v15, v99, v65, v15
	v_fma_f32 v16, v96, v65, v16
	v_fma_f32 v17, v97, v65, v17
	v_fma_f32 v10, v98, v66, v10
	v_fma_f32 v11, v99, v66, v11
	v_fma_f32 v12, v96, v66, v12
	v_fma_f32 v13, v97, v66, v13
	v_fma_f32 v8, v98, v114, v8
	v_fma_f32 v9, v99, v114, v9
	v_fma_f32 v6, v96, v114, v6
	v_fma_f32 v7, v97, v114, v7
	s_cbranch_scc0 .LBB0_173
	s_lshl_b32 s24, s29, 9
	s_add_i32 s24, s24, s38
	v_add_u32_e32 v34, s24, v23
	s_lshl_b32 s34, s28, 1
	v_ashrrev_i32_e32 v35, 31, v34
	v_lshl_add_u64 v[36:37], v[2:3], 0, s[34:35]
	v_cvt_pk_bf16_f32 v20, v20, v21
	v_cvt_pk_bf16_f32 v21, v18, v19
	v_lshlrev_b64 v[18:19], 12, v[34:35]
	v_lshl_add_u64 v[18:19], v[36:37], 0, v[18:19]
	global_store_dwordx2 v[18:19], v[20:21], off
	v_cvt_pk_bf16_f32 v16, v16, v17
	v_cvt_pk_bf16_f32 v17, v14, v15
	v_or_b32_e32 v14, 1, v34
	v_ashrrev_i32_e32 v15, 31, v14
	v_lshlrev_b64 v[14:15], 12, v[14:15]
	v_lshl_add_u64 v[14:15], v[36:37], 0, v[14:15]
	global_store_dwordx2 v[14:15], v[16:17], off
	v_cvt_pk_bf16_f32 v12, v12, v13
	v_cvt_pk_bf16_f32 v13, v10, v11
	v_or_b32_e32 v10, 2, v34
	v_ashrrev_i32_e32 v11, 31, v10
	v_lshlrev_b64 v[10:11], 12, v[10:11]
	v_lshl_add_u64 v[10:11], v[36:37], 0, v[10:11]
	global_store_dwordx2 v[10:11], v[12:13], off
	v_cvt_pk_bf16_f32 v6, v6, v7
	v_cvt_pk_bf16_f32 v7, v8, v9
	v_or_b32_e32 v8, 3, v34
	v_ashrrev_i32_e32 v9, 31, v8
	v_lshlrev_b64 v[8:9], 12, v[8:9]
	s_add_i32 s0, s0, s26
	v_lshl_add_u64 v[8:9], v[36:37], 0, v[8:9]
	s_cmpk_gt_i32 s0, 0xff
	global_store_dwordx2 v[8:9], v[6:7], off
	s_barrier
	s_cbranch_scc0 .LBB0_144

; __device__ __forceinline__ void ssm_build_mef(const Params& p, const Ctx& c, int l) {
;     ...
;   for (long i = c.gtid; i < 32L * 2 * 32 * 256; i += c.nthr) { const int hp = (int)(i & 15), h = (int)((i >> 4) & 15), j = (int)((i >> 8) & 31), gd = (int)(i >> 13), d = gd & 1, g = gd >> 1;
;     const size_t ci = ((size_t)((l * 2 + d) * 32 + g) * 16 + h) * 64; const float2* pw = PW + ((size_t)gd * 33 + j) * 64; const float2* bb = BB + (size_t)gd * 64 * 16 + hp; float a = 0.f;
;     for (int pp = 0; pp < 64; ++pp) { const float cr = p.ssm_c_re[ci + pp], cim = p.ssm_c_im[ci + pp]; const float2 b = bb[pp * 16], w = pw[pp];
;       const float wr = cr * b.x - cim * b.y, wi = cr * b.y + cim * b.x; a += wr * w.x - wi * w.y; }
;     MK[i] = a; }
.LBB0_178:
	v_lshl_add_u64 v[28:29], v[18:19], 0, s[36:37]
	v_lshl_add_u64 v[32:33], s[10:11], 0, v[12:13]
	v_lshl_add_u64 v[30:31], v[16:17], 0, s[36:37]
	global_load_dwordx4 v[20:23], v[28:29], off
	global_load_dwordx4 v[24:27], v[30:31], off
	v_add_co_u32_e32 v28, vcc, 0xabcc000, v32
	v_lshl_add_u64 v[34:35], s[10:11], 0, v[14:15]
	s_nop 0
	v_addc_co_u32_e32 v29, vcc, 0, v33, vcc
	v_add_co_u32_e32 v38, vcc, 0xa9bc000, v34
	global_load_dwordx2 v[40:41], v[28:29], off
	global_load_dwordx2 v[42:43], v[28:29], off offset:128
	global_load_dwordx2 v[44:45], v[28:29], off offset:256
	global_load_dwordx2 v[46:47], v[28:29], off offset:384
	v_addc_co_u32_e32 v39, vcc, 0, v35, vcc
	v_lshl_add_u64 v[36:37], v[34:35], 0, s[20:21]
	global_load_dwordx4 v[28:31], v[38:39], off
	global_load_dwordx4 v[32:35], v[36:37], off offset:16
	s_add_u32 s36, s36, 16
	s_addc_u32 s37, s37, 0
	v_lshl_add_u64 v[12:13], v[12:13], 0, s[24:25]
	v_lshl_add_u64 v[14:15], v[14:15], 0, 32
	s_cmpk_eq_i32 s36, 0x100
	v_lshl_add_u64 v[158:159], v[18:19], 0, s[36:37]
	v_lshl_add_u64 v[162:163], s[10:11], 0, v[12:13]
	v_lshl_add_u64 v[160:161], v[16:17], 0, s[36:37]
	global_load_dwordx4 v[150:153], v[158:159], off
	global_load_dwordx4 v[154:157], v[160:161], off
	v_add_co_u32_e32 v158, vcc, 0xabcc000, v162
	v_lshl_add_u64 v[164:165], s[10:11], 0, v[14:15]
	s_nop 0
	v_addc_co_u32_e32 v159, vcc, 0, v163, vcc
	v_add_co_u32_e32 v168, vcc, 0xa9bc000, v164
	global_load_dwordx2 v[170:171], v[158:159], off
	global_load_dwordx2 v[172:173], v[158:159], off offset:128
	global_load_dwordx2 v[174:175], v[158:159], off offset:256
	global_load_dwordx2 v[176:177], v[158:159], off offset:384
	v_addc_co_u32_e32 v169, vcc, 0, v165, vcc
	v_lshl_add_u64 v[166:167], v[164:165], 0, s[20:21]
	global_load_dwordx4 v[158:161], v[168:169], off
	global_load_dwordx4 v[162:165], v[166:167], off offset:16
	s_add_u32 s36, s36, 16
	s_addc_u32 s37, s37, 0
	v_lshl_add_u64 v[12:13], v[12:13], 0, s[24:25]
	v_lshl_add_u64 v[14:15], v[14:15], 0, 32
	s_cmpk_eq_i32 s36, 0x100
	s_waitcnt vmcnt(15)
	v_mov_b32_e32 v36, v21
	s_waitcnt vmcnt(14)
	v_mov_b32_e32 v50, v27
	v_mov_b32_e32 v38, v23
	v_mov_b32_e32 v48, v23
	s_waitcnt vmcnt(13)
	v_mul_f32_e64 v52, v24, v41
	v_mul_f32_e64 v53, v24, v40
	s_waitcnt vmcnt(12)
	v_mul_f32_e64 v24, v25, v43
	v_mul_f32_e64 v25, v25, v42
	v_fma_f32 v54, v20, v40, -v52
	v_fma_f32 v55, v21, v41, -v53
	v_fma_f32 v40, v20, v40, v52
	v_fma_f32 v41, v20, v41, v53
	s_waitcnt vmcnt(11)
	v_mul_f32_e64 v27, v26, v44
	v_mul_f32_e64 v26, v26, v45
	v_fma_f32 v36, v36, v42, -v24
	v_fma_f32 v37, v37, v43, -v25
	v_fma_f32 v20, v21, v42, v24
	v_fma_f32 v21, v21, v43, v25
	v_mov_b32_e32 v55, v41
	s_waitcnt vmcnt(10)
	v_mul_f32_e64 v51, v50, v46
	v_mul_f32_e64 v50, v50, v47
	v_fma_f32 v24, v22, v44, -v26
	v_fma_f32 v25, v23, v45, -v27
	v_fma_f32 v23, v22, v45, v27
	v_fma_f32 v22, v22, v44, v26
	v_mov_b32_e32 v37, v21
	s_waitcnt vmcnt(9)
	v_mul_f32_e64 v20, v28, v54
	v_mul_f32_e64 v21, v29, v55
	v_fma_f32 v26, v38, v46, -v50
	v_fma_f32 v27, v39, v47, -v51
	v_fma_f32 v38, v48, v46, v50
	v_fma_f32 v39, v48, v47, v51
	v_mov_b32_e32 v25, v23
	v_mul_f32_e64 v22, v30, v36
	v_mul_f32_e64 v23, v31, v37
	v_sub_f32_e32 v20, v20, v21
	v_mov_b32_e32 v27, v39
	s_waitcnt vmcnt(8)
	v_mul_f32_e64 v24, v32, v24
	v_mul_f32_e64 v25, v33, v25
	v_sub_f32_e32 v21, v22, v23
	v_add_f32_e32 v6, v6, v20
	v_mul_f32_e64 v26, v34, v26
	v_mul_f32_e64 v27, v35, v27
	v_sub_f32_e32 v22, v24, v25
	v_add_f32_e32 v6, v6, v21
	v_sub_f32_e32 v23, v26, v27
	v_add_f32_e32 v6, v6, v22
	v_add_f32_e32 v6, v6, v23
	s_waitcnt vmcnt(7)
	v_mov_b32_e32 v166, v151
	s_waitcnt vmcnt(6)
	v_mov_b32_e32 v180, v157
	v_mov_b32_e32 v168, v153
	v_mov_b32_e32 v178, v153
	s_waitcnt vmcnt(5)
	v_mul_f32_e64 v182, v154, v171
	v_mul_f32_e64 v183, v154, v170
	s_waitcnt vmcnt(4)
	v_mul_f32_e64 v154, v155, v173
	v_mul_f32_e64 v155, v155, v172
	v_fma_f32 v184, v150, v170, -v182
	v_fma_f32 v185, v151, v171, -v183
	v_fma_f32 v170, v150, v170, v182
	v_fma_f32 v171, v150, v171, v183
	s_waitcnt vmcnt(3)
	v_mul_f32_e64 v157, v156, v174
	v_mul_f32_e64 v156, v156, v175
	v_fma_f32 v166, v166, v172, -v154
	v_fma_f32 v167, v167, v173, -v155
	v_fma_f32 v150, v151, v172, v154
	v_fma_f32 v151, v151, v173, v155
	v_mov_b32_e32 v185, v171
	s_waitcnt vmcnt(2)
	v_mul_f32_e64 v181, v180, v176
	v_mul_f32_e64 v180, v180, v177
	v_fma_f32 v154, v152, v174, -v156
	v_fma_f32 v155, v153, v175, -v157
	v_fma_f32 v153, v152, v175, v157
	v_fma_f32 v152, v152, v174, v156
	v_mov_b32_e32 v167, v151
	s_waitcnt vmcnt(1)
	v_mul_f32_e64 v150, v158, v184
	v_mul_f32_e64 v151, v159, v185
	v_fma_f32 v156, v168, v176, -v180
	v_fma_f32 v157, v169, v177, -v181
	v_fma_f32 v168, v178, v176, v180
	v_fma_f32 v169, v178, v177, v181
	v_mov_b32_e32 v155, v153
	v_mul_f32_e64 v152, v160, v166
	v_mul_f32_e64 v153, v161, v167
	v_sub_f32_e32 v150, v150, v151
	v_mov_b32_e32 v157, v169
	s_waitcnt vmcnt(0)
	v_mul_f32_e64 v154, v162, v154
	v_mul_f32_e64 v155, v163, v155
	v_sub_f32_e32 v151, v152, v153
	v_add_f32_e32 v6, v6, v150
	v_mul_f32_e64 v156, v164, v156
	v_mul_f32_e64 v157, v165, v157
	v_sub_f32_e32 v152, v154, v155
	v_add_f32_e32 v6, v6, v151
	v_sub_f32_e32 v153, v156, v157
	v_add_f32_e32 v6, v6, v152
	v_add_f32_e32 v6, v6, v153
	s_cbranch_scc0 .LBB0_178
	v_readlane_b32 s22, v250, 2
	v_readlane_b32 s23, v250, 3
	v_lshl_add_u64 v[12:13], v[10:11], 2, s[14:15]
	v_lshl_add_u64 v[8:9], v[8:9], 0, s[18:19]
	v_lshl_add_u64 v[10:11], v[10:11], 0, s[22:23]
	v_cmp_lt_i64_e32 vcc, s[34:35], v[10:11]
	s_or_b64 s[16:17], vcc, s[16:17]
	global_store_dword v[12:13], v6, off
	s_andn2_b64 exec, exec, s[16:17]
	s_cbranch_execnz .LBB0_177
	s_or_b64 exec, exec, s[16:17]
	s_add_u32 s14, s10, 0xa9bc000
	s_addc_u32 s15, s11, 0
	s_add_u32 s4, s10, 0xabcc000
	s_addc_u32 s5, s11, 0
	s_add_u32 s6, s10, 0xc8cc000
	s_addc_u32 s7, s11, 0
	s_lshl_b64 s[0:1], s[12:13], 12
	v_lshl_add_u64 v[4:5], v[4:5], 3, s[0:1]
	s_lshl_b64 s[16:17], s[30:31], 12
	s_mov_b64 s[12:13], 0
	s_movk_i32 s0, 0x80
	v_mov_b32_e32 v7, 0
	s_mov_b64 s[18:19], 0x7ffff
	v_mov_b64_e32 v[8:9], v[0:1]
; __device__ __forceinline__ unsigned cvtpk(float lo, float hi) { unsigned r; asm volatile("v_cvt_pk_bf16_f32 %0, %1, %2" : "=v"(r) : "v"(lo), "v"(hi)); return r; }
; __device__ __forceinline__ void ssm_build_mef(const Params& p, const Ctx& c, int l) {
;     ...
;   for (long i = c.gtid; i < 32L * 256 * 32 * 2; i += c.nthr) { const int hh = (int)(i & 1), s = (int)((i >> 1) & 31), n = (int)((i >> 6) & 255), g = (int)(i >> 14), ri = n & 1, pp = (n >> 1) & 63, d = n >> 7;
;     const int gd = g * 2 + d, e = d ? s : 31 - s; const float2 w = PW[((size_t)gd * 33 + e) * 64 + pp]; const float2* bb = BB + ((size_t)gd * 64 + pp) * 16 + hh * 8; float v[8];
; #pragma unroll
;     for (int k = 0; k < 8; ++k) { const float2 b = bb[k]; v[k] = ri ? (w.x * b.y + w.y * b.x) : (w.x * b.x - w.y * b.y); }
;     u32x4 o = {cvtpk(v[0], v[1]), cvtpk(v[2], v[3]), cvtpk(v[4], v[5]), cvtpk(v[6], v[7])}; *(u32x4*)(EM + ((size_t)g * 256 + n) * 512 + s * 16 + hh * 8) = o; }
;   for (long i = c.gtid; i < 32L * 512 * 2 * 16; i += c.nthr) { const int pq = (int)(i & 15), d = (int)((i >> 4) & 1), n = (int)((i >> 5) & 511), g = (int)(i >> 14), h = n & 15, t = n >> 4;
;     const int gd = g * 2 + d, f = d ? 32 - t : t + 1; const size_t ci = ((size_t)((l * 2 + d) * 32 + g) * 16 + h) * 64 + pq * 4; const float2* pw = PW + ((size_t)gd * 33 + f) * 64 + pq * 4; float v[8];
; #pragma unroll
;     for (int k = 0; k < 4; ++k) { const float cr = p.ssm_c_re[ci + k], cim = p.ssm_c_im[ci + k]; const float2 w = pw[k]; v[2 * k] = cr * w.x - cim * w.y; v[2 * k + 1] = -(cr * w.y + cim * w.x); }
;     u32x4 o = {cvtpk(v[0], v[1]), cvtpk(v[2], v[3]), cvtpk(v[4], v[5]), cvtpk(v[6], v[7])}; *(u32x4*)(TF + ((size_t)g * 512 + n) * 768 + 512 + d * 128 + pq * 8) = o; }
.LBB0_181:
	v_lshrrev_b32_e32 v6, 1, v8
	v_lshrrev_b32_e32 v10, 6, v8
	v_bfe_u32 v33, v8, 6, 8
	v_bfe_u32 v32, v8, 1, 5
	v_alignbit_b32 v27, v9, v8, 14
	v_bfe_u32 v10, v10, 7, 1
	v_bitop3_b32 v6, v6, 31, v6 bitop3:0xc
	v_cmp_gt_u32_e32 vcc, s0, v33
	v_lshl_or_b32 v10, v27, 1, v10
	v_bfe_u32 v14, v8, 7, 6
	v_cndmask_b32_e32 v6, v32, v6, vcc
	v_mad_i64_i32 v[12:13], s[20:21], v10, 33, v[6:7]
	v_ashrrev_i32_e32 v11, 31, v10
	v_lshlrev_b64 v[12:13], 9, v[12:13]
	v_lshlrev_b32_e32 v6, 3, v14
	v_lshlrev_b64 v[10:11], 13, v[10:11]
	v_lshl_add_u64 v[12:13], s[14:15], 0, v[12:13]
	v_and_b32_e32 v34, 8, v4
	v_lshl_add_u64 v[10:11], s[4:5], 0, v[10:11]
	v_lshl_add_u64 v[12:13], v[12:13], 0, v[6:7]
	v_lshlrev_b32_e32 v6, 7, v14
	v_lshl_add_u64 v[10:11], v[10:11], 0, v[6:7]
	v_lshlrev_b32_e32 v6, 3, v34
	global_load_dwordx2 v[28:29], v[12:13], off
	v_lshl_add_u64 v[30:31], v[10:11], 0, v[6:7]
	global_load_dwordx4 v[10:13], v[30:31], off
	global_load_dwordx4 v[14:17], v[30:31], off offset:16
	global_load_dwordx4 v[18:21], v[30:31], off offset:32
	global_load_dwordx4 v[22:25], v[30:31], off offset:48
	v_mov_b32_e32 v26, v7
	v_ashrrev_i64 v[26:27], 24, v[26:27]
	v_or_b32_e32 v26, v26, v33
	v_lshlrev_b64 v[26:27], 10, v[26:27]
	v_and_b32_e32 v46, 64, v8
	v_lshl_add_u64 v[8:9], v[8:9], 0, s[22:23]
	v_lshl_add_u64 v[26:27], s[6:7], 0, v[26:27]
	v_lshlrev_b32_e32 v6, 5, v32
	v_cmp_lt_i64_e32 vcc, s[18:19], v[8:9]
	v_lshl_add_u64 v[26:27], v[26:27], 0, v[6:7]
	v_lshlrev_b32_e32 v6, 1, v34
	s_or_b64 s[12:13], vcc, s[12:13]
	v_lshl_add_u64 v[26:27], v[26:27], 0, v[6:7]
	v_cmp_eq_u32_e32 vcc, 0, v46
	v_lshl_add_u64 v[4:5], v[4:5], 0, s[16:17]
	s_waitcnt vmcnt(3)
	v_mul_f32_e64 v30, v29, v10
	v_mul_f32_e64 v31, v28, v11
	v_mul_f32_e64 v10, v28, v10
	v_mul_f32_e64 v11, v29, v11
	v_mul_f32_e64 v32, v29, v12
	v_mul_f32_e64 v33, v28, v13
	v_mul_f32_e64 v12, v28, v12
	v_mul_f32_e64 v13, v29, v13
	s_waitcnt vmcnt(2)
	v_mul_f32_e64 v34, v29, v14
	v_mul_f32_e64 v35, v28, v15
	v_mul_f32_e64 v14, v28, v14
	v_mul_f32_e64 v15, v29, v15
	v_mul_f32_e64 v36, v29, v16
	v_mul_f32_e64 v37, v28, v17
	v_mul_f32_e64 v16, v28, v16
	v_mul_f32_e64 v17, v29, v17
	s_waitcnt vmcnt(1)
	v_mul_f32_e64 v38, v29, v18
	v_mul_f32_e64 v39, v28, v19
	v_mul_f32_e64 v18, v28, v18
	v_mul_f32_e64 v19, v29, v19
	v_mul_f32_e64 v40, v29, v20
	v_mul_f32_e64 v41, v28, v21
	v_mul_f32_e64 v20, v28, v20
	v_mul_f32_e64 v21, v29, v21
	s_waitcnt vmcnt(0)
	v_mul_f32_e64 v42, v29, v22
	v_mul_f32_e64 v43, v28, v23
	v_mul_f32_e64 v22, v28, v22
	v_mul_f32_e64 v23, v29, v23
	v_mul_f32_e64 v44, v29, v24
	v_mul_f32_e64 v45, v28, v25
	v_mul_f32_e64 v24, v28, v24
	v_mul_f32_e64 v25, v29, v25
	v_add_f32_e32 v6, v30, v31
	v_sub_f32_e32 v10, v10, v11
	v_add_f32_e32 v11, v32, v33
	v_sub_f32_e32 v12, v12, v13
	v_add_f32_e32 v13, v34, v35
	v_sub_f32_e32 v14, v14, v15
	v_add_f32_e32 v15, v36, v37
	v_sub_f32_e32 v16, v16, v17
	v_add_f32_e32 v17, v38, v39
	v_sub_f32_e32 v18, v18, v19
	v_add_f32_e32 v19, v40, v41
	v_sub_f32_e32 v20, v20, v21
	v_add_f32_e32 v21, v42, v43
	v_sub_f32_e32 v22, v22, v23
	v_add_f32_e32 v23, v44, v45
	v_sub_f32_e32 v24, v24, v25
	v_cndmask_b32_e32 v6, v6, v10, vcc
	v_cndmask_b32_e32 v10, v11, v12, vcc
	v_cndmask_b32_e32 v11, v13, v14, vcc
	v_cndmask_b32_e32 v12, v15, v16, vcc
	v_cndmask_b32_e32 v13, v17, v18, vcc
	v_cndmask_b32_e32 v14, v19, v20, vcc
	v_cndmask_b32_e32 v15, v21, v22, vcc
	v_cndmask_b32_e32 v16, v23, v24, vcc
	v_cvt_pk_bf16_f32 v10, v6, v10
	v_cvt_pk_bf16_f32 v11, v11, v12
	v_cvt_pk_bf16_f32 v12, v13, v14
	v_cvt_pk_bf16_f32 v13, v15, v16
	global_store_dwordx4 v[26:27], v[10:13], off
	s_andn2_b64 exec, exec, s[12:13]
	s_cbranch_execnz .LBB0_181
	s_or_b64 exec, exec, s[12:13]
	s_load_dwordx4 s[4:7], s[84:85], 0xb0
	v_mov_b32_e32 v7, 0
	v_lshlrev_b32_e32 v6, 5, v3
	v_lshlrev_b32_e32 v4, 2, v3
	v_lshl_add_u64 v[8:9], s[14:15], 0, v[6:7]
	s_mov_b64 s[12:13], 0
	s_movk_i32 s0, 0x3c0
	s_movk_i32 s1, 0x600
	v_lshlrev_b32_e32 v2, 1, v2
	s_mov_b64 s[14:15], 0x7ffff
.LBB0_183:
	v_bfe_u32 v5, v0, 4, 1
	v_lshrrev_b32_e32 v3, 5, v0
	v_alignbit_b32 v27, v1, v0, 14
	v_bfe_u32 v3, v3, 4, 5
	v_lshl_add_u32 v10, v5, 5, v27
	v_sub_u32_e32 v6, 32, v3
	v_add_u32_e32 v3, 1, v3
	v_ashrrev_i32_e32 v11, 31, v10
	v_cmp_eq_u32_e32 vcc, 0, v5
	v_lshlrev_b32_e32 v12, 1, v0
	v_lshl_or_b32 v13, v27, 1, v5
	v_cndmask_b32_e32 v6, v6, v3, vcc
	v_lshlrev_b64 v[10:11], 10, v[10:11]
	v_and_or_b32 v3, v12, s0, v10
	v_mad_i64_i32 v[12:13], s[16:17], v13, 33, v[6:7]
	v_or_b32_e32 v10, v3, v4
	v_lshlrev_b64 v[12:13], 9, v[12:13]
	v_lshl_add_u64 v[28:29], v[8:9], 0, v[12:13]
	v_lshlrev_b64 v[10:11], 2, v[10:11]
	s_waitcnt lgkmcnt(0)
	v_lshl_add_u64 v[30:31], s[4:5], 0, v[10:11]
	v_lshl_add_u64 v[32:33], s[6:7], 0, v[10:11]
	global_load_dwordx4 v[10:13], v[28:29], off
	global_load_dwordx4 v[14:17], v[30:31], off
	global_load_dwordx4 v[18:21], v[32:33], off
	global_load_dwordx4 v[22:25], v[28:29], off offset:16
	v_mov_b32_e32 v26, v7
	v_bfe_u32 v6, v0, 5, 9
	v_ashrrev_i64 v[26:27], 23, v[26:27]
	v_mov_b64_e32 v[28:29], s[10:11]
	v_or_b32_e32 v6, v26, v6
	v_mad_u64_u32 v[28:29], s[16:17], v6, s1, v[28:29]
	v_mad_i32_i24 v29, v27, s1, v29
	v_lshlrev_b32_e32 v6, 8, v5
	v_mov_b32_e32 v3, v7
	v_lshl_add_u64 v[0:1], v[0:1], 0, s[22:23]
	v_lshl_add_u64 v[26:27], v[28:29], 0, v[6:7]
	v_cmp_lt_i64_e32 vcc, s[14:15], v[0:1]
	v_lshl_add_u64 v[26:27], v[26:27], 0, v[2:3]
	s_or_b64 s[12:13], vcc, s[12:13]
	v_add_co_u32_e32 v26, vcc, 0xb0cc000, v26
	s_waitcnt vmcnt(2)
	v_mov_b32_e32 v28, v14
	s_waitcnt vmcnt(1)
	v_mov_b32_e32 v29, v18
	v_mov_b32_e32 v30, v18
	v_mov_b32_e32 v31, v14
	v_mov_b32_e32 v18, v15
	v_mov_b32_e32 v14, v19
	v_mov_b32_e32 v32, v16
	v_mov_b32_e32 v33, v20
	v_mov_b32_e32 v34, v20
	v_mov_b32_e32 v35, v16
	v_mov_b32_e32 v20, v17
	v_mov_b32_e32 v16, v21
	v_mul_f32_e64 v28, v28, v10
	v_mul_f32_e64 v29, v29, v11
	v_mul_f32_e64 v10, v30, v10
	v_mul_f32_e64 v11, v31, v11
	v_mul_f32_e64 v18, v18, v12
	v_mul_f32_e64 v19, v19, v13
	v_mul_f32_e64 v12, v14, v12
	v_mul_f32_e64 v13, v15, v13
	s_waitcnt vmcnt(0)
	v_mul_f32_e64 v14, v32, v22
	v_mul_f32_e64 v15, v33, v23
	v_mul_f32_e64 v22, v34, v22
	v_mul_f32_e64 v23, v35, v23
	v_mul_f32_e64 v20, v20, v24
	v_mul_f32_e64 v21, v21, v25
	v_mul_f32_e64 v16, v16, v24
	v_mul_f32_e64 v17, v17, v25
	v_addc_co_u32_e32 v27, vcc, 0, v27, vcc
	v_add_f32_e32 v5, v10, v11
	v_add_f32_e32 v10, v12, v13
	v_sub_f32_e32 v12, v14, v15
	v_add_f32_e32 v11, v22, v23
	v_sub_f32_e32 v13, v20, v21
	v_add_f32_e32 v14, v16, v17
	v_sub_f32_e32 v3, v28, v29
	v_sub_f32_e32 v6, v18, v19
	v_xor_b32_e32 v5, 0x80000000, v5
	v_xor_b32_e32 v15, 0x80000000, v10
	v_xor_b32_e32 v16, 0x80000000, v11
	v_xor_b32_e32 v14, 0x80000000, v14
	v_cvt_pk_bf16_f32 v10, v3, v5
	v_cvt_pk_bf16_f32 v11, v6, v15
	v_cvt_pk_bf16_f32 v12, v12, v16
	v_cvt_pk_bf16_f32 v13, v13, v14
	global_store_dwordx4 v[26:27], v[10:13], off offset:1024
	s_andn2_b64 exec, exec, s[12:13]
	s_cbranch_execnz .LBB0_183

; __device__ __forceinline__ void ssm_build_t(const Params& p, const Ctx& c, int l) {
;     ...
;     else { const float* m0 = MK + ((size_t)((g * 2) * 32) * 16 + h) * 16 + hh * 8; const float* m1 = MK + ((size_t)((g * 2 + 1) * 32) * 16 + h) * 16 + hh * 8; const float dsk = p.ssm_d[(size_t)l * 512 + g * 16 + h];
; #pragma unroll
;       for (int k = 0; k < 8; ++k) v[k] = m0[k] + m1[k] + ((hh * 8 + k) == h ? dsk : 0.f); }
.LBB0_242:
	s_andn2_saveexec_b64 s[16:17], s[16:17]
	s_cbranch_execz .LBB0_239
	s_waitcnt vmcnt(0)
	v_lshlrev_b32_e32 v10, 4, v21
	v_ashrrev_i32_e32 v11, 31, v10
	v_lshl_add_u64 v[10:11], v[10:11], 2, s[6:7]
	v_lshlrev_b32_e32 v12, 2, v19
	v_mov_b32_e32 v13, v18
	v_lshlrev_b32_e32 v8, 6, v21
	v_lshl_add_u64 v[10:11], v[10:11], 0, v[12:13]
	global_load_dword v25, v[10:11], off
	v_ashrrev_i32_e32 v9, 31, v8
	v_lshlrev_b64 v[10:11], 10, v[8:9]
	v_or_b32_e32 v8, 32, v8
	v_ashrrev_i32_e32 v9, 31, v8
	v_lshlrev_b64 v[8:9], 10, v[8:9]
	v_mov_b32_e32 v23, v18
	v_lshl_add_u64 v[8:9], s[8:9], 0, v[8:9]
	v_lshl_add_u64 v[10:11], s[8:9], 0, v[10:11]
	v_mov_b32_e32 v21, v18
	v_lshl_add_u64 v[8:9], v[8:9], 0, v[22:23]
	v_lshl_add_u64 v[10:11], v[10:11], 0, v[22:23]
	v_lshl_add_u64 v[22:23], v[8:9], 0, v[20:21]
	v_lshl_add_u64 v[34:35], v[10:11], 0, v[20:21]
	global_load_dwordx4 v[8:11], v[22:23], off
	global_load_dwordx4 v[12:15], v[34:35], off
	global_load_dwordx4 v[26:29], v[34:35], off offset:16
	global_load_dwordx4 v[30:33], v[22:23], off offset:16
	v_cmp_eq_u32_e32 vcc, v1, v19
	s_waitcnt vmcnt(2)
	v_add_f32_e64 v12, v12, v8
	v_add_f32_e64 v13, v13, v9
	v_cndmask_b32_e32 v23, 0, v25, vcc
	v_cmp_eq_u32_e32 vcc, v0, v19
	v_add_f32_e64 v14, v14, v10
	v_add_f32_e64 v15, v15, v11
	s_waitcnt vmcnt(0)
	v_add_f32_e64 v8, v26, v30
	v_add_f32_e64 v9, v27, v31
	v_cndmask_b32_e32 v22, 0, v25, vcc
	v_cmp_eq_u32_e32 vcc, v3, v19
	v_add_f32_e64 v10, v28, v32
	v_add_f32_e64 v11, v29, v33
	v_add_f32_e64 v12, v22, v12
	v_add_f32_e64 v13, v23, v13
	v_cndmask_b32_e32 v35, 0, v25, vcc
	v_cmp_eq_u32_e32 vcc, v2, v19
	s_nop 1
	v_cndmask_b32_e32 v34, 0, v25, vcc
	v_cmp_eq_u32_e32 vcc, v5, v19
	v_add_f32_e64 v14, v34, v14
	v_add_f32_e64 v15, v35, v15
	s_nop 0
	v_cndmask_b32_e32 v37, 0, v25, vcc
	v_cmp_eq_u32_e32 vcc, v4, v19
	s_nop 1
	v_cndmask_b32_e32 v36, 0, v25, vcc
	v_cmp_eq_u32_e32 vcc, v7, v19
	v_add_f32_e64 v8, v36, v8
	v_add_f32_e64 v9, v37, v9
	s_nop 0
	v_cndmask_b32_e32 v39, 0, v25, vcc
	v_cmp_eq_u32_e32 vcc, v6, v19
	s_nop 1
	v_cndmask_b32_e32 v38, 0, v25, vcc
	v_add_f32_e64 v10, v38, v10
	v_add_f32_e64 v11, v39, v11
	s_branch .LBB0_239

; __device__ __forceinline__ unsigned cvtpk(float lo, float hi) { unsigned r; asm volatile("v_cvt_pk_bf16_f32 %0, %1, %2" : "=v"(r) : "v"(lo), "v"(hi)); return r; }
; __device__ __forceinline__ const float* modp(const Params& p, int l, int v, int j) { return (const float*)(p.ws + OFF_MOD) + ((size_t)(l * 5 + v) * NMODC + (size_t)j * DM); }
; __device__ __forceinline__ void prenorm_row(const f32x4 (&x)[8], float rinv, const float* g, const float* sc, const float* sh, bf16_t* dst, int lane) {
; #pragma unroll
;   for (int i = 0; i < 8; ++i) { const int col = (lane + 64 * i) * 4; const f32x4 gg = *(const f32x4*)(g + col), s1 = *(const f32x4*)(sc + col), s0 = *(const f32x4*)(sh + col);
;     const f32x4 y = (x[i] * rinv * gg) * (s1 + 1.f) + s0; u32x2 o = {cvtpk(y[0], y[1]), cvtpk(y[2], y[3])}; *(u32x2*)(dst + col) = o; }
; }
; #pragma unroll
;   for (int i = 0; i < 8; ++i) s += x[i][0] * x[i][0] + x[i][1] * x[i][1] + x[i][2] * x[i][2] + x[i][3] * x[i][3];
;   return wave_sum(s); }
; __device__ __forceinline__ f32x4 ldx(const _Float16* p) { const h16x4 h = *(const h16x4*)p; return __builtin_convertvector(h, f32x4); }
; __device__ __forceinline__ void stx(_Float16* p, f32x4 v) { *(h16x4*)p = __builtin_convertvector(v, h16x4); }
; __device__ __forceinline__ void phase_prenorm(const Params& p, const Ctx& c, int l) {
;   bf16_t* Hn = (bf16_t*)(p.ws + OFF_HN);
;   for (int row = c.gwave; row < TT; row += c.nwave) { const int b = row / TPB, t = row % TPB, v = t < CTXL ? 4 : b;
;     f32x4 x[8]; const f32x4* xr = (const f32x4*)xrow_src(p, l, b, t, row);
; #pragma unroll
;     for (int i = 0; i < 8; ++i) x[i] = xr[c.lane + 64 * i];
;     const float rinv = rsqrtf(sumsq8(x) * (1.f / DM) + 1e-6f);
;     prenorm_row(x, rinv, p.g_mix_pre + (size_t)l * DM, modp(p, l, v, 1), modp(p, l, v, 0), Hn + (size_t)row * DM, c.lane); }
.LBB0_246:
	v_mul_hi_i32 v0, v12, s1
	v_ashrrev_i32_e32 v13, 31, v12
	v_lshrrev_b32_e32 v2, 31, v0
	v_ashrrev_i32_e32 v3, 11, v0
	v_lshlrev_b64 v[0:1], 12, v[12:13]
	v_add_u32_e32 v2, v3, v2
	v_lshl_add_u64 v[46:47], v[26:27], 0, v[0:1]
	v_mul_i32_i24_e32 v0, 0x1100, v2
	v_sub_u32_e32 v4, v12, v0
	v_cmp_gt_i32_e32 vcc, s0, v4
	v_add_u32_e32 v6, 0xffffff00, v4
	v_ashrrev_i32_e32 v5, 31, v4
	v_cndmask_b32_e64 v14, 0, 16, vcc
	v_lshl_add_u64 v[0:1], s[84:85], 0, v[14:15]
	global_load_dwordx2 v[0:1], v[0:1], off
	v_ashrrev_i32_e32 v3, 31, v2
	v_cndmask_b32_e32 v5, 0, v5, vcc
	v_cndmask_b32_e32 v4, v6, v4, vcc
	v_cndmask_b32_e64 v6, 23, 19, vcc
	v_cndmask_b32_e64 v8, v2, 4, vcc
	v_lshlrev_b64 v[2:3], v6, v[2:3]
	v_lshlrev_b64 v[4:5], 13, v[4:5]
	v_mul_hi_i32_i24_e32 v7, 0xc000, v8
	v_mul_i32_i24_e32 v6, 0xc000, v8
	v_lshl_add_u64 v[48:49], s[6:7], 0, v[6:7]
	v_lshl_add_u64 v[50:51], v[48:49], 0, s[10:11]
	v_lshl_add_u64 v[6:7], v[50:51], 0, v[30:31]
	global_load_dwordx4 v[54:57], v[16:17], off
	v_lshl_add_u64 v[86:87], v[48:49], 0, v[30:31]
	global_load_dwordx4 v[58:61], v[6:7], off
	global_load_dwordx4 v[62:65], v[86:87], off
	v_lshl_add_u64 v[88:89], v[50:51], 0, v[32:33]
	v_add_u32_e32 v12, s16, v12
	s_waitcnt vmcnt(3)
	v_lshl_add_u64 v[0:1], v[0:1], 0, v[4:5]
	v_lshl_add_u64 v[0:1], v[2:3], 2, v[0:1]
	v_lshl_add_u64 v[0:1], v[0:1], 0, v[28:29]
	global_load_dwordx4 v[66:69], v[0:1], off
	global_load_dwordx4 v[70:73], v[0:1], off offset:1024
	global_load_dwordx4 v[74:77], v[0:1], off offset:3072
	global_load_dwordx4 v[78:81], v[0:1], off offset:2048
	v_add_co_u32_e32 v90, vcc, s2, v0
	s_waitcnt vmcnt(5)
	v_add_f32_e64 v58, v58, 1.0
	v_add_f32_e64 v59, v59, 1.0
	v_addc_co_u32_e32 v91, vcc, 0, v1, vcc
	global_load_dwordx4 v[8:11], v[90:91], off offset:1024
	global_load_dwordx4 v[82:85], v[90:91], off
	global_load_dwordx4 v[0:3], v[90:91], off offset:3072
	global_load_dwordx4 v[4:7], v[90:91], off offset:2048
	v_add_f32_e64 v60, v60, 1.0
	v_add_f32_e64 v61, v61, 1.0
	s_waitcnt vmcnt(7)
	v_mul_f32_e32 v13, v67, v67
	s_waitcnt vmcnt(6)
	v_mul_f32_e32 v14, v71, v71
	s_waitcnt vmcnt(5)
	v_mov_b32_e32 v92, v75
	s_waitcnt vmcnt(4)
	v_mov_b32_e32 v93, v79
	v_mov_b32_e32 v90, v74
	v_mov_b32_e32 v91, v78
	v_fmac_f32_e32 v13, v66, v66
	v_fmac_f32_e32 v14, v70, v70
	v_mul_f32_e64 v92, v92, v92
	v_mul_f32_e64 v93, v93, v93
	v_mov_b32_e32 v94, v76
	v_mov_b32_e32 v95, v80
	v_fmac_f32_e32 v13, v68, v68
	v_fmac_f32_e32 v14, v72, v72
	v_fma_f32 v90, v90, v90, v92
	v_fma_f32 v91, v91, v91, v93
	s_waitcnt vmcnt(3)
	v_mov_b32_e32 v100, v9
	s_waitcnt vmcnt(2)
	v_mov_b32_e32 v101, v83
	v_mov_b32_e32 v96, v77
	v_mov_b32_e32 v97, v81
	v_mov_b32_e32 v98, v8
	v_mov_b32_e32 v99, v82
	v_mul_f32_e64 v92, v100, v100
	v_mul_f32_e64 v93, v101, v101
	v_fmac_f32_e32 v13, v69, v69
	v_fmac_f32_e32 v14, v73, v73
	v_fma_f32 v90, v94, v94, v90
	v_fma_f32 v91, v95, v95, v91
	v_mov_b32_e32 v102, v10
	v_mov_b32_e32 v103, v84
	s_waitcnt vmcnt(1)
	v_mov_b32_e32 v108, v1
	s_waitcnt vmcnt(0)
	v_mov_b32_e32 v109, v5
	v_fma_f32 v92, v98, v98, v92
	v_fma_f32 v93, v99, v99, v93
	v_add_f32_e32 v13, v13, v14
	v_fma_f32 v90, v96, v96, v90
	v_fma_f32 v91, v97, v97, v91
	v_mov_b32_e32 v104, v11
	v_mov_b32_e32 v105, v85
	v_mov_b32_e32 v106, v0
	v_mov_b32_e32 v107, v4
	v_mul_f32_e64 v100, v108, v108
	v_mul_f32_e64 v101, v109, v109
	v_fma_f32 v92, v102, v102, v92
	v_fma_f32 v93, v103, v103, v93
	v_add_f32_e32 v13, v91, v13
	v_mov_b32_e32 v110, v2
	v_mov_b32_e32 v111, v6
	v_fma_f32 v94, v106, v106, v100
	v_fma_f32 v95, v107, v107, v101
	v_fma_f32 v92, v104, v104, v92
	v_fma_f32 v93, v105, v105, v93
	v_add_f32_e32 v13, v90, v13
	v_mov_b32_e32 v112, v3
	v_mov_b32_e32 v113, v7
	v_fma_f32 v94, v110, v110, v94
	v_fma_f32 v95, v111, v111, v95
	v_add_f32_e32 v13, v93, v13
	v_fma_f32 v94, v112, v112, v94
	v_fma_f32 v95, v113, v113, v95
	v_add_f32_e32 v13, v92, v13
	v_add_f32_e32 v13, v95, v13
	v_add_f32_e32 v13, v94, v13
	s_nop 1
	v_add_f32_dpp v13, v13, v13 quad_perm:[1,0,3,2] row_mask:0xf bank_mask:0xf bound_ctrl:1
	s_nop 1
	v_add_f32_dpp v13, v13, v13 quad_perm:[2,3,0,1] row_mask:0xf bank_mask:0xf bound_ctrl:1
	s_nop 1
	v_add_f32_dpp v13, v13, v13 row_half_mirror row_mask:0xf bank_mask:0xf bound_ctrl:1
	s_nop 1
	v_add_f32_dpp v13, v13, v13 row_mirror row_mask:0xf bank_mask:0xf bound_ctrl:1
	s_nop 0
	v_readlane_b32 s17, v13, 16
	v_readlane_b32 s18, v13, 48
	v_readlane_b32 s14, v13, 0
	v_readlane_b32 s15, v13, 32
	v_mov_b32_e32 v90, s17
	v_mov_b32_e32 v91, s18
	v_add_f32_e64 v90, s14, v90
	v_add_f32_e64 v91, s15, v91
	s_nop 0
	v_add_f32_e32 v13, v90, v91
	v_fmamk_f32 v13, v13, 0x3a000000, v52
	v_mul_f32_e32 v14, 0x4b800000, v13
	v_cmp_gt_f32_e32 vcc, s12, v13
	s_nop 1
	v_cndmask_b32_e32 v13, v13, v14, vcc
	v_rsq_f32_e32 v13, v13
	s_nop 0
	v_mul_f32_e32 v14, 0x45800000, v13
	v_cndmask_b32_e32 v14, v13, v14, vcc
	v_mul_f32_e64 v66, v66, v14
	v_mul_f32_e64 v67, v67, v14
	v_mul_f32_e64 v68, v68, v14
	v_mul_f32_e64 v69, v69, v14
	v_mul_f32_e64 v54, v54, v66
	v_mul_f32_e64 v55, v55, v67
	v_mul_f32_e64 v56, v56, v68
	v_mul_f32_e64 v57, v57, v69
	v_fma_f32 v54, v58, v54, v62
	v_fma_f32 v55, v59, v55, v63
	v_fma_f32 v56, v60, v56, v64
	v_fma_f32 v57, v61, v57, v65
	v_cvt_pk_bf16_f32 v54, v54, v55
	v_mul_f32_e64 v70, v70, v14
	v_mul_f32_e64 v71, v71, v14
	v_cvt_pk_bf16_f32 v55, v56, v57
	global_store_dwordx2 v[46:47], v[54:55], off
	global_load_dwordx4 v[54:57], v[16:17], off offset:1024
	s_nop 0
	global_load_dwordx4 v[58:61], v[88:89], off
	global_load_dwordx4 v[62:65], v[86:87], off offset:1024
	v_mul_f32_e64 v68, v72, v14
	v_mul_f32_e64 v69, v73, v14
	v_lshl_add_u64 v[66:67], v[50:51], 0, v[34:35]
	v_mul_f32_e64 v72, v74, v14
	v_mul_f32_e64 v73, v75, v14
	v_mul_f32_e64 v10, v10, v14
	v_mul_f32_e64 v11, v11, v14
	v_mul_f32_e64 v8, v8, v14
	v_mul_f32_e64 v9, v9, v14
	v_mul_f32_e64 v6, v6, v14
	v_mul_f32_e64 v7, v7, v14
	v_mul_f32_e64 v4, v4, v14
	v_mul_f32_e64 v5, v5, v14
	v_mul_f32_e64 v2, v2, v14
	v_mul_f32_e64 v3, v3, v14
	v_mul_f32_e64 v0, v0, v14
	v_mul_f32_e64 v1, v1, v14
	v_cmp_lt_i32_e32 vcc, s13, v12
	s_or_b64 s[8:9], vcc, s[8:9]
	s_waitcnt vmcnt(2)
; __device__ __forceinline__ unsigned cvtpk(float lo, float hi) { unsigned r; asm volatile("v_cvt_pk_bf16_f32 %0, %1, %2" : "=v"(r) : "v"(lo), "v"(hi)); return r; }
; __device__ __forceinline__ void prenorm_row(const f32x4 (&x)[8], float rinv, const float* g, const float* sc, const float* sh, bf16_t* dst, int lane) {
; #pragma unroll
;   for (int i = 0; i < 8; ++i) { const int col = (lane + 64 * i) * 4; const f32x4 gg = *(const f32x4*)(g + col), s1 = *(const f32x4*)(sc + col), s0 = *(const f32x4*)(sh + col);
;     const f32x4 y = (x[i] * rinv * gg) * (s1 + 1.f) + s0; u32x2 o = {cvtpk(y[0], y[1]), cvtpk(y[2], y[3])}; *(u32x2*)(dst + col) = o; }
; }
	v_mul_f32_e64 v54, v54, v70
	v_mul_f32_e64 v55, v55, v71
	s_waitcnt vmcnt(1)
	v_add_f32_e64 v58, v58, 1.0
	v_add_f32_e64 v59, v59, 1.0
	v_mul_f32_e64 v56, v56, v68
	v_mul_f32_e64 v57, v57, v69
	v_add_f32_e64 v60, v60, 1.0
	v_add_f32_e64 v61, v61, 1.0
	s_waitcnt vmcnt(0)
	v_fma_f32 v54, v58, v54, v62
	v_fma_f32 v55, v59, v55, v63
	v_fma_f32 v56, v60, v56, v64
	v_fma_f32 v57, v61, v57, v65
	v_cvt_pk_bf16_f32 v54, v54, v55
	v_mul_f32_e64 v70, v78, v14
	v_mul_f32_e64 v71, v79, v14
	v_cvt_pk_bf16_f32 v55, v56, v57
	global_store_dwordx2 v[46:47], v[54:55], off offset:512
	global_load_dwordx4 v[54:57], v[16:17], off offset:2048
	s_nop 0
	global_load_dwordx4 v[58:61], v[66:67], off
	global_load_dwordx4 v[62:65], v[86:87], off offset:2048
	v_mul_f32_e64 v68, v80, v14
	v_mul_f32_e64 v69, v81, v14
	v_lshl_add_u64 v[66:67], v[50:51], 0, v[36:37]
	s_waitcnt vmcnt(2)
	v_mul_f32_e64 v54, v70, v54
	v_mul_f32_e64 v55, v71, v55
	s_waitcnt vmcnt(1)
	v_add_f32_e64 v58, v58, 1.0
	v_add_f32_e64 v59, v59, 1.0
	v_mul_f32_e64 v56, v68, v56
	v_mul_f32_e64 v57, v69, v57
	v_add_f32_e64 v60, v60, 1.0
	v_add_f32_e64 v61, v61, 1.0
	s_waitcnt vmcnt(0)
	v_fma_f32 v54, v54, v58, v62
	v_fma_f32 v55, v55, v59, v63
	v_fma_f32 v56, v56, v60, v64
	v_fma_f32 v57, v57, v61, v65
	v_cvt_pk_bf16_f32 v54, v54, v55
	v_mul_f32_e64 v70, v76, v14
	v_mul_f32_e64 v71, v77, v14
	v_cvt_pk_bf16_f32 v55, v56, v57
	global_store_dwordx2 v[46:47], v[54:55], off offset:1024
	global_load_dwordx4 v[54:57], v[16:17], off offset:3072
	s_nop 0
	global_load_dwordx4 v[58:61], v[66:67], off
	global_load_dwordx4 v[62:65], v[86:87], off offset:3072
	v_lshl_add_u64 v[66:67], v[48:49], 0, v[38:39]
	v_lshl_add_u64 v[68:69], v[50:51], 0, v[38:39]
	s_waitcnt vmcnt(2)
	v_mul_f32_e64 v54, v72, v54
	v_mul_f32_e64 v55, v73, v55
	s_waitcnt vmcnt(1)
	v_add_f32_e64 v58, v58, 1.0
	v_add_f32_e64 v59, v59, 1.0
	v_mul_f32_e64 v56, v70, v56
	v_mul_f32_e64 v57, v71, v57
	v_add_f32_e64 v60, v60, 1.0
	v_add_f32_e64 v61, v61, 1.0
	s_waitcnt vmcnt(0)
	v_fma_f32 v54, v54, v58, v62
	v_fma_f32 v55, v55, v59, v63
	v_fma_f32 v56, v56, v60, v64
	v_fma_f32 v57, v57, v61, v65
	v_cvt_pk_bf16_f32 v54, v54, v55
	v_mul_f32_e64 v72, v82, v14
	v_mul_f32_e64 v73, v83, v14
	v_cvt_pk_bf16_f32 v55, v56, v57
	global_store_dwordx2 v[46:47], v[54:55], off offset:1536
	global_load_dwordx4 v[54:57], v[18:19], off
	s_nop 0
	global_load_dwordx4 v[58:61], v[68:69], off
	global_load_dwordx4 v[62:65], v[66:67], off
	v_mul_f32_e64 v70, v84, v14
	v_mul_f32_e64 v71, v85, v14
	v_lshl_add_u64 v[66:67], v[48:49], 0, v[40:41]
	v_lshl_add_u64 v[68:69], v[50:51], 0, v[40:41]
	s_waitcnt vmcnt(2)
	v_mul_f32_e64 v54, v72, v54
	v_mul_f32_e64 v55, v73, v55
	s_waitcnt vmcnt(1)
	v_add_f32_e64 v58, v58, 1.0
	v_add_f32_e64 v59, v59, 1.0
	v_mul_f32_e64 v56, v70, v56
	v_mul_f32_e64 v57, v71, v57
	v_add_f32_e64 v60, v60, 1.0
	v_add_f32_e64 v61, v61, 1.0
	s_waitcnt vmcnt(0)
	v_fma_f32 v54, v54, v58, v62
	v_fma_f32 v55, v55, v59, v63
	v_fma_f32 v56, v56, v60, v64
	v_fma_f32 v57, v57, v61, v65
	v_cvt_pk_bf16_f32 v54, v54, v55
	s_nop 0
	v_cvt_pk_bf16_f32 v55, v56, v57
	global_store_dwordx2 v[46:47], v[54:55], off offset:2048
	global_load_dwordx4 v[54:57], v[20:21], off
	s_nop 0
	global_load_dwordx4 v[58:61], v[68:69], off
	global_load_dwordx4 v[62:65], v[66:67], off
	v_lshl_add_u64 v[66:67], v[48:49], 0, v[42:43]
	v_lshl_add_u64 v[68:69], v[50:51], 0, v[42:43]
	s_waitcnt vmcnt(2)
	v_mul_f32_e64 v8, v8, v54
	v_mul_f32_e64 v9, v9, v55
	v_mul_f32_e64 v10, v10, v56
	v_mul_f32_e64 v11, v11, v57
	s_waitcnt vmcnt(1)
	v_add_f32_e64 v56, v58, 1.0
	v_add_f32_e64 v57, v59, 1.0
	v_add_f32_e64 v54, v60, 1.0
	v_add_f32_e64 v55, v61, 1.0
	s_waitcnt vmcnt(0)
	v_fma_f32 v8, v8, v56, v62
	v_fma_f32 v9, v9, v57, v63
	v_fma_f32 v10, v10, v54, v64
	v_fma_f32 v11, v11, v55, v65
	v_cvt_pk_bf16_f32 v8, v8, v9
	v_lshl_add_u64 v[62:63], v[48:49], 0, v[44:45]
	v_cvt_pk_bf16_f32 v9, v10, v11
	global_store_dwordx2 v[46:47], v[8:9], off offset:2560
	global_load_dwordx4 v[8:11], v[22:23], off
	s_nop 0
	global_load_dwordx4 v[54:57], v[68:69], off
	global_load_dwordx4 v[58:61], v[66:67], off
	v_lshl_add_u64 v[64:65], v[50:51], 0, v[44:45]
	s_waitcnt vmcnt(2)
	v_mul_f32_e64 v4, v4, v8
	v_mul_f32_e64 v5, v5, v9
	v_mul_f32_e64 v6, v6, v10
	v_mul_f32_e64 v7, v7, v11
	s_waitcnt vmcnt(1)
	v_add_f32_e64 v10, v54, 1.0
	v_add_f32_e64 v11, v55, 1.0
	v_add_f32_e64 v8, v56, 1.0
	v_add_f32_e64 v9, v57, 1.0
	s_waitcnt vmcnt(0)
	v_fma_f32 v4, v4, v10, v58
	v_fma_f32 v5, v5, v11, v59
	v_fma_f32 v6, v6, v8, v60
	v_fma_f32 v7, v7, v9, v61
	v_cvt_pk_bf16_f32 v4, v4, v5
	s_nop 0
	v_cvt_pk_bf16_f32 v5, v6, v7
	global_store_dwordx2 v[46:47], v[4:5], off offset:3072
	global_load_dwordx4 v[4:7], v[24:25], off
	s_nop 0
	global_load_dwordx4 v[8:11], v[64:65], off
	global_load_dwordx4 v[48:51], v[62:63], off
	s_waitcnt vmcnt(2)
	v_mul_f32_e64 v0, v0, v4
	v_mul_f32_e64 v1, v1, v5
	v_mul_f32_e64 v2, v2, v6
	v_mul_f32_e64 v3, v3, v7
	s_waitcnt vmcnt(1)
	v_add_f32_e64 v6, v8, 1.0
	v_add_f32_e64 v7, v9, 1.0
	v_add_f32_e64 v4, v10, 1.0
	v_add_f32_e64 v5, v11, 1.0
	s_waitcnt vmcnt(0)
	v_fma_f32 v0, v0, v6, v48
	v_fma_f32 v1, v1, v7, v49
	v_fma_f32 v2, v2, v4, v50
	v_fma_f32 v3, v3, v5, v51
	v_cvt_pk_bf16_f32 v0, v0, v1
	s_nop 0
	v_cvt_pk_bf16_f32 v1, v2, v3
	global_store_dwordx2 v[46:47], v[0:1], off offset:3584
	s_andn2_b64 exec, exec, s[8:9]
	s_cbranch_execnz .LBB0_246

; __device__ __forceinline__ unsigned cvtpk(float lo, float hi) { unsigned r; asm volatile("v_cvt_pk_bf16_f32 %0, %1, %2" : "=v"(r) : "v"(lo), "v"(hi)); return r; }
;   __device__ __forceinline__ void operator()(const Acc& acc, const gm::Unit& u, int wr, int wc, int fr, int fq) const {
;     ...
;         if (pn < 8) { bf16_t* dst = Qb + (size_t)(pn >> 2) * TT * 1024 + ((size_t)(pm * 4 + (pn & 3)) * 256 + (row - brow)) * 256 + wc * 32 + fq * 8;
;           f32x4 cs = {1.f, 1.f, 1.f, 1.f}, sn = {0.f, 0.f, 0.f, 0.f};
;           if (!isctx) { const int tl = (row % TPB) - CTXL; const int pos = (wc >> 1) ? (tl & 63) : (tl >> 6); const int p0 = (wc & 1) * 16 + fq * 4;
;             cs = *(const f32x4*)(rc + pos * 32 + p0); sn = *(const f32x4*)(rs + pos * 32 + p0); }
; #pragma unroll
;           for (int bj = 0; bj < 2; ++bj) { const f32x4 v1 = acc[ai][bj][m][0], v2 = acc[ai][bj][m][1]; const f32x4 o1 = v1 * cs - v2 * sn, o2 = v2 * cs + v1 * sn;
;             u32x4 w = {cvtpk(o1[0], o1[1]), cvtpk(o1[2], o1[3]), cvtpk(o2[0], o2[1]), cvtpk(o2[2], o2[3])}; *(u32x4*)(dst + bj * 128) = w; } }
.LBB0_341:
	s_add_u32 s10, s44, s1
	s_addc_u32 s11, s2, s33
	v_subrev_u32_e32 v164, s65, v163
	v_ashrrev_i32_e32 v165, 31, v164
	s_add_u32 s10, s10, s78
	s_addc_u32 s11, s11, s79
	v_lshlrev_b64 v[164:165], 9, v[164:165]
	v_lshl_add_u64 v[164:165], s[10:11], 0, v[164:165]
	s_lshl_b32 s30, s45, 1
	s_waitcnt vmcnt(0)
	v_mul_f32_e64 v166, v124, v136
	v_mul_f32_e64 v167, v125, v137
	v_mul_f32_e64 v168, v122, v134
	v_mul_f32_e64 v169, v123, v135
	v_mul_f32_e64 v124, v124, v132
	v_mul_f32_e64 v125, v125, v133
	v_mul_f32_e64 v122, v122, v130
	v_mul_f32_e64 v123, v123, v131
	v_lshl_add_u64 v[164:165], v[164:165], 0, s[30:31]
	v_fma_f32 v166, v128, v132, -v166
	v_fma_f32 v167, v129, v133, -v167
	v_fma_f32 v128, v128, v136, v124
	v_fma_f32 v129, v129, v137, v125
	v_fma_f32 v124, v126, v134, v122
	v_fma_f32 v125, v127, v135, v123
	v_lshl_add_u64 v[164:165], v[150:151], 1, v[164:165]
	v_fma_f32 v168, v126, v130, -v168
	v_fma_f32 v169, v127, v131, -v169
	s_nop 0
	v_cvt_pk_bf16_f32 v122, v168, v169
	v_cvt_pk_bf16_f32 v123, v166, v167
	v_cvt_pk_bf16_f32 v124, v124, v125
	v_cvt_pk_bf16_f32 v125, v128, v129
	global_store_dwordx4 v[164:165], v[122:125], off
	s_nop 1
	v_mul_f32_e64 v122, v116, v136
	v_mul_f32_e64 v123, v117, v137
	v_mul_f32_e64 v124, v114, v134
	v_mul_f32_e64 v125, v115, v135
	v_mul_f32_e64 v116, v116, v132
	v_mul_f32_e64 v117, v117, v133
	v_mul_f32_e64 v114, v114, v130
	v_mul_f32_e64 v115, v115, v131
	v_fma_f32 v122, v120, v132, -v122
	v_fma_f32 v123, v121, v133, -v123
	v_fma_f32 v120, v120, v136, v116
	v_fma_f32 v121, v121, v137, v117
	v_fma_f32 v116, v118, v134, v114
	v_fma_f32 v117, v119, v135, v115
	v_fma_f32 v124, v118, v130, -v124
	v_fma_f32 v125, v119, v131, -v125
	s_nop 0
	v_cvt_pk_bf16_f32 v114, v124, v125
	v_cvt_pk_bf16_f32 v115, v122, v123
	v_cvt_pk_bf16_f32 v116, v116, v117
	v_cvt_pk_bf16_f32 v117, v120, v121
	global_store_dwordx4 v[164:165], v[114:117], off offset:256

; __device__ __forceinline__ unsigned cvtpk(float lo, float hi) { unsigned r; asm volatile("v_cvt_pk_bf16_f32 %0, %1, %2" : "=v"(r) : "v"(lo), "v"(hi)); return r; }
;   __device__ __forceinline__ void operator()(const Acc& acc, const gm::Unit& u, int wr, int wc, int fr, int fq) const {
;     ...
;         if (pn < 8) { bf16_t* dst = Qb + (size_t)(pn >> 2) * TT * 1024 + ((size_t)(pm * 4 + (pn & 3)) * 256 + (row - brow)) * 256 + wc * 32 + fq * 8;
;           f32x4 cs = {1.f, 1.f, 1.f, 1.f}, sn = {0.f, 0.f, 0.f, 0.f};
;           if (!isctx) { const int tl = (row % TPB) - CTXL; const int pos = (wc >> 1) ? (tl & 63) : (tl >> 6); const int p0 = (wc & 1) * 16 + fq * 4;
;             cs = *(const f32x4*)(rc + pos * 32 + p0); sn = *(const f32x4*)(rs + pos * 32 + p0); }
; #pragma unroll
;           for (int bj = 0; bj < 2; ++bj) { const f32x4 v1 = acc[ai][bj][m][0], v2 = acc[ai][bj][m][1]; const f32x4 o1 = v1 * cs - v2 * sn, o2 = v2 * cs + v1 * sn;
;             u32x4 w = {cvtpk(o1[0], o1[1]), cvtpk(o1[2], o1[3]), cvtpk(o2[0], o2[1]), cvtpk(o2[2], o2[3])}; *(u32x4*)(dst + bj * 128) = w; } }
.LBB0_356:
	s_add_u32 s30, s44, s1
	s_addc_u32 s83, s2, s33
	v_subrev_u32_e32 v122, s65, v122
	v_ashrrev_i32_e32 v123, 31, v122
	s_add_u32 s82, s30, s78
	s_addc_u32 s83, s83, s79
	v_lshlrev_b64 v[122:123], 9, v[122:123]
	v_lshl_add_u64 v[122:123], s[82:83], 0, v[122:123]
	s_lshl_b32 s30, s45, 1
	s_waitcnt vmcnt(0)
	v_mul_f32_e64 v124, v108, v120
	v_mul_f32_e64 v125, v109, v121
	v_mul_f32_e64 v126, v106, v118
	v_mul_f32_e64 v127, v107, v119
	v_mul_f32_e64 v108, v108, v116
	v_mul_f32_e64 v109, v109, v117
	v_mul_f32_e64 v106, v106, v114
	v_mul_f32_e64 v107, v107, v115
	v_lshl_add_u64 v[122:123], v[122:123], 0, s[30:31]
	v_fma_f32 v124, v112, v116, -v124
	v_fma_f32 v125, v113, v117, -v125
	v_fma_f32 v112, v112, v120, v108
	v_fma_f32 v113, v113, v121, v109
	v_fma_f32 v108, v110, v118, v106
	v_fma_f32 v109, v111, v119, v107
	v_lshl_add_u64 v[122:123], v[150:151], 1, v[122:123]
	v_fma_f32 v126, v110, v114, -v126
	v_fma_f32 v127, v111, v115, -v127
	s_nop 0
	v_cvt_pk_bf16_f32 v106, v126, v127
	v_cvt_pk_bf16_f32 v107, v124, v125
	v_cvt_pk_bf16_f32 v108, v108, v109
	v_cvt_pk_bf16_f32 v109, v112, v113
	global_store_dwordx4 v[122:123], v[106:109], off
	s_nop 1
	v_mul_f32_e64 v106, v100, v120
	v_mul_f32_e64 v107, v101, v121
	v_mul_f32_e64 v108, v98, v118
	v_mul_f32_e64 v109, v99, v119
	v_mul_f32_e64 v100, v100, v116
	v_mul_f32_e64 v101, v101, v117
	v_mul_f32_e64 v98, v98, v114
	v_mul_f32_e64 v99, v99, v115
	v_fma_f32 v106, v104, v116, -v106
	v_fma_f32 v107, v105, v117, -v107
	v_fma_f32 v104, v104, v120, v100
	v_fma_f32 v105, v105, v121, v101
	v_fma_f32 v100, v102, v118, v98
	v_fma_f32 v101, v103, v119, v99
	v_fma_f32 v108, v102, v114, -v108
	v_fma_f32 v109, v103, v115, -v109
	s_nop 0
	v_cvt_pk_bf16_f32 v98, v108, v109
	v_cvt_pk_bf16_f32 v99, v106, v107
	v_cvt_pk_bf16_f32 v100, v100, v101
	v_cvt_pk_bf16_f32 v101, v104, v105
	global_store_dwordx4 v[122:123], v[98:101], off offset:256

; __device__ __forceinline__ unsigned cvtpk(float lo, float hi) { unsigned r; asm volatile("v_cvt_pk_bf16_f32 %0, %1, %2" : "=v"(r) : "v"(lo), "v"(hi)); return r; }
;   __device__ __forceinline__ void operator()(const Acc& acc, const gm::Unit& u, int wr, int wc, int fr, int fq) const {
;     ...
;         if (pn < 8) { bf16_t* dst = Qb + (size_t)(pn >> 2) * TT * 1024 + ((size_t)(pm * 4 + (pn & 3)) * 256 + (row - brow)) * 256 + wc * 32 + fq * 8;
;           f32x4 cs = {1.f, 1.f, 1.f, 1.f}, sn = {0.f, 0.f, 0.f, 0.f};
;           if (!isctx) { const int tl = (row % TPB) - CTXL; const int pos = (wc >> 1) ? (tl & 63) : (tl >> 6); const int p0 = (wc & 1) * 16 + fq * 4;
;             cs = *(const f32x4*)(rc + pos * 32 + p0); sn = *(const f32x4*)(rs + pos * 32 + p0); }
; #pragma unroll
;           for (int bj = 0; bj < 2; ++bj) { const f32x4 v1 = acc[ai][bj][m][0], v2 = acc[ai][bj][m][1]; const f32x4 o1 = v1 * cs - v2 * sn, o2 = v2 * cs + v1 * sn;
;             u32x4 w = {cvtpk(o1[0], o1[1]), cvtpk(o1[2], o1[3]), cvtpk(o2[0], o2[1]), cvtpk(o2[2], o2[3])}; *(u32x4*)(dst + bj * 128) = w; } }
.LBB0_411:
	s_add_u32 s30, s44, s1
	s_addc_u32 s83, s2, s33
	v_subrev_u32_e32 v106, s65, v106
	v_ashrrev_i32_e32 v107, 31, v106
	s_add_u32 s82, s30, s78
	s_addc_u32 s83, s83, s79
	v_lshlrev_b64 v[106:107], 9, v[106:107]
	v_lshl_add_u64 v[106:107], s[82:83], 0, v[106:107]
	s_lshl_b32 s30, s45, 1
	s_waitcnt vmcnt(0)
	v_mul_f32_e64 v108, v92, v104
	v_mul_f32_e64 v109, v93, v105
	v_mul_f32_e64 v110, v90, v102
	v_mul_f32_e64 v111, v91, v103
	v_mul_f32_e64 v92, v92, v100
	v_mul_f32_e64 v93, v93, v101
	v_mul_f32_e64 v90, v90, v98
	v_mul_f32_e64 v91, v91, v99
	v_lshl_add_u64 v[106:107], v[106:107], 0, s[30:31]
	v_fma_f32 v108, v96, v100, -v108
	v_fma_f32 v109, v97, v101, -v109
	v_fma_f32 v96, v96, v104, v92
	v_fma_f32 v97, v97, v105, v93
	v_fma_f32 v92, v94, v102, v90
	v_fma_f32 v93, v95, v103, v91
	v_lshl_add_u64 v[106:107], v[150:151], 1, v[106:107]
	v_fma_f32 v110, v94, v98, -v110
	v_fma_f32 v111, v95, v99, -v111
	s_nop 0
	v_cvt_pk_bf16_f32 v90, v110, v111
	v_cvt_pk_bf16_f32 v91, v108, v109
	v_cvt_pk_bf16_f32 v92, v92, v93
	v_cvt_pk_bf16_f32 v93, v96, v97
	global_store_dwordx4 v[106:107], v[90:93], off
	s_nop 1
	v_mul_f32_e64 v90, v84, v104
	v_mul_f32_e64 v91, v85, v105
	v_mul_f32_e64 v92, v82, v102
	v_mul_f32_e64 v93, v83, v103
	v_mul_f32_e64 v84, v84, v100
	v_mul_f32_e64 v85, v85, v101
	v_mul_f32_e64 v82, v82, v98
	v_mul_f32_e64 v83, v83, v99
	v_fma_f32 v90, v88, v100, -v90
	v_fma_f32 v91, v89, v101, -v91
	v_fma_f32 v88, v88, v104, v84
	v_fma_f32 v89, v89, v105, v85
	v_fma_f32 v84, v86, v102, v82
	v_fma_f32 v85, v87, v103, v83
	v_fma_f32 v92, v86, v98, -v92
	v_fma_f32 v93, v87, v99, -v93
	s_nop 0
	v_cvt_pk_bf16_f32 v82, v92, v93
	v_cvt_pk_bf16_f32 v83, v90, v91
	v_cvt_pk_bf16_f32 v84, v84, v85
	v_cvt_pk_bf16_f32 v85, v88, v89
	global_store_dwordx4 v[106:107], v[82:85], off offset:256
	v_add_u32_e32 v90, 48, v163
	s_and_b64 vcc, exec, s[12:13]
	s_mov_b64 s[82:83], -1
	s_cbranch_vccz .LBB0_368

; __device__ __forceinline__ unsigned cvtpk(float lo, float hi) { unsigned r; asm volatile("v_cvt_pk_bf16_f32 %0, %1, %2" : "=v"(r) : "v"(lo), "v"(hi)); return r; }
;   __device__ __forceinline__ void operator()(const Acc& acc, const gm::Unit& u, int wr, int wc, int fr, int fq) const {
;     ...
;         if (pn < 8) { bf16_t* dst = Qb + (size_t)(pn >> 2) * TT * 1024 + ((size_t)(pm * 4 + (pn & 3)) * 256 + (row - brow)) * 256 + wc * 32 + fq * 8;
;           f32x4 cs = {1.f, 1.f, 1.f, 1.f}, sn = {0.f, 0.f, 0.f, 0.f};
;           if (!isctx) { const int tl = (row % TPB) - CTXL; const int pos = (wc >> 1) ? (tl & 63) : (tl >> 6); const int p0 = (wc & 1) * 16 + fq * 4;
;             cs = *(const f32x4*)(rc + pos * 32 + p0); sn = *(const f32x4*)(rs + pos * 32 + p0); }
; #pragma unroll
;           for (int bj = 0; bj < 2; ++bj) { const f32x4 v1 = acc[ai][bj][m][0], v2 = acc[ai][bj][m][1]; const f32x4 o1 = v1 * cs - v2 * sn, o2 = v2 * cs + v1 * sn;
;             u32x4 w = {cvtpk(o1[0], o1[1]), cvtpk(o1[2], o1[3]), cvtpk(o2[0], o2[1]), cvtpk(o2[2], o2[3])}; *(u32x4*)(dst + bj * 128) = w; } }
.LBB0_416:
	s_add_u32 s30, s44, s1
	s_addc_u32 s83, s2, s33
	v_subrev_u32_e32 v90, s65, v90
	v_ashrrev_i32_e32 v91, 31, v90
	s_add_u32 s82, s30, s78
	s_addc_u32 s83, s83, s79
	v_lshlrev_b64 v[90:91], 9, v[90:91]
	v_lshl_add_u64 v[90:91], s[82:83], 0, v[90:91]
	s_lshl_b32 s30, s45, 1
	s_waitcnt vmcnt(0)
	v_mul_f32_e64 v92, v76, v88
	v_mul_f32_e64 v93, v77, v89
	v_mul_f32_e64 v94, v74, v86
	v_mul_f32_e64 v95, v75, v87
	v_mul_f32_e64 v76, v76, v84
	v_mul_f32_e64 v77, v77, v85
	v_mul_f32_e64 v74, v74, v82
	v_mul_f32_e64 v75, v75, v83
	v_lshl_add_u64 v[90:91], v[90:91], 0, s[30:31]
	v_fma_f32 v92, v80, v84, -v92
	v_fma_f32 v93, v81, v85, -v93
	v_fma_f32 v80, v80, v88, v76
	v_fma_f32 v81, v81, v89, v77
	v_fma_f32 v76, v78, v86, v74
	v_fma_f32 v77, v79, v87, v75
	v_lshl_add_u64 v[90:91], v[150:151], 1, v[90:91]
	v_fma_f32 v94, v78, v82, -v94
	v_fma_f32 v95, v79, v83, -v95
	s_nop 0
	v_cvt_pk_bf16_f32 v74, v94, v95
	v_cvt_pk_bf16_f32 v75, v92, v93
	v_cvt_pk_bf16_f32 v76, v76, v77
	v_cvt_pk_bf16_f32 v77, v80, v81
	global_store_dwordx4 v[90:91], v[74:77], off
	s_nop 1
	v_mul_f32_e64 v74, v68, v88
	v_mul_f32_e64 v75, v69, v89
	v_mul_f32_e64 v76, v66, v86
	v_mul_f32_e64 v77, v67, v87
	v_mul_f32_e64 v68, v68, v84
	v_mul_f32_e64 v69, v69, v85
	v_mul_f32_e64 v66, v66, v82
	v_mul_f32_e64 v67, v67, v83
	v_fma_f32 v74, v72, v84, -v74
	v_fma_f32 v75, v73, v85, -v75
	v_fma_f32 v72, v72, v88, v68
	v_fma_f32 v73, v73, v89, v69
	v_fma_f32 v68, v70, v86, v66
	v_fma_f32 v69, v71, v87, v67
	v_fma_f32 v76, v70, v82, -v76
	v_fma_f32 v77, v71, v83, -v77
	s_nop 0
	v_cvt_pk_bf16_f32 v66, v76, v77
	v_cvt_pk_bf16_f32 v67, v74, v75
	v_cvt_pk_bf16_f32 v68, v68, v69
	v_cvt_pk_bf16_f32 v69, v72, v73
	global_store_dwordx4 v[90:91], v[66:69], off offset:256
	v_add_u32_e32 v74, 0x80, v163
	s_and_b64 vcc, exec, s[12:13]
	s_mov_b64 s[82:83], -1
	s_cbranch_vccz .LBB0_378

; __device__ __forceinline__ unsigned cvtpk(float lo, float hi) { unsigned r; asm volatile("v_cvt_pk_bf16_f32 %0, %1, %2" : "=v"(r) : "v"(lo), "v"(hi)); return r; }
;   __device__ __forceinline__ void operator()(const Acc& acc, const gm::Unit& u, int wr, int wc, int fr, int fq) const {
;     ...
;         if (pn < 8) { bf16_t* dst = Qb + (size_t)(pn >> 2) * TT * 1024 + ((size_t)(pm * 4 + (pn & 3)) * 256 + (row - brow)) * 256 + wc * 32 + fq * 8;
;           f32x4 cs = {1.f, 1.f, 1.f, 1.f}, sn = {0.f, 0.f, 0.f, 0.f};
;           if (!isctx) { const int tl = (row % TPB) - CTXL; const int pos = (wc >> 1) ? (tl & 63) : (tl >> 6); const int p0 = (wc & 1) * 16 + fq * 4;
;             cs = *(const f32x4*)(rc + pos * 32 + p0); sn = *(const f32x4*)(rs + pos * 32 + p0); }
; #pragma unroll
;           for (int bj = 0; bj < 2; ++bj) { const f32x4 v1 = acc[ai][bj][m][0], v2 = acc[ai][bj][m][1]; const f32x4 o1 = v1 * cs - v2 * sn, o2 = v2 * cs + v1 * sn;
;             u32x4 w = {cvtpk(o1[0], o1[1]), cvtpk(o1[2], o1[3]), cvtpk(o2[0], o2[1]), cvtpk(o2[2], o2[3])}; *(u32x4*)(dst + bj * 128) = w; } }
.LBB0_421:
	s_add_u32 s30, s44, s1
	s_addc_u32 s83, s2, s33
	v_subrev_u32_e32 v74, s65, v74
	v_ashrrev_i32_e32 v75, 31, v74
	s_add_u32 s82, s30, s78
	s_addc_u32 s83, s83, s79
	v_lshlrev_b64 v[74:75], 9, v[74:75]
	v_lshl_add_u64 v[74:75], s[82:83], 0, v[74:75]
	s_lshl_b32 s30, s45, 1
	s_waitcnt vmcnt(0)
	v_mul_f32_e64 v76, v60, v72
	v_mul_f32_e64 v77, v61, v73
	v_mul_f32_e64 v78, v58, v70
	v_mul_f32_e64 v79, v59, v71
	v_mul_f32_e64 v60, v60, v68
	v_mul_f32_e64 v61, v61, v69
	v_mul_f32_e64 v58, v58, v66
	v_mul_f32_e64 v59, v59, v67
	v_lshl_add_u64 v[74:75], v[74:75], 0, s[30:31]
	v_fma_f32 v76, v64, v68, -v76
	v_fma_f32 v77, v65, v69, -v77
	v_fma_f32 v64, v64, v72, v60
	v_fma_f32 v65, v65, v73, v61
	v_fma_f32 v60, v62, v70, v58
	v_fma_f32 v61, v63, v71, v59
	v_lshl_add_u64 v[74:75], v[150:151], 1, v[74:75]
	v_fma_f32 v78, v62, v66, -v78
	v_fma_f32 v79, v63, v67, -v79
	s_nop 0
	v_cvt_pk_bf16_f32 v58, v78, v79
	v_cvt_pk_bf16_f32 v59, v76, v77
	v_cvt_pk_bf16_f32 v60, v60, v61
	v_cvt_pk_bf16_f32 v61, v64, v65
	global_store_dwordx4 v[74:75], v[58:61], off
	s_nop 1
	v_mul_f32_e64 v58, v52, v72
	v_mul_f32_e64 v59, v53, v73
	v_mul_f32_e64 v60, v50, v70
	v_mul_f32_e64 v61, v51, v71
	v_mul_f32_e64 v52, v52, v68
	v_mul_f32_e64 v53, v53, v69
	v_mul_f32_e64 v50, v50, v66
	v_mul_f32_e64 v51, v51, v67
	v_fma_f32 v58, v56, v68, -v58
	v_fma_f32 v59, v57, v69, -v59
	v_fma_f32 v56, v56, v72, v52
	v_fma_f32 v57, v57, v73, v53
	v_fma_f32 v52, v54, v70, v50
	v_fma_f32 v53, v55, v71, v51
	v_fma_f32 v60, v54, v66, -v60
	v_fma_f32 v61, v55, v67, -v61
	s_nop 0
	v_cvt_pk_bf16_f32 v50, v60, v61
	v_cvt_pk_bf16_f32 v51, v58, v59
	v_cvt_pk_bf16_f32 v52, v52, v53
	v_cvt_pk_bf16_f32 v53, v56, v57
	global_store_dwordx4 v[74:75], v[50:53], off offset:256
	v_add_u32_e32 v58, 0x90, v163
	s_and_b64 vcc, exec, s[12:13]
	s_mov_b64 s[82:83], -1
	s_cbranch_vccz .LBB0_388

; __device__ __forceinline__ unsigned cvtpk(float lo, float hi) { unsigned r; asm volatile("v_cvt_pk_bf16_f32 %0, %1, %2" : "=v"(r) : "v"(lo), "v"(hi)); return r; }
;   __device__ __forceinline__ void operator()(const Acc& acc, const gm::Unit& u, int wr, int wc, int fr, int fq) const {
;     ...
;         if (pn < 8) { bf16_t* dst = Qb + (size_t)(pn >> 2) * TT * 1024 + ((size_t)(pm * 4 + (pn & 3)) * 256 + (row - brow)) * 256 + wc * 32 + fq * 8;
;           f32x4 cs = {1.f, 1.f, 1.f, 1.f}, sn = {0.f, 0.f, 0.f, 0.f};
;           if (!isctx) { const int tl = (row % TPB) - CTXL; const int pos = (wc >> 1) ? (tl & 63) : (tl >> 6); const int p0 = (wc & 1) * 16 + fq * 4;
;             cs = *(const f32x4*)(rc + pos * 32 + p0); sn = *(const f32x4*)(rs + pos * 32 + p0); }
; #pragma unroll
;           for (int bj = 0; bj < 2; ++bj) { const f32x4 v1 = acc[ai][bj][m][0], v2 = acc[ai][bj][m][1]; const f32x4 o1 = v1 * cs - v2 * sn, o2 = v2 * cs + v1 * sn;
;             u32x4 w = {cvtpk(o1[0], o1[1]), cvtpk(o1[2], o1[3]), cvtpk(o2[0], o2[1]), cvtpk(o2[2], o2[3])}; *(u32x4*)(dst + bj * 128) = w; } }
.LBB0_426:
	s_add_u32 s30, s44, s1
	s_addc_u32 s83, s2, s33
	v_subrev_u32_e32 v58, s65, v58
	v_ashrrev_i32_e32 v59, 31, v58
	s_add_u32 s82, s30, s78
	s_addc_u32 s83, s83, s79
	v_lshlrev_b64 v[58:59], 9, v[58:59]
	v_lshl_add_u64 v[58:59], s[82:83], 0, v[58:59]
	s_lshl_b32 s30, s45, 1
	s_waitcnt vmcnt(0)
	v_mul_f32_e64 v60, v44, v56
	v_mul_f32_e64 v61, v45, v57
	v_mul_f32_e64 v62, v42, v54
	v_mul_f32_e64 v63, v43, v55
	v_mul_f32_e64 v44, v44, v52
	v_mul_f32_e64 v45, v45, v53
	v_mul_f32_e64 v42, v42, v50
	v_mul_f32_e64 v43, v43, v51
	v_lshl_add_u64 v[58:59], v[58:59], 0, s[30:31]
	v_fma_f32 v60, v48, v52, -v60
	v_fma_f32 v61, v49, v53, -v61
	v_fma_f32 v48, v48, v56, v44
	v_fma_f32 v49, v49, v57, v45
	v_fma_f32 v44, v46, v54, v42
	v_fma_f32 v45, v47, v55, v43
	v_lshl_add_u64 v[58:59], v[150:151], 1, v[58:59]
	v_fma_f32 v62, v46, v50, -v62
	v_fma_f32 v63, v47, v51, -v63
	s_nop 0
	v_cvt_pk_bf16_f32 v42, v62, v63
	v_cvt_pk_bf16_f32 v43, v60, v61
	v_cvt_pk_bf16_f32 v44, v44, v45
	v_cvt_pk_bf16_f32 v45, v48, v49
	global_store_dwordx4 v[58:59], v[42:45], off
	s_nop 1
	v_mul_f32_e64 v42, v36, v56
	v_mul_f32_e64 v43, v37, v57
	v_mul_f32_e64 v44, v34, v54
	v_mul_f32_e64 v45, v35, v55
	v_mul_f32_e64 v36, v36, v52
	v_mul_f32_e64 v37, v37, v53
	v_mul_f32_e64 v34, v34, v50
	v_mul_f32_e64 v35, v35, v51
	v_fma_f32 v42, v40, v52, -v42
	v_fma_f32 v43, v41, v53, -v43
	v_fma_f32 v40, v40, v56, v36
	v_fma_f32 v41, v41, v57, v37
	v_fma_f32 v36, v38, v54, v34
	v_fma_f32 v37, v39, v55, v35
	v_fma_f32 v44, v38, v50, -v44
	v_fma_f32 v45, v39, v51, -v45
	s_nop 0
	v_cvt_pk_bf16_f32 v34, v44, v45
	v_cvt_pk_bf16_f32 v35, v42, v43
	v_cvt_pk_bf16_f32 v36, v36, v37
	v_cvt_pk_bf16_f32 v37, v40, v41
	global_store_dwordx4 v[58:59], v[34:37], off offset:256
	v_add_u32_e32 v42, 0xa0, v163
	s_and_b64 vcc, exec, s[12:13]
	s_mov_b64 s[82:83], -1
	s_cbranch_vccz .LBB0_398

; __device__ __forceinline__ unsigned cvtpk(float lo, float hi) { unsigned r; asm volatile("v_cvt_pk_bf16_f32 %0, %1, %2" : "=v"(r) : "v"(lo), "v"(hi)); return r; }
;   __device__ __forceinline__ void operator()(const Acc& acc, const gm::Unit& u, int wr, int wc, int fr, int fq) const {
;     ...
;         if (pn < 8) { bf16_t* dst = Qb + (size_t)(pn >> 2) * TT * 1024 + ((size_t)(pm * 4 + (pn & 3)) * 256 + (row - brow)) * 256 + wc * 32 + fq * 8;
;           f32x4 cs = {1.f, 1.f, 1.f, 1.f}, sn = {0.f, 0.f, 0.f, 0.f};
;           if (!isctx) { const int tl = (row % TPB) - CTXL; const int pos = (wc >> 1) ? (tl & 63) : (tl >> 6); const int p0 = (wc & 1) * 16 + fq * 4;
;             cs = *(const f32x4*)(rc + pos * 32 + p0); sn = *(const f32x4*)(rs + pos * 32 + p0); }
; #pragma unroll
;           for (int bj = 0; bj < 2; ++bj) { const f32x4 v1 = acc[ai][bj][m][0], v2 = acc[ai][bj][m][1]; const f32x4 o1 = v1 * cs - v2 * sn, o2 = v2 * cs + v1 * sn;
;             u32x4 w = {cvtpk(o1[0], o1[1]), cvtpk(o1[2], o1[3]), cvtpk(o2[0], o2[1]), cvtpk(o2[2], o2[3])}; *(u32x4*)(dst + bj * 128) = w; } }
.LBB0_431:
	s_add_u32 s30, s44, s1
	s_addc_u32 s83, s2, s33
	v_subrev_u32_e32 v42, s65, v42
	v_ashrrev_i32_e32 v43, 31, v42
	s_add_u32 s82, s30, s78
	s_addc_u32 s83, s83, s79
	v_lshlrev_b64 v[42:43], 9, v[42:43]
	v_lshl_add_u64 v[42:43], s[82:83], 0, v[42:43]
	s_lshl_b32 s30, s45, 1
	s_waitcnt vmcnt(0)
	v_mul_f32_e64 v44, v28, v40
	v_mul_f32_e64 v45, v29, v41
	v_mul_f32_e64 v46, v26, v38
	v_mul_f32_e64 v47, v27, v39
	v_mul_f32_e64 v28, v28, v36
	v_mul_f32_e64 v29, v29, v37
	v_mul_f32_e64 v26, v26, v34
	v_mul_f32_e64 v27, v27, v35
	v_lshl_add_u64 v[42:43], v[42:43], 0, s[30:31]
	v_fma_f32 v44, v32, v36, -v44
	v_fma_f32 v45, v33, v37, -v45
	v_fma_f32 v32, v32, v40, v28
	v_fma_f32 v33, v33, v41, v29
	v_fma_f32 v28, v30, v38, v26
	v_fma_f32 v29, v31, v39, v27
	v_lshl_add_u64 v[42:43], v[150:151], 1, v[42:43]
	v_fma_f32 v46, v30, v34, -v46
	v_fma_f32 v47, v31, v35, -v47
	s_nop 0
	v_cvt_pk_bf16_f32 v26, v46, v47
	v_cvt_pk_bf16_f32 v27, v44, v45
	v_cvt_pk_bf16_f32 v28, v28, v29
	v_cvt_pk_bf16_f32 v29, v32, v33
	global_store_dwordx4 v[42:43], v[26:29], off
	s_nop 1
	v_mul_f32_e64 v26, v20, v40
	v_mul_f32_e64 v27, v21, v41
	v_mul_f32_e64 v28, v18, v38
	v_mul_f32_e64 v29, v19, v39
	v_mul_f32_e64 v20, v20, v36
	v_mul_f32_e64 v21, v21, v37
	v_mul_f32_e64 v18, v18, v34
	v_mul_f32_e64 v19, v19, v35
	v_fma_f32 v26, v24, v36, -v26
	v_fma_f32 v27, v25, v37, -v27
	v_fma_f32 v24, v24, v40, v20
	v_fma_f32 v25, v25, v41, v21
	v_fma_f32 v20, v22, v38, v18
	v_fma_f32 v21, v23, v39, v19
	v_fma_f32 v28, v22, v34, -v28
	v_fma_f32 v29, v23, v35, -v29
	s_nop 0
	v_cvt_pk_bf16_f32 v18, v28, v29
	v_cvt_pk_bf16_f32 v19, v26, v27
	v_cvt_pk_bf16_f32 v20, v20, v21
	v_cvt_pk_bf16_f32 v21, v24, v25
	global_store_dwordx4 v[42:43], v[18:21], off offset:256

; __device__ __forceinline__ unsigned cvtpk(float lo, float hi) { unsigned r; asm volatile("v_cvt_pk_bf16_f32 %0, %1, %2" : "=v"(r) : "v"(lo), "v"(hi)); return r; }
;   __device__ __forceinline__ void operator()(const Acc& acc, const gm::Unit& u, int wr, int wc, int fr, int fq) const {
;     ...
;         if (pn < 8) { bf16_t* dst = Qb + (size_t)(pn >> 2) * TT * 1024 + ((size_t)(pm * 4 + (pn & 3)) * 256 + (row - brow)) * 256 + wc * 32 + fq * 8;
;           f32x4 cs = {1.f, 1.f, 1.f, 1.f}, sn = {0.f, 0.f, 0.f, 0.f};
;           if (!isctx) { const int tl = (row % TPB) - CTXL; const int pos = (wc >> 1) ? (tl & 63) : (tl >> 6); const int p0 = (wc & 1) * 16 + fq * 4;
;             cs = *(const f32x4*)(rc + pos * 32 + p0); sn = *(const f32x4*)(rs + pos * 32 + p0); }
; #pragma unroll
;           for (int bj = 0; bj < 2; ++bj) { const f32x4 v1 = acc[ai][bj][m][0], v2 = acc[ai][bj][m][1]; const f32x4 o1 = v1 * cs - v2 * sn, o2 = v2 * cs + v1 * sn;
;             u32x4 w = {cvtpk(o1[0], o1[1]), cvtpk(o1[2], o1[3]), cvtpk(o2[0], o2[1]), cvtpk(o2[2], o2[3])}; *(u32x4*)(dst + bj * 128) = w; } }
.LBB0_446:
	s_add_u32 s0, s44, s1
	s_addc_u32 s1, s2, s33
	v_subrev_u32_e32 v26, s65, v26
	v_ashrrev_i32_e32 v27, 31, v26
	s_add_u32 s0, s0, s78
	s_addc_u32 s1, s1, s79
	v_lshlrev_b64 v[26:27], 9, v[26:27]
	v_lshl_add_u64 v[26:27], s[0:1], 0, v[26:27]
	s_lshl_b32 s30, s45, 1
	s_waitcnt vmcnt(0)
	v_mul_f32_e64 v28, v12, v24
	v_mul_f32_e64 v29, v13, v25
	v_mul_f32_e64 v30, v10, v22
	v_mul_f32_e64 v31, v11, v23
	v_mul_f32_e64 v12, v12, v20
	v_mul_f32_e64 v13, v13, v21
	v_mul_f32_e64 v10, v10, v18
	v_mul_f32_e64 v11, v11, v19
	v_lshl_add_u64 v[26:27], v[26:27], 0, s[30:31]
	v_fma_f32 v28, v16, v20, -v28
	v_fma_f32 v29, v17, v21, -v29
	v_fma_f32 v16, v16, v24, v12
	v_fma_f32 v17, v17, v25, v13
	v_fma_f32 v12, v14, v22, v10
	v_fma_f32 v13, v15, v23, v11
	v_lshl_add_u64 v[26:27], v[150:151], 1, v[26:27]
	v_fma_f32 v30, v14, v18, -v30
	v_fma_f32 v31, v15, v19, -v31
	s_nop 0
	v_cvt_pk_bf16_f32 v10, v30, v31
	v_cvt_pk_bf16_f32 v11, v28, v29
	v_cvt_pk_bf16_f32 v12, v12, v13
	v_cvt_pk_bf16_f32 v13, v16, v17
	global_store_dwordx4 v[26:27], v[10:13], off
	s_nop 1
	v_mul_f32_e64 v10, v4, v24
	v_mul_f32_e64 v11, v5, v25
	v_mul_f32_e64 v12, v2, v22
	v_mul_f32_e64 v13, v3, v23
	v_mul_f32_e64 v4, v4, v20
	v_mul_f32_e64 v5, v5, v21
	v_mul_f32_e64 v2, v2, v18
	v_mul_f32_e64 v3, v3, v19
	v_fma_f32 v10, v8, v20, -v10
	v_fma_f32 v11, v9, v21, -v11
	v_fma_f32 v8, v8, v24, v4
	v_fma_f32 v9, v9, v25, v5
	v_fma_f32 v4, v6, v22, v2
	v_fma_f32 v5, v7, v23, v3
	v_fma_f32 v12, v6, v18, -v12
	v_fma_f32 v13, v7, v19, -v13
	s_nop 0
	v_cvt_pk_bf16_f32 v2, v12, v13
	v_cvt_pk_bf16_f32 v3, v10, v11
	v_cvt_pk_bf16_f32 v4, v4, v5
	v_cvt_pk_bf16_f32 v5, v8, v9
	global_store_dwordx4 v[26:27], v[2:5], off offset:256

; __device__ __forceinline__ unsigned cvtpk(float lo, float hi) { unsigned r; asm volatile("v_cvt_pk_bf16_f32 %0, %1, %2" : "=v"(r) : "v"(lo), "v"(hi)); return r; }
; __device__ __forceinline__ void ssm_carry(const Params& p, const Ctx& c, int l, float* lds) {
;     ...
;   if (act) {
; #pragma unroll
;     for (int kk = 0; kk < 17; ++kk) { const int k = 17 * w + kk; const int ch = d == 0 ? k : (k < 8 ? 7 - k : 143 - k);
;       *(unsigned*)(UG + (rbase + ch) * 768 + 512 + col) = cvtpk(hl[kk].x + pr, hl[kk].y + pi);
;       const float nr = a32.x * pr - a32.y * pi, ni = a32.x * pi + a32.y * pr; pr = nr; pi = ni; } }
.LBB0_600:
	s_or_b64 exec, exec, s[54:55]
	v_cvt_pk_bf16_f32 v39, v64, v65
	v_mov_b64_e32 v[64:65], s[8:9]
	v_mad_u64_u32 v[92:93], s[2:3], v20, s35, v[64:65]
	v_mad_i32_i24 v93, v21, s35, v93
	v_lshlrev_b32_e32 v20, 1, v118
	v_mov_b32_e32 v21, v0
	v_lshl_add_u64 v[92:93], v[92:93], 0, v[20:21]
	v_add_co_u32_e32 v92, vcc, 0x1e0d0000, v92
	v_add_f32_e32 v41, v87, v89
	s_nop 0
	v_addc_co_u32_e32 v93, vcc, 0, v93, vcc
	global_store_dword v[92:93], v39, off offset:1024
	v_add_f32_e32 v39, v86, v88
	v_mad_u64_u32 v[86:87], s[2:3], v14, s35, v[64:65]
	v_mad_i32_i24 v87, v15, s35, v87
	v_lshl_add_u64 v[14:15], v[86:87], 0, v[20:21]
	s_mov_b32 s1, 0x1e0d0000
	v_add_co_u32_e32 v14, vcc, s1, v14
	v_mov_b32_e32 v90, v89
	s_nop 0
	v_addc_co_u32_e32 v15, vcc, 0, v15, vcc
	v_mov_b32_e32 v91, v88
	v_cvt_pk_bf16_f32 v39, v39, v41
	global_store_dword v[14:15], v39, off offset:1024
	v_mul_f32_e32 v14, v2, v88
	v_fma_f32 v39, -v3, v89, v14
	v_mul_f32_e64 v14, v2, v90
	v_mul_f32_e64 v15, v3, v91
	s_add_i32 s0, s0, s5
	v_add_f32_e32 v41, v14, v15
	v_add_f32_e32 v14, v80, v39
	v_add_f32_e32 v15, v82, v41
	v_cvt_pk_bf16_f32 v80, v14, v15
	v_mad_u64_u32 v[14:15], s[2:3], v8, s35, v[64:65]
	v_mad_i32_i24 v15, v9, s35, v15
	v_lshl_add_u64 v[8:9], v[14:15], 0, v[20:21]
	v_add_co_u32_e32 v8, vcc, s1, v8
	v_mul_f32_e32 v15, v3, v39
	s_nop 0
	v_addc_co_u32_e32 v9, vcc, 0, v9, vcc
	global_store_dword v[8:9], v80, off offset:1024
	v_mul_f32_e32 v8, v2, v39
	v_fma_f32 v14, -v3, v41, v8
	v_fmac_f32_e32 v15, v2, v41
	v_add_f32_e32 v8, v84, v14
	v_add_f32_e32 v9, v85, v15
	v_cvt_pk_bf16_f32 v39, v8, v9
	v_mad_u64_u32 v[8:9], s[2:3], v4, s35, v[64:65]
	v_mad_i32_i24 v9, v5, s35, v9
	v_lshl_add_u64 v[4:5], v[8:9], 0, v[20:21]
	v_add_co_u32_e32 v4, vcc, s1, v4
	v_mul_f32_e32 v9, v3, v14
	s_nop 0
	v_addc_co_u32_e32 v5, vcc, 0, v5, vcc
	global_store_dword v[4:5], v39, off offset:1024
	v_mul_f32_e32 v4, v2, v14
	v_fma_f32 v8, -v3, v15, v4
	v_fmac_f32_e32 v9, v2, v15
	v_add_f32_e32 v4, v76, v8
	v_add_f32_e32 v5, v78, v9
	v_cvt_pk_bf16_f32 v14, v4, v5
	v_mad_u64_u32 v[4:5], s[2:3], v36, s35, v[64:65]
	v_mad_i32_i24 v5, v37, s35, v5
	v_lshl_add_u64 v[4:5], v[4:5], 0, v[20:21]
	v_add_co_u32_e32 v4, vcc, s1, v4
	s_cmpk_gt_i32 s0, 0x3fff
	s_nop 0
	v_addc_co_u32_e32 v5, vcc, 0, v5, vcc
	global_store_dword v[4:5], v14, off offset:1024
	v_mul_f32_e32 v4, v2, v8
	v_mul_f32_e32 v8, v3, v8
	v_fma_f32 v14, -v3, v9, v4
	v_fmac_f32_e32 v8, v2, v9
	v_add_f32_e32 v4, v74, v14
	v_add_f32_e32 v5, v75, v8
	v_cvt_pk_bf16_f32 v9, v4, v5
	v_mad_u64_u32 v[4:5], s[2:3], v34, s35, v[64:65]
	v_mad_i32_i24 v5, v35, s35, v5
	v_lshl_add_u64 v[4:5], v[4:5], 0, v[20:21]
	v_add_co_u32_e32 v4, vcc, s1, v4
	s_nop 1
	v_addc_co_u32_e32 v5, vcc, 0, v5, vcc
	global_store_dword v[4:5], v9, off offset:1024
	v_mul_f32_e32 v4, v2, v14
	v_mul_f32_e32 v14, v3, v14
	v_fma_f32 v9, -v3, v8, v4
	v_fmac_f32_e32 v14, v2, v8
	v_add_f32_e32 v4, v70, v9
	v_add_f32_e32 v5, v72, v14
	v_cvt_pk_bf16_f32 v8, v4, v5
	v_mad_u64_u32 v[4:5], s[2:3], v30, s35, v[64:65]
	v_mad_i32_i24 v5, v31, s35, v5
	v_lshl_add_u64 v[4:5], v[4:5], 0, v[20:21]
	v_add_co_u32_e32 v4, vcc, s1, v4
	s_nop 1
	v_addc_co_u32_e32 v5, vcc, 0, v5, vcc
	global_store_dword v[4:5], v8, off offset:1024
	v_mul_f32_e32 v4, v2, v9
	v_mul_f32_e32 v9, v3, v9
	v_fma_f32 v8, -v3, v14, v4
	v_fmac_f32_e32 v9, v2, v14
	v_add_f32_e32 v4, v68, v8
	v_add_f32_e32 v5, v69, v9
	v_cvt_pk_bf16_f32 v14, v4, v5
	v_mad_u64_u32 v[4:5], s[2:3], v26, s35, v[64:65]
	v_mad_i32_i24 v5, v27, s35, v5
	v_lshl_add_u64 v[4:5], v[4:5], 0, v[20:21]
	v_add_co_u32_e32 v4, vcc, s1, v4
	s_nop 1
	v_addc_co_u32_e32 v5, vcc, 0, v5, vcc
	global_store_dword v[4:5], v14, off offset:1024
	v_mul_f32_e32 v4, v2, v8
	v_mul_f32_e32 v8, v3, v8
	v_fma_f32 v14, -v3, v9, v4
	v_fmac_f32_e32 v8, v2, v9
	v_add_f32_e32 v4, v62, v14
	v_add_f32_e32 v5, v66, v8
	v_cvt_pk_bf16_f32 v9, v4, v5
	v_mad_u64_u32 v[4:5], s[2:3], v32, s35, v[64:65]
	v_mad_i32_i24 v5, v33, s35, v5
	v_lshl_add_u64 v[4:5], v[4:5], 0, v[20:21]
	v_add_co_u32_e32 v4, vcc, s1, v4
	s_nop 1
	v_addc_co_u32_e32 v5, vcc, 0, v5, vcc
	global_store_dword v[4:5], v9, off offset:1024
	v_mul_f32_e32 v4, v2, v14
	v_mul_f32_e32 v14, v3, v14
	v_fma_f32 v9, -v3, v8, v4
	v_fmac_f32_e32 v14, v2, v8
	v_add_f32_e32 v4, v60, v9
	v_add_f32_e32 v5, v61, v14
	v_cvt_pk_bf16_f32 v8, v4, v5
	v_mad_u64_u32 v[4:5], s[2:3], v28, s35, v[64:65]
	v_mad_i32_i24 v5, v29, s35, v5
	v_lshl_add_u64 v[4:5], v[4:5], 0, v[20:21]
	v_add_co_u32_e32 v4, vcc, s1, v4
	s_nop 1
	v_addc_co_u32_e32 v5, vcc, 0, v5, vcc
	global_store_dword v[4:5], v8, off offset:1024
	v_mul_f32_e32 v4, v2, v9
	v_mul_f32_e32 v9, v3, v9
	v_fma_f32 v8, -v3, v14, v4
	v_fmac_f32_e32 v9, v2, v14
	v_add_f32_e32 v4, v56, v8
	v_add_f32_e32 v5, v58, v9
	v_cvt_pk_bf16_f32 v14, v4, v5
	v_mad_u64_u32 v[4:5], s[2:3], v22, s35, v[64:65]
	v_mad_i32_i24 v5, v23, s35, v5
	v_lshl_add_u64 v[4:5], v[4:5], 0, v[20:21]
	v_add_co_u32_e32 v4, vcc, s1, v4
	s_nop 1
	v_addc_co_u32_e32 v5, vcc, 0, v5, vcc
	global_store_dword v[4:5], v14, off offset:1024
	v_mul_f32_e32 v4, v2, v8
	v_mul_f32_e32 v8, v3, v8
	v_fma_f32 v14, -v3, v9, v4
	v_fmac_f32_e32 v8, v2, v9
	v_add_f32_e32 v4, v54, v14
	v_add_f32_e32 v5, v55, v8
	v_cvt_pk_bf16_f32 v9, v4, v5
	v_mad_u64_u32 v[4:5], s[2:3], v16, s35, v[64:65]
	v_mad_i32_i24 v5, v17, s35, v5
	v_lshl_add_u64 v[4:5], v[4:5], 0, v[20:21]
	v_add_co_u32_e32 v4, vcc, s1, v4
	s_nop 1
	v_addc_co_u32_e32 v5, vcc, 0, v5, vcc
	global_store_dword v[4:5], v9, off offset:1024
	v_mul_f32_e32 v4, v2, v14
	v_mul_f32_e32 v14, v3, v14
	v_fma_f32 v9, -v3, v8, v4
	v_fmac_f32_e32 v14, v2, v8
	v_add_f32_e32 v4, v50, v9
	v_add_f32_e32 v5, v52, v14
; __device__ __forceinline__ unsigned cvtpk(float lo, float hi) { unsigned r; asm volatile("v_cvt_pk_bf16_f32 %0, %1, %2" : "=v"(r) : "v"(lo), "v"(hi)); return r; }
; __device__ __forceinline__ void ssm_carry(const Params& p, const Ctx& c, int l, float* lds) {
;     ...
;   const int i = base + c.lane; const bool act = true; const int ii = i;
;   const int pp = ii & 63, d = (ii >> 6) & 1, g = (ii >> 7) & 31, b = ii >> 12, w = c.wid;
;   const float2 a32 = PW[((size_t)(g * 2 + d) * 33 + 32) * 64 + pp];
;   const size_t rbase = (size_t)g * 768 + b * 136; const int col = (d * 64 + pp) * 2;
;   float2 s[17], hl[17];
; #pragma unroll
;   for (int kk = 0; kk < 17; ++kk) { const int k = 17 * w + kk; const int ch = d == 0 ? k : (k < 8 ? 7 - k : 143 - k); s[kk] = *(const float2*)(SB + (rbase + ch) * 256 + col); }
;     ...
;     for (int kk = 0; kk < 17; ++kk) { const int k = 17 * w + kk; const int ch = d == 0 ? k : (k < 8 ? 7 - k : 143 - k);
;       *(unsigned*)(UG + (rbase + ch) * 768 + 512 + col) = cvtpk(hl[kk].x + pr, hl[kk].y + pi);
;       const float nr = a32.x * pr - a32.y * pi, ni = a32.x * pi + a32.y * pr; pr = nr; pi = ni; } }
	v_cvt_pk_bf16_f32 v8, v4, v5
	v_mad_u64_u32 v[4:5], s[2:3], v24, s35, v[64:65]
	v_mad_i32_i24 v5, v25, s35, v5
	v_lshl_add_u64 v[4:5], v[4:5], 0, v[20:21]
	v_add_co_u32_e32 v4, vcc, s1, v4
	s_nop 1
	v_addc_co_u32_e32 v5, vcc, 0, v5, vcc
	global_store_dword v[4:5], v8, off offset:1024
	v_mul_f32_e32 v4, v2, v9
	v_mul_f32_e32 v9, v3, v9
	v_fma_f32 v8, -v3, v14, v4
	v_fmac_f32_e32 v9, v2, v14
	v_add_f32_e32 v4, v48, v8
	v_add_f32_e32 v5, v49, v9
	v_cvt_pk_bf16_f32 v14, v4, v5
	v_mad_u64_u32 v[4:5], s[2:3], v18, s35, v[64:65]
	v_mad_i32_i24 v5, v19, s35, v5
	v_lshl_add_u64 v[4:5], v[4:5], 0, v[20:21]
	v_add_co_u32_e32 v4, vcc, s1, v4
	s_nop 1
	v_addc_co_u32_e32 v5, vcc, 0, v5, vcc
	global_store_dword v[4:5], v14, off offset:1024
	v_mul_f32_e32 v4, v2, v8
	v_mul_f32_e32 v8, v3, v8
	v_fma_f32 v14, -v3, v9, v4
	v_fmac_f32_e32 v8, v2, v9
	v_add_f32_e32 v4, v44, v14
	v_add_f32_e32 v5, v46, v8
	v_cvt_pk_bf16_f32 v9, v4, v5
	v_mad_u64_u32 v[4:5], s[2:3], v10, s35, v[64:65]
	v_mad_i32_i24 v5, v11, s35, v5
	v_lshl_add_u64 v[4:5], v[4:5], 0, v[20:21]
	v_add_co_u32_e32 v4, vcc, s1, v4
	v_mul_f32_e32 v10, v3, v14
	s_nop 0
	v_addc_co_u32_e32 v5, vcc, 0, v5, vcc
	global_store_dword v[4:5], v9, off offset:1024
	v_mul_f32_e32 v4, v2, v14
	v_fma_f32 v9, -v3, v8, v4
	v_fmac_f32_e32 v10, v2, v8
	v_add_f32_e32 v4, v42, v9
	v_add_f32_e32 v5, v43, v10
	v_cvt_pk_bf16_f32 v8, v4, v5
	v_mad_u64_u32 v[4:5], s[2:3], v6, s35, v[64:65]
	v_mad_i32_i24 v5, v7, s35, v5
	v_lshl_add_u64 v[4:5], v[4:5], 0, v[20:21]
	v_add_co_u32_e32 v4, vcc, s1, v4
	s_nop 1
	v_addc_co_u32_e32 v5, vcc, 0, v5, vcc
	global_store_dword v[4:5], v8, off offset:1024
	v_mul_f32_e32 v4, v2, v9
	v_fma_f32 v4, -v3, v10, v4
	v_mul_f32_e32 v3, v3, v9
	v_fmac_f32_e32 v3, v2, v10
	v_add_f32_e32 v2, v38, v4
	v_add_f32_e32 v3, v40, v3
	v_cvt_pk_bf16_f32 v4, v2, v3
	v_mad_u64_u32 v[2:3], s[2:3], v12, s35, v[64:65]
	v_mad_i32_i24 v3, v13, s35, v3
	v_lshl_add_u64 v[2:3], v[2:3], 0, v[20:21]
	v_add_co_u32_e32 v2, vcc, 0x1e0d0000, v2
	s_nop 1
	v_addc_co_u32_e32 v3, vcc, 0, v3, vcc
	global_store_dword v[2:3], v4, off offset:1024
	s_barrier
	s_cbranch_scc1 .LBB0_605
.LBB0_601:
	s_bfe_u32 s2, s0, 0x50007
	s_bfe_u32 s1, s0, 0x10006
	s_lshl_b32 s4, s2, 1
	s_ashr_i32 s3, s0, 12
	s_or_b32 s4, s4, s1
	s_mulk_i32 s4, 0x840
	s_mulk_i32 s3, 0x88
	v_add_lshl_u32 v18, s4, v45, 3
	s_mulk_i32 s2, 0x300
	s_ashr_i32 s4, s3, 31
	s_add_u32 s54, s2, s3
	s_addc_u32 s55, 0, s4
	v_lshl_or_b32 v118, s1, 7, v47
	s_cmp_eq_u32 s1, 0
	v_lshlrev_b32_e32 v2, 2, v118
	v_mov_b32_e32 v3, v0
	s_cselect_b64 vcc, -1, 0
	v_lshl_add_u64 v[40:41], s[12:13], 0, v[2:3]
	v_cndmask_b32_e32 v2, v53, v51, vcc
	v_ashrrev_i32_e32 v3, 31, v2
	v_lshl_add_u64 v[20:21], s[54:55], 0, v[2:3]
	v_lshlrev_b64 v[2:3], 10, v[20:21]
	v_lshl_add_u64 v[6:7], v[40:41], 0, v[2:3]
	v_cndmask_b32_e32 v2, v59, v57, vcc
	v_ashrrev_i32_e32 v3, 31, v2
	v_lshl_add_u64 v[14:15], s[54:55], 0, v[2:3]
	v_lshlrev_b64 v[2:3], 10, v[14:15]
	v_lshl_add_u64 v[10:11], v[40:41], 0, v[2:3]
	v_cndmask_b32_e32 v2, v67, v63, vcc
	v_ashrrev_i32_e32 v3, 31, v2
	v_lshl_add_u64 v[8:9], s[54:55], 0, v[2:3]
	v_lshlrev_b64 v[2:3], 10, v[8:9]
	v_lshl_add_u64 v[12:13], v[40:41], 0, v[2:3]
	v_cndmask_b32_e32 v2, v73, v71, vcc
	v_ashrrev_i32_e32 v3, 31, v2
	v_lshl_add_u64 v[4:5], s[54:55], 0, v[2:3]
	v_lshlrev_b64 v[2:3], 10, v[4:5]
	v_lshl_add_u64 v[2:3], v[40:41], 0, v[2:3]
	global_load_dwordx2 v[38:39], v[2:3], off
	s_nop 0
	global_load_dwordx2 v[2:3], v18, s[10:11]
	global_load_dwordx2 v[42:43], v[10:11], off
	global_load_dwordx2 v[48:49], v[12:13], off
	global_load_dwordx2 v[54:55], v[6:7], off
	v_cndmask_b32_e32 v16, v79, v77, vcc
	v_ashrrev_i32_e32 v17, 31, v16
	v_lshl_add_u64 v[36:37], s[54:55], 0, v[16:17]
	v_cndmask_b32_e32 v10, v83, v81, vcc
	v_cndmask_b32_e32 v16, v97, v96, vcc
	v_ashrrev_i32_e32 v11, 31, v10
	v_cndmask_b32_e32 v12, v95, v94, vcc
	v_ashrrev_i32_e32 v17, 31, v16
	v_lshl_add_u64 v[34:35], s[54:55], 0, v[10:11]
	v_ashrrev_i32_e32 v13, 31, v12
	v_lshl_add_u64 v[26:27], s[54:55], 0, v[16:17]
	v_lshlrev_b64 v[10:11], 10, v[34:35]
	v_lshl_add_u64 v[30:31], s[54:55], 0, v[12:13]
	v_lshlrev_b64 v[16:17], 10, v[26:27]
	v_lshlrev_b64 v[6:7], 10, v[36:37]
	v_lshl_add_u64 v[10:11], v[40:41], 0, v[10:11]
	v_lshlrev_b64 v[12:13], 10, v[30:31]
	v_lshl_add_u64 v[16:17], v[40:41], 0, v[16:17]
	v_lshl_add_u64 v[6:7], v[40:41], 0, v[6:7]
	v_lshl_add_u64 v[12:13], v[40:41], 0, v[12:13]
	global_load_dwordx2 v[60:61], v[16:17], off
	global_load_dwordx2 v[68:69], v[10:11], off
	global_load_dwordx2 v[90:91], v[12:13], off
	global_load_dwordx2 v[74:75], v[6:7], off
	v_cndmask_b32_e32 v16, v99, v98, vcc
	v_ashrrev_i32_e32 v17, 31, v16
	v_cndmask_b32_e32 v10, v101, v100, vcc
	v_lshl_add_u64 v[32:33], s[54:55], 0, v[16:17]
	v_ashrrev_i32_e32 v11, 31, v10
	v_cndmask_b32_e32 v12, v103, v102, vcc
	v_cndmask_b32_e32 v16, v105, v104, vcc
	v_lshl_add_u64 v[28:29], s[54:55], 0, v[10:11]
	v_ashrrev_i32_e32 v13, 31, v12
	v_ashrrev_i32_e32 v17, 31, v16
	v_lshlrev_b64 v[10:11], 10, v[28:29]
	v_lshl_add_u64 v[22:23], s[54:55], 0, v[12:13]
	v_lshl_add_u64 v[16:17], s[54:55], 0, v[16:17]
	v_lshlrev_b64 v[6:7], 10, v[32:33]
	v_lshl_add_u64 v[10:11], v[40:41], 0, v[10:11]
	v_lshlrev_b64 v[12:13], 10, v[22:23]
	v_lshlrev_b64 v[18:19], 10, v[16:17]
	v_lshl_add_u64 v[6:7], v[40:41], 0, v[6:7]
	v_lshl_add_u64 v[12:13], v[40:41], 0, v[12:13]
	v_lshl_add_u64 v[18:19], v[40:41], 0, v[18:19]
	global_load_dwordx2 v[92:93], v[10:11], off
	global_load_dwordx2 v[120:121], v[12:13], off
	global_load_dwordx2 v[122:123], v[6:7], off
	global_load_dwordx2 v[124:125], v[18:19], off
	v_cndmask_b32_e32 v6, v107, v106, vcc
	v_ashrrev_i32_e32 v7, 31, v6
	v_lshl_add_u64 v[24:25], s[54:55], 0, v[6:7]
	v_lshlrev_b64 v[6:7], 10, v[24:25]
	v_lshl_add_u64 v[12:13], v[40:41], 0, v[6:7]
	v_cndmask_b32_e32 v6, v109, v108, vcc
	v_ashrrev_i32_e32 v7, 31, v6
	v_lshl_add_u64 v[18:19], s[54:55], 0, v[6:7]
	v_lshlrev_b64 v[6:7], 10, v[18:19]
	v_lshl_add_u64 v[64:65], v[40:41], 0, v[6:7]
	v_cndmask_b32_e32 v6, v111, v110, vcc
	v_ashrrev_i32_e32 v7, 31, v6
	v_lshl_add_u64 v[10:11], s[54:55], 0, v[6:7]
	v_lshlrev_b64 v[6:7], 10, v[10:11]
	v_lshl_add_u64 v[84:85], v[40:41], 0, v[6:7]
	global_load_dwordx2 v[126:127], v[64:65], off
	global_load_dwordx2 v[128:129], v[84:85], off
	global_load_dwordx2 v[130:131], v[12:13], off
	v_cndmask_b32_e32 v6, v113, v112, vcc
	v_ashrrev_i32_e32 v7, 31, v6
	v_lshl_add_u64 v[6:7], s[54:55], 0, v[6:7]
	v_lshlrev_b64 v[12:13], 10, v[6:7]
	v_lshl_add_u64 v[12:13], v[40:41], 0, v[12:13]
	global_load_dwordx2 v[132:133], v[12:13], off
	v_cndmask_b32_e32 v12, v115, v114, vcc
	v_ashrrev_i32_e32 v13, 31, v12
	v_lshl_add_u64 v[12:13], s[54:55], 0, v[12:13]
	v_lshlrev_b64 v[64:65], 10, v[12:13]
	v_lshl_add_u64 v[40:41], v[40:41], 0, v[64:65]
	global_load_dwordx2 v[134:135], v[40:41], off
	v_mov_b32_e32 v65, 0
	v_mov_b32_e32 v64, 0
	s_waitcnt vmcnt(16)
; __device__ __forceinline__ unsigned cvtpk(float lo, float hi) { unsigned r; asm volatile("v_cvt_pk_bf16_f32 %0, %1, %2" : "=v"(r) : "v"(lo), "v"(hi)); return r; }
; __device__ __forceinline__ void ssm_carry(const Params& p, const Ctx& c, int l, float* lds) {
;     ...
;   float hr = 0.f, hi = 0.f;
; #pragma unroll
;   for (int kk = 0; kk < 17; ++kk) { hl[kk] = make_float2(hr, hi); const float nr = a32.x * hr - a32.y * hi + s[kk].x, ni = a32.x * hi + a32.y * hr + s[kk].y; hr = nr; hi = ni; }
;   E[w * 64 + c.lane] = make_float2(hr, hi);
;   float ar = a32.x, ai = a32.y;
; #pragma unroll
;   for (int q = 0; q < 4; ++q) { const float t = ar * ar - ai * ai; ai = 2.f * ar * ai; ar = t; }
;   { const float t = ar * a32.x - ai * a32.y; ai = ar * a32.y + ai * a32.x; ar = t; }
;   __syncthreads();
;   float pr = 0.f, pi = 0.f;
;   for (int q = 0; q < w; ++q) { const float2 e = E[q * 64 + c.lane]; const float nr = ar * pr - ai * pi + e.x, ni = ar * pi + ai * pr + e.y; pr = nr; pi = ni; }
;   if (act) {
; #pragma unroll
;     for (int kk = 0; kk < 17; ++kk) { const int k = 17 * w + kk; const int ch = d == 0 ? k : (k < 8 ? 7 - k : 143 - k);
;       *(unsigned*)(UG + (rbase + ch) * 768 + 512 + col) = cvtpk(hl[kk].x + pr, hl[kk].y + pi);
;       const float nr = a32.x * pr - a32.y * pi, ni = a32.x * pi + a32.y * pr; pr = nr; pi = ni; } }
	v_mul_f32_e32 v89, 0, v3
	v_fma_f32 v88, v2, 0, -v89
	v_fmac_f32_e32 v89, 0, v2
	s_waitcnt vmcnt(13)
	v_add_f32_e64 v86, v54, v88
	v_add_f32_e64 v87, v55, v89
	s_nop 0
	v_mul_f32_e64 v54, v2, v86
	v_mul_f32_e64 v55, v3, v87
	s_nop 0
	v_sub_f32_e32 v44, v54, v55
	v_mul_f32_e64 v54, v2, v87
	v_mul_f32_e64 v55, v3, v86
	v_add_f32_e32 v80, v42, v44
	v_add_f32_e32 v42, v54, v55
	v_add_f32_e32 v82, v43, v42
	v_mul_f32_e64 v42, v3, v82
	v_mul_f32_e64 v43, v2, v82
	v_fma_f32 v54, v2, v80, -v42
	v_fma_f32 v55, v3, v81, -v43
	v_fma_f32 v40, v2, v80, v42
	v_fma_f32 v41, v3, v80, v43
	s_nop 0
	v_mov_b32_e32 v55, v41
	v_add_f32_e64 v84, v48, v54
	v_add_f32_e64 v85, v49, v55
	s_nop 0
	v_mul_f32_e64 v40, v2, v84
	v_mul_f32_e64 v41, v3, v85
	s_nop 0
	v_sub_f32_e32 v40, v40, v41
	v_add_f32_e32 v76, v38, v40
	v_mul_f32_e64 v40, v2, v85
	v_mul_f32_e64 v41, v3, v84
	s_nop 0
	v_add_f32_e32 v38, v40, v41
	v_add_f32_e32 v78, v39, v38
	v_mul_f32_e64 v38, v3, v78
	v_mul_f32_e64 v39, v2, v78
	v_fma_f32 v40, v2, v76, -v38
	v_fma_f32 v41, v3, v77, -v39
	v_fma_f32 v38, v2, v76, v38
	v_fma_f32 v39, v3, v76, v39
	s_nop 0
	v_mov_b32_e32 v41, v39
	s_waitcnt vmcnt(9)
	v_add_f32_e64 v74, v74, v40
	v_add_f32_e64 v75, v75, v41
	s_nop 0
	v_mul_f32_e64 v38, v2, v74
	v_mul_f32_e64 v39, v3, v75
	s_nop 0
	v_sub_f32_e32 v38, v38, v39
	v_add_f32_e32 v70, v68, v38
	v_mul_f32_e64 v38, v2, v75
	v_mul_f32_e64 v39, v3, v74
	s_nop 0
	v_add_f32_e32 v38, v38, v39
	v_add_f32_e32 v72, v69, v38
	v_mul_f32_e64 v38, v3, v72
	v_mul_f32_e64 v39, v2, v72
	v_fma_f32 v40, v2, v70, -v38
	v_fma_f32 v41, v3, v71, -v39
	v_fma_f32 v38, v2, v70, v38
	v_fma_f32 v39, v3, v70, v39
	s_nop 0
	v_mov_b32_e32 v41, v39
	v_add_f32_e64 v68, v90, v40
	v_add_f32_e64 v69, v91, v41
	s_nop 0
	v_mul_f32_e64 v38, v2, v68
	v_mul_f32_e64 v39, v3, v69
	s_nop 0
	v_sub_f32_e32 v38, v38, v39
	v_add_f32_e32 v62, v60, v38
	v_mul_f32_e64 v38, v2, v69
	v_mul_f32_e64 v39, v3, v68
	s_nop 0
	v_add_f32_e32 v38, v38, v39
	v_add_f32_e32 v66, v61, v38
	v_mul_f32_e64 v38, v3, v66
	v_mul_f32_e64 v39, v2, v66
	v_fma_f32 v40, v2, v62, -v38
	v_fma_f32 v41, v3, v63, -v39
	v_fma_f32 v38, v2, v62, v38
	v_fma_f32 v39, v3, v62, v39
	s_nop 0
	v_mov_b32_e32 v41, v39
	s_waitcnt vmcnt(6)
	v_add_f32_e64 v60, v122, v40
	v_add_f32_e64 v61, v123, v41
	s_nop 0
	v_mul_f32_e64 v38, v2, v60
	v_mul_f32_e64 v39, v3, v61
	s_nop 0
	v_sub_f32_e32 v38, v38, v39
	v_add_f32_e32 v56, v92, v38
	v_mul_f32_e64 v38, v2, v61
	v_mul_f32_e64 v39, v3, v60
	s_nop 0
	v_add_f32_e32 v38, v38, v39
	v_add_f32_e32 v58, v93, v38
	v_mul_f32_e64 v38, v3, v58
	v_mul_f32_e64 v39, v2, v58
	v_fma_f32 v40, v2, v56, -v38
	v_fma_f32 v41, v3, v57, -v39
	v_fma_f32 v38, v2, v56, v38
	v_fma_f32 v39, v3, v56, v39
	s_nop 0
	v_mov_b32_e32 v41, v39
	v_add_f32_e64 v54, v120, v40
	v_add_f32_e64 v55, v121, v41
	s_nop 0
	v_mul_f32_e64 v38, v2, v54
	v_mul_f32_e64 v39, v3, v55
	s_nop 0
	v_sub_f32_e32 v38, v38, v39
	s_waitcnt vmcnt(5)
	v_add_f32_e32 v50, v124, v38
	v_mul_f32_e64 v38, v2, v55
	v_mul_f32_e64 v39, v3, v54
	s_nop 0
	v_add_f32_e32 v38, v38, v39
	v_add_f32_e32 v52, v125, v38
	v_mul_f32_e64 v38, v3, v52
	v_mul_f32_e64 v39, v2, v52
	v_fma_f32 v40, v2, v50, -v38
	v_fma_f32 v41, v3, v51, -v39
	v_fma_f32 v38, v2, v50, v38
	v_fma_f32 v39, v3, v50, v39
	s_nop 0
	v_mov_b32_e32 v41, v39
	s_waitcnt vmcnt(2)
	v_add_f32_e64 v48, v130, v40
	v_add_f32_e64 v49, v131, v41
	s_nop 0
	v_mul_f32_e64 v38, v2, v48
	v_mul_f32_e64 v39, v3, v49
	s_nop 0
	v_sub_f32_e32 v38, v38, v39
	v_add_f32_e32 v44, v126, v38
	v_mul_f32_e64 v38, v2, v49
	v_mul_f32_e64 v39, v3, v48
	s_nop 0
	v_add_f32_e32 v38, v38, v39
	v_add_f32_e32 v46, v127, v38
	v_mul_f32_e64 v38, v3, v46
	v_mul_f32_e64 v39, v2, v46
	v_fma_f32 v40, v2, v44, -v38
	v_fma_f32 v41, v3, v45, -v39
	v_fma_f32 v38, v2, v44, v38
	v_fma_f32 v39, v3, v44, v39
	s_nop 0
	v_mov_b32_e32 v41, v39
	v_add_f32_e64 v42, v128, v40
	v_add_f32_e64 v43, v129, v41
	s_nop 0
	v_mul_f32_e64 v38, v2, v42
	v_mul_f32_e64 v39, v3, v43
	v_mul_f32_e64 v40, v2, v43
	v_mul_f32_e64 v41, v3, v42
	v_sub_f32_e32 v38, v38, v39
	v_add_f32_e32 v39, v40, v41
	s_waitcnt vmcnt(1)
	v_add_f32_e32 v40, v133, v39
	v_add_f32_e32 v38, v132, v38
	v_mul_f32_e64 v90, v3, v40
	v_mul_f32_e64 v91, v2, v40
	v_fma_f32 v92, v2, v38, -v90
	v_fma_f32 v93, v3, v39, -v91
	v_fma_f32 v90, v2, v38, v90
	v_fma_f32 v91, v3, v38, v91
	s_nop 0
	v_mov_b32_e32 v93, v91
	s_waitcnt vmcnt(0)
	v_add_f32_e64 v90, v134, v92
	v_add_f32_e64 v91, v135, v93
	ds_write_b64 v117, v[90:91]
	s_waitcnt lgkmcnt(0)
	s_barrier
	s_and_saveexec_b64 s[54:55], s[6:7]
	s_cbranch_execz .LBB0_600
	v_mul_f32_e64 v88, v2, v2
	v_mul_f32_e64 v89, v3, v3
	v_add_f32_e32 v41, v2, v2
	v_sub_f32_e32 v39, v88, v89
	v_mul_f32_e32 v41, v3, v41
	v_mul_f32_e32 v88, v39, v39
	v_add_f32_e32 v39, v39, v39
	v_mul_f32_e32 v39, v41, v39
	v_fma_f32 v88, -v41, v41, v88
	v_mul_f32_e32 v41, v39, v39
	v_fma_f32 v41, v88, v88, -v41
	v_add_f32_e32 v88, v88, v88
	v_mul_f32_e32 v39, v39, v88
	v_mul_f32_e32 v88, v39, v39
	v_fma_f32 v89, v41, v41, -v88
	v_add_f32_e32 v41, v41, v41
	v_mul_f32_e32 v39, v39, v41
	v_mul_f32_e32 v41, v3, v39
	v_mul_f32_e32 v90, v3, v89
	v_fma_f32 v88, v2, v89, -v41
	v_fmac_f32_e32 v90, v2, v39
	v_mov_b32_e32 v92, 0
	v_pk_mov_b32 v[64:65], v[2:3], v[2:3] op_sel:[1,0]
	v_mov_b32_e32 v89, v88
	v_mov_b32_e32 v91, v90
	s_mov_b64 s[56:57], 0
	v_mov_b32_e32 v39, v116
	v_mov_b32_e32 v41, v1
	v_mov_b32_e32 v93, v92
.LBB0_603:
	ds_read_b64 v[122:123], v39
	v_mul_f32_e64 v120, v90, v93
	v_mul_f32_e64 v121, v91, v92
	v_add_u32_e32 v41, -1, v41
	v_fma_f32 v124, v88, v92, -v120
	v_fma_f32 v125, v89, v93, -v121
	v_fma_f32 v92, v88, v92, v120
	v_fma_f32 v93, v89, v93, v121
	v_cmp_eq_u32_e32 vcc, 0, v41
	v_mov_b32_e32 v125, v93
	v_add_u32_e32 v39, 0x200, v39
	s_or_b64 s[56:57], vcc, s[56:57]
	s_waitcnt lgkmcnt(0)
	v_add_f32_e64 v92, v122, v124
	v_add_f32_e64 v93, v123, v125
	s_andn2_b64 exec, exec, s[56:57]
	s_cbranch_execnz .LBB0_603
	s_or_b64 exec, exec, s[56:57]
	v_mul_f32_e64 v88, v2, v93
	v_mul_f32_e64 v89, v3, v93
	v_mul_f32_e64 v90, v64, v92
	v_mul_f32_e64 v91, v65, v93
	v_fma_f32 v120, v64, v92, -v88
	v_fma_f32 v121, v65, v92, -v89
	v_add_f32_e64 v64, v92, 0
	v_add_f32_e64 v65, v93, 0
	v_add_f32_e32 v89, v90, v88
	v_mov_b32_e32 v88, v121
	s_branch .LBB0_600

; __device__ __forceinline__ unsigned cvtpk(float lo, float hi) { unsigned r; asm volatile("v_cvt_pk_bf16_f32 %0, %1, %2" : "=v"(r) : "v"(lo), "v"(hi)); return r; }
; __device__ __forceinline__ void phase_combine(const Params& p, const Ctx& c, int l, bool last) {
;     ...
;   for (int row = c.gwave; row < TT; row += c.nwave) { const int t = row % TPB; if (last && t < CTXL) continue;
;     const bf16_t* orow = O + (size_t)row * DM; bf16_t* crow_ = Cat + (size_t)row * DM;
; #pragma unroll
;     for (int h = 0; h < 4; ++h) { const u32x2 a = *(const u32x2*)(orow + (h * 2) * 256 + c.lane * 4), bq = *(const u32x2*)(orow + (h * 2 + 1) * 256 + c.lane * 4);
;       f32x4 o; o[0] = __uint_as_float(a[0] << 16) - lam * __uint_as_float(bq[0] << 16); o[1] = __uint_as_float(a[0] & 0xffff0000u) - lam * __uint_as_float(bq[0] & 0xffff0000u);
;       o[2] = __uint_as_float(a[1] << 16) - lam * __uint_as_float(bq[1] << 16); o[3] = __uint_as_float(a[1] & 0xffff0000u) - lam * __uint_as_float(bq[1] & 0xffff0000u);
;       const float ss = wave_sum(o[0] * o[0] + o[1] * o[1] + o[2] * o[2] + o[3] * o[3]); const float r = rsqrtf(ss * (1.f / 256.f) + 1e-5f) * (1.f - lam_init);
;       o = o * r * gs; u32x2 w = {cvtpk(o[0], o[1]), cvtpk(o[2], o[3])}; *(u32x2*)(crow_ + h * 256 + c.lane * 4) = w; }
.Lcmb_go:
	v_readlane_b32 s2, v250, 9
	v_readlane_b32 s3, v250, 10
	s_mov_b32 s100, 1
	s_nop 1
	v_lshl_add_u64 v[56:57], v[12:13], 0, s[2:3]
	global_load_dwordx2 v[40:41], v[56:57], off offset:-4096
	global_load_dwordx2 v[42:43], v[56:57], off offset:-3584
	global_load_dwordx2 v[44:45], v[56:57], off offset:-3072
	global_load_dwordx2 v[46:47], v[56:57], off offset:-2560
	global_load_dwordx2 v[48:49], v[56:57], off offset:-2048
	global_load_dwordx2 v[50:51], v[56:57], off offset:-1536
	global_load_dwordx2 v[52:53], v[56:57], off offset:-1024
	global_load_dwordx2 v[54:55], v[56:57], off offset:-512
	s_waitcnt vmcnt(14)
	v_lshlrev_b32_e32 v18, 16, v24
	v_and_b32_e32 v19, 0xffff0000, v24
	v_lshlrev_b32_e32 v14, 16, v25
	v_and_b32_e32 v15, 0xffff0000, v25
	v_lshlrev_b32_e32 v20, 16, v26
	v_and_b32_e32 v21, 0xffff0000, v26
	v_lshlrev_b32_e32 v16, 16, v27
	v_and_b32_e32 v17, 0xffff0000, v27
	v_fma_f32 v18, -v8, v20, v18
	v_fma_f32 v19, -v9, v21, v19
	v_fma_f32 v14, -v8, v16, v14
	v_fma_f32 v15, -v9, v17, v15
	v_mul_f32_e64 v16, v18, v18
	v_mul_f32_e64 v17, v19, v19
	v_mul_f32_e64 v20, v14, v14
	v_mul_f32_e64 v21, v15, v15
	v_add_f32_e32 v7, v16, v17
	v_add_f32_e32 v7, v20, v7
	v_add_f32_e32 v7, v21, v7
	s_nop 1
	v_add_f32_dpp v7, v7, v7 quad_perm:[1,0,3,2] row_mask:0xf bank_mask:0xf bound_ctrl:1
	s_nop 1
	v_add_f32_dpp v7, v7, v7 quad_perm:[2,3,0,1] row_mask:0xf bank_mask:0xf bound_ctrl:1
	s_nop 1
	v_add_f32_dpp v7, v7, v7 row_half_mirror row_mask:0xf bank_mask:0xf bound_ctrl:1
	s_nop 1
	v_add_f32_dpp v7, v7, v7 row_mirror row_mask:0xf bank_mask:0xf bound_ctrl:1
	s_nop 0
	v_readlane_b32 s2, v7, 16
	v_readlane_b32 s3, v7, 48
	v_readlane_b32 s0, v7, 0
	v_readlane_b32 s1, v7, 32
	v_mov_b32_e32 v16, s2
	v_mov_b32_e32 v17, s3
	v_add_f32_e64 v16, s0, v16
	v_add_f32_e64 v17, s1, v17
	s_nop 0
	v_add_f32_e32 v7, v16, v17
	v_fmamk_f32 v7, v7, 0x3b800000, v226
	v_mul_f32_e32 v16, 0x4b800000, v7
	v_cmp_gt_f32_e32 vcc, s4, v7
	s_nop 1
	v_cndmask_b32_e32 v7, v7, v16, vcc
	v_rsq_f32_e32 v7, v7
	s_nop 0
	v_mul_f32_e32 v16, 0x45800000, v7
	v_cndmask_b32_e32 v7, v7, v16, vcc
	v_mul_f32_e32 v16, v1, v7
	v_mul_f32_e64 v18, v18, v16
	v_mul_f32_e64 v19, v19, v16
	v_mul_f32_e64 v14, v14, v16
	v_mul_f32_e64 v15, v15, v16
	v_mul_f32_e64 v16, v2, v18
	v_mul_f32_e64 v17, v3, v19
	v_mul_f32_e64 v14, v4, v14
	v_mul_f32_e64 v15, v5, v15
	v_cvt_pk_bf16_f32 v16, v16, v17
	s_nop 0
	v_cvt_pk_bf16_f32 v17, v14, v15
	s_waitcnt vmcnt(12)
	v_lshlrev_b32_e32 v20, 16, v28
	v_and_b32_e32 v21, 0xffff0000, v28
	v_lshlrev_b32_e32 v22, 16, v30
	v_and_b32_e32 v23, 0xffff0000, v30
	v_lshlrev_b32_e32 v14, 16, v29
	v_and_b32_e32 v15, 0xffff0000, v29
	v_lshlrev_b32_e32 v18, 16, v31
	v_and_b32_e32 v19, 0xffff0000, v31
	v_fma_f32 v20, -v8, v22, v20
	v_fma_f32 v21, -v9, v23, v21
	v_fma_f32 v14, -v8, v18, v14
	v_fma_f32 v15, -v9, v19, v15
	v_mul_f32_e64 v18, v20, v20
	v_mul_f32_e64 v19, v21, v21
	v_mul_f32_e64 v22, v14, v14
	v_mul_f32_e64 v23, v15, v15
	v_add_f32_e32 v7, v18, v19
	v_add_f32_e32 v7, v22, v7
	v_add_f32_e32 v7, v23, v7
	global_store_dwordx2 v[10:11], v[16:17], off
	s_nop 0
	v_add_f32_dpp v7, v7, v7 quad_perm:[1,0,3,2] row_mask:0xf bank_mask:0xf bound_ctrl:1
	s_nop 1
	v_add_f32_dpp v7, v7, v7 quad_perm:[2,3,0,1] row_mask:0xf bank_mask:0xf bound_ctrl:1
	s_nop 1
	v_add_f32_dpp v7, v7, v7 row_half_mirror row_mask:0xf bank_mask:0xf bound_ctrl:1
	s_nop 1
	v_add_f32_dpp v7, v7, v7 row_mirror row_mask:0xf bank_mask:0xf bound_ctrl:1
	s_nop 0
	v_readlane_b32 s2, v7, 16
	v_readlane_b32 s3, v7, 48
	v_readlane_b32 s0, v7, 0
	v_readlane_b32 s1, v7, 32
	v_mov_b32_e32 v18, s2
	v_mov_b32_e32 v19, s3
	v_add_f32_e64 v18, s0, v18
	v_add_f32_e64 v19, s1, v19
	s_nop 0
	v_add_f32_e32 v7, v18, v19
	v_fmamk_f32 v7, v7, 0x3b800000, v226
	v_mul_f32_e32 v18, 0x4b800000, v7
	v_cmp_gt_f32_e32 vcc, s4, v7
	s_nop 1
	v_cndmask_b32_e32 v7, v7, v18, vcc
	v_rsq_f32_e32 v7, v7
	s_nop 0
	v_mul_f32_e32 v16, 0x45800000, v7
	v_cndmask_b32_e32 v7, v7, v16, vcc
	v_mul_f32_e32 v16, v1, v7
	v_mul_f32_e64 v18, v20, v16
	v_mul_f32_e64 v19, v21, v16
	v_mul_f32_e64 v14, v14, v16
	v_mul_f32_e64 v15, v15, v16
	v_mul_f32_e64 v16, v2, v18
	v_mul_f32_e64 v17, v3, v19
	v_mul_f32_e64 v14, v4, v14
	v_mul_f32_e64 v15, v5, v15
	v_cvt_pk_bf16_f32 v16, v16, v17
	s_nop 0
	v_cvt_pk_bf16_f32 v17, v14, v15
	s_waitcnt vmcnt(11)
; __device__ __forceinline__ unsigned cvtpk(float lo, float hi) { unsigned r; asm volatile("v_cvt_pk_bf16_f32 %0, %1, %2" : "=v"(r) : "v"(lo), "v"(hi)); return r; }
; __device__ __forceinline__ void phase_combine(const Params& p, const Ctx& c, int l, bool last) {
;     ...
;     for (int h = 0; h < 4; ++h) { const u32x2 a = *(const u32x2*)(orow + (h * 2) * 256 + c.lane * 4), bq = *(const u32x2*)(orow + (h * 2 + 1) * 256 + c.lane * 4);
;       f32x4 o; o[0] = __uint_as_float(a[0] << 16) - lam * __uint_as_float(bq[0] << 16); o[1] = __uint_as_float(a[0] & 0xffff0000u) - lam * __uint_as_float(bq[0] & 0xffff0000u);
;       o[2] = __uint_as_float(a[1] << 16) - lam * __uint_as_float(bq[1] << 16); o[3] = __uint_as_float(a[1] & 0xffff0000u) - lam * __uint_as_float(bq[1] & 0xffff0000u);
;       const float ss = wave_sum(o[0] * o[0] + o[1] * o[1] + o[2] * o[2] + o[3] * o[3]); const float r = rsqrtf(ss * (1.f / 256.f) + 1e-5f) * (1.f - lam_init);
;       o = o * r * gs; u32x2 w = {cvtpk(o[0], o[1]), cvtpk(o[2], o[3])}; *(u32x2*)(crow_ + h * 256 + c.lane * 4) = w; }
	v_lshlrev_b32_e32 v20, 16, v32
	v_and_b32_e32 v21, 0xffff0000, v32
	v_lshlrev_b32_e32 v22, 16, v34
	v_and_b32_e32 v23, 0xffff0000, v34
	v_lshlrev_b32_e32 v14, 16, v33
	v_and_b32_e32 v15, 0xffff0000, v33
	v_lshlrev_b32_e32 v18, 16, v35
	v_and_b32_e32 v19, 0xffff0000, v35
	v_fma_f32 v20, -v8, v22, v20
	v_fma_f32 v21, -v9, v23, v21
	v_fma_f32 v14, -v8, v18, v14
	v_fma_f32 v15, -v9, v19, v15
	v_mul_f32_e64 v18, v20, v20
	v_mul_f32_e64 v19, v21, v21
	v_mul_f32_e64 v22, v14, v14
	v_mul_f32_e64 v23, v15, v15
	v_add_f32_e32 v7, v18, v19
	v_add_f32_e32 v7, v22, v7
	v_add_f32_e32 v7, v23, v7
	global_store_dwordx2 v[10:11], v[16:17], off offset:512
	s_nop 0
	v_add_f32_dpp v7, v7, v7 quad_perm:[1,0,3,2] row_mask:0xf bank_mask:0xf bound_ctrl:1
	s_nop 1
	v_add_f32_dpp v7, v7, v7 quad_perm:[2,3,0,1] row_mask:0xf bank_mask:0xf bound_ctrl:1
	s_nop 1
	v_add_f32_dpp v7, v7, v7 row_half_mirror row_mask:0xf bank_mask:0xf bound_ctrl:1
	s_nop 1
	v_add_f32_dpp v7, v7, v7 row_mirror row_mask:0xf bank_mask:0xf bound_ctrl:1
	s_nop 0
	v_readlane_b32 s2, v7, 16
	v_readlane_b32 s3, v7, 48
	v_readlane_b32 s0, v7, 0
	v_readlane_b32 s1, v7, 32
	v_mov_b32_e32 v18, s2
	v_mov_b32_e32 v19, s3
	v_add_f32_e64 v18, s0, v18
	v_add_f32_e64 v19, s1, v19
	s_nop 0
	v_add_f32_e32 v7, v18, v19
	v_fmamk_f32 v7, v7, 0x3b800000, v226
	v_mul_f32_e32 v18, 0x4b800000, v7
	v_cmp_gt_f32_e32 vcc, s4, v7
	s_nop 1
	v_cndmask_b32_e32 v7, v7, v18, vcc
	v_rsq_f32_e32 v7, v7
	s_nop 0
	v_mul_f32_e32 v16, 0x45800000, v7
	v_cndmask_b32_e32 v7, v7, v16, vcc
	v_mul_f32_e32 v16, v1, v7
	v_mul_f32_e64 v18, v20, v16
	v_mul_f32_e64 v19, v21, v16
	v_mul_f32_e64 v14, v14, v16
	v_mul_f32_e64 v15, v15, v16
	v_mul_f32_e64 v16, v2, v18
	v_mul_f32_e64 v17, v3, v19
	v_mul_f32_e64 v14, v4, v14
	v_mul_f32_e64 v15, v5, v15
	v_cvt_pk_bf16_f32 v16, v16, v17
	s_nop 0
	v_cvt_pk_bf16_f32 v17, v14, v15
	s_waitcnt vmcnt(10)
	v_lshlrev_b32_e32 v18, 16, v36
	v_and_b32_e32 v19, 0xffff0000, v36
	v_lshlrev_b32_e32 v20, 16, v38
	v_and_b32_e32 v21, 0xffff0000, v38
	v_lshlrev_b32_e32 v14, 16, v37
	v_and_b32_e32 v15, 0xffff0000, v37
	v_lshlrev_b32_e32 v12, 16, v39
	v_and_b32_e32 v13, 0xffff0000, v39
	v_fma_f32 v18, -v8, v20, v18
	v_fma_f32 v19, -v9, v21, v19
	v_fma_f32 v12, -v8, v12, v14
	v_fma_f32 v13, -v9, v13, v15
	v_mul_f32_e64 v14, v18, v18
	v_mul_f32_e64 v15, v19, v19
	v_mul_f32_e64 v20, v12, v12
	v_mul_f32_e64 v21, v13, v13
	v_add_f32_e32 v7, v14, v15
	v_add_f32_e32 v7, v20, v7
	v_add_f32_e32 v7, v21, v7
	global_store_dwordx2 v[10:11], v[16:17], off offset:1024
	s_nop 0
	v_add_f32_dpp v7, v7, v7 quad_perm:[1,0,3,2] row_mask:0xf bank_mask:0xf bound_ctrl:1
	s_nop 1
	v_add_f32_dpp v7, v7, v7 quad_perm:[2,3,0,1] row_mask:0xf bank_mask:0xf bound_ctrl:1
	s_nop 1
	v_add_f32_dpp v7, v7, v7 row_half_mirror row_mask:0xf bank_mask:0xf bound_ctrl:1
	s_nop 1
	v_add_f32_dpp v7, v7, v7 row_mirror row_mask:0xf bank_mask:0xf bound_ctrl:1
	s_nop 0
	v_readlane_b32 s2, v7, 16
	v_readlane_b32 s3, v7, 48
	v_readlane_b32 s0, v7, 0
	v_readlane_b32 s1, v7, 32
	v_mov_b32_e32 v14, s2
	v_mov_b32_e32 v15, s3
	v_add_f32_e64 v14, s0, v14
	v_add_f32_e64 v15, s1, v15
	s_nop 0
	v_add_f32_e32 v7, v14, v15
	v_fmamk_f32 v7, v7, 0x3b800000, v226
	v_mul_f32_e32 v14, 0x4b800000, v7
	v_cmp_gt_f32_e32 vcc, s4, v7
	s_nop 1
	v_cndmask_b32_e32 v7, v7, v14, vcc
	v_rsq_f32_e32 v7, v7
	s_nop 0
	v_mul_f32_e32 v14, 0x45800000, v7
	v_cndmask_b32_e32 v7, v7, v14, vcc
	v_mul_f32_e32 v14, v1, v7
	v_mul_f32_e64 v16, v18, v14
	v_mul_f32_e64 v17, v19, v14
	v_mul_f32_e64 v12, v12, v14
	v_mul_f32_e64 v13, v13, v14
	v_mul_f32_e64 v14, v2, v16
	v_mul_f32_e64 v15, v3, v17
	v_mul_f32_e64 v12, v4, v12
	v_mul_f32_e64 v13, v5, v13
	v_cvt_pk_bf16_f32 v14, v14, v15
	s_nop 0
	v_cvt_pk_bf16_f32 v15, v12, v13
	global_store_dwordx2 v[10:11], v[14:15], off offset:1536
	s_branch .LBB0_724

; __device__ __forceinline__ unsigned cvtpk(float lo, float hi) { unsigned r; asm volatile("v_cvt_pk_bf16_f32 %0, %1, %2" : "=v"(r) : "v"(lo), "v"(hi)); return r; }
; __device__ __forceinline__ float sigmoidf_(float x) { return __builtin_amdgcn_rcpf(1.f + __builtin_amdgcn_exp2f(x * -1.4426950408889634f)); }
;   __device__ __forceinline__ void operator()(const Acc& acc, const gm::Unit& u, int wr, int wc, int fr, int fq) const { const int pm = u.pm, pn = u.pn;
;     ...
;     for (int ai = 0; ai < 2; ++ai)
; #pragma unroll
;       for (int m = 0; m < 4; ++m) { const int row = pm * 256 + ai * 128 + wr * 64 + m * 16 + fr;
; #pragma unroll
;         for (int bj = 0; bj < 2; ++bj)
; #pragma unroll
;           for (int n = 0; n < 2; ++n) { const int col = pn * 256 + bj * 128 + wc * 32 + n * 16 + fq * 4; const f32x4 z = acc[ai][bj][m][n] + *(const f32x4*)(bg + col);
;             const u32x2 gw = *(const u32x2*)(Gg + (size_t)row * 512 + col);
;             const float g0 = __uint_as_float(gw[0] << 16), g1 = __uint_as_float(gw[0] & 0xffff0000u), g2 = __uint_as_float(gw[1] << 16), g3 = __uint_as_float(gw[1] & 0xffff0000u);
;             u32x2 w = {cvtpk(g0 * sigmoidf_(z[0]), g1 * sigmoidf_(z[1])), cvtpk(g2 * sigmoidf_(z[2]), g3 * sigmoidf_(z[3]))};
;             *(u32x2*)(Cat + (size_t)row * DM + 1024 + col) = w; } }
.LBB0_794:
	s_lshl_b32 s0, s0, 8
	v_mov_b32_e32 v138, v144
	v_mov_b32_e32 v139, v1
	s_or_b32 s0, s0, s87
	s_lshl_b32 s1, s68, 8
	v_lshl_add_u32 v142, v138, 2, s0
	s_add_i32 s1, s1, s86
	v_ashrrev_i32_e32 v143, 31, v142
	v_add_u32_e32 v140, s1, v139
	v_lshl_add_u64 v[138:139], v[142:143], 2, s[54:55]
	global_load_dwordx4 v[156:159], v[138:139], off
	global_load_dwordx4 v[160:163], v[138:139], off offset:64
	global_load_dwordx4 v[164:167], v[138:139], off offset:512
	global_load_dwordx4 v[168:171], v[138:139], off offset:576
	s_waitcnt vmcnt(3)
	v_mov_b64_e32 v[148:149], v[156:157]
	v_mov_b64_e32 v[150:151], v[158:159]
	v_ashrrev_i32_e32 v141, 31, v140
	v_lshlrev_b64 v[152:153], 10, v[140:141]
	v_lshlrev_b64 v[154:155], 12, v[140:141]
	s_mov_b64 s[68:69], -1
	s_andn2_b64 vcc, exec, s[66:67]
	v_add_f32_e64 v150, v128, v150
	v_add_f32_e64 v151, v129, v151
	v_add_f32_e64 v148, v126, v148
	v_add_f32_e64 v149, v127, v149
	v_lshl_add_u64 v[128:129], s[8:9], 0, v[152:153]
	v_lshlrev_b64 v[126:127], 1, v[142:143]
	v_lshl_add_u64 v[128:129], v[128:129], 0, v[126:127]
	global_load_dwordx2 v[172:173], v[128:129], off
	global_load_dwordx2 v[174:175], v[128:129], off offset:32
	global_load_dwordx2 v[176:177], v[128:129], off offset:256
	global_load_dwordx2 v[178:179], v[128:129], off offset:288
	s_waitcnt vmcnt(3)
	v_mov_b64_e32 v[142:143], v[172:173]
	v_mul_f32_e32 v148, 0xbfb8aa3b, v148
	v_exp_f32_e32 v148, v148
	v_lshlrev_b32_e32 v141, 16, v142
	v_add_f32_e32 v148, 1.0, v148
	v_rcp_f32_e32 v148, v148
	v_and_b32_e32 v142, 0xffff0000, v142
	v_lshlrev_b32_e32 v147, 16, v143
	v_and_b32_e32 v143, 0xffff0000, v143
	v_mul_f32_e32 v141, v148, v141
	v_mul_f32_e32 v148, 0xbfb8aa3b, v149
	v_exp_f32_e32 v148, v148
	s_nop 0
	v_add_f32_e32 v148, 1.0, v148
	v_rcp_f32_e32 v148, v148
	s_nop 0
	v_mul_f32_e32 v142, v148, v142
	v_cvt_pk_bf16_f32 v148, v141, v142
	v_mul_f32_e32 v142, 0xbfb8aa3b, v151
	v_mul_f32_e32 v141, 0xbfb8aa3b, v150
	v_exp_f32_e32 v142, v142
	v_exp_f32_e32 v141, v141
	v_add_f32_e32 v142, 1.0, v142
	v_add_f32_e32 v141, 1.0, v141
	v_rcp_f32_e32 v142, v142
	v_rcp_f32_e32 v141, v141
	v_mul_f32_e32 v142, v142, v143
	v_mul_f32_e32 v141, v141, v147
	v_cvt_pk_bf16_f32 v149, v141, v142
	v_lshl_add_u64 v[142:143], s[12:13], 0, v[154:155]
	v_lshl_add_u64 v[142:143], v[142:143], 0, v[126:127]
	global_store_dwordx2 v[142:143], v[148:149], off offset:2048
	s_waitcnt vmcnt(7)
	v_mov_b64_e32 v[148:149], v[160:161]
	v_mov_b64_e32 v[150:151], v[162:163]
	v_add_f32_e64 v122, v122, v148
	v_add_f32_e64 v123, v123, v149
	s_waitcnt vmcnt(3)
	v_mov_b64_e32 v[148:149], v[174:175]
	v_mul_f32_e32 v122, 0xbfb8aa3b, v122
	v_mul_f32_e32 v123, 0xbfb8aa3b, v123
	v_exp_f32_e32 v122, v122
	v_exp_f32_e32 v123, v123
	v_add_f32_e64 v124, v124, v150
	v_add_f32_e64 v125, v125, v151
	v_add_f32_e32 v122, 1.0, v122
	v_add_f32_e32 v123, 1.0, v123
	v_rcp_f32_e32 v122, v122
	v_rcp_f32_e32 v123, v123
	v_lshlrev_b32_e32 v141, 16, v148
	v_and_b32_e32 v147, 0xffff0000, v148
	v_mul_f32_e32 v122, v122, v141
	v_mul_f32_e32 v123, v123, v147
	v_cvt_pk_bf16_f32 v122, v122, v123
	v_mul_f32_e32 v123, 0xbfb8aa3b, v124
	v_exp_f32_e32 v123, v123
	v_mul_f32_e32 v124, 0xbfb8aa3b, v125
	v_exp_f32_e32 v124, v124
	v_lshlrev_b32_e32 v148, 16, v149
	v_add_f32_e32 v123, 1.0, v123
	v_rcp_f32_e32 v123, v123
	v_add_f32_e32 v124, 1.0, v124
	v_rcp_f32_e32 v124, v124
	v_and_b32_e32 v149, 0xffff0000, v149
	v_mul_f32_e32 v123, v123, v148
	v_mul_f32_e32 v124, v124, v149
	v_cvt_pk_bf16_f32 v123, v123, v124
	global_store_dwordx2 v[142:143], v[122:123], off offset:2080
	s_waitcnt vmcnt(7)
	v_mov_b64_e32 v[122:123], v[164:165]
	v_mov_b64_e32 v[124:125], v[166:167]
	v_add_f32_e64 v118, v118, v122
	v_add_f32_e64 v119, v119, v123
	s_waitcnt vmcnt(3)
	v_mov_b64_e32 v[122:123], v[176:177]
	v_mul_f32_e32 v118, 0xbfb8aa3b, v118
	v_mul_f32_e32 v119, 0xbfb8aa3b, v119
	v_exp_f32_e32 v118, v118
	v_exp_f32_e32 v119, v119
	v_add_f32_e64 v120, v120, v124
	v_add_f32_e64 v121, v121, v125
	v_add_f32_e32 v118, 1.0, v118
	v_add_f32_e32 v119, 1.0, v119
	v_rcp_f32_e32 v118, v118
	v_rcp_f32_e32 v119, v119
	v_lshlrev_b32_e32 v124, 16, v122
	v_and_b32_e32 v122, 0xffff0000, v122
	v_mul_f32_e32 v118, v118, v124
	v_mul_f32_e32 v119, v119, v122
	v_cvt_pk_bf16_f32 v118, v118, v119
	v_mul_f32_e32 v119, 0xbfb8aa3b, v120
	v_exp_f32_e32 v119, v119
	v_mul_f32_e32 v120, 0xbfb8aa3b, v121
	v_exp_f32_e32 v120, v120
	v_lshlrev_b32_e32 v125, 16, v123
	v_add_f32_e32 v119, 1.0, v119
	v_rcp_f32_e32 v119, v119
	v_add_f32_e32 v120, 1.0, v120
	v_rcp_f32_e32 v120, v120
	v_and_b32_e32 v123, 0xffff0000, v123
	v_mul_f32_e32 v119, v119, v125
	v_mul_f32_e32 v120, v120, v123
	v_cvt_pk_bf16_f32 v119, v119, v120
	global_store_dwordx2 v[142:143], v[118:119], off offset:2304
	s_waitcnt vmcnt(7)
	v_mov_b64_e32 v[118:119], v[168:169]
	v_mov_b64_e32 v[120:121], v[170:171]
	v_add_f32_e64 v114, v114, v118
	v_add_f32_e64 v115, v115, v119
	s_waitcnt vmcnt(3)
	v_mov_b64_e32 v[118:119], v[178:179]
	v_mul_f32_e32 v114, 0xbfb8aa3b, v114
	v_mul_f32_e32 v115, 0xbfb8aa3b, v115
	v_exp_f32_e32 v114, v114
	v_exp_f32_e32 v115, v115
	v_add_f32_e64 v116, v116, v120
	v_add_f32_e64 v117, v117, v121
	v_add_f32_e32 v114, 1.0, v114
	v_add_f32_e32 v115, 1.0, v115
	v_rcp_f32_e32 v114, v114
	v_rcp_f32_e32 v115, v115
	v_lshlrev_b32_e32 v120, 16, v118
	v_and_b32_e32 v118, 0xffff0000, v118
	v_mul_f32_e32 v114, v114, v120
	v_mul_f32_e32 v115, v115, v118
	v_cvt_pk_bf16_f32 v114, v114, v115
	v_mul_f32_e32 v115, 0xbfb8aa3b, v116
	v_exp_f32_e32 v115, v115
	v_mul_f32_e32 v116, 0xbfb8aa3b, v117
	v_exp_f32_e32 v116, v116
	v_lshlrev_b32_e32 v121, 16, v119
	v_add_f32_e32 v115, 1.0, v115
	v_rcp_f32_e32 v115, v115
	v_add_f32_e32 v116, 1.0, v116
	v_rcp_f32_e32 v116, v116
	v_and_b32_e32 v119, 0xffff0000, v119
	v_mul_f32_e32 v115, v115, v121
	v_mul_f32_e32 v116, v116, v119
	v_cvt_pk_bf16_f32 v115, v115, v116
	global_store_dwordx2 v[142:143], v[114:115], off offset:2336
	s_waitcnt vmcnt(11)
; __device__ __forceinline__ unsigned cvtpk(float lo, float hi) { unsigned r; asm volatile("v_cvt_pk_bf16_f32 %0, %1, %2" : "=v"(r) : "v"(lo), "v"(hi)); return r; }
; __device__ __forceinline__ float sigmoidf_(float x) { return __builtin_amdgcn_rcpf(1.f + __builtin_amdgcn_exp2f(x * -1.4426950408889634f)); }
;   __device__ __forceinline__ void operator()(const Acc& acc, const gm::Unit& u, int wr, int wc, int fr, int fq) const { const int pm = u.pm, pn = u.pn;
;     ...
;     for (int ai = 0; ai < 2; ++ai)
; #pragma unroll
;       for (int m = 0; m < 4; ++m) { const int row = pm * 256 + ai * 128 + wr * 64 + m * 16 + fr;
; #pragma unroll
;         for (int bj = 0; bj < 2; ++bj)
; #pragma unroll
;           for (int n = 0; n < 2; ++n) { const int col = pn * 256 + bj * 128 + wc * 32 + n * 16 + fq * 4; const f32x4 z = acc[ai][bj][m][n] + *(const f32x4*)(bg + col);
;             const u32x2 gw = *(const u32x2*)(Gg + (size_t)row * 512 + col);
;             const float g0 = __uint_as_float(gw[0] << 16), g1 = __uint_as_float(gw[0] & 0xffff0000u), g2 = __uint_as_float(gw[1] << 16), g3 = __uint_as_float(gw[1] & 0xffff0000u);
;             u32x2 w = {cvtpk(g0 * sigmoidf_(z[0]), g1 * sigmoidf_(z[1])), cvtpk(g2 * sigmoidf_(z[2]), g3 * sigmoidf_(z[3]))};
;             *(u32x2*)(Cat + (size_t)row * DM + 1024 + col) = w; } }
	v_mov_b64_e32 v[116:117], v[156:157]
	v_mov_b64_e32 v[118:119], v[158:159]
	v_add_u32_e32 v114, 16, v140
	v_ashrrev_i32_e32 v115, 31, v114
	v_lshlrev_b64 v[120:121], 10, v[114:115]
	v_lshlrev_b64 v[114:115], 12, v[114:115]
	v_add_f32_e64 v116, v110, v116
	v_add_f32_e64 v117, v111, v117
	v_lshl_add_u64 v[110:111], s[8:9], 0, v[120:121]
	v_lshl_add_u64 v[110:111], v[110:111], 0, v[126:127]
	v_add_f32_e64 v112, v112, v118
	v_add_f32_e64 v113, v113, v119
	global_load_dwordx2 v[180:181], v[110:111], off
	global_load_dwordx2 v[182:183], v[110:111], off offset:32
	global_load_dwordx2 v[184:185], v[110:111], off offset:256
	global_load_dwordx2 v[186:187], v[110:111], off offset:288
	s_waitcnt vmcnt(3)
	v_mov_b64_e32 v[118:119], v[180:181]
	v_mul_f32_e32 v116, 0xbfb8aa3b, v116
	v_mul_f32_e32 v117, 0xbfb8aa3b, v117
	v_mul_f32_e32 v112, 0xbfb8aa3b, v112
	v_mul_f32_e32 v113, 0xbfb8aa3b, v113
	v_exp_f32_e32 v116, v116
	v_exp_f32_e32 v117, v117
	v_exp_f32_e32 v112, v112
	v_exp_f32_e32 v113, v113
	v_add_f32_e32 v116, 1.0, v116
	v_add_f32_e32 v117, 1.0, v117
	v_add_f32_e32 v112, 1.0, v112
	v_add_f32_e32 v113, 1.0, v113
	v_rcp_f32_e32 v116, v116
	v_rcp_f32_e32 v117, v117
	v_rcp_f32_e32 v112, v112
	v_rcp_f32_e32 v113, v113
	v_lshlrev_b32_e32 v120, 16, v118
	v_and_b32_e32 v118, 0xffff0000, v118
	v_lshlrev_b32_e32 v121, 16, v119
	v_and_b32_e32 v119, 0xffff0000, v119
	v_mul_f32_e32 v116, v116, v120
	v_mul_f32_e32 v117, v117, v118
	v_mul_f32_e32 v112, v112, v121
	v_mul_f32_e32 v113, v113, v119
	v_cvt_pk_bf16_f32 v116, v116, v117
	v_cvt_pk_bf16_f32 v117, v112, v113
	v_lshl_add_u64 v[112:113], s[12:13], 0, v[114:115]
	v_lshl_add_u64 v[112:113], v[112:113], 0, v[126:127]
	global_store_dwordx2 v[112:113], v[116:117], off offset:2048
	s_waitcnt vmcnt(15)
	v_mov_b64_e32 v[114:115], v[160:161]
	v_mov_b64_e32 v[116:117], v[162:163]
	v_add_f32_e64 v106, v106, v114
	v_add_f32_e64 v107, v107, v115
	s_waitcnt vmcnt(3)
	v_mov_b64_e32 v[114:115], v[182:183]
	v_mul_f32_e32 v106, 0xbfb8aa3b, v106
	v_mul_f32_e32 v107, 0xbfb8aa3b, v107
	v_exp_f32_e32 v106, v106
	v_exp_f32_e32 v107, v107
	v_add_f32_e64 v108, v108, v116
	v_add_f32_e64 v109, v109, v117
	v_add_f32_e32 v106, 1.0, v106
	v_add_f32_e32 v107, 1.0, v107
	v_rcp_f32_e32 v106, v106
	v_rcp_f32_e32 v107, v107
	v_lshlrev_b32_e32 v116, 16, v114
	v_and_b32_e32 v114, 0xffff0000, v114
	v_mul_f32_e32 v106, v106, v116
	v_mul_f32_e32 v107, v107, v114
	v_cvt_pk_bf16_f32 v106, v106, v107
	v_mul_f32_e32 v107, 0xbfb8aa3b, v108
	v_exp_f32_e32 v107, v107
	v_mul_f32_e32 v108, 0xbfb8aa3b, v109
	v_exp_f32_e32 v108, v108
	v_lshlrev_b32_e32 v117, 16, v115
	v_add_f32_e32 v107, 1.0, v107
	v_rcp_f32_e32 v107, v107
	v_add_f32_e32 v108, 1.0, v108
	v_rcp_f32_e32 v108, v108
	v_and_b32_e32 v115, 0xffff0000, v115
	v_mul_f32_e32 v107, v107, v117
	v_mul_f32_e32 v108, v108, v115
	v_cvt_pk_bf16_f32 v107, v107, v108
	global_store_dwordx2 v[112:113], v[106:107], off offset:2080
	s_waitcnt vmcnt(15)
	v_mov_b64_e32 v[106:107], v[164:165]
	v_mov_b64_e32 v[108:109], v[166:167]
	v_add_f32_e64 v102, v102, v106
	v_add_f32_e64 v103, v103, v107
	s_waitcnt vmcnt(3)
	v_mov_b64_e32 v[106:107], v[184:185]
	v_mul_f32_e32 v102, 0xbfb8aa3b, v102
	v_mul_f32_e32 v103, 0xbfb8aa3b, v103
	v_exp_f32_e32 v102, v102
	v_exp_f32_e32 v103, v103
	v_add_f32_e64 v104, v104, v108
	v_add_f32_e64 v105, v105, v109
	v_add_f32_e32 v102, 1.0, v102
	v_add_f32_e32 v103, 1.0, v103
	v_rcp_f32_e32 v102, v102
	v_rcp_f32_e32 v103, v103
	v_lshlrev_b32_e32 v108, 16, v106
	v_and_b32_e32 v106, 0xffff0000, v106
	v_mul_f32_e32 v102, v102, v108
	v_mul_f32_e32 v103, v103, v106
	v_cvt_pk_bf16_f32 v102, v102, v103
	v_mul_f32_e32 v103, 0xbfb8aa3b, v104
	v_exp_f32_e32 v103, v103
	v_mul_f32_e32 v104, 0xbfb8aa3b, v105
	v_exp_f32_e32 v104, v104
	v_lshlrev_b32_e32 v109, 16, v107
	v_add_f32_e32 v103, 1.0, v103
	v_rcp_f32_e32 v103, v103
	v_add_f32_e32 v104, 1.0, v104
	v_rcp_f32_e32 v104, v104
	v_and_b32_e32 v107, 0xffff0000, v107
	v_mul_f32_e32 v103, v103, v109
	v_mul_f32_e32 v104, v104, v107
	v_cvt_pk_bf16_f32 v103, v103, v104
	global_store_dwordx2 v[112:113], v[102:103], off offset:2304
	s_waitcnt vmcnt(15)
	v_mov_b64_e32 v[102:103], v[168:169]
	v_mov_b64_e32 v[104:105], v[170:171]
	v_add_f32_e64 v98, v98, v102
	v_add_f32_e64 v99, v99, v103
	s_waitcnt vmcnt(3)
	v_mov_b64_e32 v[102:103], v[186:187]
	v_mul_f32_e32 v98, 0xbfb8aa3b, v98
	v_mul_f32_e32 v99, 0xbfb8aa3b, v99
	v_exp_f32_e32 v98, v98
	v_exp_f32_e32 v99, v99
	v_add_f32_e64 v100, v100, v104
	v_add_f32_e64 v101, v101, v105
	v_add_f32_e32 v98, 1.0, v98
	v_add_f32_e32 v99, 1.0, v99
	v_rcp_f32_e32 v98, v98
	v_rcp_f32_e32 v99, v99
	v_lshlrev_b32_e32 v104, 16, v102
	v_and_b32_e32 v102, 0xffff0000, v102
	v_mul_f32_e32 v98, v98, v104
	v_mul_f32_e32 v99, v99, v102
	v_cvt_pk_bf16_f32 v98, v98, v99
	v_mul_f32_e32 v99, 0xbfb8aa3b, v100
	v_exp_f32_e32 v99, v99
	v_mul_f32_e32 v100, 0xbfb8aa3b, v101
	v_exp_f32_e32 v100, v100
	v_lshlrev_b32_e32 v105, 16, v103
	v_add_f32_e32 v99, 1.0, v99
	v_rcp_f32_e32 v99, v99
	v_add_f32_e32 v100, 1.0, v100
	v_rcp_f32_e32 v100, v100
	v_and_b32_e32 v103, 0xffff0000, v103
	v_mul_f32_e32 v99, v99, v105
	v_mul_f32_e32 v100, v100, v103
	v_cvt_pk_bf16_f32 v99, v99, v100
	global_store_dwordx2 v[112:113], v[98:99], off offset:2336
	s_waitcnt vmcnt(19)
	v_mov_b64_e32 v[100:101], v[156:157]
	v_mov_b64_e32 v[102:103], v[158:159]
	v_add_u32_e32 v98, 32, v140
	v_ashrrev_i32_e32 v99, 31, v98
	v_lshlrev_b64 v[104:105], 10, v[98:99]
	v_lshlrev_b64 v[98:99], 12, v[98:99]
	v_add_f32_e64 v100, v94, v100
	v_add_f32_e64 v101, v95, v101
	v_lshl_add_u64 v[94:95], s[8:9], 0, v[104:105]
	v_lshl_add_u64 v[94:95], v[94:95], 0, v[126:127]
	v_add_f32_e64 v96, v96, v102
	v_add_f32_e64 v97, v97, v103
	global_load_dwordx2 v[172:173], v[94:95], off
	global_load_dwordx2 v[174:175], v[94:95], off offset:32
	global_load_dwordx2 v[176:177], v[94:95], off offset:256
	global_load_dwordx2 v[178:179], v[94:95], off offset:288
	s_waitcnt vmcnt(3)
; __device__ __forceinline__ unsigned cvtpk(float lo, float hi) { unsigned r; asm volatile("v_cvt_pk_bf16_f32 %0, %1, %2" : "=v"(r) : "v"(lo), "v"(hi)); return r; }
; __device__ __forceinline__ float sigmoidf_(float x) { return __builtin_amdgcn_rcpf(1.f + __builtin_amdgcn_exp2f(x * -1.4426950408889634f)); }
;   __device__ __forceinline__ void operator()(const Acc& acc, const gm::Unit& u, int wr, int wc, int fr, int fq) const { const int pm = u.pm, pn = u.pn;
;     ...
;     for (int ai = 0; ai < 2; ++ai)
; #pragma unroll
;       for (int m = 0; m < 4; ++m) { const int row = pm * 256 + ai * 128 + wr * 64 + m * 16 + fr;
; #pragma unroll
;         for (int bj = 0; bj < 2; ++bj)
; #pragma unroll
;           for (int n = 0; n < 2; ++n) { const int col = pn * 256 + bj * 128 + wc * 32 + n * 16 + fq * 4; const f32x4 z = acc[ai][bj][m][n] + *(const f32x4*)(bg + col);
;             const u32x2 gw = *(const u32x2*)(Gg + (size_t)row * 512 + col);
;             const float g0 = __uint_as_float(gw[0] << 16), g1 = __uint_as_float(gw[0] & 0xffff0000u), g2 = __uint_as_float(gw[1] << 16), g3 = __uint_as_float(gw[1] & 0xffff0000u);
;             u32x2 w = {cvtpk(g0 * sigmoidf_(z[0]), g1 * sigmoidf_(z[1])), cvtpk(g2 * sigmoidf_(z[2]), g3 * sigmoidf_(z[3]))};
;             *(u32x2*)(Cat + (size_t)row * DM + 1024 + col) = w; } }
	v_mov_b64_e32 v[102:103], v[172:173]
	v_mul_f32_e32 v100, 0xbfb8aa3b, v100
	v_mul_f32_e32 v101, 0xbfb8aa3b, v101
	v_mul_f32_e32 v96, 0xbfb8aa3b, v96
	v_mul_f32_e32 v97, 0xbfb8aa3b, v97
	v_exp_f32_e32 v100, v100
	v_exp_f32_e32 v101, v101
	v_exp_f32_e32 v96, v96
	v_exp_f32_e32 v97, v97
	v_add_f32_e32 v100, 1.0, v100
	v_add_f32_e32 v101, 1.0, v101
	v_add_f32_e32 v96, 1.0, v96
	v_add_f32_e32 v97, 1.0, v97
	v_rcp_f32_e32 v100, v100
	v_rcp_f32_e32 v101, v101
	v_rcp_f32_e32 v96, v96
	v_rcp_f32_e32 v97, v97
	v_lshlrev_b32_e32 v104, 16, v102
	v_and_b32_e32 v102, 0xffff0000, v102
	v_lshlrev_b32_e32 v105, 16, v103
	v_and_b32_e32 v103, 0xffff0000, v103
	v_mul_f32_e32 v100, v100, v104
	v_mul_f32_e32 v101, v101, v102
	v_mul_f32_e32 v96, v96, v105
	v_mul_f32_e32 v97, v97, v103
	v_cvt_pk_bf16_f32 v100, v100, v101
	v_cvt_pk_bf16_f32 v101, v96, v97
	v_lshl_add_u64 v[96:97], s[12:13], 0, v[98:99]
	v_lshl_add_u64 v[96:97], v[96:97], 0, v[126:127]
	global_store_dwordx2 v[96:97], v[100:101], off offset:2048
	s_waitcnt vmcnt(23)
	v_mov_b64_e32 v[98:99], v[160:161]
	v_mov_b64_e32 v[100:101], v[162:163]
	v_add_f32_e64 v90, v90, v98
	v_add_f32_e64 v91, v91, v99
	s_waitcnt vmcnt(3)
	v_mov_b64_e32 v[98:99], v[174:175]
	v_mul_f32_e32 v90, 0xbfb8aa3b, v90
	v_mul_f32_e32 v91, 0xbfb8aa3b, v91
	v_exp_f32_e32 v90, v90
	v_exp_f32_e32 v91, v91
	v_add_f32_e64 v92, v92, v100
	v_add_f32_e64 v93, v93, v101
	v_add_f32_e32 v90, 1.0, v90
	v_add_f32_e32 v91, 1.0, v91
	v_rcp_f32_e32 v90, v90
	v_rcp_f32_e32 v91, v91
	v_lshlrev_b32_e32 v100, 16, v98
	v_and_b32_e32 v98, 0xffff0000, v98
	v_mul_f32_e32 v90, v90, v100
	v_mul_f32_e32 v91, v91, v98
	v_cvt_pk_bf16_f32 v90, v90, v91
	v_mul_f32_e32 v91, 0xbfb8aa3b, v92
	v_exp_f32_e32 v91, v91
	v_mul_f32_e32 v92, 0xbfb8aa3b, v93
	v_exp_f32_e32 v92, v92
	v_lshlrev_b32_e32 v101, 16, v99
	v_add_f32_e32 v91, 1.0, v91
	v_rcp_f32_e32 v91, v91
	v_add_f32_e32 v92, 1.0, v92
	v_rcp_f32_e32 v92, v92
	v_and_b32_e32 v99, 0xffff0000, v99
	v_mul_f32_e32 v91, v91, v101
	v_mul_f32_e32 v92, v92, v99
	v_cvt_pk_bf16_f32 v91, v91, v92
	global_store_dwordx2 v[96:97], v[90:91], off offset:2080
	s_waitcnt vmcnt(23)
	v_mov_b64_e32 v[90:91], v[164:165]
	v_mov_b64_e32 v[92:93], v[166:167]
	v_add_f32_e64 v86, v86, v90
	v_add_f32_e64 v87, v87, v91
	s_waitcnt vmcnt(3)
	v_mov_b64_e32 v[90:91], v[176:177]
	v_mul_f32_e32 v86, 0xbfb8aa3b, v86
	v_mul_f32_e32 v87, 0xbfb8aa3b, v87
	v_exp_f32_e32 v86, v86
	v_exp_f32_e32 v87, v87
	v_add_f32_e64 v88, v88, v92
	v_add_f32_e64 v89, v89, v93
	v_add_f32_e32 v86, 1.0, v86
	v_add_f32_e32 v87, 1.0, v87
	v_rcp_f32_e32 v86, v86
	v_rcp_f32_e32 v87, v87
	v_lshlrev_b32_e32 v92, 16, v90
	v_and_b32_e32 v90, 0xffff0000, v90
	v_mul_f32_e32 v86, v86, v92
	v_mul_f32_e32 v87, v87, v90
	v_cvt_pk_bf16_f32 v86, v86, v87
	v_mul_f32_e32 v87, 0xbfb8aa3b, v88
	v_exp_f32_e32 v87, v87
	v_mul_f32_e32 v88, 0xbfb8aa3b, v89
	v_exp_f32_e32 v88, v88
	v_lshlrev_b32_e32 v93, 16, v91
	v_add_f32_e32 v87, 1.0, v87
	v_rcp_f32_e32 v87, v87
	v_add_f32_e32 v88, 1.0, v88
	v_rcp_f32_e32 v88, v88
	v_and_b32_e32 v91, 0xffff0000, v91
	v_mul_f32_e32 v87, v87, v93
	v_mul_f32_e32 v88, v88, v91
	v_cvt_pk_bf16_f32 v87, v87, v88
	global_store_dwordx2 v[96:97], v[86:87], off offset:2304
	s_waitcnt vmcnt(23)
	v_mov_b64_e32 v[86:87], v[168:169]
	v_mov_b64_e32 v[88:89], v[170:171]
	v_add_f32_e64 v82, v82, v86
	v_add_f32_e64 v83, v83, v87
	s_waitcnt vmcnt(3)
	v_mov_b64_e32 v[86:87], v[178:179]
	v_mul_f32_e32 v82, 0xbfb8aa3b, v82
	v_mul_f32_e32 v83, 0xbfb8aa3b, v83
	v_exp_f32_e32 v82, v82
	v_exp_f32_e32 v83, v83
	v_add_f32_e64 v84, v84, v88
	v_add_f32_e64 v85, v85, v89
	v_add_f32_e32 v82, 1.0, v82
	v_add_f32_e32 v83, 1.0, v83
	v_rcp_f32_e32 v82, v82
	v_rcp_f32_e32 v83, v83
	v_lshlrev_b32_e32 v88, 16, v86
	v_and_b32_e32 v86, 0xffff0000, v86
	v_mul_f32_e32 v82, v82, v88
	v_mul_f32_e32 v83, v83, v86
	v_cvt_pk_bf16_f32 v82, v82, v83
	v_mul_f32_e32 v83, 0xbfb8aa3b, v84
	v_exp_f32_e32 v83, v83
	v_mul_f32_e32 v84, 0xbfb8aa3b, v85
	v_exp_f32_e32 v84, v84
	v_lshlrev_b32_e32 v89, 16, v87
	v_add_f32_e32 v83, 1.0, v83
	v_rcp_f32_e32 v83, v83
	v_add_f32_e32 v84, 1.0, v84
	v_rcp_f32_e32 v84, v84
	v_and_b32_e32 v87, 0xffff0000, v87
	v_mul_f32_e32 v83, v83, v89
	v_mul_f32_e32 v84, v84, v87
	v_cvt_pk_bf16_f32 v83, v83, v84
	global_store_dwordx2 v[96:97], v[82:83], off offset:2336
	s_waitcnt vmcnt(27)
	v_mov_b64_e32 v[84:85], v[156:157]
	v_mov_b64_e32 v[86:87], v[158:159]
	v_add_u32_e32 v82, 48, v140
	v_ashrrev_i32_e32 v83, 31, v82
	v_lshlrev_b64 v[88:89], 10, v[82:83]
	v_lshlrev_b64 v[82:83], 12, v[82:83]
	v_add_f32_e64 v84, v78, v84
	v_add_f32_e64 v85, v79, v85
	v_lshl_add_u64 v[78:79], s[8:9], 0, v[88:89]
	v_lshl_add_u64 v[78:79], v[78:79], 0, v[126:127]
	v_add_f32_e64 v80, v80, v86
	v_add_f32_e64 v81, v81, v87
	global_load_dwordx2 v[180:181], v[78:79], off
	global_load_dwordx2 v[182:183], v[78:79], off offset:32
	global_load_dwordx2 v[184:185], v[78:79], off offset:256
	global_load_dwordx2 v[186:187], v[78:79], off offset:288
	s_waitcnt vmcnt(3)
	v_mov_b64_e32 v[86:87], v[180:181]
	v_mul_f32_e32 v84, 0xbfb8aa3b, v84
	v_mul_f32_e32 v85, 0xbfb8aa3b, v85
	v_mul_f32_e32 v80, 0xbfb8aa3b, v80
	v_mul_f32_e32 v81, 0xbfb8aa3b, v81
	v_exp_f32_e32 v84, v84
	v_exp_f32_e32 v85, v85
	v_exp_f32_e32 v80, v80
	v_exp_f32_e32 v81, v81
	v_add_f32_e32 v84, 1.0, v84
	v_add_f32_e32 v85, 1.0, v85
	v_add_f32_e32 v80, 1.0, v80
	v_add_f32_e32 v81, 1.0, v81
	v_rcp_f32_e32 v84, v84
	v_rcp_f32_e32 v85, v85
	v_rcp_f32_e32 v80, v80
	v_rcp_f32_e32 v81, v81
	v_lshlrev_b32_e32 v88, 16, v86
	v_and_b32_e32 v86, 0xffff0000, v86
	v_lshlrev_b32_e32 v89, 16, v87
	v_and_b32_e32 v87, 0xffff0000, v87
	v_mul_f32_e32 v84, v84, v88
	v_mul_f32_e32 v85, v85, v86
	v_mul_f32_e32 v80, v80, v89
	v_mul_f32_e32 v81, v81, v87
	v_cvt_pk_bf16_f32 v84, v84, v85
	v_cvt_pk_bf16_f32 v85, v80, v81
	v_lshl_add_u64 v[80:81], s[12:13], 0, v[82:83]
	v_lshl_add_u64 v[80:81], v[80:81], 0, v[126:127]
	global_store_dwordx2 v[80:81], v[84:85], off offset:2048
	s_waitcnt vmcnt(31)
; __device__ __forceinline__ unsigned cvtpk(float lo, float hi) { unsigned r; asm volatile("v_cvt_pk_bf16_f32 %0, %1, %2" : "=v"(r) : "v"(lo), "v"(hi)); return r; }
; __device__ __forceinline__ float sigmoidf_(float x) { return __builtin_amdgcn_rcpf(1.f + __builtin_amdgcn_exp2f(x * -1.4426950408889634f)); }
;   __device__ __forceinline__ void operator()(const Acc& acc, const gm::Unit& u, int wr, int wc, int fr, int fq) const { const int pm = u.pm, pn = u.pn;
;     ...
;     for (int ai = 0; ai < 2; ++ai)
; #pragma unroll
;       for (int m = 0; m < 4; ++m) { const int row = pm * 256 + ai * 128 + wr * 64 + m * 16 + fr;
; #pragma unroll
;         for (int bj = 0; bj < 2; ++bj)
; #pragma unroll
;           for (int n = 0; n < 2; ++n) { const int col = pn * 256 + bj * 128 + wc * 32 + n * 16 + fq * 4; const f32x4 z = acc[ai][bj][m][n] + *(const f32x4*)(bg + col);
;             const u32x2 gw = *(const u32x2*)(Gg + (size_t)row * 512 + col);
;             const float g0 = __uint_as_float(gw[0] << 16), g1 = __uint_as_float(gw[0] & 0xffff0000u), g2 = __uint_as_float(gw[1] << 16), g3 = __uint_as_float(gw[1] & 0xffff0000u);
;             u32x2 w = {cvtpk(g0 * sigmoidf_(z[0]), g1 * sigmoidf_(z[1])), cvtpk(g2 * sigmoidf_(z[2]), g3 * sigmoidf_(z[3]))};
;             *(u32x2*)(Cat + (size_t)row * DM + 1024 + col) = w; } }
	v_mov_b64_e32 v[82:83], v[160:161]
	v_mov_b64_e32 v[84:85], v[162:163]
	v_add_f32_e64 v74, v74, v82
	v_add_f32_e64 v75, v75, v83
	s_waitcnt vmcnt(3)
	v_mov_b64_e32 v[82:83], v[182:183]
	v_mul_f32_e32 v74, 0xbfb8aa3b, v74
	v_mul_f32_e32 v75, 0xbfb8aa3b, v75
	v_exp_f32_e32 v74, v74
	v_exp_f32_e32 v75, v75
	v_add_f32_e64 v76, v76, v84
	v_add_f32_e64 v77, v77, v85
	v_add_f32_e32 v74, 1.0, v74
	v_add_f32_e32 v75, 1.0, v75
	v_rcp_f32_e32 v74, v74
	v_rcp_f32_e32 v75, v75
	v_lshlrev_b32_e32 v84, 16, v82
	v_and_b32_e32 v82, 0xffff0000, v82
	v_mul_f32_e32 v74, v74, v84
	v_mul_f32_e32 v75, v75, v82
	v_cvt_pk_bf16_f32 v74, v74, v75
	v_mul_f32_e32 v75, 0xbfb8aa3b, v76
	v_exp_f32_e32 v75, v75
	v_mul_f32_e32 v76, 0xbfb8aa3b, v77
	v_exp_f32_e32 v76, v76
	v_lshlrev_b32_e32 v85, 16, v83
	v_add_f32_e32 v75, 1.0, v75
	v_rcp_f32_e32 v75, v75
	v_add_f32_e32 v76, 1.0, v76
	v_rcp_f32_e32 v76, v76
	v_and_b32_e32 v83, 0xffff0000, v83
	v_mul_f32_e32 v75, v75, v85
	v_mul_f32_e32 v76, v76, v83
	v_cvt_pk_bf16_f32 v75, v75, v76
	global_store_dwordx2 v[80:81], v[74:75], off offset:2080
	s_waitcnt vmcnt(31)
	v_mov_b64_e32 v[74:75], v[164:165]
	v_mov_b64_e32 v[76:77], v[166:167]
	v_add_f32_e64 v70, v70, v74
	v_add_f32_e64 v71, v71, v75
	s_waitcnt vmcnt(3)
	v_mov_b64_e32 v[74:75], v[184:185]
	v_mul_f32_e32 v70, 0xbfb8aa3b, v70
	v_mul_f32_e32 v71, 0xbfb8aa3b, v71
	v_exp_f32_e32 v70, v70
	v_exp_f32_e32 v71, v71
	v_add_f32_e64 v72, v72, v76
	v_add_f32_e64 v73, v73, v77
	v_add_f32_e32 v70, 1.0, v70
	v_add_f32_e32 v71, 1.0, v71
	v_rcp_f32_e32 v70, v70
	v_rcp_f32_e32 v71, v71
	v_lshlrev_b32_e32 v76, 16, v74
	v_and_b32_e32 v74, 0xffff0000, v74
	v_mul_f32_e32 v70, v70, v76
	v_mul_f32_e32 v71, v71, v74
	v_cvt_pk_bf16_f32 v70, v70, v71
	v_mul_f32_e32 v71, 0xbfb8aa3b, v72
	v_exp_f32_e32 v71, v71
	v_mul_f32_e32 v72, 0xbfb8aa3b, v73
	v_exp_f32_e32 v72, v72
	v_lshlrev_b32_e32 v77, 16, v75
	v_add_f32_e32 v71, 1.0, v71
	v_rcp_f32_e32 v71, v71
	v_add_f32_e32 v72, 1.0, v72
	v_rcp_f32_e32 v72, v72
	v_and_b32_e32 v75, 0xffff0000, v75
	v_mul_f32_e32 v71, v71, v77
	v_mul_f32_e32 v72, v72, v75
	v_cvt_pk_bf16_f32 v71, v71, v72
	global_store_dwordx2 v[80:81], v[70:71], off offset:2304
	s_waitcnt vmcnt(31)
	v_mov_b64_e32 v[70:71], v[168:169]
	v_mov_b64_e32 v[72:73], v[170:171]
	v_add_f32_e64 v66, v66, v70
	v_add_f32_e64 v67, v67, v71
	s_waitcnt vmcnt(3)
	v_mov_b64_e32 v[70:71], v[186:187]
	v_mul_f32_e32 v66, 0xbfb8aa3b, v66
	v_mul_f32_e32 v67, 0xbfb8aa3b, v67
	v_exp_f32_e32 v66, v66
	v_exp_f32_e32 v67, v67
	v_add_f32_e64 v68, v68, v72
	v_add_f32_e64 v69, v69, v73
	v_add_f32_e32 v66, 1.0, v66
	v_add_f32_e32 v67, 1.0, v67
	v_rcp_f32_e32 v66, v66
	v_rcp_f32_e32 v67, v67
	v_lshlrev_b32_e32 v72, 16, v70
	v_and_b32_e32 v70, 0xffff0000, v70
	v_mul_f32_e32 v66, v66, v72
	v_mul_f32_e32 v67, v67, v70
	v_cvt_pk_bf16_f32 v66, v66, v67
	v_mul_f32_e32 v67, 0xbfb8aa3b, v68
	v_exp_f32_e32 v67, v67
	v_mul_f32_e32 v68, 0xbfb8aa3b, v69
	v_exp_f32_e32 v68, v68
	v_lshlrev_b32_e32 v73, 16, v71
	v_add_f32_e32 v67, 1.0, v67
	v_rcp_f32_e32 v67, v67
	v_add_f32_e32 v68, 1.0, v68
	v_rcp_f32_e32 v68, v68
	v_and_b32_e32 v71, 0xffff0000, v71
	v_mul_f32_e32 v67, v67, v73
	v_mul_f32_e32 v68, v68, v71
	v_cvt_pk_bf16_f32 v67, v67, v68
	global_store_dwordx2 v[80:81], v[66:67], off offset:2336
	s_waitcnt vmcnt(35)
	v_mov_b64_e32 v[68:69], v[156:157]
	v_mov_b64_e32 v[70:71], v[158:159]
	v_add_u32_e32 v66, 0x80, v140
	v_ashrrev_i32_e32 v67, 31, v66
	v_lshlrev_b64 v[72:73], 10, v[66:67]
	v_lshlrev_b64 v[66:67], 12, v[66:67]
	v_add_f32_e64 v68, v62, v68
	v_add_f32_e64 v69, v63, v69
	v_lshl_add_u64 v[62:63], s[8:9], 0, v[72:73]
	v_lshl_add_u64 v[62:63], v[62:63], 0, v[126:127]
	v_add_f32_e64 v64, v64, v70
	v_add_f32_e64 v65, v65, v71
	global_load_dwordx2 v[172:173], v[62:63], off
	global_load_dwordx2 v[174:175], v[62:63], off offset:32
	global_load_dwordx2 v[176:177], v[62:63], off offset:256
	global_load_dwordx2 v[178:179], v[62:63], off offset:288
	s_waitcnt vmcnt(3)
	v_mov_b64_e32 v[70:71], v[172:173]
	v_mul_f32_e32 v68, 0xbfb8aa3b, v68
	v_mul_f32_e32 v69, 0xbfb8aa3b, v69
	v_mul_f32_e32 v64, 0xbfb8aa3b, v64
	v_mul_f32_e32 v65, 0xbfb8aa3b, v65
	v_exp_f32_e32 v68, v68
	v_exp_f32_e32 v69, v69
	v_exp_f32_e32 v64, v64
	v_exp_f32_e32 v65, v65
	v_add_f32_e32 v68, 1.0, v68
	v_add_f32_e32 v69, 1.0, v69
	v_add_f32_e32 v64, 1.0, v64
	v_add_f32_e32 v65, 1.0, v65
	v_rcp_f32_e32 v68, v68
	v_rcp_f32_e32 v69, v69
	v_rcp_f32_e32 v64, v64
	v_rcp_f32_e32 v65, v65
	v_lshlrev_b32_e32 v72, 16, v70
	v_and_b32_e32 v70, 0xffff0000, v70
	v_lshlrev_b32_e32 v73, 16, v71
	v_and_b32_e32 v71, 0xffff0000, v71
	v_mul_f32_e32 v68, v68, v72
	v_mul_f32_e32 v69, v69, v70
	v_mul_f32_e32 v64, v64, v73
	v_mul_f32_e32 v65, v65, v71
	v_cvt_pk_bf16_f32 v68, v68, v69
	v_cvt_pk_bf16_f32 v69, v64, v65
	v_lshl_add_u64 v[64:65], s[12:13], 0, v[66:67]
	v_lshl_add_u64 v[64:65], v[64:65], 0, v[126:127]
	global_store_dwordx2 v[64:65], v[68:69], off offset:2048
	s_waitcnt vmcnt(39)
	v_mov_b64_e32 v[66:67], v[160:161]
	v_mov_b64_e32 v[68:69], v[162:163]
	v_add_f32_e64 v58, v58, v66
	v_add_f32_e64 v59, v59, v67
	s_waitcnt vmcnt(3)
	v_mov_b64_e32 v[66:67], v[174:175]
	v_mul_f32_e32 v58, 0xbfb8aa3b, v58
	v_mul_f32_e32 v59, 0xbfb8aa3b, v59
	v_exp_f32_e32 v58, v58
	v_exp_f32_e32 v59, v59
	v_add_f32_e64 v60, v60, v68
	v_add_f32_e64 v61, v61, v69
	v_add_f32_e32 v58, 1.0, v58
	v_add_f32_e32 v59, 1.0, v59
	v_rcp_f32_e32 v58, v58
	v_rcp_f32_e32 v59, v59
	v_lshlrev_b32_e32 v68, 16, v66
	v_and_b32_e32 v66, 0xffff0000, v66
	v_mul_f32_e32 v58, v58, v68
	v_mul_f32_e32 v59, v59, v66
	v_cvt_pk_bf16_f32 v58, v58, v59
	v_mul_f32_e32 v59, 0xbfb8aa3b, v60
	v_exp_f32_e32 v59, v59
	v_mul_f32_e32 v60, 0xbfb8aa3b, v61
	v_exp_f32_e32 v60, v60
	v_lshlrev_b32_e32 v69, 16, v67
	v_add_f32_e32 v59, 1.0, v59
	v_rcp_f32_e32 v59, v59
	v_add_f32_e32 v60, 1.0, v60
	v_rcp_f32_e32 v60, v60
	v_and_b32_e32 v67, 0xffff0000, v67
	v_mul_f32_e32 v59, v59, v69
	v_mul_f32_e32 v60, v60, v67
	v_cvt_pk_bf16_f32 v59, v59, v60
	global_store_dwordx2 v[64:65], v[58:59], off offset:2080
	s_waitcnt vmcnt(39)
; __device__ __forceinline__ unsigned cvtpk(float lo, float hi) { unsigned r; asm volatile("v_cvt_pk_bf16_f32 %0, %1, %2" : "=v"(r) : "v"(lo), "v"(hi)); return r; }
; __device__ __forceinline__ float sigmoidf_(float x) { return __builtin_amdgcn_rcpf(1.f + __builtin_amdgcn_exp2f(x * -1.4426950408889634f)); }
;   __device__ __forceinline__ void operator()(const Acc& acc, const gm::Unit& u, int wr, int wc, int fr, int fq) const { const int pm = u.pm, pn = u.pn;
;     ...
;     for (int ai = 0; ai < 2; ++ai)
; #pragma unroll
;       for (int m = 0; m < 4; ++m) { const int row = pm * 256 + ai * 128 + wr * 64 + m * 16 + fr;
; #pragma unroll
;         for (int bj = 0; bj < 2; ++bj)
; #pragma unroll
;           for (int n = 0; n < 2; ++n) { const int col = pn * 256 + bj * 128 + wc * 32 + n * 16 + fq * 4; const f32x4 z = acc[ai][bj][m][n] + *(const f32x4*)(bg + col);
;             const u32x2 gw = *(const u32x2*)(Gg + (size_t)row * 512 + col);
;             const float g0 = __uint_as_float(gw[0] << 16), g1 = __uint_as_float(gw[0] & 0xffff0000u), g2 = __uint_as_float(gw[1] << 16), g3 = __uint_as_float(gw[1] & 0xffff0000u);
;             u32x2 w = {cvtpk(g0 * sigmoidf_(z[0]), g1 * sigmoidf_(z[1])), cvtpk(g2 * sigmoidf_(z[2]), g3 * sigmoidf_(z[3]))};
;             *(u32x2*)(Cat + (size_t)row * DM + 1024 + col) = w; } }
	v_mov_b64_e32 v[58:59], v[164:165]
	v_mov_b64_e32 v[60:61], v[166:167]
	v_add_f32_e64 v54, v54, v58
	v_add_f32_e64 v55, v55, v59
	s_waitcnt vmcnt(3)
	v_mov_b64_e32 v[58:59], v[176:177]
	v_mul_f32_e32 v54, 0xbfb8aa3b, v54
	v_mul_f32_e32 v55, 0xbfb8aa3b, v55
	v_exp_f32_e32 v54, v54
	v_exp_f32_e32 v55, v55
	v_add_f32_e64 v56, v56, v60
	v_add_f32_e64 v57, v57, v61
	v_add_f32_e32 v54, 1.0, v54
	v_add_f32_e32 v55, 1.0, v55
	v_rcp_f32_e32 v54, v54
	v_rcp_f32_e32 v55, v55
	v_lshlrev_b32_e32 v60, 16, v58
	v_and_b32_e32 v58, 0xffff0000, v58
	v_mul_f32_e32 v54, v54, v60
	v_mul_f32_e32 v55, v55, v58
	v_cvt_pk_bf16_f32 v54, v54, v55
	v_mul_f32_e32 v55, 0xbfb8aa3b, v56
	v_exp_f32_e32 v55, v55
	v_mul_f32_e32 v56, 0xbfb8aa3b, v57
	v_exp_f32_e32 v56, v56
	v_lshlrev_b32_e32 v61, 16, v59
	v_add_f32_e32 v55, 1.0, v55
	v_rcp_f32_e32 v55, v55
	v_add_f32_e32 v56, 1.0, v56
	v_rcp_f32_e32 v56, v56
	v_and_b32_e32 v59, 0xffff0000, v59
	v_mul_f32_e32 v55, v55, v61
	v_mul_f32_e32 v56, v56, v59
	v_cvt_pk_bf16_f32 v55, v55, v56
	global_store_dwordx2 v[64:65], v[54:55], off offset:2304
	s_waitcnt vmcnt(39)
	v_mov_b64_e32 v[54:55], v[168:169]
	v_mov_b64_e32 v[56:57], v[170:171]
	v_add_f32_e64 v50, v50, v54
	v_add_f32_e64 v51, v51, v55
	s_waitcnt vmcnt(3)
	v_mov_b64_e32 v[54:55], v[178:179]
	v_mul_f32_e32 v50, 0xbfb8aa3b, v50
	v_mul_f32_e32 v51, 0xbfb8aa3b, v51
	v_exp_f32_e32 v50, v50
	v_exp_f32_e32 v51, v51
	v_add_f32_e64 v52, v52, v56
	v_add_f32_e64 v53, v53, v57
	v_add_f32_e32 v50, 1.0, v50
	v_add_f32_e32 v51, 1.0, v51
	v_rcp_f32_e32 v50, v50
	v_rcp_f32_e32 v51, v51
	v_lshlrev_b32_e32 v56, 16, v54
	v_and_b32_e32 v54, 0xffff0000, v54
	v_mul_f32_e32 v50, v50, v56
	v_mul_f32_e32 v51, v51, v54
	v_cvt_pk_bf16_f32 v50, v50, v51
	v_mul_f32_e32 v51, 0xbfb8aa3b, v52
	v_exp_f32_e32 v51, v51
	v_mul_f32_e32 v52, 0xbfb8aa3b, v53
	v_exp_f32_e32 v52, v52
	v_lshlrev_b32_e32 v57, 16, v55
	v_add_f32_e32 v51, 1.0, v51
	v_rcp_f32_e32 v51, v51
	v_add_f32_e32 v52, 1.0, v52
	v_rcp_f32_e32 v52, v52
	v_and_b32_e32 v55, 0xffff0000, v55
	v_mul_f32_e32 v51, v51, v57
	v_mul_f32_e32 v52, v52, v55
	v_cvt_pk_bf16_f32 v51, v51, v52
	global_store_dwordx2 v[64:65], v[50:51], off offset:2336
	s_waitcnt vmcnt(43)
	v_mov_b64_e32 v[52:53], v[156:157]
	v_mov_b64_e32 v[54:55], v[158:159]
	v_add_u32_e32 v50, 0x90, v140
	v_ashrrev_i32_e32 v51, 31, v50
	v_lshlrev_b64 v[56:57], 10, v[50:51]
	v_lshlrev_b64 v[50:51], 12, v[50:51]
	v_add_f32_e64 v52, v46, v52
	v_add_f32_e64 v53, v47, v53
	v_lshl_add_u64 v[46:47], s[8:9], 0, v[56:57]
	v_lshl_add_u64 v[46:47], v[46:47], 0, v[126:127]
	v_add_f32_e64 v48, v48, v54
	v_add_f32_e64 v49, v49, v55
	global_load_dwordx2 v[180:181], v[46:47], off
	global_load_dwordx2 v[182:183], v[46:47], off offset:32
	global_load_dwordx2 v[184:185], v[46:47], off offset:256
	global_load_dwordx2 v[186:187], v[46:47], off offset:288
	s_waitcnt vmcnt(3)
	v_mov_b64_e32 v[54:55], v[180:181]
	v_mul_f32_e32 v52, 0xbfb8aa3b, v52
	v_mul_f32_e32 v53, 0xbfb8aa3b, v53
	v_mul_f32_e32 v48, 0xbfb8aa3b, v48
	v_mul_f32_e32 v49, 0xbfb8aa3b, v49
	v_exp_f32_e32 v52, v52
	v_exp_f32_e32 v53, v53
	v_exp_f32_e32 v48, v48
	v_exp_f32_e32 v49, v49
	v_add_f32_e32 v52, 1.0, v52
	v_add_f32_e32 v53, 1.0, v53
	v_add_f32_e32 v48, 1.0, v48
	v_add_f32_e32 v49, 1.0, v49
	v_rcp_f32_e32 v52, v52
	v_rcp_f32_e32 v53, v53
	v_rcp_f32_e32 v48, v48
	v_rcp_f32_e32 v49, v49
	v_lshlrev_b32_e32 v56, 16, v54
	v_and_b32_e32 v54, 0xffff0000, v54
	v_lshlrev_b32_e32 v57, 16, v55
	v_and_b32_e32 v55, 0xffff0000, v55
	v_mul_f32_e32 v52, v52, v56
	v_mul_f32_e32 v53, v53, v54
	v_mul_f32_e32 v48, v48, v57
	v_mul_f32_e32 v49, v49, v55
	v_cvt_pk_bf16_f32 v52, v52, v53
	v_cvt_pk_bf16_f32 v53, v48, v49
	v_lshl_add_u64 v[48:49], s[12:13], 0, v[50:51]
	v_lshl_add_u64 v[48:49], v[48:49], 0, v[126:127]
	global_store_dwordx2 v[48:49], v[52:53], off offset:2048
	s_waitcnt vmcnt(47)
	v_mov_b64_e32 v[50:51], v[160:161]
	v_mov_b64_e32 v[52:53], v[162:163]
	v_add_f32_e64 v42, v42, v50
	v_add_f32_e64 v43, v43, v51
	s_waitcnt vmcnt(3)
	v_mov_b64_e32 v[50:51], v[182:183]
	v_mul_f32_e32 v42, 0xbfb8aa3b, v42
	v_mul_f32_e32 v43, 0xbfb8aa3b, v43
	v_exp_f32_e32 v42, v42
	v_exp_f32_e32 v43, v43
	v_add_f32_e64 v44, v44, v52
	v_add_f32_e64 v45, v45, v53
	v_add_f32_e32 v42, 1.0, v42
	v_add_f32_e32 v43, 1.0, v43
	v_rcp_f32_e32 v42, v42
	v_rcp_f32_e32 v43, v43
	v_lshlrev_b32_e32 v52, 16, v50
	v_and_b32_e32 v50, 0xffff0000, v50
	v_mul_f32_e32 v42, v42, v52
	v_mul_f32_e32 v43, v43, v50
	v_cvt_pk_bf16_f32 v42, v42, v43
	v_mul_f32_e32 v43, 0xbfb8aa3b, v44
	v_exp_f32_e32 v43, v43
	v_mul_f32_e32 v44, 0xbfb8aa3b, v45
	v_exp_f32_e32 v44, v44
	v_lshlrev_b32_e32 v53, 16, v51
	v_add_f32_e32 v43, 1.0, v43
	v_rcp_f32_e32 v43, v43
	v_add_f32_e32 v44, 1.0, v44
	v_rcp_f32_e32 v44, v44
	v_and_b32_e32 v51, 0xffff0000, v51
	v_mul_f32_e32 v43, v43, v53
	v_mul_f32_e32 v44, v44, v51
	v_cvt_pk_bf16_f32 v43, v43, v44
	global_store_dwordx2 v[48:49], v[42:43], off offset:2080
	s_waitcnt vmcnt(47)
	v_mov_b64_e32 v[42:43], v[164:165]
	v_mov_b64_e32 v[44:45], v[166:167]
	v_add_f32_e64 v38, v38, v42
	v_add_f32_e64 v39, v39, v43
	s_waitcnt vmcnt(3)
	v_mov_b64_e32 v[42:43], v[184:185]
	v_mul_f32_e32 v38, 0xbfb8aa3b, v38
	v_mul_f32_e32 v39, 0xbfb8aa3b, v39
	v_exp_f32_e32 v38, v38
	v_exp_f32_e32 v39, v39
	v_add_f32_e64 v40, v40, v44
	v_add_f32_e64 v41, v41, v45
	v_add_f32_e32 v38, 1.0, v38
	v_add_f32_e32 v39, 1.0, v39
	v_rcp_f32_e32 v38, v38
	v_rcp_f32_e32 v39, v39
	v_lshlrev_b32_e32 v44, 16, v42
	v_and_b32_e32 v42, 0xffff0000, v42
	v_mul_f32_e32 v38, v38, v44
	v_mul_f32_e32 v39, v39, v42
	v_cvt_pk_bf16_f32 v38, v38, v39
	v_mul_f32_e32 v39, 0xbfb8aa3b, v40
	v_exp_f32_e32 v39, v39
	v_mul_f32_e32 v40, 0xbfb8aa3b, v41
	v_exp_f32_e32 v40, v40
	v_lshlrev_b32_e32 v45, 16, v43
	v_add_f32_e32 v39, 1.0, v39
	v_rcp_f32_e32 v39, v39
	v_add_f32_e32 v40, 1.0, v40
	v_rcp_f32_e32 v40, v40
	v_and_b32_e32 v43, 0xffff0000, v43
	v_mul_f32_e32 v39, v39, v45
	v_mul_f32_e32 v40, v40, v43
	v_cvt_pk_bf16_f32 v39, v39, v40
	global_store_dwordx2 v[48:49], v[38:39], off offset:2304
	s_waitcnt vmcnt(47)
; __device__ __forceinline__ unsigned cvtpk(float lo, float hi) { unsigned r; asm volatile("v_cvt_pk_bf16_f32 %0, %1, %2" : "=v"(r) : "v"(lo), "v"(hi)); return r; }
; __device__ __forceinline__ float sigmoidf_(float x) { return __builtin_amdgcn_rcpf(1.f + __builtin_amdgcn_exp2f(x * -1.4426950408889634f)); }
;   __device__ __forceinline__ void operator()(const Acc& acc, const gm::Unit& u, int wr, int wc, int fr, int fq) const { const int pm = u.pm, pn = u.pn;
;     ...
;     for (int ai = 0; ai < 2; ++ai)
; #pragma unroll
;       for (int m = 0; m < 4; ++m) { const int row = pm * 256 + ai * 128 + wr * 64 + m * 16 + fr;
; #pragma unroll
;         for (int bj = 0; bj < 2; ++bj)
; #pragma unroll
;           for (int n = 0; n < 2; ++n) { const int col = pn * 256 + bj * 128 + wc * 32 + n * 16 + fq * 4; const f32x4 z = acc[ai][bj][m][n] + *(const f32x4*)(bg + col);
;             const u32x2 gw = *(const u32x2*)(Gg + (size_t)row * 512 + col);
;             const float g0 = __uint_as_float(gw[0] << 16), g1 = __uint_as_float(gw[0] & 0xffff0000u), g2 = __uint_as_float(gw[1] << 16), g3 = __uint_as_float(gw[1] & 0xffff0000u);
;             u32x2 w = {cvtpk(g0 * sigmoidf_(z[0]), g1 * sigmoidf_(z[1])), cvtpk(g2 * sigmoidf_(z[2]), g3 * sigmoidf_(z[3]))};
;             *(u32x2*)(Cat + (size_t)row * DM + 1024 + col) = w; } }
	v_mov_b64_e32 v[38:39], v[168:169]
	v_mov_b64_e32 v[40:41], v[170:171]
	v_add_f32_e64 v34, v34, v38
	v_add_f32_e64 v35, v35, v39
	s_waitcnt vmcnt(3)
	v_mov_b64_e32 v[38:39], v[186:187]
	v_mul_f32_e32 v34, 0xbfb8aa3b, v34
	v_mul_f32_e32 v35, 0xbfb8aa3b, v35
	v_exp_f32_e32 v34, v34
	v_exp_f32_e32 v35, v35
	v_add_f32_e64 v36, v36, v40
	v_add_f32_e64 v37, v37, v41
	v_add_f32_e32 v34, 1.0, v34
	v_add_f32_e32 v35, 1.0, v35
	v_rcp_f32_e32 v34, v34
	v_rcp_f32_e32 v35, v35
	v_lshlrev_b32_e32 v40, 16, v38
	v_and_b32_e32 v38, 0xffff0000, v38
	v_mul_f32_e32 v34, v34, v40
	v_mul_f32_e32 v35, v35, v38
	v_cvt_pk_bf16_f32 v34, v34, v35
	v_mul_f32_e32 v35, 0xbfb8aa3b, v36
	v_exp_f32_e32 v35, v35
	v_mul_f32_e32 v36, 0xbfb8aa3b, v37
	v_exp_f32_e32 v36, v36
	v_lshlrev_b32_e32 v41, 16, v39
	v_add_f32_e32 v35, 1.0, v35
	v_rcp_f32_e32 v35, v35
	v_add_f32_e32 v36, 1.0, v36
	v_rcp_f32_e32 v36, v36
	v_and_b32_e32 v39, 0xffff0000, v39
	v_mul_f32_e32 v35, v35, v41
	v_mul_f32_e32 v36, v36, v39
	v_cvt_pk_bf16_f32 v35, v35, v36
	global_store_dwordx2 v[48:49], v[34:35], off offset:2336
	s_waitcnt vmcnt(51)
	v_mov_b64_e32 v[36:37], v[156:157]
	v_mov_b64_e32 v[38:39], v[158:159]
	v_add_u32_e32 v34, 0xa0, v140
	v_ashrrev_i32_e32 v35, 31, v34
	v_lshlrev_b64 v[40:41], 10, v[34:35]
	v_lshlrev_b64 v[34:35], 12, v[34:35]
	v_add_f32_e64 v36, v30, v36
	v_add_f32_e64 v37, v31, v37
	v_lshl_add_u64 v[30:31], s[8:9], 0, v[40:41]
	v_lshl_add_u64 v[30:31], v[30:31], 0, v[126:127]
	v_add_f32_e64 v32, v32, v38
	v_add_f32_e64 v33, v33, v39
	global_load_dwordx2 v[172:173], v[30:31], off
	global_load_dwordx2 v[174:175], v[30:31], off offset:32
	global_load_dwordx2 v[176:177], v[30:31], off offset:256
	global_load_dwordx2 v[178:179], v[30:31], off offset:288
	s_waitcnt vmcnt(3)
	v_mov_b64_e32 v[38:39], v[172:173]
	v_mul_f32_e32 v36, 0xbfb8aa3b, v36
	v_mul_f32_e32 v37, 0xbfb8aa3b, v37
	v_mul_f32_e32 v32, 0xbfb8aa3b, v32
	v_mul_f32_e32 v33, 0xbfb8aa3b, v33
	v_exp_f32_e32 v36, v36
	v_exp_f32_e32 v37, v37
	v_exp_f32_e32 v32, v32
	v_exp_f32_e32 v33, v33
	v_add_f32_e32 v36, 1.0, v36
	v_add_f32_e32 v37, 1.0, v37
	v_add_f32_e32 v32, 1.0, v32
	v_add_f32_e32 v33, 1.0, v33
	v_rcp_f32_e32 v36, v36
	v_rcp_f32_e32 v37, v37
	v_rcp_f32_e32 v32, v32
	v_rcp_f32_e32 v33, v33
	v_lshlrev_b32_e32 v40, 16, v38
	v_and_b32_e32 v38, 0xffff0000, v38
	v_lshlrev_b32_e32 v41, 16, v39
	v_and_b32_e32 v39, 0xffff0000, v39
	v_mul_f32_e32 v36, v36, v40
	v_mul_f32_e32 v37, v37, v38
	v_mul_f32_e32 v32, v32, v41
	v_mul_f32_e32 v33, v33, v39
	v_cvt_pk_bf16_f32 v36, v36, v37
	v_cvt_pk_bf16_f32 v37, v32, v33
	v_lshl_add_u64 v[32:33], s[12:13], 0, v[34:35]
	v_lshl_add_u64 v[32:33], v[32:33], 0, v[126:127]
	global_store_dwordx2 v[32:33], v[36:37], off offset:2048
	s_waitcnt vmcnt(55)
	v_mov_b64_e32 v[34:35], v[160:161]
	v_mov_b64_e32 v[36:37], v[162:163]
	v_add_f32_e64 v26, v26, v34
	v_add_f32_e64 v27, v27, v35
	s_waitcnt vmcnt(3)
	v_mov_b64_e32 v[34:35], v[174:175]
	v_mul_f32_e32 v26, 0xbfb8aa3b, v26
	v_mul_f32_e32 v27, 0xbfb8aa3b, v27
	v_exp_f32_e32 v26, v26
	v_exp_f32_e32 v27, v27
	v_add_f32_e64 v28, v28, v36
	v_add_f32_e64 v29, v29, v37
	v_add_f32_e32 v26, 1.0, v26
	v_add_f32_e32 v27, 1.0, v27
	v_rcp_f32_e32 v26, v26
	v_rcp_f32_e32 v27, v27
	v_lshlrev_b32_e32 v36, 16, v34
	v_and_b32_e32 v34, 0xffff0000, v34
	v_mul_f32_e32 v26, v26, v36
	v_mul_f32_e32 v27, v27, v34
	v_cvt_pk_bf16_f32 v26, v26, v27
	v_mul_f32_e32 v27, 0xbfb8aa3b, v28
	v_exp_f32_e32 v27, v27
	v_mul_f32_e32 v28, 0xbfb8aa3b, v29
	v_exp_f32_e32 v28, v28
	v_lshlrev_b32_e32 v37, 16, v35
	v_add_f32_e32 v27, 1.0, v27
	v_rcp_f32_e32 v27, v27
	v_add_f32_e32 v28, 1.0, v28
	v_rcp_f32_e32 v28, v28
	v_and_b32_e32 v35, 0xffff0000, v35
	v_mul_f32_e32 v27, v27, v37
	v_mul_f32_e32 v28, v28, v35
	v_cvt_pk_bf16_f32 v27, v27, v28
	global_store_dwordx2 v[32:33], v[26:27], off offset:2080
	s_waitcnt vmcnt(55)
	v_mov_b64_e32 v[26:27], v[164:165]
	v_mov_b64_e32 v[28:29], v[166:167]
	v_add_f32_e64 v22, v22, v26
	v_add_f32_e64 v23, v23, v27
	s_waitcnt vmcnt(3)
	v_mov_b64_e32 v[26:27], v[176:177]
	v_mul_f32_e32 v22, 0xbfb8aa3b, v22
	v_mul_f32_e32 v23, 0xbfb8aa3b, v23
	v_exp_f32_e32 v22, v22
	v_exp_f32_e32 v23, v23
	v_add_f32_e64 v24, v24, v28
	v_add_f32_e64 v25, v25, v29
	v_add_f32_e32 v22, 1.0, v22
	v_add_f32_e32 v23, 1.0, v23
	v_rcp_f32_e32 v22, v22
	v_rcp_f32_e32 v23, v23
	v_lshlrev_b32_e32 v28, 16, v26
	v_and_b32_e32 v26, 0xffff0000, v26
	v_mul_f32_e32 v22, v22, v28
	v_mul_f32_e32 v23, v23, v26
	v_cvt_pk_bf16_f32 v22, v22, v23
	v_mul_f32_e32 v23, 0xbfb8aa3b, v24
	v_exp_f32_e32 v23, v23
	v_mul_f32_e32 v24, 0xbfb8aa3b, v25
	v_exp_f32_e32 v24, v24
	v_lshlrev_b32_e32 v29, 16, v27
	v_add_f32_e32 v23, 1.0, v23
	v_rcp_f32_e32 v23, v23
	v_add_f32_e32 v24, 1.0, v24
	v_rcp_f32_e32 v24, v24
	v_and_b32_e32 v27, 0xffff0000, v27
	v_mul_f32_e32 v23, v23, v29
	v_mul_f32_e32 v24, v24, v27
	v_cvt_pk_bf16_f32 v23, v23, v24
	global_store_dwordx2 v[32:33], v[22:23], off offset:2304
	s_waitcnt vmcnt(55)
	v_mov_b64_e32 v[22:23], v[168:169]
	v_mov_b64_e32 v[24:25], v[170:171]
	v_add_f32_e64 v18, v18, v22
	v_add_f32_e64 v19, v19, v23
	s_waitcnt vmcnt(3)
; __device__ __forceinline__ unsigned cvtpk(float lo, float hi) { unsigned r; asm volatile("v_cvt_pk_bf16_f32 %0, %1, %2" : "=v"(r) : "v"(lo), "v"(hi)); return r; }
; __device__ __forceinline__ float sigmoidf_(float x) { return __builtin_amdgcn_rcpf(1.f + __builtin_amdgcn_exp2f(x * -1.4426950408889634f)); }
;   __device__ __forceinline__ void operator()(const Acc& acc, const gm::Unit& u, int wr, int wc, int fr, int fq) const { const int pm = u.pm, pn = u.pn;
;     ...
;     for (int ai = 0; ai < 2; ++ai)
; #pragma unroll
;       for (int m = 0; m < 4; ++m) { const int row = pm * 256 + ai * 128 + wr * 64 + m * 16 + fr;
; #pragma unroll
;         for (int bj = 0; bj < 2; ++bj)
; #pragma unroll
;           for (int n = 0; n < 2; ++n) { const int col = pn * 256 + bj * 128 + wc * 32 + n * 16 + fq * 4; const f32x4 z = acc[ai][bj][m][n] + *(const f32x4*)(bg + col);
;             const u32x2 gw = *(const u32x2*)(Gg + (size_t)row * 512 + col);
;             const float g0 = __uint_as_float(gw[0] << 16), g1 = __uint_as_float(gw[0] & 0xffff0000u), g2 = __uint_as_float(gw[1] << 16), g3 = __uint_as_float(gw[1] & 0xffff0000u);
;             u32x2 w = {cvtpk(g0 * sigmoidf_(z[0]), g1 * sigmoidf_(z[1])), cvtpk(g2 * sigmoidf_(z[2]), g3 * sigmoidf_(z[3]))};
;             *(u32x2*)(Cat + (size_t)row * DM + 1024 + col) = w; } }
	v_mov_b64_e32 v[22:23], v[178:179]
	v_mul_f32_e32 v18, 0xbfb8aa3b, v18
	v_mul_f32_e32 v19, 0xbfb8aa3b, v19
	v_exp_f32_e32 v18, v18
	v_exp_f32_e32 v19, v19
	v_add_f32_e64 v20, v20, v24
	v_add_f32_e64 v21, v21, v25
	v_add_f32_e32 v18, 1.0, v18
	v_add_f32_e32 v19, 1.0, v19
	v_rcp_f32_e32 v18, v18
	v_rcp_f32_e32 v19, v19
	v_lshlrev_b32_e32 v24, 16, v22
	v_and_b32_e32 v22, 0xffff0000, v22
	v_mul_f32_e32 v18, v18, v24
	v_mul_f32_e32 v19, v19, v22
	v_cvt_pk_bf16_f32 v18, v18, v19
	v_mul_f32_e32 v19, 0xbfb8aa3b, v20
	v_exp_f32_e32 v19, v19
	v_mul_f32_e32 v20, 0xbfb8aa3b, v21
	v_exp_f32_e32 v20, v20
	v_lshlrev_b32_e32 v25, 16, v23
	v_add_f32_e32 v19, 1.0, v19
	v_rcp_f32_e32 v19, v19
	v_add_f32_e32 v20, 1.0, v20
	v_rcp_f32_e32 v20, v20
	v_and_b32_e32 v23, 0xffff0000, v23
	v_mul_f32_e32 v19, v19, v25
	v_mul_f32_e32 v20, v20, v23
	v_cvt_pk_bf16_f32 v19, v19, v20
	global_store_dwordx2 v[32:33], v[18:19], off offset:2336
	s_waitcnt vmcnt(59)
	v_mov_b64_e32 v[20:21], v[156:157]
	v_mov_b64_e32 v[22:23], v[158:159]
	v_add_u32_e32 v18, 0xb0, v140
	v_ashrrev_i32_e32 v19, 31, v18
	v_lshlrev_b64 v[24:25], 10, v[18:19]
	v_lshlrev_b64 v[18:19], 12, v[18:19]
	v_add_f32_e64 v20, v14, v20
	v_add_f32_e64 v21, v15, v21
	v_lshl_add_u64 v[14:15], s[8:9], 0, v[24:25]
	v_lshl_add_u64 v[14:15], v[14:15], 0, v[126:127]
	v_add_f32_e64 v16, v16, v22
	v_add_f32_e64 v17, v17, v23
	global_load_dwordx2 v[180:181], v[14:15], off
	global_load_dwordx2 v[182:183], v[14:15], off offset:32
	global_load_dwordx2 v[184:185], v[14:15], off offset:256
	global_load_dwordx2 v[186:187], v[14:15], off offset:288
	s_waitcnt vmcnt(3)
	v_mov_b64_e32 v[22:23], v[180:181]
	v_mul_f32_e32 v20, 0xbfb8aa3b, v20
	v_mul_f32_e32 v21, 0xbfb8aa3b, v21
	v_mul_f32_e32 v16, 0xbfb8aa3b, v16
	v_mul_f32_e32 v17, 0xbfb8aa3b, v17
	v_exp_f32_e32 v20, v20
	v_exp_f32_e32 v21, v21
	v_exp_f32_e32 v16, v16
	v_exp_f32_e32 v17, v17
	v_add_f32_e32 v20, 1.0, v20
	v_add_f32_e32 v21, 1.0, v21
	v_add_f32_e32 v16, 1.0, v16
	v_add_f32_e32 v17, 1.0, v17
	v_rcp_f32_e32 v20, v20
	v_rcp_f32_e32 v21, v21
	v_rcp_f32_e32 v16, v16
	v_rcp_f32_e32 v17, v17
	v_lshlrev_b32_e32 v24, 16, v22
	v_and_b32_e32 v22, 0xffff0000, v22
	v_lshlrev_b32_e32 v25, 16, v23
	v_and_b32_e32 v23, 0xffff0000, v23
	v_mul_f32_e32 v20, v20, v24
	v_mul_f32_e32 v21, v21, v22
	v_mul_f32_e32 v16, v16, v25
	v_mul_f32_e32 v17, v17, v23
	v_cvt_pk_bf16_f32 v20, v20, v21
	v_cvt_pk_bf16_f32 v21, v16, v17
	v_lshl_add_u64 v[16:17], s[12:13], 0, v[18:19]
	v_lshl_add_u64 v[16:17], v[16:17], 0, v[126:127]
	global_store_dwordx2 v[16:17], v[20:21], off offset:2048
	s_waitcnt vmcnt(63)
	v_mov_b64_e32 v[18:19], v[160:161]
	v_mov_b64_e32 v[20:21], v[162:163]
	v_add_f32_e64 v10, v10, v18
	v_add_f32_e64 v11, v11, v19
	s_waitcnt vmcnt(3)
	v_mov_b64_e32 v[18:19], v[182:183]
	v_mul_f32_e32 v10, 0xbfb8aa3b, v10
	v_mul_f32_e32 v11, 0xbfb8aa3b, v11
	v_exp_f32_e32 v10, v10
	v_exp_f32_e32 v11, v11
	v_add_f32_e64 v12, v12, v20
	v_add_f32_e64 v13, v13, v21
	v_add_f32_e32 v10, 1.0, v10
	v_add_f32_e32 v11, 1.0, v11
	v_rcp_f32_e32 v10, v10
	v_rcp_f32_e32 v11, v11
	v_lshlrev_b32_e32 v20, 16, v18
	v_and_b32_e32 v18, 0xffff0000, v18
	v_mul_f32_e32 v10, v10, v20
	v_mul_f32_e32 v11, v11, v18
	v_cvt_pk_bf16_f32 v10, v10, v11
	v_mul_f32_e32 v11, 0xbfb8aa3b, v12
	v_exp_f32_e32 v11, v11
	v_mul_f32_e32 v12, 0xbfb8aa3b, v13
	v_exp_f32_e32 v12, v12
	v_lshlrev_b32_e32 v21, 16, v19
	v_add_f32_e32 v11, 1.0, v11
	v_rcp_f32_e32 v11, v11
	v_add_f32_e32 v12, 1.0, v12
	v_rcp_f32_e32 v12, v12
	v_and_b32_e32 v19, 0xffff0000, v19
	v_mul_f32_e32 v11, v11, v21
	v_mul_f32_e32 v12, v12, v19
	v_cvt_pk_bf16_f32 v11, v11, v12
	global_store_dwordx2 v[16:17], v[10:11], off offset:2080
	s_waitcnt vmcnt(63)
	v_mov_b64_e32 v[10:11], v[164:165]
	v_mov_b64_e32 v[12:13], v[166:167]
	v_add_f32_e64 v6, v6, v10
	v_add_f32_e64 v7, v7, v11
	s_waitcnt vmcnt(3)
	v_mov_b64_e32 v[10:11], v[184:185]
	v_mul_f32_e32 v6, 0xbfb8aa3b, v6
	v_mul_f32_e32 v7, 0xbfb8aa3b, v7
	v_exp_f32_e32 v6, v6
	v_exp_f32_e32 v7, v7
	v_add_f32_e64 v8, v8, v12
	v_add_f32_e64 v9, v9, v13
	v_add_f32_e32 v6, 1.0, v6
	v_add_f32_e32 v7, 1.0, v7
	v_rcp_f32_e32 v6, v6
	v_rcp_f32_e32 v7, v7
	v_lshlrev_b32_e32 v12, 16, v10
	v_and_b32_e32 v10, 0xffff0000, v10
	v_mul_f32_e32 v6, v6, v12
	v_mul_f32_e32 v7, v7, v10
	v_cvt_pk_bf16_f32 v6, v6, v7
	v_mul_f32_e32 v7, 0xbfb8aa3b, v8
	v_exp_f32_e32 v7, v7
	v_mul_f32_e32 v8, 0xbfb8aa3b, v9
	v_exp_f32_e32 v8, v8
	v_lshlrev_b32_e32 v13, 16, v11
	v_add_f32_e32 v7, 1.0, v7
	v_rcp_f32_e32 v7, v7
	v_add_f32_e32 v8, 1.0, v8
	v_rcp_f32_e32 v8, v8
	v_and_b32_e32 v11, 0xffff0000, v11
	v_mul_f32_e32 v7, v7, v13
	v_mul_f32_e32 v8, v8, v11
	v_cvt_pk_bf16_f32 v7, v7, v8
	global_store_dwordx2 v[16:17], v[6:7], off offset:2304
	s_waitcnt vmcnt(63)
	v_mov_b64_e32 v[6:7], v[168:169]
	v_mov_b64_e32 v[8:9], v[170:171]
	v_add_f32_e64 v2, v2, v6
	v_add_f32_e64 v3, v3, v7
	s_waitcnt vmcnt(3)
	v_mov_b64_e32 v[6:7], v[186:187]
	v_mul_f32_e32 v2, 0xbfb8aa3b, v2
	v_mul_f32_e32 v3, 0xbfb8aa3b, v3
	v_exp_f32_e32 v2, v2
	v_exp_f32_e32 v3, v3
	v_add_f32_e64 v4, v4, v8
	v_add_f32_e64 v5, v5, v9
	v_add_f32_e32 v2, 1.0, v2
	v_add_f32_e32 v3, 1.0, v3
	v_rcp_f32_e32 v2, v2
	v_rcp_f32_e32 v3, v3
	v_lshlrev_b32_e32 v8, 16, v6
	v_and_b32_e32 v6, 0xffff0000, v6
	v_mul_f32_e32 v2, v2, v8
	v_mul_f32_e32 v3, v3, v6
	v_cvt_pk_bf16_f32 v2, v2, v3
	v_mul_f32_e32 v3, 0xbfb8aa3b, v4
	v_exp_f32_e32 v3, v3
	v_mul_f32_e32 v4, 0xbfb8aa3b, v5
	v_exp_f32_e32 v4, v4
	v_lshlrev_b32_e32 v9, 16, v7
	v_add_f32_e32 v3, 1.0, v3
	v_rcp_f32_e32 v3, v3
	v_add_f32_e32 v4, 1.0, v4
	v_rcp_f32_e32 v4, v4
	v_and_b32_e32 v7, 0xffff0000, v7
	v_mul_f32_e32 v3, v3, v9
	v_mul_f32_e32 v4, v4, v7
	v_cvt_pk_bf16_f32 v3, v3, v4
	global_store_dwordx2 v[16:17], v[2:3], off offset:2336
	s_cbranch_vccnz .LBB0_786
	s_andn2_b64 vcc, exec, s[10:11]
	s_cbranch_vccnz .LBB0_785
	s_barrier
	s_branch .LBB0_785

.LBB0_812:
	s_lshl_b32 s29, s29, 8
	s_and_b32 s29, s29, 0x100
	s_mul_hi_i32 s30, s34, 0x1100
	s_mulk_i32 s34, 0x1100
	s_add_u32 s66, s34, s66
	s_addc_u32 s67, s30, s67
	s_lshl_b32 s30, s29, 1
	s_lshl_b32 s29, s29, 2
	v_lshlrev_b32_e32 v150, 2, v138
	s_add_u32 s42, s25, s29
	v_ashrrev_i32_e32 v151, 31, v150
	s_addc_u32 s43, s27, 0
	v_lshl_add_u64 v[138:139], v[150:151], 2, s[42:43]
	global_load_dwordx4 v[156:159], v[138:139], off
	global_load_dwordx4 v[160:163], v[138:139], off offset:64
	global_load_dwordx4 v[164:167], v[138:139], off offset:512
	global_load_dwordx4 v[168:171], v[138:139], off offset:576
	s_waitcnt vmcnt(3)
	v_mov_b64_e32 v[146:147], v[156:157]
	v_mov_b64_e32 v[148:149], v[158:159]
	v_add_u32_e32 v140, s19, v140
	v_mul_lo_u32 v152, s33, v140
	v_ashrrev_i32_e32 v153, 31, v152
	v_lshlrev_b64 v[140:141], 1, v[150:151]
	v_lshl_add_u64 v[150:151], s[66:67], 0, v[152:153]
	v_lshlrev_b64 v[150:151], 12, v[150:151]
	v_lshl_add_u64 v[150:151], s[54:55], 0, v[150:151]
	s_mov_b32 s61, s31
	v_lshl_add_u64 v[150:151], v[150:151], 0, s[30:31]
	v_lshl_add_u64 v[150:151], v[150:151], 0, s[60:61]
	v_lshl_add_u64 v[150:151], v[150:151], 0, v[140:141]
	s_lshl_b32 s29, s33, 4
	s_mulk_i32 s33, 0x50
	s_andn2_b64 vcc, exec, s[64:65]
	s_mov_b64 s[64:65], -1
	v_add_f32_e64 v126, v126, v146
	v_add_f32_e64 v127, v127, v147
	v_add_f32_e64 v128, v128, v148
	v_add_f32_e64 v129, v129, v149
	v_cvt_pk_bf16_f32 v126, v126, v127
	s_nop 0
	v_cvt_pk_bf16_f32 v127, v128, v129
	global_store_dwordx2 v[150:151], v[126:127], off offset:3072
	s_waitcnt vmcnt(3)
	v_mov_b64_e32 v[126:127], v[160:161]
	v_mov_b64_e32 v[128:129], v[162:163]
	v_add_f32_e64 v122, v122, v126
	v_add_f32_e64 v123, v123, v127
	v_add_f32_e64 v124, v124, v128
	v_add_f32_e64 v125, v125, v129
	v_cvt_pk_bf16_f32 v122, v122, v123
	s_nop 0
	v_cvt_pk_bf16_f32 v123, v124, v125
	global_store_dwordx2 v[150:151], v[122:123], off offset:3104
	s_waitcnt vmcnt(3)
	v_mov_b64_e32 v[122:123], v[164:165]
	v_mov_b64_e32 v[124:125], v[166:167]
	v_add_f32_e64 v118, v118, v122
	v_add_f32_e64 v119, v119, v123
	v_add_f32_e64 v120, v120, v124
	v_add_f32_e64 v121, v121, v125
	v_cvt_pk_bf16_f32 v118, v118, v119
	s_nop 0
	v_cvt_pk_bf16_f32 v119, v120, v121
	global_store_dwordx2 v[150:151], v[118:119], off offset:3328
	s_waitcnt vmcnt(3)
	v_mov_b64_e32 v[118:119], v[168:169]
	v_mov_b64_e32 v[120:121], v[170:171]
	v_add_f32_e64 v114, v114, v118
	v_add_f32_e64 v115, v115, v119
	v_add_f32_e64 v116, v116, v120
	v_add_f32_e64 v117, v117, v121
	v_cvt_pk_bf16_f32 v114, v114, v115
	v_add_u32_e32 v118, s29, v152
	v_cvt_pk_bf16_f32 v115, v116, v117
	global_store_dwordx2 v[150:151], v[114:115], off offset:3360
	s_waitcnt vmcnt(7)
	v_mov_b64_e32 v[114:115], v[156:157]
	v_mov_b64_e32 v[116:117], v[158:159]
	v_ashrrev_i32_e32 v119, 31, v118
	v_lshl_add_u64 v[120:121], s[66:67], 0, v[118:119]
	v_lshlrev_b64 v[120:121], 12, v[120:121]
	v_lshl_add_u64 v[120:121], s[54:55], 0, v[120:121]
	v_lshl_add_u64 v[120:121], v[120:121], 0, s[30:31]
	v_lshl_add_u64 v[120:121], v[120:121], 0, s[60:61]
	v_lshl_add_u64 v[120:121], v[120:121], 0, v[140:141]
	v_add_f32_e64 v110, v110, v114
	v_add_f32_e64 v111, v111, v115
	v_add_f32_e64 v112, v112, v116
	v_add_f32_e64 v113, v113, v117
	v_cvt_pk_bf16_f32 v110, v110, v111
	s_nop 0
	v_cvt_pk_bf16_f32 v111, v112, v113
	global_store_dwordx2 v[120:121], v[110:111], off offset:3072
	s_waitcnt vmcnt(7)
	v_mov_b64_e32 v[110:111], v[160:161]
	v_mov_b64_e32 v[112:113], v[162:163]
	v_add_f32_e64 v106, v106, v110
	v_add_f32_e64 v107, v107, v111
	v_add_f32_e64 v108, v108, v112
	v_add_f32_e64 v109, v109, v113
	v_cvt_pk_bf16_f32 v106, v106, v107
	s_nop 0
	v_cvt_pk_bf16_f32 v107, v108, v109
	global_store_dwordx2 v[120:121], v[106:107], off offset:3104
	s_waitcnt vmcnt(7)
	v_mov_b64_e32 v[106:107], v[164:165]
	v_mov_b64_e32 v[108:109], v[166:167]
	v_add_f32_e64 v102, v102, v106
	v_add_f32_e64 v103, v103, v107
	v_add_f32_e64 v104, v104, v108
	v_add_f32_e64 v105, v105, v109
	v_cvt_pk_bf16_f32 v102, v102, v103
	s_nop 0
	v_cvt_pk_bf16_f32 v103, v104, v105
	global_store_dwordx2 v[120:121], v[102:103], off offset:3328
	s_waitcnt vmcnt(7)
	v_mov_b64_e32 v[102:103], v[168:169]
	v_mov_b64_e32 v[104:105], v[170:171]
	v_add_f32_e64 v98, v98, v102
	v_add_f32_e64 v99, v99, v103
	v_add_f32_e64 v100, v100, v104
	v_add_f32_e64 v101, v101, v105
	v_cvt_pk_bf16_f32 v98, v98, v99
	v_add_u32_e32 v102, s29, v118
	v_cvt_pk_bf16_f32 v99, v100, v101
	global_store_dwordx2 v[120:121], v[98:99], off offset:3360
	s_waitcnt vmcnt(11)
	v_mov_b64_e32 v[98:99], v[156:157]
	v_mov_b64_e32 v[100:101], v[158:159]
	v_ashrrev_i32_e32 v103, 31, v102
	v_lshl_add_u64 v[104:105], s[66:67], 0, v[102:103]
	v_lshlrev_b64 v[104:105], 12, v[104:105]
	v_lshl_add_u64 v[104:105], s[54:55], 0, v[104:105]
	v_lshl_add_u64 v[104:105], v[104:105], 0, s[30:31]
	v_lshl_add_u64 v[104:105], v[104:105], 0, s[60:61]
	v_lshl_add_u64 v[104:105], v[104:105], 0, v[140:141]
	v_add_f32_e64 v94, v94, v98
	v_add_f32_e64 v95, v95, v99
	v_add_f32_e64 v96, v96, v100
	v_add_f32_e64 v97, v97, v101
	v_cvt_pk_bf16_f32 v94, v94, v95
	s_nop 0
	v_cvt_pk_bf16_f32 v95, v96, v97
	global_store_dwordx2 v[104:105], v[94:95], off offset:3072
	s_waitcnt vmcnt(11)
	v_mov_b64_e32 v[94:95], v[160:161]
	v_mov_b64_e32 v[96:97], v[162:163]
	v_add_f32_e64 v90, v90, v94
	v_add_f32_e64 v91, v91, v95
	v_add_f32_e64 v92, v92, v96
	v_add_f32_e64 v93, v93, v97
	v_cvt_pk_bf16_f32 v90, v90, v91
	s_nop 0
	v_cvt_pk_bf16_f32 v91, v92, v93
	global_store_dwordx2 v[104:105], v[90:91], off offset:3104
	s_waitcnt vmcnt(11)
	v_mov_b64_e32 v[90:91], v[164:165]
	v_mov_b64_e32 v[92:93], v[166:167]
	v_add_f32_e64 v86, v86, v90
	v_add_f32_e64 v87, v87, v91
	v_add_f32_e64 v88, v88, v92
	v_add_f32_e64 v89, v89, v93
	v_cvt_pk_bf16_f32 v86, v86, v87
	s_nop 0
	v_cvt_pk_bf16_f32 v87, v88, v89
	global_store_dwordx2 v[104:105], v[86:87], off offset:3328
	s_waitcnt vmcnt(11)
	v_mov_b64_e32 v[86:87], v[168:169]
	v_mov_b64_e32 v[88:89], v[170:171]
	v_add_f32_e64 v82, v82, v86
	v_add_f32_e64 v83, v83, v87
	v_add_f32_e64 v84, v84, v88
	v_add_f32_e64 v85, v85, v89
	v_cvt_pk_bf16_f32 v82, v82, v83
	v_add_u32_e32 v86, s29, v102
	v_cvt_pk_bf16_f32 v83, v84, v85
	global_store_dwordx2 v[104:105], v[82:83], off offset:3360
	s_waitcnt vmcnt(15)
	v_mov_b64_e32 v[82:83], v[156:157]
	v_mov_b64_e32 v[84:85], v[158:159]
	v_ashrrev_i32_e32 v87, 31, v86
	v_lshl_add_u64 v[88:89], s[66:67], 0, v[86:87]
	v_lshlrev_b64 v[88:89], 12, v[88:89]
	v_lshl_add_u64 v[88:89], s[54:55], 0, v[88:89]
	v_lshl_add_u64 v[88:89], v[88:89], 0, s[30:31]
	v_lshl_add_u64 v[88:89], v[88:89], 0, s[60:61]
	v_lshl_add_u64 v[88:89], v[88:89], 0, v[140:141]
	v_add_f32_e64 v78, v78, v82
	v_add_f32_e64 v79, v79, v83
	v_add_f32_e64 v80, v80, v84
	v_add_f32_e64 v81, v81, v85
	v_cvt_pk_bf16_f32 v78, v78, v79
	s_nop 0
	v_cvt_pk_bf16_f32 v79, v80, v81
	global_store_dwordx2 v[88:89], v[78:79], off offset:3072
	s_waitcnt vmcnt(15)
	v_mov_b64_e32 v[78:79], v[160:161]
	v_mov_b64_e32 v[80:81], v[162:163]
	v_add_f32_e64 v74, v74, v78
	v_add_f32_e64 v75, v75, v79
	v_add_f32_e64 v76, v76, v80
	v_add_f32_e64 v77, v77, v81
	v_cvt_pk_bf16_f32 v74, v74, v75
	s_nop 0
	v_cvt_pk_bf16_f32 v75, v76, v77
	global_store_dwordx2 v[88:89], v[74:75], off offset:3104
	s_waitcnt vmcnt(15)
	v_mov_b64_e32 v[74:75], v[164:165]
	v_mov_b64_e32 v[76:77], v[166:167]
	v_add_f32_e64 v70, v70, v74
	v_add_f32_e64 v71, v71, v75
	v_add_f32_e64 v72, v72, v76
	v_add_f32_e64 v73, v73, v77
	v_cvt_pk_bf16_f32 v70, v70, v71
	s_nop 0
	v_cvt_pk_bf16_f32 v71, v72, v73
	global_store_dwordx2 v[88:89], v[70:71], off offset:3328
	s_waitcnt vmcnt(15)
	v_mov_b64_e32 v[70:71], v[168:169]
	v_mov_b64_e32 v[72:73], v[170:171]
	v_add_f32_e64 v66, v66, v70
	v_add_f32_e64 v67, v67, v71
	v_add_f32_e64 v68, v68, v72
	v_add_f32_e64 v69, v69, v73
	v_cvt_pk_bf16_f32 v66, v66, v67
	v_add_u32_e32 v70, s33, v86
	v_cvt_pk_bf16_f32 v67, v68, v69
	global_store_dwordx2 v[88:89], v[66:67], off offset:3360
	s_waitcnt vmcnt(19)
	v_mov_b64_e32 v[66:67], v[156:157]
	v_mov_b64_e32 v[68:69], v[158:159]
	v_ashrrev_i32_e32 v71, 31, v70
	v_lshl_add_u64 v[72:73], s[66:67], 0, v[70:71]
	v_lshlrev_b64 v[72:73], 12, v[72:73]
	v_lshl_add_u64 v[72:73], s[54:55], 0, v[72:73]
	v_lshl_add_u64 v[72:73], v[72:73], 0, s[30:31]
	v_lshl_add_u64 v[72:73], v[72:73], 0, s[60:61]
	v_lshl_add_u64 v[72:73], v[72:73], 0, v[140:141]
	v_add_f32_e64 v62, v62, v66
	v_add_f32_e64 v63, v63, v67
	v_add_f32_e64 v64, v64, v68
	v_add_f32_e64 v65, v65, v69
	v_cvt_pk_bf16_f32 v62, v62, v63
	s_nop 0
	v_cvt_pk_bf16_f32 v63, v64, v65
	global_store_dwordx2 v[72:73], v[62:63], off offset:3072
	s_waitcnt vmcnt(19)
	v_mov_b64_e32 v[62:63], v[160:161]
	v_mov_b64_e32 v[64:65], v[162:163]
	v_add_f32_e64 v58, v58, v62
	v_add_f32_e64 v59, v59, v63
	v_add_f32_e64 v60, v60, v64
	v_add_f32_e64 v61, v61, v65
	v_cvt_pk_bf16_f32 v58, v58, v59
	s_nop 0
	v_cvt_pk_bf16_f32 v59, v60, v61
	global_store_dwordx2 v[72:73], v[58:59], off offset:3104
	s_waitcnt vmcnt(19)
	v_mov_b64_e32 v[58:59], v[164:165]
	v_mov_b64_e32 v[60:61], v[166:167]
	v_add_f32_e64 v54, v54, v58
	v_add_f32_e64 v55, v55, v59
	v_add_f32_e64 v56, v56, v60
	v_add_f32_e64 v57, v57, v61
	v_cvt_pk_bf16_f32 v54, v54, v55
	s_nop 0
	v_cvt_pk_bf16_f32 v55, v56, v57
	global_store_dwordx2 v[72:73], v[54:55], off offset:3328
	s_waitcnt vmcnt(19)
	v_mov_b64_e32 v[54:55], v[168:169]
	v_mov_b64_e32 v[56:57], v[170:171]
	v_add_f32_e64 v50, v50, v54
	v_add_f32_e64 v51, v51, v55
	v_add_f32_e64 v52, v52, v56
	v_add_f32_e64 v53, v53, v57
	v_cvt_pk_bf16_f32 v50, v50, v51
	v_add_u32_e32 v54, s29, v70
	v_cvt_pk_bf16_f32 v51, v52, v53
	global_store_dwordx2 v[72:73], v[50:51], off offset:3360
	s_waitcnt vmcnt(23)
	v_mov_b64_e32 v[50:51], v[156:157]
	v_mov_b64_e32 v[52:53], v[158:159]
	v_ashrrev_i32_e32 v55, 31, v54
	v_lshl_add_u64 v[56:57], s[66:67], 0, v[54:55]
	v_lshlrev_b64 v[56:57], 12, v[56:57]
	v_lshl_add_u64 v[56:57], s[54:55], 0, v[56:57]
	v_lshl_add_u64 v[56:57], v[56:57], 0, s[30:31]
	v_lshl_add_u64 v[56:57], v[56:57], 0, s[60:61]
	v_lshl_add_u64 v[56:57], v[56:57], 0, v[140:141]
	v_add_f32_e64 v46, v46, v50
	v_add_f32_e64 v47, v47, v51
	v_add_f32_e64 v48, v48, v52
	v_add_f32_e64 v49, v49, v53
	v_cvt_pk_bf16_f32 v46, v46, v47
	s_nop 0
	v_cvt_pk_bf16_f32 v47, v48, v49
	global_store_dwordx2 v[56:57], v[46:47], off offset:3072
	s_waitcnt vmcnt(23)
	v_mov_b64_e32 v[46:47], v[160:161]
	v_mov_b64_e32 v[48:49], v[162:163]
	v_add_f32_e64 v42, v42, v46
	v_add_f32_e64 v43, v43, v47
	v_add_f32_e64 v44, v44, v48
	v_add_f32_e64 v45, v45, v49
	v_cvt_pk_bf16_f32 v42, v42, v43
	s_nop 0
	v_cvt_pk_bf16_f32 v43, v44, v45
	global_store_dwordx2 v[56:57], v[42:43], off offset:3104
	s_waitcnt vmcnt(23)
	v_mov_b64_e32 v[42:43], v[164:165]
	v_mov_b64_e32 v[44:45], v[166:167]
	v_add_f32_e64 v38, v38, v42
	v_add_f32_e64 v39, v39, v43
	v_add_f32_e64 v40, v40, v44
	v_add_f32_e64 v41, v41, v45
	v_cvt_pk_bf16_f32 v38, v38, v39
	s_nop 0
	v_cvt_pk_bf16_f32 v39, v40, v41
	global_store_dwordx2 v[56:57], v[38:39], off offset:3328
	s_waitcnt vmcnt(23)
	v_mov_b64_e32 v[38:39], v[168:169]
	v_mov_b64_e32 v[40:41], v[170:171]
	v_add_f32_e64 v34, v34, v38
	v_add_f32_e64 v35, v35, v39
	v_add_f32_e64 v36, v36, v40
	v_add_f32_e64 v37, v37, v41
	v_cvt_pk_bf16_f32 v34, v34, v35
	v_add_u32_e32 v38, s29, v54
	v_cvt_pk_bf16_f32 v35, v36, v37
	global_store_dwordx2 v[56:57], v[34:35], off offset:3360
	s_waitcnt vmcnt(27)
	v_mov_b64_e32 v[34:35], v[156:157]
	v_mov_b64_e32 v[36:37], v[158:159]
	v_ashrrev_i32_e32 v39, 31, v38
	v_lshl_add_u64 v[40:41], s[66:67], 0, v[38:39]
	v_lshlrev_b64 v[40:41], 12, v[40:41]
	v_lshl_add_u64 v[40:41], s[54:55], 0, v[40:41]
	v_lshl_add_u64 v[40:41], v[40:41], 0, s[30:31]
	v_lshl_add_u64 v[40:41], v[40:41], 0, s[60:61]
	v_lshl_add_u64 v[40:41], v[40:41], 0, v[140:141]
	v_add_f32_e64 v30, v30, v34
	v_add_f32_e64 v31, v31, v35
	v_add_f32_e64 v32, v32, v36
	v_add_f32_e64 v33, v33, v37
	v_cvt_pk_bf16_f32 v30, v30, v31
	s_nop 0
	v_cvt_pk_bf16_f32 v31, v32, v33
	global_store_dwordx2 v[40:41], v[30:31], off offset:3072
	s_waitcnt vmcnt(27)
	v_mov_b64_e32 v[30:31], v[160:161]
	v_mov_b64_e32 v[32:33], v[162:163]
	v_add_f32_e64 v26, v26, v30
	v_add_f32_e64 v27, v27, v31
	v_add_f32_e64 v28, v28, v32
	v_add_f32_e64 v29, v29, v33
	v_cvt_pk_bf16_f32 v26, v26, v27
	s_nop 0
	v_cvt_pk_bf16_f32 v27, v28, v29
	global_store_dwordx2 v[40:41], v[26:27], off offset:3104
	s_waitcnt vmcnt(27)
	v_mov_b64_e32 v[26:27], v[164:165]
	v_mov_b64_e32 v[28:29], v[166:167]
	v_add_f32_e64 v22, v22, v26
	v_add_f32_e64 v23, v23, v27
	v_add_f32_e64 v24, v24, v28
	v_add_f32_e64 v25, v25, v29
	v_cvt_pk_bf16_f32 v22, v22, v23
	s_nop 0
	v_cvt_pk_bf16_f32 v23, v24, v25
	global_store_dwordx2 v[40:41], v[22:23], off offset:3328
	s_waitcnt vmcnt(27)
	v_mov_b64_e32 v[22:23], v[168:169]
	v_mov_b64_e32 v[24:25], v[170:171]
	v_add_f32_e64 v18, v18, v22
	v_add_f32_e64 v19, v19, v23
	v_add_f32_e64 v20, v20, v24
	v_add_f32_e64 v21, v21, v25
	v_cvt_pk_bf16_f32 v18, v18, v19
	v_add_u32_e32 v22, s29, v38
	v_cvt_pk_bf16_f32 v19, v20, v21
	global_store_dwordx2 v[40:41], v[18:19], off offset:3360
	s_waitcnt vmcnt(31)
	v_mov_b64_e32 v[18:19], v[156:157]
	v_mov_b64_e32 v[20:21], v[158:159]
	v_ashrrev_i32_e32 v23, 31, v22
	v_lshl_add_u64 v[22:23], s[66:67], 0, v[22:23]
	v_lshlrev_b64 v[22:23], 12, v[22:23]
	v_lshl_add_u64 v[22:23], s[54:55], 0, v[22:23]
	v_lshl_add_u64 v[22:23], v[22:23], 0, s[30:31]
	v_lshl_add_u64 v[22:23], v[22:23], 0, s[60:61]
	v_lshl_add_u64 v[22:23], v[22:23], 0, v[140:141]
	v_add_f32_e64 v14, v14, v18
	v_add_f32_e64 v15, v15, v19
	v_add_f32_e64 v16, v16, v20
	v_add_f32_e64 v17, v17, v21
	v_cvt_pk_bf16_f32 v14, v14, v15
	s_nop 0
	v_cvt_pk_bf16_f32 v15, v16, v17
	global_store_dwordx2 v[22:23], v[14:15], off offset:3072
	s_waitcnt vmcnt(31)
	v_mov_b64_e32 v[14:15], v[160:161]
	v_mov_b64_e32 v[16:17], v[162:163]
	v_add_f32_e64 v10, v10, v14
	v_add_f32_e64 v11, v11, v15
	v_add_f32_e64 v12, v12, v16
	v_add_f32_e64 v13, v13, v17
	v_cvt_pk_bf16_f32 v10, v10, v11
	s_nop 0
	v_cvt_pk_bf16_f32 v11, v12, v13
	global_store_dwordx2 v[22:23], v[10:11], off offset:3104
	s_waitcnt vmcnt(31)
	v_mov_b64_e32 v[10:11], v[164:165]
	v_mov_b64_e32 v[12:13], v[166:167]
	v_add_f32_e64 v6, v6, v10
	v_add_f32_e64 v7, v7, v11
	v_add_f32_e64 v8, v8, v12
	v_add_f32_e64 v9, v9, v13
	v_cvt_pk_bf16_f32 v6, v6, v7
	s_nop 0
	v_cvt_pk_bf16_f32 v7, v8, v9
	global_store_dwordx2 v[22:23], v[6:7], off offset:3328
	s_waitcnt vmcnt(31)
	v_mov_b64_e32 v[6:7], v[168:169]
	v_mov_b64_e32 v[8:9], v[170:171]
	v_add_f32_e64 v2, v2, v6
	v_add_f32_e64 v3, v3, v7
	v_add_f32_e64 v4, v4, v8
	v_add_f32_e64 v5, v5, v9
	v_cvt_pk_bf16_f32 v2, v2, v3
	s_nop 0
	v_cvt_pk_bf16_f32 v3, v4, v5
	global_store_dwordx2 v[22:23], v[2:3], off offset:3360
	s_cbranch_vccnz .LBB0_803
	s_andn2_b64 vcc, exec, s[14:15]
	s_cbranch_vccnz .LBB0_802
	s_barrier
	s_branch .LBB0_802

; __device__ __forceinline__ void ssm_build_mef(const Params& p, const Ctx& c, int l) {
;     ...
;   for (long i = c.gtid; i < 32L * 2 * 32 * 256; i += c.nthr) { const int hp = (int)(i & 15), h = (int)((i >> 4) & 15), j = (int)((i >> 8) & 31), gd = (int)(i >> 13), d = gd & 1, g = gd >> 1;
;     const size_t ci = ((size_t)((l * 2 + d) * 32 + g) * 16 + h) * 64; const float2* pw = PW + ((size_t)gd * 33 + j) * 64; const float2* bb = BB + (size_t)gd * 64 * 16 + hp; float a = 0.f;
;     for (int pp = 0; pp < 64; ++pp) { const float cr = p.ssm_c_re[ci + pp], cim = p.ssm_c_im[ci + pp]; const float2 b = bb[pp * 16], w = pw[pp];
;       const float wr = cr * b.x - cim * b.y, wi = cr * b.y + cim * b.x; a += wr * w.x - wi * w.y; }
;     MK[i] = a; }
.LBB0_967:
	v_lshl_add_u64 v[16:17], v[14:15], 0, s[62:63]
	global_load_dwordx4 v[22:25], v[16:17], off
	v_lshl_add_u64 v[16:17], v[12:13], 0, s[62:63]
	global_load_dwordx4 v[26:29], v[16:17], off
	v_lshl_add_u64 v[16:17], s[54:55], 0, v[8:9]
	v_add_co_u32_e32 v16, vcc, 0xac4c000, v16
	v_lshl_add_u64 v[30:31], s[54:55], 0, v[10:11]
	s_nop 0
	v_addc_co_u32_e32 v17, vcc, 0, v17, vcc
	global_load_dwordx2 v[38:39], v[16:17], off
	global_load_dwordx2 v[60:61], v[16:17], off offset:128
	global_load_dwordx2 v[62:63], v[16:17], off offset:256
	global_load_dwordx2 v[64:65], v[16:17], off offset:384
	s_mov_b64 s[0:1], 0xaac4000
	v_lshl_add_u64 v[34:35], v[30:31], 0, s[0:1]
	v_add_co_u32_e32 v30, vcc, 0xaac4000, v30
	s_add_u32 s62, s62, 16
	s_nop 0
	v_addc_co_u32_e32 v31, vcc, 0, v31, vcc
	global_load_dwordx4 v[30:33], v[30:31], off
	s_nop 0
	global_load_dwordx4 v[34:37], v[34:35], off offset:16
	s_mov_b64 s[0:1], 0x200
	s_addc_u32 s63, s63, 0
	v_lshl_add_u64 v[8:9], v[8:9], 0, s[0:1]
	v_lshl_add_u64 v[10:11], v[10:11], 0, 32
	s_cmpk_eq_i32 s62, 0x100
	v_lshl_add_u64 v[86:87], v[14:15], 0, s[62:63]
	global_load_dwordx4 v[92:95], v[86:87], off
	v_lshl_add_u64 v[86:87], v[12:13], 0, s[62:63]
	global_load_dwordx4 v[96:99], v[86:87], off
	v_lshl_add_u64 v[86:87], s[54:55], 0, v[8:9]
	v_add_co_u32_e32 v86, vcc, 0xac4c000, v86
	v_lshl_add_u64 v[100:101], s[54:55], 0, v[10:11]
	s_nop 0
	v_addc_co_u32_e32 v87, vcc, 0, v87, vcc
	global_load_dwordx2 v[108:109], v[86:87], off
	global_load_dwordx2 v[130:131], v[86:87], off offset:128
	global_load_dwordx2 v[132:133], v[86:87], off offset:256
	global_load_dwordx2 v[134:135], v[86:87], off offset:384
	s_mov_b64 s[0:1], 0xaac4000
	v_lshl_add_u64 v[104:105], v[100:101], 0, s[0:1]
	v_add_co_u32_e32 v100, vcc, 0xaac4000, v100
	s_add_u32 s62, s62, 16
	s_nop 0
	v_addc_co_u32_e32 v101, vcc, 0, v101, vcc
	global_load_dwordx4 v[100:103], v[100:101], off
	s_nop 0
	global_load_dwordx4 v[104:107], v[104:105], off offset:16
	s_mov_b64 s[0:1], 0x200
	s_addc_u32 s63, s63, 0
	v_lshl_add_u64 v[8:9], v[8:9], 0, s[0:1]
	v_lshl_add_u64 v[10:11], v[10:11], 0, 32
	s_cmpk_eq_i32 s62, 0x100
	s_waitcnt vmcnt(13)
	v_mul_f32_e64 v40, v26, v39
	v_mul_f32_e64 v41, v26, v38
	v_fma_f32 v42, v22, v38, -v40
	v_fma_f32 v43, v23, v39, -v41
	v_fma_f32 v38, v22, v38, v40
	v_fma_f32 v39, v22, v39, v41
	v_mov_b32_e32 v43, v39
	v_mov_b32_e32 v38, v23
	s_waitcnt vmcnt(9)
	v_mul_f32_e64 v30, v30, v42
	v_mul_f32_e64 v31, v31, v43
	s_nop 0
	v_sub_f32_e32 v30, v30, v31
	v_add_f32_e32 v1, v1, v30
	s_waitcnt vmcnt(8)
	v_mov_b64_e32 v[30:31], v[60:61]
	v_mul_f32_e64 v26, v27, v31
	v_mul_f32_e64 v27, v27, v30
	s_nop 0
	v_fma_f32 v38, v38, v30, -v26
	v_fma_f32 v39, v39, v31, -v27
	v_fma_f32 v22, v23, v30, v26
	v_fma_f32 v23, v23, v31, v27
	s_nop 0
	v_mov_b32_e32 v39, v23
	v_mul_f32_e64 v22, v32, v38
	v_mul_f32_e64 v23, v33, v39
	s_nop 0
	v_sub_f32_e32 v22, v22, v23
	v_add_f32_e32 v1, v1, v22
	s_waitcnt vmcnt(8)
	v_mov_b64_e32 v[22:23], v[62:63]
	v_mul_f32_e64 v26, v28, v23
	v_mul_f32_e64 v27, v28, v22
	v_mov_b64_e32 v[16:17], v[64:65]
	v_fma_f32 v30, v24, v22, -v26
	v_fma_f32 v31, v25, v23, -v27
	v_fma_f32 v22, v24, v22, v26
	v_fma_f32 v23, v24, v23, v27
	v_mov_b32_e32 v31, v23
	v_mul_f32_e64 v22, v34, v30
	v_mul_f32_e64 v23, v35, v31
	v_mov_b32_e32 v26, v29
	v_sub_f32_e32 v22, v22, v23
	v_add_f32_e32 v1, v1, v22
	v_mov_b32_e32 v22, v25
	v_mov_b32_e32 v24, v25
	s_waitcnt vmcnt(8)
	v_mul_f32_e64 v27, v26, v16
	v_mul_f32_e64 v26, v26, v17
	v_fma_f32 v22, v22, v16, -v26
	v_fma_f32 v23, v23, v17, -v27
	v_fma_f32 v16, v24, v16, v26
	v_fma_f32 v17, v24, v17, v27
	v_mov_b32_e32 v23, v17
	v_mul_f32_e64 v16, v36, v22
	v_mul_f32_e64 v17, v37, v23
	s_nop 0
	v_sub_f32_e32 v16, v16, v17
	v_add_f32_e32 v1, v1, v16
	s_waitcnt vmcnt(5)
	v_mul_f32_e64 v110, v96, v109
	v_mul_f32_e64 v111, v96, v108
	v_fma_f32 v112, v92, v108, -v110
	v_fma_f32 v113, v93, v109, -v111
	v_fma_f32 v108, v92, v108, v110
	v_fma_f32 v109, v92, v109, v111
	v_mov_b32_e32 v113, v109
	v_mov_b32_e32 v108, v93
	s_waitcnt vmcnt(1)
	v_mul_f32_e64 v100, v100, v112
	v_mul_f32_e64 v101, v101, v113
	s_nop 0
	v_sub_f32_e32 v100, v100, v101
	v_add_f32_e32 v1, v1, v100
	s_waitcnt vmcnt(0)
	v_mov_b64_e32 v[100:101], v[130:131]
	v_mul_f32_e64 v96, v97, v101
	v_mul_f32_e64 v97, v97, v100
	s_nop 0
	v_fma_f32 v108, v108, v100, -v96
	v_fma_f32 v109, v109, v101, -v97
	v_fma_f32 v92, v93, v100, v96
	v_fma_f32 v93, v93, v101, v97
	s_nop 0
	v_mov_b32_e32 v109, v93
	v_mul_f32_e64 v92, v102, v108
	v_mul_f32_e64 v93, v103, v109
	s_nop 0
	v_sub_f32_e32 v92, v92, v93
	v_add_f32_e32 v1, v1, v92
	s_waitcnt vmcnt(0)
	v_mov_b64_e32 v[92:93], v[132:133]
	v_mul_f32_e64 v96, v98, v93
	v_mul_f32_e64 v97, v98, v92
	v_mov_b64_e32 v[86:87], v[134:135]
	v_fma_f32 v100, v94, v92, -v96
	v_fma_f32 v101, v95, v93, -v97
	v_fma_f32 v92, v94, v92, v96
	v_fma_f32 v93, v94, v93, v97
	v_mov_b32_e32 v101, v93
	v_mul_f32_e64 v92, v104, v100
	v_mul_f32_e64 v93, v105, v101
	v_mov_b32_e32 v96, v99
	v_sub_f32_e32 v92, v92, v93
	v_add_f32_e32 v1, v1, v92
	v_mov_b32_e32 v92, v95
	v_mov_b32_e32 v94, v95
	s_waitcnt vmcnt(0)
	v_mul_f32_e64 v97, v96, v86
	v_mul_f32_e64 v96, v96, v87
	v_fma_f32 v92, v92, v86, -v96
	v_fma_f32 v93, v93, v87, -v97
	v_fma_f32 v86, v94, v86, v96
	v_fma_f32 v87, v94, v87, v97
	v_mov_b32_e32 v93, v87
	v_mul_f32_e64 v86, v106, v92
	v_mul_f32_e64 v87, v107, v93
	s_nop 0
	v_sub_f32_e32 v86, v86, v87
	v_add_f32_e32 v1, v1, v86
	s_cbranch_scc0 .LBB0_967
	v_lshl_add_u64 v[8:9], v[6:7], 2, s[56:57]
	v_lshl_add_u64 v[6:7], v[6:7], 0, s[22:23]
	v_readlane_b32 s0, v250, 5
	v_cmp_lt_i64_e32 vcc, s[70:71], v[6:7]
	v_readlane_b32 s1, v250, 6
	s_or_b64 s[60:61], vcc, s[60:61]
	global_store_dword v[8:9], v1, off
	v_lshl_add_u64 v[4:5], v[4:5], 0, s[0:1]
	s_andn2_b64 exec, exec, s[60:61]
	s_cbranch_execnz .LBB0_966
	s_or_b64 exec, exec, s[60:61]
	s_add_u32 s56, s54, 0xaac4000
	s_addc_u32 s57, s55, 0
	s_add_u32 s12, s54, 0xac4c000
	s_addc_u32 s13, s55, 0
	s_add_u32 s14, s54, 0xc8cc000
	s_addc_u32 s15, s55, 0
	s_lshl_b64 s[0:1], s[58:59], 12
	v_lshl_add_u64 v[22:23], v[2:3], 3, s[0:1]
	s_mov_b64 s[58:59], 0
	v_mov_b64_e32 v[24:25], v[18:19]
; __device__ __forceinline__ unsigned cvtpk(float lo, float hi) { unsigned r; asm volatile("v_cvt_pk_bf16_f32 %0, %1, %2" : "=v"(r) : "v"(lo), "v"(hi)); return r; }
; __device__ __forceinline__ void ssm_build_mef(const Params& p, const Ctx& c, int l) {
;     ...
;   for (long i = c.gtid; i < 32L * 256 * 32 * 2; i += c.nthr) { const int hh = (int)(i & 1), s = (int)((i >> 1) & 31), n = (int)((i >> 6) & 255), g = (int)(i >> 14), ri = n & 1, pp = (n >> 1) & 63, d = n >> 7;
;     const int gd = g * 2 + d, e = d ? s : 31 - s; const float2 w = PW[((size_t)gd * 33 + e) * 64 + pp]; const float2* bb = BB + ((size_t)gd * 64 + pp) * 16 + hh * 8; float v[8];
; #pragma unroll
;     for (int k = 0; k < 8; ++k) { const float2 b = bb[k]; v[k] = ri ? (w.x * b.y + w.y * b.x) : (w.x * b.x - w.y * b.y); }
;     u32x4 o = {cvtpk(v[0], v[1]), cvtpk(v[2], v[3]), cvtpk(v[4], v[5]), cvtpk(v[6], v[7])}; *(u32x4*)(EM + ((size_t)g * 256 + n) * 512 + s * 16 + hh * 8) = o; }
;   for (long i = c.gtid; i < 32L * 512 * 2 * 16; i += c.nthr) { const int pq = (int)(i & 15), d = (int)((i >> 4) & 1), n = (int)((i >> 5) & 511), g = (int)(i >> 14), h = n & 15, t = n >> 4;
;     const int gd = g * 2 + d, f = d ? 32 - t : t + 1; const size_t ci = ((size_t)((l * 2 + d) * 32 + g) * 16 + h) * 64 + pq * 4; const float2* pw = PW + ((size_t)gd * 33 + f) * 64 + pq * 4; float v[8];
; #pragma unroll
;     for (int k = 0; k < 4; ++k) { const float cr = p.ssm_c_re[ci + k], cim = p.ssm_c_im[ci + k]; const float2 w = pw[k]; v[2 * k] = cr * w.x - cim * w.y; v[2 * k + 1] = -(cr * w.y + cim * w.x); }
;     u32x4 o = {cvtpk(v[0], v[1]), cvtpk(v[2], v[3]), cvtpk(v[4], v[5]), cvtpk(v[6], v[7])}; *(u32x4*)(TF + ((size_t)g * 512 + n) * 768 + 512 + d * 128 + pq * 8) = o; }
.LBB0_970:
	v_lshrrev_b32_e32 v2, 1, v24
	v_lshrrev_b32_e32 v4, 6, v24
	v_bfe_u32 v34, v24, 6, 8
	v_bfe_u32 v28, v24, 1, 5
	v_alignbit_b32 v1, v25, v24, 14
	v_bfe_u32 v10, v4, 7, 1
	v_bitop3_b32 v2, v2, 31, v2 bitop3:0xc
	v_cmp_gt_u32_e32 vcc, s82, v34
	v_mov_b32_e32 v3, v0
	v_lshl_or_b32 v10, v1, 1, v10
	v_cndmask_b32_e32 v2, v28, v2, vcc
	v_ashrrev_i32_e32 v11, 31, v10
	v_mad_i64_i32 v[2:3], s[0:1], v10, 33, v[2:3]
	v_bfe_u32 v6, v24, 7, 6
	v_lshlrev_b64 v[2:3], 9, v[2:3]
	v_lshlrev_b64 v[10:11], 13, v[10:11]
	v_mov_b32_e32 v5, v0
	v_mov_b32_e32 v7, v0
	v_and_b32_e32 v30, 8, v22
	v_lshlrev_b32_e32 v4, 3, v6
	v_lshlrev_b32_e32 v6, 7, v6
	v_lshl_add_u64 v[2:3], s[56:57], 0, v[2:3]
	v_lshl_add_u64 v[10:11], s[12:13], 0, v[10:11]
	v_mov_b32_e32 v9, v0
	v_lshlrev_b32_e32 v8, 3, v30
	v_lshl_add_u64 v[2:3], v[2:3], 0, v[4:5]
	v_lshl_add_u64 v[4:5], v[10:11], 0, v[6:7]
	v_lshl_add_u64 v[4:5], v[4:5], 0, v[8:9]
	global_load_dwordx2 v[26:27], v[2:3], off
	global_load_dwordx4 v[14:17], v[4:5], off
	global_load_dwordx4 v[10:13], v[4:5], off offset:16
	global_load_dwordx4 v[6:9], v[4:5], off offset:32
	s_nop 0
	global_load_dwordx4 v[2:5], v[4:5], off offset:48
	v_ashrrev_i64 v[32:33], 24, v[0:1]
	v_or_b32_e32 v32, v32, v34
	v_lshlrev_b64 v[32:33], 10, v[32:33]
	v_mov_b32_e32 v29, v0
	v_lshlrev_b32_e32 v28, 5, v28
	v_lshl_add_u64 v[32:33], s[14:15], 0, v[32:33]
	v_and_b32_e32 v46, 64, v24
	v_mov_b32_e32 v31, v0
	v_lshl_add_u64 v[24:25], v[24:25], 0, s[22:23]
	v_lshlrev_b32_e32 v30, 1, v30
	v_lshl_add_u64 v[28:29], v[32:33], 0, v[28:29]
	v_cmp_lt_i64_e32 vcc, s[70:71], v[24:25]
	v_lshl_add_u64 v[28:29], v[28:29], 0, v[30:31]
	s_or_b64 s[58:59], vcc, s[58:59]
	v_cmp_eq_u32_e32 vcc, 0, v46
	v_lshl_add_u64 v[22:23], v[22:23], 0, s[28:29]
	s_waitcnt vmcnt(3)
	v_mul_f32_e64 v30, v27, v14
	v_mul_f32_e64 v31, v26, v15
	v_mul_f32_e64 v14, v26, v14
	v_mul_f32_e64 v15, v27, v15
	v_mul_f32_e64 v32, v27, v16
	v_mul_f32_e64 v33, v26, v17
	v_mul_f32_e64 v16, v26, v16
	v_mul_f32_e64 v17, v27, v17
	s_waitcnt vmcnt(2)
	v_mul_f32_e64 v34, v27, v10
	v_mul_f32_e64 v35, v26, v11
	v_mul_f32_e64 v10, v26, v10
	v_mul_f32_e64 v11, v27, v11
	v_mul_f32_e64 v36, v27, v12
	v_mul_f32_e64 v37, v26, v13
	v_mul_f32_e64 v12, v26, v12
	v_mul_f32_e64 v13, v27, v13
	s_waitcnt vmcnt(1)
	v_mul_f32_e64 v38, v27, v6
	v_mul_f32_e64 v39, v26, v7
	v_mul_f32_e64 v6, v26, v6
	v_mul_f32_e64 v7, v27, v7
	v_mul_f32_e64 v40, v27, v8
	v_mul_f32_e64 v41, v26, v9
	v_mul_f32_e64 v8, v26, v8
	v_mul_f32_e64 v9, v27, v9
	s_waitcnt vmcnt(0)
	v_mul_f32_e64 v42, v27, v2
	v_mul_f32_e64 v43, v26, v3
	v_mul_f32_e64 v2, v26, v2
	v_mul_f32_e64 v3, v27, v3
	v_mul_f32_e64 v44, v27, v4
	v_mul_f32_e64 v45, v26, v5
	v_mul_f32_e64 v4, v26, v4
	v_mul_f32_e64 v5, v27, v5
	v_sub_f32_e32 v14, v14, v15
	v_add_f32_e32 v15, v32, v33
	v_sub_f32_e32 v16, v16, v17
	v_add_f32_e32 v1, v30, v31
	v_add_f32_e32 v17, v34, v35
	v_sub_f32_e32 v10, v10, v11
	v_add_f32_e32 v11, v36, v37
	v_sub_f32_e32 v12, v12, v13
	v_add_f32_e32 v13, v38, v39
	v_sub_f32_e32 v6, v6, v7
	v_add_f32_e32 v7, v40, v41
	v_sub_f32_e32 v8, v8, v9
	v_add_f32_e32 v9, v42, v43
	v_sub_f32_e32 v2, v2, v3
	v_add_f32_e32 v3, v44, v45
	v_sub_f32_e32 v4, v4, v5
	v_cndmask_b32_e32 v5, v15, v16, vcc
	v_cndmask_b32_e32 v1, v1, v14, vcc
	v_cndmask_b32_e32 v10, v17, v10, vcc
	v_cndmask_b32_e32 v11, v11, v12, vcc
	v_cndmask_b32_e32 v6, v13, v6, vcc
	v_cndmask_b32_e32 v7, v7, v8, vcc
	v_cndmask_b32_e32 v8, v9, v2, vcc
	v_cndmask_b32_e32 v9, v3, v4, vcc
	v_cvt_pk_bf16_f32 v2, v1, v5
	v_cvt_pk_bf16_f32 v3, v10, v11
	v_cvt_pk_bf16_f32 v4, v6, v7
	v_cvt_pk_bf16_f32 v5, v8, v9
	global_store_dwordx4 v[28:29], v[2:5], off
	s_andn2_b64 exec, exec, s[58:59]
	s_cbranch_execnz .LBB0_970
	s_or_b64 exec, exec, s[58:59]
	s_load_dwordx4 s[12:15], s[84:85], 0xb0
	v_lshlrev_b32_e32 v2, 5, v21
	v_mov_b32_e32 v3, v0
	v_lshlrev_b32_e32 v22, 2, v21
	v_lshl_add_u64 v[24:25], s[56:57], 0, v[2:3]
	s_mov_b64 s[56:57], 0
	v_lshlrev_b32_e32 v20, 1, v20
.LBB0_972:
	v_bfe_u32 v23, v18, 4, 1
	v_lshrrev_b32_e32 v2, 5, v18
	v_alignbit_b32 v1, v19, v18, 14
	v_bfe_u32 v2, v2, 4, 5
	v_lshlrev_b32_e32 v4, 5, v23
	v_sub_u32_e32 v5, 32, v2
	v_add_u32_e32 v2, 1, v2
	v_add3_u32 v4, v1, v4, 64
	v_cmp_eq_u32_e32 vcc, 0, v23
	v_lshlrev_b32_e32 v6, 1, v18
	s_movk_i32 s2, 0x3c0
	v_cndmask_b32_e32 v2, v5, v2, vcc
	v_ashrrev_i32_e32 v5, 31, v4
	v_mov_b32_e32 v3, v0
	v_lshl_or_b32 v7, v1, 1, v23
	v_lshlrev_b64 v[4:5], 10, v[4:5]
	v_mad_i64_i32 v[2:3], s[0:1], v7, 33, v[2:3]
	v_and_or_b32 v4, v6, s2, v4
	v_lshlrev_b64 v[2:3], 9, v[2:3]
	v_or_b32_e32 v4, v4, v22
	v_lshl_add_u64 v[14:15], v[24:25], 0, v[2:3]
	v_lshlrev_b64 v[2:3], 2, v[4:5]
	s_waitcnt lgkmcnt(0)
	v_lshl_add_u64 v[4:5], s[12:13], 0, v[2:3]
	v_lshl_add_u64 v[10:11], s[14:15], 0, v[2:3]
	global_load_dwordx4 v[6:9], v[14:15], off
	s_nop 0
	global_load_dwordx4 v[2:5], v[4:5], off
	s_nop 0
	global_load_dwordx4 v[10:13], v[10:11], off
	s_nop 0
	global_load_dwordx4 v[14:17], v[14:15], off offset:16
	v_bfe_u32 v32, v18, 5, 9
	v_ashrrev_i64 v[30:31], 23, v[0:1]
	v_mov_b64_e32 v[26:27], s[54:55]
	v_or_b32_e32 v1, v30, v32
	v_mad_u64_u32 v[26:27], s[0:1], v1, s35, v[26:27]
	v_mov_b32_e32 v29, v0
	v_lshlrev_b32_e32 v28, 8, v23
	v_mad_i32_i24 v27, v31, s35, v27
	v_mov_b32_e32 v21, v0
	v_lshl_add_u64 v[18:19], v[18:19], 0, s[22:23]
	v_lshl_add_u64 v[26:27], v[26:27], 0, v[28:29]
	v_cmp_lt_i64_e32 vcc, s[70:71], v[18:19]
	v_lshl_add_u64 v[26:27], v[26:27], 0, v[20:21]
	s_or_b64 s[56:57], vcc, s[56:57]
	v_add_co_u32_e32 v26, vcc, 0xb0cc000, v26
	s_waitcnt vmcnt(2)
	v_mov_b32_e32 v28, v2
	s_waitcnt vmcnt(1)
	v_mov_b32_e32 v29, v10
	v_mov_b32_e32 v30, v10
	v_mov_b32_e32 v31, v2
	v_mov_b32_e32 v10, v3
	v_mov_b32_e32 v2, v11
	v_mov_b32_e32 v32, v4
	v_mov_b32_e32 v33, v12
	v_mov_b32_e32 v34, v12
	v_mov_b32_e32 v35, v4
	v_mov_b32_e32 v4, v13
	v_mul_f32_e64 v28, v28, v6
	v_mul_f32_e64 v29, v29, v7
	v_mul_f32_e64 v6, v30, v6
	v_mul_f32_e64 v7, v31, v7
	v_mov_b32_e32 v12, v5
	v_mul_f32_e64 v10, v10, v8
	v_mul_f32_e64 v11, v11, v9
	v_mul_f32_e64 v2, v2, v8
	v_mul_f32_e64 v3, v3, v9
	s_waitcnt vmcnt(0)
	v_mul_f32_e64 v8, v32, v14
	v_mul_f32_e64 v9, v33, v15
	v_mul_f32_e64 v14, v34, v14
	v_mul_f32_e64 v15, v35, v15
	v_mul_f32_e64 v4, v4, v16
	v_mul_f32_e64 v5, v5, v17
	v_add_f32_e32 v6, v6, v7
	v_addc_co_u32_e32 v27, vcc, 0, v27, vcc
	v_mul_f32_e64 v12, v12, v16
	v_mul_f32_e64 v13, v13, v17
	v_add_f32_e32 v2, v2, v3
	v_add_f32_e32 v3, v14, v15
	v_add_f32_e32 v4, v4, v5
	v_xor_b32_e32 v5, 0x80000000, v6
	v_sub_f32_e32 v1, v28, v29
	v_sub_f32_e32 v7, v10, v11
	v_sub_f32_e32 v8, v8, v9
	v_sub_f32_e32 v9, v12, v13
	v_xor_b32_e32 v6, 0x80000000, v2
	v_xor_b32_e32 v10, 0x80000000, v3
	v_xor_b32_e32 v11, 0x80000000, v4
	v_cvt_pk_bf16_f32 v2, v1, v5
	v_cvt_pk_bf16_f32 v3, v7, v6
	v_cvt_pk_bf16_f32 v4, v8, v10
	v_cvt_pk_bf16_f32 v5, v9, v11
	global_store_dwordx4 v[26:27], v[2:5], off offset:1024
	s_andn2_b64 exec, exec, s[56:57]
	s_cbranch_execnz .LBB0_972

; __device__ __forceinline__ f32x4 bf4(const u32x2 w) { return (f32x4){__uint_as_float(w[0] << 16), __uint_as_float(w[0] & 0xffff0000u), __uint_as_float(w[1] << 16), __uint_as_float(w[1] & 0xffff0000u)}; }
; __device__ __forceinline__ void phase_postmix(const Params& p, const Ctx& c, int l, bool last) {
;     ...
;     if (t < CTXL) { const u32x2* sl = (const u32x2*)(p.ws + OFF_Z2) + ((size_t)b * CTXL + t) * (DM / 4);
; #pragma unroll
;       for (int i = 0; i < 8; ++i) { m[i] = (f32x4){0.f, 0.f, 0.f, 0.f}; x[i] = xs[c.lane + 64 * i]; }
;       for (int s = 0; s < 8; ++s) {
; #pragma unroll
;         for (int i = 0; i < 8; ++i) m[i] += bf4(sl[(size_t)s * NB * CTXL * (DM / 4) + c.lane + 64 * i]); } }
.LBB0_1015:
	v_lshl_add_u64 v[40:41], v[38:39], 0, s[56:57]
	v_add_co_u32_e32 v42, vcc, s74, v40
	s_add_u32 s56, s56, 0x800000
	s_nop 0
	v_addc_co_u32_e32 v43, vcc, 0, v41, vcc
	v_add_co_u32_e32 v40, vcc, s75, v40
	s_addc_u32 s57, s57, 0
	s_nop 0
	v_addc_co_u32_e32 v41, vcc, 0, v41, vcc
	global_load_dwordx2 v[44:45], v[42:43], off
	global_load_dwordx2 v[46:47], v[42:43], off offset:512
	global_load_dwordx2 v[48:49], v[42:43], off offset:1024
	global_load_dwordx2 v[50:51], v[42:43], off offset:1536
	global_load_dwordx2 v[52:53], v[42:43], off offset:2048
	global_load_dwordx2 v[54:55], v[42:43], off offset:2560
	global_load_dwordx2 v[56:57], v[42:43], off offset:3072
	s_nop 0
	global_load_dwordx2 v[42:43], v[42:43], off offset:3584
	s_nop 0
	global_load_dwordx2 v[58:59], v[40:41], off
	global_load_dwordx2 v[60:61], v[40:41], off offset:512
	global_load_dwordx2 v[62:63], v[40:41], off offset:1024
	global_load_dwordx2 v[64:65], v[40:41], off offset:1536
	global_load_dwordx2 v[66:67], v[40:41], off offset:2048
	global_load_dwordx2 v[68:69], v[40:41], off offset:2560
	global_load_dwordx2 v[70:71], v[40:41], off offset:3072
	s_nop 0
	global_load_dwordx2 v[40:41], v[40:41], off offset:3584
	s_cmp_eq_u32 s56, 0x2000000
	s_waitcnt vmcnt(15)
	v_lshlrev_b32_e32 v72, 16, v44
	v_and_b32_e32 v73, 0xffff0000, v44
	v_lshlrev_b32_e32 v44, 16, v45
	v_and_b32_e32 v45, 0xffff0000, v45
	s_waitcnt vmcnt(14)
	v_lshlrev_b32_e32 v74, 16, v46
	v_and_b32_e32 v75, 0xffff0000, v46
	v_lshlrev_b32_e32 v46, 16, v47
	v_and_b32_e32 v47, 0xffff0000, v47
	s_waitcnt vmcnt(13)
	v_lshlrev_b32_e32 v76, 16, v48
	v_and_b32_e32 v77, 0xffff0000, v48
	v_lshlrev_b32_e32 v48, 16, v49
	v_and_b32_e32 v49, 0xffff0000, v49
	s_waitcnt vmcnt(12)
	v_lshlrev_b32_e32 v114, 16, v50
	v_and_b32_e32 v115, 0xffff0000, v50
	v_lshlrev_b32_e32 v50, 16, v51
	v_and_b32_e32 v51, 0xffff0000, v51
	s_waitcnt vmcnt(11)
	v_lshlrev_b32_e32 v116, 16, v52
	v_and_b32_e32 v117, 0xffff0000, v52
	v_lshlrev_b32_e32 v52, 16, v53
	v_and_b32_e32 v53, 0xffff0000, v53
	s_waitcnt vmcnt(10)
	v_lshlrev_b32_e32 v118, 16, v54
	v_and_b32_e32 v119, 0xffff0000, v54
	v_lshlrev_b32_e32 v54, 16, v55
	v_and_b32_e32 v55, 0xffff0000, v55
	s_waitcnt vmcnt(9)
	v_lshlrev_b32_e32 v120, 16, v56
	v_and_b32_e32 v121, 0xffff0000, v56
	v_lshlrev_b32_e32 v56, 16, v57
	v_and_b32_e32 v57, 0xffff0000, v57
	s_waitcnt vmcnt(8)
	v_lshlrev_b32_e32 v122, 16, v42
	v_and_b32_e32 v123, 0xffff0000, v42
	v_lshlrev_b32_e32 v42, 16, v43
	v_and_b32_e32 v43, 0xffff0000, v43
	s_waitcnt vmcnt(7)
	v_lshlrev_b32_e32 v124, 16, v58
	v_and_b32_e32 v125, 0xffff0000, v58
	v_lshlrev_b32_e32 v58, 16, v59
	v_and_b32_e32 v59, 0xffff0000, v59
	s_waitcnt vmcnt(6)
	v_lshlrev_b32_e32 v126, 16, v60
	v_and_b32_e32 v127, 0xffff0000, v60
	v_lshlrev_b32_e32 v60, 16, v61
	v_and_b32_e32 v61, 0xffff0000, v61
	s_waitcnt vmcnt(5)
	v_lshlrev_b32_e32 v128, 16, v62
	v_and_b32_e32 v129, 0xffff0000, v62
	v_lshlrev_b32_e32 v62, 16, v63
	v_and_b32_e32 v63, 0xffff0000, v63
	s_waitcnt vmcnt(4)
	v_lshlrev_b32_e32 v130, 16, v64
	v_and_b32_e32 v131, 0xffff0000, v64
	v_lshlrev_b32_e32 v64, 16, v65
	v_and_b32_e32 v65, 0xffff0000, v65
	s_waitcnt vmcnt(3)
	v_lshlrev_b32_e32 v132, 16, v66
	v_and_b32_e32 v133, 0xffff0000, v66
	v_lshlrev_b32_e32 v66, 16, v67
	v_and_b32_e32 v67, 0xffff0000, v67
	s_waitcnt vmcnt(2)
	v_lshlrev_b32_e32 v134, 16, v68
	v_and_b32_e32 v135, 0xffff0000, v68
	v_lshlrev_b32_e32 v68, 16, v69
	v_and_b32_e32 v69, 0xffff0000, v69
	s_waitcnt vmcnt(1)
	v_lshlrev_b32_e32 v136, 16, v70
	v_and_b32_e32 v137, 0xffff0000, v70
	v_lshlrev_b32_e32 v70, 16, v71
	v_and_b32_e32 v71, 0xffff0000, v71
	s_waitcnt vmcnt(0)
	v_lshlrev_b32_e32 v138, 16, v40
	v_and_b32_e32 v139, 0xffff0000, v40
	v_lshlrev_b32_e32 v40, 16, v41
	v_and_b32_e32 v41, 0xffff0000, v41
	v_add_f32_e64 v72, v110, v72
	v_add_f32_e64 v73, v111, v73
	v_add_f32_e64 v44, v112, v44
	v_add_f32_e64 v45, v113, v45
	v_add_f32_e64 v74, v102, v74
	v_add_f32_e64 v75, v103, v75
	v_add_f32_e64 v46, v106, v46
	v_add_f32_e64 v47, v107, v47
	v_add_f32_e64 v76, v98, v76
	v_add_f32_e64 v77, v99, v77
	v_add_f32_e64 v48, v100, v48
	v_add_f32_e64 v49, v101, v49
	v_add_f32_e64 v104, v104, v114
	v_add_f32_e64 v105, v105, v115
	v_add_f32_e64 v50, v108, v50
	v_add_f32_e64 v51, v109, v51
	v_add_f32_e64 v90, v90, v116
	v_add_f32_e64 v91, v91, v117
	v_add_f32_e64 v52, v92, v52
	v_add_f32_e64 v53, v93, v53
	v_add_f32_e64 v86, v86, v118
	v_add_f32_e64 v87, v87, v119
	v_add_f32_e64 v54, v88, v54
	v_add_f32_e64 v55, v89, v55
	v_add_f32_e64 v82, v82, v120
	v_add_f32_e64 v83, v83, v121
	v_add_f32_e64 v56, v84, v56
	v_add_f32_e64 v57, v85, v57
	v_add_f32_e64 v94, v94, v122
	v_add_f32_e64 v95, v95, v123
	v_add_f32_e64 v42, v96, v42
	v_add_f32_e64 v43, v97, v43
	v_add_f32_e64 v112, v44, v58
	v_add_f32_e64 v113, v45, v59
	v_add_f32_e64 v110, v72, v124
	v_add_f32_e64 v111, v73, v125
	v_add_f32_e64 v106, v46, v60
	v_add_f32_e64 v107, v47, v61
	v_add_f32_e64 v102, v74, v126
	v_add_f32_e64 v103, v75, v127
	v_add_f32_e64 v100, v48, v62
	v_add_f32_e64 v101, v49, v63
	v_add_f32_e64 v98, v76, v128
	v_add_f32_e64 v99, v77, v129
	v_add_f32_e64 v108, v50, v64
	v_add_f32_e64 v109, v51, v65
	v_add_f32_e64 v104, v104, v130
	v_add_f32_e64 v105, v105, v131
	v_add_f32_e64 v92, v52, v66
	v_add_f32_e64 v93, v53, v67
	v_add_f32_e64 v90, v90, v132
	v_add_f32_e64 v91, v91, v133
	v_add_f32_e64 v88, v54, v68
	v_add_f32_e64 v89, v55, v69
	v_add_f32_e64 v86, v86, v134
	v_add_f32_e64 v87, v87, v135
	v_add_f32_e64 v84, v56, v70
	v_add_f32_e64 v85, v57, v71
	v_add_f32_e64 v82, v82, v136
	v_add_f32_e64 v83, v83, v137
	v_add_f32_e64 v96, v42, v40
	v_add_f32_e64 v97, v43, v41
	v_add_f32_e64 v94, v94, v138
	v_add_f32_e64 v95, v95, v139
	s_cbranch_scc0 .LBB0_1015

; __device__ __forceinline__ f32x4 bf4(const u32x2 w) { return (f32x4){__uint_as_float(w[0] << 16), __uint_as_float(w[0] & 0xffff0000u), __uint_as_float(w[1] << 16), __uint_as_float(w[1] & 0xffff0000u)}; }
; __device__ __forceinline__ void phase_postmix(const Params& p, const Ctx& c, int l, bool last) {
;     ...
;     if (t < CTXL) { const u32x2* sl = (const u32x2*)(p.ws + OFF_Z2) + ((size_t)b * CTXL + t) * (DM / 4);
; #pragma unroll
;       for (int i = 0; i < 8; ++i) { m[i] = (f32x4){0.f, 0.f, 0.f, 0.f}; x[i] = xs[c.lane + 64 * i]; }
;       for (int s = 0; s < 8; ++s) {
; #pragma unroll
;         for (int i = 0; i < 8; ++i) m[i] += bf4(sl[(size_t)s * NB * CTXL * (DM / 4) + c.lane + 64 * i]); } }
.LBB0_1059:
	v_lshl_add_u64 v[68:69], v[66:67], 0, s[60:61]
	v_add_co_u32_e32 v70, vcc, s74, v68
	s_add_u32 s60, s60, 0x800000
	s_nop 0
	v_addc_co_u32_e32 v71, vcc, 0, v69, vcc
	global_load_dwordx2 v[72:73], v[70:71], off
	global_load_dwordx2 v[76:77], v[70:71], off offset:512
	v_add_co_u32_e32 v68, vcc, s75, v68
	s_addc_u32 s61, s61, 0
	s_nop 0
	v_addc_co_u32_e32 v69, vcc, 0, v69, vcc
	s_cmp_eq_u32 s60, 0x2000000
	s_waitcnt vmcnt(1)
	v_lshlrev_b32_e32 v74, 16, v72
	v_and_b32_e32 v75, 0xffff0000, v72
	v_add_f32_e64 v74, v160, v74
	v_add_f32_e64 v75, v161, v75
	s_waitcnt vmcnt(0)
	v_lshlrev_b32_e32 v160, 16, v76
	v_and_b32_e32 v161, 0xffff0000, v76
	v_add_f32_e64 v164, v164, v160
	v_add_f32_e64 v165, v165, v161
	global_load_dwordx2 v[160:161], v[70:71], off offset:1024
	v_lshlrev_b32_e32 v72, 16, v73
	v_and_b32_e32 v73, 0xffff0000, v73
	v_add_f32_e64 v72, v162, v72
	v_add_f32_e64 v73, v163, v73
	v_lshlrev_b32_e32 v76, 16, v77
	v_and_b32_e32 v77, 0xffff0000, v77
	v_add_f32_e64 v76, v166, v76
	v_add_f32_e64 v77, v167, v77
	s_waitcnt vmcnt(0)
	v_lshlrev_b32_e32 v162, 16, v160
	v_and_b32_e32 v163, 0xffff0000, v160
	v_lshlrev_b32_e32 v160, 16, v161
	v_and_b32_e32 v161, 0xffff0000, v161
	v_add_f32_e64 v170, v170, v160
	v_add_f32_e64 v171, v171, v161
	global_load_dwordx2 v[160:161], v[70:71], off offset:1536
	v_add_f32_e64 v168, v168, v162
	v_add_f32_e64 v169, v169, v163
	s_waitcnt vmcnt(0)
	v_lshlrev_b32_e32 v162, 16, v160
	v_and_b32_e32 v163, 0xffff0000, v160
	v_lshlrev_b32_e32 v160, 16, v161
	v_and_b32_e32 v161, 0xffff0000, v161
	v_add_f32_e64 v186, v186, v160
	v_add_f32_e64 v187, v187, v161
	global_load_dwordx2 v[160:161], v[70:71], off offset:2048
	v_add_f32_e64 v182, v182, v162
	v_add_f32_e64 v183, v183, v163
	s_waitcnt vmcnt(0)
	v_lshlrev_b32_e32 v162, 16, v160
	v_and_b32_e32 v163, 0xffff0000, v160
	v_lshlrev_b32_e32 v160, 16, v161
	v_and_b32_e32 v161, 0xffff0000, v161
	v_add_f32_e64 v178, v178, v160
	v_add_f32_e64 v179, v179, v161
	global_load_dwordx2 v[160:161], v[70:71], off offset:2560
	v_add_f32_e64 v176, v176, v162
	v_add_f32_e64 v177, v177, v163
	s_waitcnt vmcnt(0)
	v_lshlrev_b32_e32 v162, 16, v160
	v_and_b32_e32 v163, 0xffff0000, v160
	v_lshlrev_b32_e32 v160, 16, v161
	v_and_b32_e32 v161, 0xffff0000, v161
	v_add_f32_e64 v184, v184, v160
	v_add_f32_e64 v185, v185, v161
	global_load_dwordx2 v[160:161], v[70:71], off offset:3072
	v_add_f32_e64 v180, v180, v162
	v_add_f32_e64 v181, v181, v163
	global_load_dwordx2 v[70:71], v[70:71], off offset:3584
	s_waitcnt vmcnt(1)
	v_lshlrev_b32_e32 v162, 16, v160
	v_and_b32_e32 v163, 0xffff0000, v160
	v_lshlrev_b32_e32 v160, 16, v161
	v_and_b32_e32 v161, 0xffff0000, v161
	v_add_f32_e64 v190, v190, v160
	v_add_f32_e64 v191, v191, v161
	s_waitcnt vmcnt(0)
	v_lshlrev_b32_e32 v160, 16, v70
	v_and_b32_e32 v161, 0xffff0000, v70
	v_add_f32_e64 v172, v172, v160
	v_add_f32_e64 v173, v173, v161
	global_load_dwordx2 v[160:161], v[68:69], off
	v_add_f32_e64 v188, v188, v162
	v_add_f32_e64 v189, v189, v163
	v_lshlrev_b32_e32 v70, 16, v71
	v_and_b32_e32 v71, 0xffff0000, v71
	v_add_f32_e64 v70, v174, v70
	v_add_f32_e64 v71, v175, v71
	s_waitcnt vmcnt(0)
	v_lshlrev_b32_e32 v166, 16, v160
	v_and_b32_e32 v167, 0xffff0000, v160
	v_lshlrev_b32_e32 v160, 16, v161
	v_and_b32_e32 v161, 0xffff0000, v161
	v_add_f32_e64 v162, v72, v160
	v_add_f32_e64 v163, v73, v161
	global_load_dwordx2 v[72:73], v[68:69], off offset:512
	v_add_f32_e64 v160, v74, v166
	v_add_f32_e64 v161, v75, v167
	s_waitcnt vmcnt(0)
	v_lshlrev_b32_e32 v74, 16, v72
	v_and_b32_e32 v75, 0xffff0000, v72
	v_lshlrev_b32_e32 v72, 16, v73
	v_and_b32_e32 v73, 0xffff0000, v73
	v_add_f32_e64 v166, v76, v72
	v_add_f32_e64 v167, v77, v73
	global_load_dwordx2 v[72:73], v[68:69], off offset:1024
	v_add_f32_e64 v164, v164, v74
	v_add_f32_e64 v165, v165, v75
	s_waitcnt vmcnt(0)
	v_lshlrev_b32_e32 v74, 16, v72
	v_and_b32_e32 v75, 0xffff0000, v72
	v_lshlrev_b32_e32 v72, 16, v73
	v_and_b32_e32 v73, 0xffff0000, v73
	v_add_f32_e64 v170, v170, v72
	v_add_f32_e64 v171, v171, v73
	global_load_dwordx2 v[72:73], v[68:69], off offset:1536
	v_add_f32_e64 v168, v168, v74
	v_add_f32_e64 v169, v169, v75
	s_waitcnt vmcnt(0)
	v_lshlrev_b32_e32 v74, 16, v72
	v_and_b32_e32 v75, 0xffff0000, v72
	v_lshlrev_b32_e32 v72, 16, v73
	v_and_b32_e32 v73, 0xffff0000, v73
	v_add_f32_e64 v186, v186, v72
	v_add_f32_e64 v187, v187, v73
	global_load_dwordx2 v[72:73], v[68:69], off offset:2048
	v_add_f32_e64 v182, v182, v74
	v_add_f32_e64 v183, v183, v75
	s_waitcnt vmcnt(0)
	v_lshlrev_b32_e32 v74, 16, v72
	v_and_b32_e32 v75, 0xffff0000, v72
	v_lshlrev_b32_e32 v72, 16, v73
	v_and_b32_e32 v73, 0xffff0000, v73
	v_add_f32_e64 v178, v178, v72
	v_add_f32_e64 v179, v179, v73
	global_load_dwordx2 v[72:73], v[68:69], off offset:2560
	v_add_f32_e64 v176, v176, v74
	v_add_f32_e64 v177, v177, v75
	s_waitcnt vmcnt(0)
	v_lshlrev_b32_e32 v74, 16, v72
	v_and_b32_e32 v75, 0xffff0000, v72
	v_lshlrev_b32_e32 v72, 16, v73
	v_and_b32_e32 v73, 0xffff0000, v73
	v_add_f32_e64 v184, v184, v72
	v_add_f32_e64 v185, v185, v73
	global_load_dwordx2 v[72:73], v[68:69], off offset:3072
	v_add_f32_e64 v180, v180, v74
	v_add_f32_e64 v181, v181, v75
	global_load_dwordx2 v[68:69], v[68:69], off offset:3584
	s_waitcnt vmcnt(1)
	v_lshlrev_b32_e32 v74, 16, v72
	v_and_b32_e32 v75, 0xffff0000, v72
	v_lshlrev_b32_e32 v72, 16, v73
	v_and_b32_e32 v73, 0xffff0000, v73
	v_add_f32_e64 v190, v190, v72
	v_add_f32_e64 v191, v191, v73
	s_waitcnt vmcnt(0)
	v_lshlrev_b32_e32 v72, 16, v68
	v_and_b32_e32 v73, 0xffff0000, v68
	v_lshlrev_b32_e32 v68, 16, v69
	v_and_b32_e32 v69, 0xffff0000, v69
	v_add_f32_e64 v188, v188, v74
	v_add_f32_e64 v189, v189, v75
	v_add_f32_e64 v174, v70, v68
	v_add_f32_e64 v175, v71, v69
	v_add_f32_e64 v172, v172, v72
	v_add_f32_e64 v173, v173, v73
	s_cbranch_scc0 .LBB0_1059

; __device__ __forceinline__ const float* modp(const Params& p, int l, int v, int j) { return (const float*)(p.ws + OFF_MOD) + ((size_t)(l * 5 + v) * NMODC + (size_t)j * DM); }
; __device__ __forceinline__ void stx(_Float16* p, f32x4 v) { *(h16x4*)p = __builtin_convertvector(v, h16x4); }
; #pragma unroll
;   for (int i = 0; i < 8; ++i) s += x[i][0] * x[i][0] + x[i][1] * x[i][1] + x[i][2] * x[i][2] + x[i][3] * x[i][3];
;   return wave_sum(s); }
; __device__ __forceinline__ void phase_postmix(const Params& p, const Ctx& c, int l, bool last) {
;     ...
;   auto process = [&](int row, f32x4 (&m)[8], f32x4 (&x)[8]) { const int b = row / TPB, t = row % TPB, v = t < CTXL ? 4 : b; _Float16* xr = X + (size_t)row * DM;
;     const float r1 = rsqrtf(sumsq8(m) * (1.f / DM) + 1e-6f); const float* gp = p.g_mix_post + (size_t)l * DM; const float* m2 = modp(p, l, v, 2);
; #pragma unroll
;     for (int i = 0; i < 8; ++i) { const int col = (c.lane + 64 * i) * 4; x[i] += *(const f32x4*)(m2 + col) * (m[i] * r1 * *(const f32x4*)(gp + col)); stx(xr + col, x[i]); }
;     const float r2 = rsqrtf(sumsq8(x) * (1.f / DM) + 1e-6f);
.LBB0_1061:
	s_or_b64 exec, exec, s[58:59]
	v_mul_hi_i32 v1, v78, s94
	v_lshrrev_b32_e32 v66, 31, v1
	v_ashrrev_i32_e32 v1, 11, v1
	v_add_u32_e32 v1, v1, v66
	v_mul_i32_i24_e32 v66, 0x1100, v1
	v_sub_u32_e32 v66, v78, v66
	v_cmp_lt_i32_e32 vcc, s27, v66
	s_mov_b64 s[0:1], 0xa844000
	v_lshlrev_b32_e32 v74, 2, v114
	v_cndmask_b32_e32 v1, 4, v1, vcc
	v_add_u32_e32 v1, s30, v1
	v_mul_hi_i32_i24_e32 v77, 0xc000, v1
	v_mul_i32_i24_e32 v76, 0xc000, v1
	v_lshl_add_u64 v[66:67], s[12:13], 0, v[76:77]
	v_lshl_add_u64 v[198:199], v[66:67], 0, s[0:1]
	v_mov_b32_e32 v75, v0
	global_load_dwordx4 v[70:73], v[116:117], off
	v_lshl_add_u64 v[66:67], v[198:199], 0, v[74:75]
	global_load_dwordx4 v[66:69], v[66:67], off
	v_mul_f32_e32 v1, v111, v111
	v_mul_f32_e32 v79, v103, v103
	v_mov_b32_e32 v194, v105
	v_mov_b32_e32 v195, v99
	v_fmac_f32_e32 v1, v110, v110
	v_fmac_f32_e32 v79, v102, v102
	v_mov_b32_e32 v192, v104
	v_mov_b32_e32 v193, v98
	v_mul_f32_e64 v194, v194, v194
	v_mul_f32_e64 v195, v195, v195
	v_fmac_f32_e32 v1, v112, v112
	v_fmac_f32_e32 v79, v106, v106
	v_fma_f32 v192, v192, v192, v194
	v_fma_f32 v193, v193, v193, v195
	v_mov_b32_e32 v194, v108
	v_mov_b32_e32 v195, v100
	v_fmac_f32_e32 v1, v113, v113
	v_fmac_f32_e32 v79, v107, v107
	v_fma_f32 v192, v194, v194, v192
	v_fma_f32 v193, v195, v195, v193
	v_mov_b32_e32 v194, v109
	v_mov_b32_e32 v195, v101
	v_add_f32_e32 v1, v79, v1
	v_fma_f32 v192, v194, v194, v192
	v_fma_f32 v193, v195, v195, v193
	v_mov_b32_e32 v194, v87
	v_add_f32_e32 v1, v193, v1
	v_mov_b32_e32 v195, v91
	v_add_f32_e32 v1, v192, v1
	v_mov_b32_e32 v192, v86
	v_mov_b32_e32 v193, v90
	v_mul_f32_e64 v194, v194, v194
	v_mul_f32_e64 v195, v195, v195
	s_mov_b32 s4, 0x800000
	v_fma_f32 v192, v192, v192, v194
	v_fma_f32 v193, v193, v193, v195
	v_mov_b32_e32 v194, v88
	v_mov_b32_e32 v195, v92
	v_fma_f32 v192, v194, v194, v192
	v_fma_f32 v193, v195, v195, v193
	v_mov_b32_e32 v194, v89
	v_mov_b32_e32 v195, v93
	v_fma_f32 v192, v194, v194, v192
	v_fma_f32 v193, v195, v195, v193
	v_mov_b32_e32 v194, v95
	v_add_f32_e32 v1, v193, v1
	v_mov_b32_e32 v195, v83
	v_add_f32_e32 v1, v192, v1
	v_mov_b32_e32 v192, v94
	v_mov_b32_e32 v193, v82
	v_mul_f32_e64 v194, v194, v194
	v_mul_f32_e64 v195, v195, v195
	v_mov_b32_e32 v145, v0
	v_fma_f32 v192, v192, v192, v194
	v_fma_f32 v193, v193, v193, v195
	v_mov_b32_e32 v194, v96
	v_mov_b32_e32 v195, v84
	v_fma_f32 v192, v194, v194, v192
	v_fma_f32 v193, v195, v195, v193
	v_mov_b32_e32 v194, v97
	v_mov_b32_e32 v195, v85
	v_fma_f32 v192, v194, v194, v192
	v_fma_f32 v193, v195, v195, v193
	v_mov_b32_e32 v147, v0
	v_add_f32_e32 v1, v193, v1
	v_add_f32_e32 v1, v192, v1
	v_mov_b32_e32 v149, v0
	v_mov_b32_e32 v151, v0
	v_add_f32_dpp v1, v1, v1 quad_perm:[1,0,3,2] row_mask:0xf bank_mask:0xf bound_ctrl:1
	v_mov_b32_e32 v153, v0
	v_mov_b32_e32 v155, v0
	v_add_f32_dpp v1, v1, v1 quad_perm:[2,3,0,1] row_mask:0xf bank_mask:0xf bound_ctrl:1
	v_mov_b32_e32 v157, v0
	v_lshl_add_u64 v[76:77], s[10:11], 0, v[76:77]
	v_add_f32_dpp v1, v1, v1 row_half_mirror row_mask:0xf bank_mask:0xf bound_ctrl:1
	s_nop 1
	v_add_f32_dpp v1, v1, v1 row_mirror row_mask:0xf bank_mask:0xf bound_ctrl:1
	s_nop 0
	v_readlane_b32 s2, v1, 16
	v_readlane_b32 s3, v1, 48
	v_readlane_b32 s0, v1, 0
	v_readlane_b32 s1, v1, 32
	v_mov_b32_e32 v192, s2
	v_mov_b32_e32 v193, s3
	v_add_f32_e64 v192, s0, v192
	v_add_f32_e64 v193, s1, v193
	s_mov_b64 s[0:1], 0x8000
	v_add_f32_e32 v1, v192, v193
	v_fmamk_f32 v1, v1, 0x3a000000, v227
	v_mul_f32_e32 v79, 0x4b800000, v1
	v_cmp_gt_f32_e32 vcc, s4, v1
	s_mov_b64 s[2:3], 0x6000
	s_nop 0
	v_cndmask_b32_e32 v1, v1, v79, vcc
	v_rsq_f32_e32 v1, v1
	v_ashrrev_i32_e32 v79, 31, v78
	v_mul_f32_e32 v115, 0x45800000, v1
	v_cndmask_b32_e32 v194, v1, v115, vcc
	v_mul_f32_e64 v192, v194, v112
	v_mul_f32_e64 v193, v194, v113
	v_mul_f32_e64 v196, v194, v110
	v_mul_f32_e64 v197, v194, v111
	s_waitcnt vmcnt(1)
	v_mul_f32_e64 v70, v70, v196
	v_mul_f32_e64 v71, v71, v197
	v_mul_f32_e64 v72, v72, v192
	v_mul_f32_e64 v73, v73, v193
	s_waitcnt vmcnt(0)
	v_fma_f32 v2, v66, v70, v2
	v_fma_f32 v3, v67, v71, v3
	v_fma_f32 v4, v68, v72, v4
	v_fma_f32 v5, v69, v73, v5
	v_lshlrev_b64 v[192:193], 12, v[78:79]
	v_lshl_add_u64 v[196:197], v[138:139], 0, v[192:193]
	v_cvt_pk_f16_f32 v67, v4, v5
	v_cvt_pk_f16_f32 v66, v2, v3
	global_store_dwordx2 v[196:197], v[66:67], off
	global_load_dwordx4 v[66:69], v[116:117], off offset:1024
	v_lshl_add_u64 v[70:71], v[198:199], 0, v[144:145]
	global_load_dwordx4 v[70:73], v[70:71], off
	v_mul_f32_e64 v200, v194, v106
	v_mul_f32_e64 v201, v194, v107
	v_mul_f32_e64 v202, v194, v102
	v_mul_f32_e64 v203, v194, v103
	v_mul_f32_e32 v1, v3, v3
	v_fmac_f32_e32 v1, v2, v2
	v_fmac_f32_e32 v1, v4, v4
	v_fmac_f32_e32 v1, v5, v5
	v_lshl_add_u64 v[192:193], v[140:141], 0, v[192:193]
	s_waitcnt vmcnt(1)
	v_mul_f32_e64 v66, v66, v202
	v_mul_f32_e64 v67, v67, v203
	v_mul_f32_e64 v68, v68, v200
	v_mul_f32_e64 v69, v69, v201
	s_waitcnt vmcnt(0)
	v_fma_f32 v6, v70, v66, v6
	v_fma_f32 v7, v71, v67, v7
	v_fma_f32 v8, v72, v68, v8
	v_fma_f32 v9, v73, v69, v9
	v_cvt_pk_f16_f32 v66, v6, v7
	v_cvt_pk_f16_f32 v67, v8, v9
	global_store_dwordx2 v[196:197], v[66:67], off offset:512
	global_load_dwordx4 v[66:69], v[116:117], off offset:2048
	v_lshl_add_u64 v[70:71], v[198:199], 0, v[146:147]
	global_load_dwordx4 v[70:73], v[70:71], off
	v_mul_f32_e64 v200, v194, v98
	v_mul_f32_e64 v201, v194, v99
	v_mul_f32_e64 v202, v194, v100
	v_mul_f32_e64 v203, v194, v101
	v_mul_f32_e32 v79, v7, v7
	v_fmac_f32_e32 v79, v6, v6
	v_fmac_f32_e32 v79, v8, v8
	v_fmac_f32_e32 v79, v9, v9
	v_add_f32_e32 v1, v1, v79
	s_waitcnt vmcnt(1)
; __device__ __forceinline__ const float* modp(const Params& p, int l, int v, int j) { return (const float*)(p.ws + OFF_MOD) + ((size_t)(l * 5 + v) * NMODC + (size_t)j * DM); }
; __device__ __forceinline__ void stx(_Float16* p, f32x4 v) { *(h16x4*)p = __builtin_convertvector(v, h16x4); }
; __device__ __forceinline__ void phase_postmix(const Params& p, const Ctx& c, int l, bool last) {
;     ...
; #pragma unroll
;     for (int i = 0; i < 8; ++i) { const int col = (c.lane + 64 * i) * 4; x[i] += *(const f32x4*)(m2 + col) * (m[i] * r1 * *(const f32x4*)(gp + col)); stx(xr + col, x[i]); }
;     const float r2 = rsqrtf(sumsq8(x) * (1.f / DM) + 1e-6f);
;     prenorm_row(x, r2, p.g_ffn_pre + (size_t)l * DM, modp(p, l, v, 4), modp(p, l, v, 3), Hn + (size_t)row * DM, c.lane); };
	v_mul_f32_e64 v68, v68, v202
	v_mul_f32_e64 v69, v69, v203
	v_mul_f32_e64 v66, v66, v200
	v_mul_f32_e64 v67, v67, v201
	s_waitcnt vmcnt(0)
	v_fma_f32 v12, v72, v68, v12
	v_fma_f32 v13, v73, v69, v13
	v_fma_f32 v10, v70, v66, v10
	v_fma_f32 v11, v71, v67, v11
	v_cvt_pk_f16_f32 v67, v12, v13
	v_cvt_pk_f16_f32 v66, v10, v11
	global_store_dwordx2 v[196:197], v[66:67], off offset:1024
	global_load_dwordx4 v[66:69], v[116:117], off offset:3072
	v_lshl_add_u64 v[70:71], v[198:199], 0, v[148:149]
	global_load_dwordx4 v[70:73], v[70:71], off
	v_mul_f32_e64 v200, v194, v104
	v_mul_f32_e64 v201, v194, v105
	v_mul_f32_e64 v202, v194, v108
	v_mul_f32_e64 v203, v194, v109
	v_mov_b32_e32 v205, v13
	s_waitcnt vmcnt(1)
	v_mul_f32_e64 v68, v68, v202
	v_mul_f32_e64 v69, v69, v203
	v_mul_f32_e64 v66, v66, v200
	v_mul_f32_e64 v67, v67, v201
	s_waitcnt vmcnt(0)
	v_fma_f32 v16, v72, v68, v16
	v_fma_f32 v17, v73, v69, v17
	v_fma_f32 v14, v70, v66, v14
	v_fma_f32 v15, v71, v67, v15
	v_cvt_pk_f16_f32 v67, v16, v17
	v_cvt_pk_f16_f32 v66, v14, v15
	global_store_dwordx2 v[196:197], v[66:67], off offset:1536
	global_load_dwordx4 v[66:69], v[118:119], off
	v_lshl_add_u64 v[70:71], v[198:199], 0, v[150:151]
	global_load_dwordx4 v[70:73], v[70:71], off
	v_mul_f32_e64 v200, v194, v90
	v_mul_f32_e64 v201, v194, v91
	v_mul_f32_e64 v202, v194, v92
	v_mul_f32_e64 v203, v194, v93
	v_mov_b32_e32 v204, v17
	s_waitcnt vmcnt(1)
	v_mul_f32_e64 v68, v202, v68
	v_mul_f32_e64 v69, v203, v69
	v_mul_f32_e64 v66, v200, v66
	v_mul_f32_e64 v67, v201, v67
	s_waitcnt vmcnt(0)
	v_fma_f32 v20, v72, v68, v20
	v_fma_f32 v21, v73, v69, v21
	v_fma_f32 v18, v70, v66, v18
	v_fma_f32 v19, v71, v67, v19
	v_cvt_pk_f16_f32 v67, v20, v21
	v_cvt_pk_f16_f32 v66, v18, v19
	global_store_dwordx2 v[196:197], v[66:67], off offset:2048
	global_load_dwordx4 v[66:69], v[120:121], off
	v_lshl_add_u64 v[70:71], v[198:199], 0, v[152:153]
	global_load_dwordx4 v[70:73], v[70:71], off
	v_mul_f32_e64 v200, v194, v86
	v_mul_f32_e64 v201, v194, v87
	v_mul_f32_e64 v202, v194, v88
	v_mul_f32_e64 v203, v194, v89
	s_waitcnt vmcnt(1)
	v_mul_f32_e64 v68, v202, v68
	v_mul_f32_e64 v69, v203, v69
	v_mul_f32_e64 v66, v200, v66
	v_mul_f32_e64 v67, v201, v67
	s_waitcnt vmcnt(0)
	v_fma_f32 v24, v72, v68, v24
	v_fma_f32 v25, v73, v69, v25
	v_fma_f32 v22, v70, v66, v22
	v_fma_f32 v23, v71, v67, v23
	v_cvt_pk_f16_f32 v67, v24, v25
	v_cvt_pk_f16_f32 v66, v22, v23
	global_store_dwordx2 v[196:197], v[66:67], off offset:2560
	global_load_dwordx4 v[66:69], v[122:123], off
	v_lshl_add_u64 v[70:71], v[198:199], 0, v[154:155]
	global_load_dwordx4 v[70:73], v[70:71], off
	v_mul_f32_e64 v200, v194, v82
	v_mul_f32_e64 v201, v194, v83
	v_mul_f32_e64 v202, v194, v84
	v_mul_f32_e64 v203, v194, v85
	s_waitcnt vmcnt(1)
	v_mul_f32_e64 v68, v202, v68
	v_mul_f32_e64 v69, v203, v69
	v_mul_f32_e64 v66, v200, v66
	v_mul_f32_e64 v67, v201, v67
	s_waitcnt vmcnt(0)
	v_fma_f32 v28, v72, v68, v28
	v_fma_f32 v29, v73, v69, v29
	v_fma_f32 v26, v70, v66, v26
	v_fma_f32 v27, v71, v67, v27
	v_cvt_pk_f16_f32 v67, v28, v29
	v_cvt_pk_f16_f32 v66, v26, v27
	global_store_dwordx2 v[196:197], v[66:67], off offset:3072
	global_load_dwordx4 v[70:73], v[124:125], off
	v_lshl_add_u64 v[66:67], v[198:199], 0, v[156:157]
	global_load_dwordx4 v[66:69], v[66:67], off
	v_lshl_add_u64 v[200:201], v[76:77], 0, s[0:1]
	v_lshl_add_u64 v[198:199], v[76:77], 0, s[2:3]
	v_mul_f32_e64 v76, v194, v94
	v_mul_f32_e64 v77, v194, v95
	v_mul_f32_e64 v195, v194, v97
	v_mul_f32_e64 v194, v194, v96
	v_mov_b32_e32 v203, v12
	v_mov_b32_e32 v202, v16
	s_waitcnt vmcnt(1)
	v_mul_f32_e64 v72, v194, v72
	v_mul_f32_e64 v73, v195, v73
	v_mul_f32_e64 v70, v76, v70
	v_mul_f32_e64 v71, v77, v71
	s_waitcnt vmcnt(0)
	v_fma_f32 v32, v68, v72, v32
	v_fma_f32 v33, v69, v73, v33
	v_fma_f32 v30, v66, v70, v30
	v_fma_f32 v31, v67, v71, v31
	v_cvt_pk_f16_f32 v67, v32, v33
	v_cvt_pk_f16_f32 v66, v30, v31
	global_store_dwordx2 v[196:197], v[66:67], off offset:3584
	v_lshl_add_u64 v[70:71], v[200:201], 0, v[74:75]
	global_load_dwordx4 v[66:69], v[126:127], off
	v_lshl_add_u64 v[74:75], v[198:199], 0, v[74:75]
	global_load_dwordx4 v[70:73], v[70:71], off
	v_mov_b32_e32 v197, v11
	global_load_dwordx4 v[74:77], v[74:75], off
	v_mov_b32_e32 v196, v15
	v_mov_b32_e32 v195, v10
	v_mov_b32_e32 v194, v14
	v_mul_f32_e64 v196, v196, v196
	v_mul_f32_e64 v197, v197, v197
	s_waitcnt vmcnt(1)
; __device__ __forceinline__ unsigned cvtpk(float lo, float hi) { unsigned r; asm volatile("v_cvt_pk_bf16_f32 %0, %1, %2" : "=v"(r) : "v"(lo), "v"(hi)); return r; }
; __device__ __forceinline__ const float* modp(const Params& p, int l, int v, int j) { return (const float*)(p.ws + OFF_MOD) + ((size_t)(l * 5 + v) * NMODC + (size_t)j * DM); }
; __device__ __forceinline__ void prenorm_row(const f32x4 (&x)[8], float rinv, const float* g, const float* sc, const float* sh, bf16_t* dst, int lane) {
; #pragma unroll
;   for (int i = 0; i < 8; ++i) { const int col = (lane + 64 * i) * 4; const f32x4 gg = *(const f32x4*)(g + col), s1 = *(const f32x4*)(sc + col), s0 = *(const f32x4*)(sh + col);
;     const f32x4 y = (x[i] * rinv * gg) * (s1 + 1.f) + s0; u32x2 o = {cvtpk(y[0], y[1]), cvtpk(y[2], y[3])}; *(u32x2*)(dst + col) = o; }
; }
; #pragma unroll
;   for (int i = 0; i < 8; ++i) s += x[i][0] * x[i][0] + x[i][1] * x[i][1] + x[i][2] * x[i][2] + x[i][3] * x[i][3];
;   return wave_sum(s); }
; __device__ __forceinline__ void phase_postmix(const Params& p, const Ctx& c, int l, bool last) {
;     ...
;     const float r2 = rsqrtf(sumsq8(x) * (1.f / DM) + 1e-6f);
;     prenorm_row(x, r2, p.g_ffn_pre + (size_t)l * DM, modp(p, l, v, 4), modp(p, l, v, 3), Hn + (size_t)row * DM, c.lane); };
	v_add_f32_e64 v70, v70, 1.0
	v_add_f32_e64 v71, v71, 1.0
	v_fma_f32 v194, v194, v194, v196
	v_fma_f32 v195, v195, v195, v197
	v_mov_b32_e32 v196, v19
	v_fma_f32 v194, v202, v202, v194
	v_fma_f32 v195, v203, v203, v195
	v_mov_b32_e32 v197, v23
	v_fma_f32 v194, v204, v204, v194
	v_fma_f32 v195, v205, v205, v195
	v_mul_f32_e64 v196, v196, v196
	v_mul_f32_e64 v197, v197, v197
	v_add_f32_e32 v1, v195, v1
	v_add_f32_e32 v1, v194, v1
	v_mov_b32_e32 v194, v18
	v_mov_b32_e32 v195, v22
	v_mov_b32_e32 v202, v20
	v_mov_b32_e32 v203, v24
	v_fma_f32 v194, v194, v194, v196
	v_fma_f32 v195, v195, v195, v197
	v_mov_b32_e32 v204, v21
	v_mov_b32_e32 v205, v25
	v_fma_f32 v194, v202, v202, v194
	v_fma_f32 v195, v203, v203, v195
	v_mov_b32_e32 v196, v27
	v_fma_f32 v194, v204, v204, v194
	v_fma_f32 v195, v205, v205, v195
	v_mov_b32_e32 v197, v31
	v_add_f32_e32 v1, v194, v1
	v_add_f32_e32 v1, v1, v195
	v_mov_b32_e32 v194, v26
	v_mov_b32_e32 v195, v30
	v_mul_f32_e64 v196, v196, v196
	v_mul_f32_e64 v197, v197, v197
	v_mov_b32_e32 v202, v28
	v_mov_b32_e32 v203, v32
	v_fma_f32 v194, v194, v194, v196
	v_fma_f32 v195, v195, v195, v197
	v_mov_b32_e32 v204, v29
	v_mov_b32_e32 v205, v33
	v_fma_f32 v194, v202, v202, v194
	v_fma_f32 v195, v203, v203, v195
	v_add_f32_e64 v72, v72, 1.0
	v_add_f32_e64 v73, v73, 1.0
	v_fma_f32 v194, v204, v204, v194
	v_fma_f32 v195, v205, v205, v195
	s_nop 0
	v_add_f32_e32 v1, v1, v194
	v_add_f32_e32 v1, v1, v195
	s_nop 1
	v_add_f32_dpp v1, v1, v1 quad_perm:[1,0,3,2] row_mask:0xf bank_mask:0xf bound_ctrl:1
	s_nop 1
	v_add_f32_dpp v1, v1, v1 quad_perm:[2,3,0,1] row_mask:0xf bank_mask:0xf bound_ctrl:1
	s_nop 1
	v_add_f32_dpp v1, v1, v1 row_half_mirror row_mask:0xf bank_mask:0xf bound_ctrl:1
	s_nop 1
	v_add_f32_dpp v1, v1, v1 row_mirror row_mask:0xf bank_mask:0xf bound_ctrl:1
	s_nop 0
	v_readlane_b32 s2, v1, 16
	v_readlane_b32 s3, v1, 48
	v_readlane_b32 s0, v1, 0
	v_readlane_b32 s1, v1, 32
	v_mov_b32_e32 v194, s2
	v_mov_b32_e32 v195, s3
	v_add_f32_e64 v194, s0, v194
	v_add_f32_e64 v195, s1, v195
	s_nop 0
	v_add_f32_e32 v1, v194, v195
	v_fmamk_f32 v1, v1, 0x3a000000, v227
	v_mul_f32_e32 v79, 0x4b800000, v1
	v_cmp_gt_f32_e32 vcc, s4, v1
	s_nop 1
	v_cndmask_b32_e32 v1, v1, v79, vcc
	v_rsq_f32_e32 v1, v1
	s_nop 0
	v_mul_f32_e32 v79, 0x45800000, v1
	v_cndmask_b32_e32 v194, v1, v79, vcc
	v_mul_f32_e64 v202, v2, v194
	v_mul_f32_e64 v203, v3, v194
	v_mul_f32_e64 v196, v4, v194
	v_mul_f32_e64 v197, v5, v194
	v_mul_f32_e64 v66, v66, v202
	v_mul_f32_e64 v67, v67, v203
	v_mul_f32_e64 v68, v68, v196
	v_mul_f32_e64 v69, v69, v197
	s_waitcnt vmcnt(0)
	v_fma_f32 v66, v70, v66, v74
	v_fma_f32 v67, v71, v67, v75
	v_fma_f32 v68, v72, v68, v76
	v_fma_f32 v69, v73, v69, v77
	v_cvt_pk_bf16_f32 v66, v66, v67
	v_lshl_add_u64 v[70:71], v[200:201], 0, v[144:145]
	v_cvt_pk_bf16_f32 v67, v68, v69
	global_store_dwordx2 v[192:193], v[66:67], off
	global_load_dwordx4 v[66:69], v[126:127], off offset:1024
	v_lshl_add_u64 v[74:75], v[198:199], 0, v[144:145]
	global_load_dwordx4 v[70:73], v[70:71], off
	v_mul_f32_e64 v202, v6, v194
	v_mul_f32_e64 v203, v7, v194
	global_load_dwordx4 v[74:77], v[74:75], off
	v_mul_f32_e64 v196, v8, v194
	v_mul_f32_e64 v197, v9, v194
	s_waitcnt vmcnt(2)
	v_mul_f32_e64 v66, v66, v202
	v_mul_f32_e64 v67, v67, v203
	v_mul_f32_e64 v68, v68, v196
	v_mul_f32_e64 v69, v69, v197
	s_waitcnt vmcnt(1)
	v_add_f32_e64 v70, v70, 1.0
	v_add_f32_e64 v71, v71, 1.0
	v_add_f32_e64 v72, v72, 1.0
	v_add_f32_e64 v73, v73, 1.0
	s_waitcnt vmcnt(0)
	v_fma_f32 v66, v70, v66, v74
	v_fma_f32 v67, v71, v67, v75
	v_fma_f32 v68, v72, v68, v76
	v_fma_f32 v69, v73, v69, v77
	v_cvt_pk_bf16_f32 v66, v66, v67
	v_lshl_add_u64 v[70:71], v[200:201], 0, v[146:147]
	v_cvt_pk_bf16_f32 v67, v68, v69
	global_store_dwordx2 v[192:193], v[66:67], off offset:512
	global_load_dwordx4 v[66:69], v[126:127], off offset:2048
	v_lshl_add_u64 v[74:75], v[198:199], 0, v[146:147]
	global_load_dwordx4 v[70:73], v[70:71], off
	v_mul_f32_e64 v202, v10, v194
	v_mul_f32_e64 v203, v11, v194
	global_load_dwordx4 v[74:77], v[74:75], off
	v_mul_f32_e64 v196, v12, v194
	v_mul_f32_e64 v197, v13, v194
	s_waitcnt vmcnt(2)
	v_mul_f32_e64 v66, v202, v66
	v_mul_f32_e64 v67, v203, v67
	v_mul_f32_e64 v68, v196, v68
	v_mul_f32_e64 v69, v197, v69
	s_waitcnt vmcnt(1)
	v_add_f32_e64 v70, v70, 1.0
	v_add_f32_e64 v71, v71, 1.0
	v_add_f32_e64 v72, v72, 1.0
	v_add_f32_e64 v73, v73, 1.0
	s_waitcnt vmcnt(0)
	v_fma_f32 v66, v66, v70, v74
	v_fma_f32 v67, v67, v71, v75
	v_fma_f32 v68, v68, v72, v76
	v_fma_f32 v69, v69, v73, v77
	v_cvt_pk_bf16_f32 v66, v66, v67
	v_lshl_add_u64 v[70:71], v[200:201], 0, v[148:149]
	v_cvt_pk_bf16_f32 v67, v68, v69
	global_store_dwordx2 v[192:193], v[66:67], off offset:1024
	global_load_dwordx4 v[66:69], v[126:127], off offset:3072
	v_lshl_add_u64 v[74:75], v[198:199], 0, v[148:149]
	global_load_dwordx4 v[70:73], v[70:71], off
	v_mul_f32_e64 v202, v14, v194
	v_mul_f32_e64 v203, v15, v194
	global_load_dwordx4 v[74:77], v[74:75], off
	v_mul_f32_e64 v196, v16, v194
	v_mul_f32_e64 v197, v17, v194
	s_waitcnt vmcnt(2)
	v_mul_f32_e64 v66, v202, v66
	v_mul_f32_e64 v67, v203, v67
	v_mul_f32_e64 v68, v196, v68
	v_mul_f32_e64 v69, v197, v69
	s_waitcnt vmcnt(1)
	v_add_f32_e64 v70, v70, 1.0
	v_add_f32_e64 v71, v71, 1.0
	v_add_f32_e64 v72, v72, 1.0
	v_add_f32_e64 v73, v73, 1.0
	s_waitcnt vmcnt(0)
; __device__ __forceinline__ unsigned cvtpk(float lo, float hi) { unsigned r; asm volatile("v_cvt_pk_bf16_f32 %0, %1, %2" : "=v"(r) : "v"(lo), "v"(hi)); return r; }
; __device__ __forceinline__ void prenorm_row(const f32x4 (&x)[8], float rinv, const float* g, const float* sc, const float* sh, bf16_t* dst, int lane) {
; #pragma unroll
;   for (int i = 0; i < 8; ++i) { const int col = (lane + 64 * i) * 4; const f32x4 gg = *(const f32x4*)(g + col), s1 = *(const f32x4*)(sc + col), s0 = *(const f32x4*)(sh + col);
;     const f32x4 y = (x[i] * rinv * gg) * (s1 + 1.f) + s0; u32x2 o = {cvtpk(y[0], y[1]), cvtpk(y[2], y[3])}; *(u32x2*)(dst + col) = o; }
; }
; __device__ __forceinline__ void phase_postmix(const Params& p, const Ctx& c, int l, bool last) {
;     ...
;   for (;;) { int nrow = row + c.nwave; while (nrow < TT && !valid(nrow)) nrow += c.nwave;
;     if (nrow < TT) load(nrow, mB, xB);
;     process(row, mA, xA);
;     if (nrow >= TT) break;
; #pragma unroll
;     for (int i = 0; i < 8; ++i) { mA[i] = mB[i]; xA[i] = xB[i]; }
;     row = nrow; }
	v_fma_f32 v66, v66, v70, v74
	v_fma_f32 v67, v67, v71, v75
	v_fma_f32 v68, v68, v72, v76
	v_fma_f32 v69, v69, v73, v77
	v_cvt_pk_bf16_f32 v66, v66, v67
	v_lshl_add_u64 v[70:71], v[200:201], 0, v[150:151]
	v_cvt_pk_bf16_f32 v67, v68, v69
	global_store_dwordx2 v[192:193], v[66:67], off offset:1536
	global_load_dwordx4 v[66:69], v[130:131], off
	v_lshl_add_u64 v[74:75], v[198:199], 0, v[150:151]
	global_load_dwordx4 v[70:73], v[70:71], off
	v_mul_f32_e64 v202, v18, v194
	v_mul_f32_e64 v203, v19, v194
	global_load_dwordx4 v[74:77], v[74:75], off
	v_mul_f32_e64 v196, v20, v194
	v_mul_f32_e64 v197, v21, v194
	s_waitcnt vmcnt(2)
	v_mul_f32_e64 v66, v202, v66
	v_mul_f32_e64 v67, v203, v67
	v_mul_f32_e64 v68, v196, v68
	v_mul_f32_e64 v69, v197, v69
	s_waitcnt vmcnt(1)
	v_add_f32_e64 v70, v70, 1.0
	v_add_f32_e64 v71, v71, 1.0
	v_add_f32_e64 v72, v72, 1.0
	v_add_f32_e64 v73, v73, 1.0
	s_waitcnt vmcnt(0)
	v_fma_f32 v66, v66, v70, v74
	v_fma_f32 v67, v67, v71, v75
	v_fma_f32 v68, v68, v72, v76
	v_fma_f32 v69, v69, v73, v77
	v_cvt_pk_bf16_f32 v66, v66, v67
	v_lshl_add_u64 v[70:71], v[200:201], 0, v[152:153]
	v_cvt_pk_bf16_f32 v67, v68, v69
	global_store_dwordx2 v[192:193], v[66:67], off offset:2048
	global_load_dwordx4 v[66:69], v[132:133], off
	v_lshl_add_u64 v[74:75], v[198:199], 0, v[152:153]
	global_load_dwordx4 v[70:73], v[70:71], off
	v_mul_f32_e64 v202, v22, v194
	v_mul_f32_e64 v203, v23, v194
	global_load_dwordx4 v[74:77], v[74:75], off
	v_mul_f32_e64 v196, v24, v194
	v_mul_f32_e64 v197, v25, v194
	s_waitcnt vmcnt(2)
	v_mul_f32_e64 v66, v202, v66
	v_mul_f32_e64 v67, v203, v67
	v_mul_f32_e64 v68, v196, v68
	v_mul_f32_e64 v69, v197, v69
	s_waitcnt vmcnt(1)
	v_add_f32_e64 v70, v70, 1.0
	v_add_f32_e64 v71, v71, 1.0
	v_add_f32_e64 v72, v72, 1.0
	v_add_f32_e64 v73, v73, 1.0
	s_waitcnt vmcnt(0)
	v_fma_f32 v66, v66, v70, v74
	v_fma_f32 v67, v67, v71, v75
	v_fma_f32 v68, v68, v72, v76
	v_fma_f32 v69, v69, v73, v77
	v_cvt_pk_bf16_f32 v66, v66, v67
	v_lshl_add_u64 v[70:71], v[200:201], 0, v[154:155]
	v_cvt_pk_bf16_f32 v67, v68, v69
	global_store_dwordx2 v[192:193], v[66:67], off offset:2560
	global_load_dwordx4 v[66:69], v[134:135], off
	v_lshl_add_u64 v[74:75], v[198:199], 0, v[154:155]
	global_load_dwordx4 v[70:73], v[70:71], off
	v_mul_f32_e64 v202, v26, v194
	v_mul_f32_e64 v203, v27, v194
	global_load_dwordx4 v[74:77], v[74:75], off
	v_mul_f32_e64 v196, v28, v194
	v_mul_f32_e64 v197, v29, v194
	s_waitcnt vmcnt(2)
	v_mul_f32_e64 v66, v202, v66
	v_mul_f32_e64 v67, v203, v67
	v_mul_f32_e64 v68, v196, v68
	v_mul_f32_e64 v69, v197, v69
	s_waitcnt vmcnt(1)
	v_add_f32_e64 v70, v70, 1.0
	v_add_f32_e64 v71, v71, 1.0
	v_add_f32_e64 v72, v72, 1.0
	v_add_f32_e64 v73, v73, 1.0
	s_waitcnt vmcnt(0)
	v_fma_f32 v66, v66, v70, v74
	v_fma_f32 v67, v67, v71, v75
	v_fma_f32 v68, v68, v72, v76
	v_fma_f32 v69, v69, v73, v77
	v_cvt_pk_bf16_f32 v66, v66, v67
	v_lshl_add_u64 v[70:71], v[200:201], 0, v[156:157]
	v_cvt_pk_bf16_f32 v67, v68, v69
	global_store_dwordx2 v[192:193], v[66:67], off offset:3072
	global_load_dwordx4 v[66:69], v[136:137], off
	v_lshl_add_u64 v[74:75], v[198:199], 0, v[156:157]
	global_load_dwordx4 v[70:73], v[70:71], off
	v_mul_f32_e64 v196, v32, v194
	v_mul_f32_e64 v197, v33, v194
	global_load_dwordx4 v[74:77], v[74:75], off
	v_mul_f32_e64 v195, v31, v194
	v_mul_f32_e64 v194, v30, v194
	s_waitcnt vmcnt(2)
	v_mul_f32_e64 v68, v196, v68
	v_mul_f32_e64 v69, v197, v69
	v_mul_f32_e64 v66, v194, v66
	v_mul_f32_e64 v67, v195, v67
	s_waitcnt vmcnt(1)
	v_add_f32_e64 v70, v70, 1.0
	v_add_f32_e64 v71, v71, 1.0
	v_add_f32_e64 v72, v72, 1.0
	v_add_f32_e64 v73, v73, 1.0
	s_waitcnt vmcnt(0)
	v_fma_f32 v66, v66, v70, v74
	v_fma_f32 v67, v67, v71, v75
	v_fma_f32 v68, v68, v72, v76
	v_fma_f32 v69, v69, v73, v77
	v_cvt_pk_bf16_f32 v66, v66, v67
	s_nop 0
	v_cvt_pk_bf16_f32 v67, v68, v69
	global_store_dwordx2 v[192:193], v[66:67], off offset:3584
	s_and_saveexec_b64 s[58:59], s[56:57]
	s_cbranch_execz .LBB0_1017
	v_mov_b64_e32 v[30:31], v[62:63]
	v_mov_b64_e32 v[26:27], v[58:59]
	v_mov_b64_e32 v[22:23], v[54:55]
	v_mov_b64_e32 v[18:19], v[50:51]
	v_mov_b64_e32 v[14:15], v[46:47]
	v_mov_b64_e32 v[10:11], v[42:43]
	v_mov_b64_e32 v[6:7], v[38:39]
	v_mov_b64_e32 v[2:3], v[34:35]
	v_mov_b64_e32 v[32:33], v[64:65]
	v_mov_b64_e32 v[28:29], v[60:61]
	v_mov_b64_e32 v[24:25], v[56:57]
	v_mov_b64_e32 v[20:21], v[52:53]
	v_mov_b64_e32 v[16:17], v[48:49]
	v_mov_b64_e32 v[12:13], v[44:45]
	v_mov_b64_e32 v[8:9], v[40:41]
	v_mov_b64_e32 v[4:5], v[36:37]
	v_mov_b32_e32 v78, v158
	v_mov_b32_e32 v94, v172
	v_mov_b32_e32 v95, v173
	v_mov_b32_e32 v96, v174
	v_mov_b32_e32 v97, v175
	v_mov_b32_e32 v82, v188
	v_mov_b32_e32 v83, v189
	v_mov_b32_e32 v84, v190
	v_mov_b32_e32 v85, v191
	v_mov_b32_e32 v86, v180
	v_mov_b32_e32 v87, v181
	v_mov_b32_e32 v88, v184
	v_mov_b32_e32 v89, v185
	v_mov_b32_e32 v90, v176
	v_mov_b32_e32 v91, v177
	v_mov_b32_e32 v92, v178
	v_mov_b32_e32 v93, v179
	v_mov_b32_e32 v104, v182
	v_mov_b32_e32 v105, v183
	v_mov_b32_e32 v108, v186
	v_mov_b32_e32 v109, v187
	v_mov_b32_e32 v98, v168
	v_mov_b32_e32 v99, v169
	v_mov_b32_e32 v100, v170
	v_mov_b32_e32 v101, v171
	v_mov_b32_e32 v102, v164
	v_mov_b32_e32 v103, v165
	v_mov_b32_e32 v106, v166
	v_mov_b32_e32 v107, v167
	v_mov_b32_e32 v110, v160
	v_mov_b32_e32 v111, v161
	v_mov_b32_e32 v112, v162
	v_mov_b32_e32 v113, v163
	s_branch .LBB0_1017

; __device__ __forceinline__ void ssm_build_t(const Params& p, const Ctx& c, int l) {
;     ...
;     else { const float* m0 = MK + ((size_t)((g * 2) * 32) * 16 + h) * 16 + hh * 8; const float* m1 = MK + ((size_t)((g * 2 + 1) * 32) * 16 + h) * 16 + hh * 8; const float dsk = p.ssm_d[(size_t)l * 512 + g * 16 + h];
; #pragma unroll
;       for (int k = 0; k < 8; ++k) v[k] = m0[k] + m1[k] + ((hh * 8 + k) == h ? dsk : 0.f); }
.LBB0_1293:
	s_andn2_saveexec_b64 s[54:55], s[54:55]
	s_cbranch_execz .LBB0_1290
	s_waitcnt vmcnt(0)
	v_lshlrev_b32_e32 v12, 4, v21
	v_ashrrev_i32_e32 v13, 31, v12
	v_lshl_add_u64 v[12:13], v[12:13], 2, s[6:7]
	v_lshlrev_b32_e32 v14, 2, v1
	v_mov_b32_e32 v15, v0
	v_lshlrev_b32_e32 v10, 6, v21
	v_lshl_add_u64 v[12:13], v[12:13], 0, v[14:15]
	global_load_dword v25, v[12:13], off offset:2048
	v_ashrrev_i32_e32 v11, 31, v10
	v_lshlrev_b64 v[12:13], 10, v[10:11]
	v_or_b32_e32 v10, 32, v10
	v_ashrrev_i32_e32 v11, 31, v10
	v_lshlrev_b64 v[10:11], 10, v[10:11]
	v_lshl_add_u64 v[12:13], s[10:11], 0, v[12:13]
	v_mov_b32_e32 v23, v0
	v_lshl_add_u64 v[10:11], s[10:11], 0, v[10:11]
	v_lshl_add_u64 v[12:13], v[12:13], 0, v[22:23]
	v_mov_b32_e32 v21, v0
	v_lshl_add_u64 v[10:11], v[10:11], 0, v[22:23]
	v_lshl_add_u64 v[26:27], v[12:13], 0, v[20:21]
	v_lshl_add_u64 v[28:29], v[10:11], 0, v[20:21]
	global_load_dwordx4 v[10:13], v[28:29], off
	global_load_dwordx4 v[14:17], v[26:27], off
	global_load_dwordx4 v[20:23], v[26:27], off offset:16
	s_nop 0
	global_load_dwordx4 v[26:29], v[28:29], off offset:16
	v_cmp_eq_u32_e32 vcc, v3, v1
	s_waitcnt vmcnt(2)
	v_add_f32_e64 v14, v14, v10
	v_add_f32_e64 v15, v15, v11
	v_cndmask_b32_e32 v31, 0, v25, vcc
	v_cmp_eq_u32_e32 vcc, v2, v1
	v_add_f32_e64 v16, v16, v12
	v_add_f32_e64 v17, v17, v13
	s_waitcnt vmcnt(0)
	v_add_f32_e64 v10, v20, v26
	v_add_f32_e64 v11, v21, v27
	v_cndmask_b32_e32 v30, 0, v25, vcc
	v_cmp_eq_u32_e32 vcc, v5, v1
	v_add_f32_e64 v12, v22, v28
	v_add_f32_e64 v13, v23, v29
	v_add_f32_e64 v14, v30, v14
	v_add_f32_e64 v15, v31, v15
	v_cndmask_b32_e32 v33, 0, v25, vcc
	v_cmp_eq_u32_e32 vcc, v4, v1
	s_nop 1
	v_cndmask_b32_e32 v32, 0, v25, vcc
	v_cmp_eq_u32_e32 vcc, v7, v1
	v_add_f32_e64 v16, v32, v16
	v_add_f32_e64 v17, v33, v17
	s_nop 0
	v_cndmask_b32_e32 v35, 0, v25, vcc
	v_cmp_eq_u32_e32 vcc, v6, v1
	s_nop 1
	v_cndmask_b32_e32 v34, 0, v25, vcc
	v_cmp_eq_u32_e32 vcc, v9, v1
	v_add_f32_e64 v10, v34, v10
	v_add_f32_e64 v11, v35, v11
	s_nop 0
	v_cndmask_b32_e32 v37, 0, v25, vcc
	v_cmp_eq_u32_e32 vcc, v8, v1
	s_nop 1
	v_cndmask_b32_e32 v36, 0, v25, vcc
	v_add_f32_e64 v12, v36, v12
	v_add_f32_e64 v13, v37, v13
	s_branch .LBB0_1290

; __device__ __forceinline__ f32x4 ldx(const _Float16* p) { const h16x4 h = *(const h16x4*)p; return __builtin_convertvector(h, f32x4); }
; __device__ __forceinline__ f32x4 bf4(const u32x2 w) { return (f32x4){__uint_as_float(w[0] << 16), __uint_as_float(w[0] & 0xffff0000u), __uint_as_float(w[1] << 16), __uint_as_float(w[1] & 0xffff0000u)}; }
; __device__ __forceinline__ void phase_postffn(const Params& p, const Ctx& c, int l, bool last) {
;     ...
;   auto load = [&](int row, f32x4 (&m)[8], f32x4 (&x)[8]) { const int b = row / TPB, t = row % TPB;
;     const u32x2* mr = (const u32x2*)(F + (size_t)row * DM); const _Float16* xr = X + (size_t)row * DM;
;     if (t < CTXL) { const u32x2* sl = (const u32x2*)(p.ws + OFF_Z1) + ((size_t)b * CTXL + t) * (DM / 4);
; #pragma unroll
;       for (int i = 0; i < 8; ++i) { m[i] = (f32x4){0.f, 0.f, 0.f, 0.f}; x[i] = ldx(xr + (c.lane + 64 * i) * 4); }
;       for (int s = 0; s < 11; ++s) {
; #pragma unroll
;         for (int i = 0; i < 8; ++i) m[i] += bf4(sl[(size_t)s * NB * CTXL * (DM / 4) + c.lane + 64 * i]); } }
.LBB0_1306:
	v_lshl_add_u64 v[22:23], v[20:21], 0, s[14:15]
	v_add_co_u32_e32 v60, vcc, s77, v22
	s_cmp_eq_u32 s14, 0x2800000
	s_nop 0
	v_addc_co_u32_e32 v61, vcc, 0, v23, vcc
	global_load_dwordx2 v[56:57], v[60:61], off
	global_load_dwordx2 v[58:59], v[60:61], off offset:512
	global_load_dwordx2 v[62:63], v[60:61], off offset:1024
	global_load_dwordx2 v[64:65], v[60:61], off offset:1536
	global_load_dwordx2 v[66:67], v[60:61], off offset:2048
	global_load_dwordx2 v[68:69], v[60:61], off offset:2560
	global_load_dwordx2 v[70:71], v[60:61], off offset:3072
	s_nop 0
	global_load_dwordx2 v[60:61], v[60:61], off offset:3584
	s_mov_b64 s[52:53], -1
	s_waitcnt vmcnt(7)
	v_lshlrev_b32_e32 v72, 16, v56
	v_and_b32_e32 v73, 0xffff0000, v56
	v_lshlrev_b32_e32 v56, 16, v57
	v_and_b32_e32 v57, 0xffff0000, v57
	s_waitcnt vmcnt(6)
	v_lshlrev_b32_e32 v74, 16, v58
	v_and_b32_e32 v75, 0xffff0000, v58
	v_lshlrev_b32_e32 v58, 16, v59
	v_and_b32_e32 v59, 0xffff0000, v59
	s_waitcnt vmcnt(5)
	v_lshlrev_b32_e32 v76, 16, v62
	v_and_b32_e32 v77, 0xffff0000, v62
	v_lshlrev_b32_e32 v62, 16, v63
	v_and_b32_e32 v63, 0xffff0000, v63
	s_waitcnt vmcnt(4)
	v_lshlrev_b32_e32 v78, 16, v64
	v_and_b32_e32 v79, 0xffff0000, v64
	v_lshlrev_b32_e32 v64, 16, v65
	v_and_b32_e32 v65, 0xffff0000, v65
	s_waitcnt vmcnt(3)
	v_lshlrev_b32_e32 v80, 16, v66
	v_and_b32_e32 v81, 0xffff0000, v66
	v_lshlrev_b32_e32 v66, 16, v67
	v_and_b32_e32 v67, 0xffff0000, v67
	s_waitcnt vmcnt(2)
	v_lshlrev_b32_e32 v104, 16, v68
	v_and_b32_e32 v105, 0xffff0000, v68
	v_lshlrev_b32_e32 v68, 16, v69
	v_and_b32_e32 v69, 0xffff0000, v69
	s_waitcnt vmcnt(1)
	v_lshlrev_b32_e32 v112, 16, v70
	v_and_b32_e32 v113, 0xffff0000, v70
	v_lshlrev_b32_e32 v70, 16, v71
	v_and_b32_e32 v71, 0xffff0000, v71
	s_waitcnt vmcnt(0)
	v_lshlrev_b32_e32 v118, 16, v60
	v_and_b32_e32 v119, 0xffff0000, v60
	v_lshlrev_b32_e32 v60, 16, v61
	v_and_b32_e32 v61, 0xffff0000, v61
	v_add_f32_e64 v88, v54, v56
	v_add_f32_e64 v89, v55, v57
	v_add_f32_e64 v100, v52, v72
	v_add_f32_e64 v101, v53, v73
	v_add_f32_e64 v90, v50, v58
	v_add_f32_e64 v91, v51, v59
	v_add_f32_e64 v102, v48, v74
	v_add_f32_e64 v103, v49, v75
	v_add_f32_e64 v92, v46, v62
	v_add_f32_e64 v93, v47, v63
	v_add_f32_e64 v106, v44, v76
	v_add_f32_e64 v107, v45, v77
	v_add_f32_e64 v94, v42, v64
	v_add_f32_e64 v95, v43, v65
	v_add_f32_e64 v108, v40, v78
	v_add_f32_e64 v109, v41, v79
	v_add_f32_e64 v96, v38, v66
	v_add_f32_e64 v97, v39, v67
	v_add_f32_e64 v110, v36, v80
	v_add_f32_e64 v111, v37, v81
	v_add_f32_e64 v98, v34, v68
	v_add_f32_e64 v99, v35, v69
	v_add_f32_e64 v114, v32, v104
	v_add_f32_e64 v115, v33, v105
	v_add_f32_e64 v104, v30, v70
	v_add_f32_e64 v105, v31, v71
	v_add_f32_e64 v116, v28, v112
	v_add_f32_e64 v117, v29, v113
	v_add_f32_e64 v112, v26, v60
	v_add_f32_e64 v113, v27, v61
	v_add_f32_e64 v118, v24, v118
	v_add_f32_e64 v119, v25, v119
	s_cbranch_scc1 .LBB0_1305
	v_add_co_u32_e32 v22, vcc, 0x118d0000, v22
	s_add_u32 s14, s14, 0x800000
	s_nop 0
	v_addc_co_u32_e32 v23, vcc, 0, v23, vcc
	global_load_dwordx2 v[24:25], v[22:23], off
	global_load_dwordx2 v[26:27], v[22:23], off offset:512
	global_load_dwordx2 v[28:29], v[22:23], off offset:1024
	global_load_dwordx2 v[30:31], v[22:23], off offset:1536
	global_load_dwordx2 v[32:33], v[22:23], off offset:2048
	global_load_dwordx2 v[34:35], v[22:23], off offset:2560
	global_load_dwordx2 v[36:37], v[22:23], off offset:3072
	s_nop 0
	global_load_dwordx2 v[22:23], v[22:23], off offset:3584
	s_addc_u32 s15, s15, 0
	s_mov_b64 s[52:53], 0
	s_waitcnt vmcnt(7)
	v_lshlrev_b32_e32 v38, 16, v24
	v_and_b32_e32 v39, 0xffff0000, v24
	v_lshlrev_b32_e32 v24, 16, v25
	v_and_b32_e32 v25, 0xffff0000, v25
	s_waitcnt vmcnt(6)
	v_lshlrev_b32_e32 v40, 16, v26
	v_and_b32_e32 v41, 0xffff0000, v26
	v_lshlrev_b32_e32 v26, 16, v27
	v_and_b32_e32 v27, 0xffff0000, v27
	s_waitcnt vmcnt(5)
	v_lshlrev_b32_e32 v42, 16, v28
	v_and_b32_e32 v43, 0xffff0000, v28
	v_lshlrev_b32_e32 v28, 16, v29
	v_and_b32_e32 v29, 0xffff0000, v29
	s_waitcnt vmcnt(4)
	v_lshlrev_b32_e32 v56, 16, v30
	v_and_b32_e32 v57, 0xffff0000, v30
	v_lshlrev_b32_e32 v30, 16, v31
	v_and_b32_e32 v31, 0xffff0000, v31
	s_waitcnt vmcnt(3)
	v_lshlrev_b32_e32 v58, 16, v32
	v_and_b32_e32 v59, 0xffff0000, v32
	v_lshlrev_b32_e32 v32, 16, v33
	v_and_b32_e32 v33, 0xffff0000, v33
	s_waitcnt vmcnt(2)
	v_lshlrev_b32_e32 v60, 16, v34
	v_and_b32_e32 v61, 0xffff0000, v34
	v_lshlrev_b32_e32 v34, 16, v35
	v_and_b32_e32 v35, 0xffff0000, v35
	s_waitcnt vmcnt(1)
	v_lshlrev_b32_e32 v62, 16, v36
	v_and_b32_e32 v63, 0xffff0000, v36
	v_lshlrev_b32_e32 v64, 16, v37
	v_and_b32_e32 v65, 0xffff0000, v37
	s_waitcnt vmcnt(0)
	v_lshlrev_b32_e32 v66, 16, v22
	v_and_b32_e32 v67, 0xffff0000, v22
	v_lshlrev_b32_e32 v22, 16, v23
	v_and_b32_e32 v23, 0xffff0000, v23
	v_add_f32_e64 v54, v88, v24
	v_add_f32_e64 v55, v89, v25
	v_add_f32_e64 v52, v100, v38
	v_add_f32_e64 v53, v101, v39
	v_add_f32_e64 v50, v90, v26
	v_add_f32_e64 v51, v91, v27
	v_add_f32_e64 v48, v102, v40
	v_add_f32_e64 v49, v103, v41
	v_add_f32_e64 v46, v92, v28
	v_add_f32_e64 v47, v93, v29
	v_add_f32_e64 v44, v106, v42
	v_add_f32_e64 v45, v107, v43
	v_add_f32_e64 v42, v94, v30
	v_add_f32_e64 v43, v95, v31
	v_add_f32_e64 v40, v108, v56
	v_add_f32_e64 v41, v109, v57
	v_add_f32_e64 v38, v96, v32
	v_add_f32_e64 v39, v97, v33
	v_add_f32_e64 v36, v110, v58
	v_add_f32_e64 v37, v111, v59
	v_add_f32_e64 v34, v98, v34
	v_add_f32_e64 v35, v99, v35
	v_add_f32_e64 v32, v114, v60
	v_add_f32_e64 v33, v115, v61
	v_add_f32_e64 v30, v104, v64
	v_add_f32_e64 v31, v105, v65
	v_add_f32_e64 v28, v116, v62
	v_add_f32_e64 v29, v117, v63
	v_add_f32_e64 v26, v112, v22
	v_add_f32_e64 v27, v113, v23
	v_add_f32_e64 v24, v118, v66
	v_add_f32_e64 v25, v119, v67
	s_branch .LBB0_1305

; __device__ __forceinline__ f32x4 ldx(const _Float16* p) { const h16x4 h = *(const h16x4*)p; return __builtin_convertvector(h, f32x4); }
; __device__ __forceinline__ f32x4 bf4(const u32x2 w) { return (f32x4){__uint_as_float(w[0] << 16), __uint_as_float(w[0] & 0xffff0000u), __uint_as_float(w[1] << 16), __uint_as_float(w[1] & 0xffff0000u)}; }
; __device__ __forceinline__ void phase_postffn(const Params& p, const Ctx& c, int l, bool last) {
;     ...
;   auto load = [&](int row, f32x4 (&m)[8], f32x4 (&x)[8]) { const int b = row / TPB, t = row % TPB;
;     const u32x2* mr = (const u32x2*)(F + (size_t)row * DM); const _Float16* xr = X + (size_t)row * DM;
;     if (t < CTXL) { const u32x2* sl = (const u32x2*)(p.ws + OFF_Z1) + ((size_t)b * CTXL + t) * (DM / 4);
; #pragma unroll
;       for (int i = 0; i < 8; ++i) { m[i] = (f32x4){0.f, 0.f, 0.f, 0.f}; x[i] = ldx(xr + (c.lane + 64 * i) * 4); }
;       for (int s = 0; s < 11; ++s) {
; #pragma unroll
;         for (int i = 0; i < 8; ++i) m[i] += bf4(sl[(size_t)s * NB * CTXL * (DM / 4) + c.lane + 64 * i]); } }
.LBB0_1321:
	v_lshl_add_u64 v[4:5], v[2:3], 0, s[56:57]
	v_add_co_u32_e32 v58, vcc, s77, v4
	s_cmp_eq_u32 s56, 0x2800000
	s_nop 0
	v_addc_co_u32_e32 v59, vcc, 0, v5, vcc
	global_load_dwordx2 v[54:55], v[58:59], off
	global_load_dwordx2 v[56:57], v[58:59], off offset:512
	global_load_dwordx2 v[60:61], v[58:59], off offset:1024
	global_load_dwordx2 v[62:63], v[58:59], off offset:1536
	global_load_dwordx2 v[64:65], v[58:59], off offset:2048
	global_load_dwordx2 v[66:67], v[58:59], off offset:2560
	global_load_dwordx2 v[68:69], v[58:59], off offset:3072
	s_nop 0
	global_load_dwordx2 v[58:59], v[58:59], off offset:3584
	s_mov_b64 s[58:59], -1
	s_waitcnt vmcnt(7)
	v_lshlrev_b32_e32 v70, 16, v54
	v_and_b32_e32 v71, 0xffff0000, v54
	v_lshlrev_b32_e32 v54, 16, v55
	v_and_b32_e32 v55, 0xffff0000, v55
	s_waitcnt vmcnt(6)
	v_lshlrev_b32_e32 v72, 16, v56
	v_and_b32_e32 v73, 0xffff0000, v56
	v_lshlrev_b32_e32 v56, 16, v57
	v_and_b32_e32 v57, 0xffff0000, v57
	s_waitcnt vmcnt(5)
	v_lshlrev_b32_e32 v74, 16, v60
	v_and_b32_e32 v75, 0xffff0000, v60
	v_lshlrev_b32_e32 v60, 16, v61
	v_and_b32_e32 v61, 0xffff0000, v61
	s_waitcnt vmcnt(4)
	v_lshlrev_b32_e32 v76, 16, v62
	v_and_b32_e32 v77, 0xffff0000, v62
	v_lshlrev_b32_e32 v62, 16, v63
	v_and_b32_e32 v63, 0xffff0000, v63
	s_waitcnt vmcnt(3)
	v_lshlrev_b32_e32 v78, 16, v64
	v_and_b32_e32 v79, 0xffff0000, v64
	v_lshlrev_b32_e32 v64, 16, v65
	v_and_b32_e32 v65, 0xffff0000, v65
	s_waitcnt vmcnt(2)
	v_lshlrev_b32_e32 v80, 16, v66
	v_and_b32_e32 v81, 0xffff0000, v66
	v_lshlrev_b32_e32 v66, 16, v67
	v_and_b32_e32 v67, 0xffff0000, v67
	s_waitcnt vmcnt(1)
	v_lshlrev_b32_e32 v112, 16, v68
	v_and_b32_e32 v113, 0xffff0000, v68
	v_lshlrev_b32_e32 v68, 16, v69
	v_and_b32_e32 v69, 0xffff0000, v69
	s_waitcnt vmcnt(0)
	v_lshlrev_b32_e32 v118, 16, v58
	v_and_b32_e32 v119, 0xffff0000, v58
	v_lshlrev_b32_e32 v58, 16, v59
	v_and_b32_e32 v59, 0xffff0000, v59
	v_add_f32_e64 v88, v52, v54
	v_add_f32_e64 v89, v53, v55
	v_add_f32_e64 v100, v50, v70
	v_add_f32_e64 v101, v51, v71
	v_add_f32_e64 v90, v48, v56
	v_add_f32_e64 v91, v49, v57
	v_add_f32_e64 v102, v46, v72
	v_add_f32_e64 v103, v47, v73
	v_add_f32_e64 v92, v44, v60
	v_add_f32_e64 v93, v45, v61
	v_add_f32_e64 v106, v42, v74
	v_add_f32_e64 v107, v43, v75
	v_add_f32_e64 v94, v40, v62
	v_add_f32_e64 v95, v41, v63
	v_add_f32_e64 v108, v38, v76
	v_add_f32_e64 v109, v39, v77
	v_add_f32_e64 v96, v36, v64
	v_add_f32_e64 v97, v37, v65
	v_add_f32_e64 v110, v32, v78
	v_add_f32_e64 v111, v33, v79
	v_add_f32_e64 v98, v28, v66
	v_add_f32_e64 v99, v29, v67
	v_add_f32_e64 v114, v24, v80
	v_add_f32_e64 v115, v25, v81
	v_add_f32_e64 v104, v20, v68
	v_add_f32_e64 v105, v21, v69
	v_add_f32_e64 v116, v16, v112
	v_add_f32_e64 v117, v17, v113
	v_add_f32_e64 v112, v12, v58
	v_add_f32_e64 v113, v13, v59
	v_add_f32_e64 v118, v8, v118
	v_add_f32_e64 v119, v9, v119
	s_cbranch_scc1 .LBB0_1320
	v_add_co_u32_e32 v4, vcc, 0x118d0000, v4
	s_add_u32 s56, s56, 0x800000
	s_nop 0
	v_addc_co_u32_e32 v5, vcc, 0, v5, vcc
	global_load_dwordx2 v[8:9], v[4:5], off
	global_load_dwordx2 v[12:13], v[4:5], off offset:512
	global_load_dwordx2 v[16:17], v[4:5], off offset:1024
	global_load_dwordx2 v[20:21], v[4:5], off offset:1536
	global_load_dwordx2 v[24:25], v[4:5], off offset:2048
	global_load_dwordx2 v[28:29], v[4:5], off offset:2560
	global_load_dwordx2 v[32:33], v[4:5], off offset:3072
	s_nop 0
	global_load_dwordx2 v[4:5], v[4:5], off offset:3584
	s_addc_u32 s57, s57, 0
	s_mov_b64 s[58:59], 0
	s_waitcnt vmcnt(7)
	v_lshlrev_b32_e32 v36, 16, v8
	v_and_b32_e32 v37, 0xffff0000, v8
	v_lshlrev_b32_e32 v8, 16, v9
	v_and_b32_e32 v9, 0xffff0000, v9
	s_waitcnt vmcnt(6)
	v_lshlrev_b32_e32 v38, 16, v12
	v_and_b32_e32 v39, 0xffff0000, v12
	v_lshlrev_b32_e32 v12, 16, v13
	v_and_b32_e32 v13, 0xffff0000, v13
	s_waitcnt vmcnt(5)
	v_lshlrev_b32_e32 v40, 16, v16
	v_and_b32_e32 v41, 0xffff0000, v16
	v_lshlrev_b32_e32 v16, 16, v17
	v_and_b32_e32 v17, 0xffff0000, v17
	s_waitcnt vmcnt(4)
	v_lshlrev_b32_e32 v54, 16, v20
	v_and_b32_e32 v55, 0xffff0000, v20
	v_lshlrev_b32_e32 v20, 16, v21
	v_and_b32_e32 v21, 0xffff0000, v21
	s_waitcnt vmcnt(3)
	v_lshlrev_b32_e32 v56, 16, v24
	v_and_b32_e32 v57, 0xffff0000, v24
	v_lshlrev_b32_e32 v24, 16, v25
	v_and_b32_e32 v25, 0xffff0000, v25
	s_waitcnt vmcnt(2)
	v_lshlrev_b32_e32 v58, 16, v28
	v_and_b32_e32 v59, 0xffff0000, v28
	v_lshlrev_b32_e32 v28, 16, v29
	v_and_b32_e32 v29, 0xffff0000, v29
	s_waitcnt vmcnt(1)
	v_lshlrev_b32_e32 v60, 16, v32
	v_and_b32_e32 v61, 0xffff0000, v32
	v_lshlrev_b32_e32 v62, 16, v33
	v_and_b32_e32 v63, 0xffff0000, v33
	s_waitcnt vmcnt(0)
	v_lshlrev_b32_e32 v64, 16, v4
	v_and_b32_e32 v65, 0xffff0000, v4
	v_lshlrev_b32_e32 v4, 16, v5
	v_and_b32_e32 v5, 0xffff0000, v5
	v_add_f32_e64 v52, v88, v8
	v_add_f32_e64 v53, v89, v9
	v_add_f32_e64 v50, v100, v36
	v_add_f32_e64 v51, v101, v37
	v_add_f32_e64 v48, v90, v12
	v_add_f32_e64 v49, v91, v13
	v_add_f32_e64 v46, v102, v38
	v_add_f32_e64 v47, v103, v39
	v_add_f32_e64 v44, v92, v16
	v_add_f32_e64 v45, v93, v17
	v_add_f32_e64 v42, v106, v40
	v_add_f32_e64 v43, v107, v41
	v_add_f32_e64 v40, v94, v20
	v_add_f32_e64 v41, v95, v21
	v_add_f32_e64 v38, v108, v54
	v_add_f32_e64 v39, v109, v55
	v_add_f32_e64 v36, v96, v24
	v_add_f32_e64 v37, v97, v25
	v_add_f32_e64 v32, v110, v56
	v_add_f32_e64 v33, v111, v57
	v_add_f32_e64 v28, v98, v28
	v_add_f32_e64 v29, v99, v29
	v_add_f32_e64 v24, v114, v58
	v_add_f32_e64 v25, v115, v59
	v_add_f32_e64 v20, v104, v62
	v_add_f32_e64 v21, v105, v63
	v_add_f32_e64 v16, v116, v60
	v_add_f32_e64 v17, v117, v61
	v_add_f32_e64 v12, v112, v4
	v_add_f32_e64 v13, v113, v5
	v_add_f32_e64 v8, v118, v64
	v_add_f32_e64 v9, v119, v65
	s_branch .LBB0_1320

; __device__ __forceinline__ const float* modp(const Params& p, int l, int v, int j) { return (const float*)(p.ws + OFF_MOD) + ((size_t)(l * 5 + v) * NMODC + (size_t)j * DM); }
; #pragma unroll
;   for (int i = 0; i < 8; ++i) s += x[i][0] * x[i][0] + x[i][1] * x[i][1] + x[i][2] * x[i][2] + x[i][3] * x[i][3];
;   return wave_sum(s); }
; __device__ __forceinline__ void phase_postffn(const Params& p, const Ctx& c, int l, bool last) {
;     ...
;   auto process = [&](int row, f32x4 (&m)[8], f32x4 (&x)[8]) { const int b = row / TPB, t = row % TPB, v = t < CTXL ? 4 : b; _Float16* xr = X + (size_t)row * DM;
;     const float r1 = rsqrtf(sumsq8(m) * (1.f / DM) + 1e-6f); const float* gp = p.g_ffn_post + (size_t)l * DM; const float* m5 = modp(p, l, v, 5);
; #pragma unroll
;     for (int i = 0; i < 8; ++i) { const int col = (c.lane + 64 * i) * 4; x[i] += *(const f32x4*)(m5 + col) * (m[i] * r1 * *(const f32x4*)(gp + col)); }
.LBB0_1325:
	s_or_b64 exec, exec, s[54:55]
	v_mul_hi_i32 v1, v180, s94
	v_lshrrev_b32_e32 v34, 31, v1
	v_ashrrev_i32_e32 v1, 11, v1
	v_add_u32_e32 v214, v1, v34
	v_mul_f32_e32 v34, v213, v213
	v_mul_f32_e32 v35, v209, v209
	v_mul_i32_i24_e32 v1, 0x1100, v214
	v_fmac_f32_e32 v34, v212, v212
	v_fmac_f32_e32 v35, v208, v208
	v_sub_u32_e32 v216, v180, v1
	v_fmac_f32_e32 v34, v210, v210
	v_fmac_f32_e32 v35, v206, v206
	v_cmp_lt_i32_e32 vcc, s27, v216
	v_fmac_f32_e32 v34, v211, v211
	v_fmac_f32_e32 v35, v207, v207
	v_mov_b32_e32 v36, v201
	v_mov_b32_e32 v37, v205
	v_cndmask_b32_e32 v1, 4, v214, vcc
	v_add_f32_e32 v46, v35, v34
	v_mov_b32_e32 v34, v200
	v_mov_b32_e32 v35, v204
	v_mul_f32_e64 v36, v36, v36
	v_mul_f32_e64 v37, v37, v37
	v_add_u32_e32 v1, s30, v1
	v_fma_f32 v34, v34, v34, v36
	v_fma_f32 v35, v35, v35, v37
	v_mov_b32_e32 v36, v198
	v_mov_b32_e32 v37, v202
	v_fma_f32 v42, v36, v36, v34
	v_fma_f32 v43, v37, v37, v35
	v_mul_hi_i32_i24_e32 v35, 0xc000, v1
	v_mul_i32_i24_e32 v34, 0xc000, v1
	v_lshl_add_u64 v[34:35], s[6:7], 0, v[34:35]
	s_mov_b64 s[0:1], 0xa84a000
	v_lshl_add_u64 v[66:67], v[34:35], 0, s[0:1]
	v_mov_b32_e32 v44, v199
	global_load_dwordx4 v[38:41], v[120:121], off
	v_lshl_add_u64 v[34:35], v[86:87], 2, v[66:67]
	v_mov_b32_e32 v45, v203
	global_load_dwordx4 v[34:37], v[34:35], off
	v_fma_f32 v50, v44, v44, v42
	v_fma_f32 v51, v45, v45, v43
	v_lshl_add_u64 v[42:43], v[122:123], 2, v[66:67]
	v_add_f32_e32 v51, v51, v46
	global_load_dwordx4 v[46:49], v[120:121], off offset:1024
	v_mov_b32_e32 v58, v193
	global_load_dwordx4 v[42:45], v[42:43], off
	v_mov_b32_e32 v59, v197
	v_add_f32_e32 v83, v50, v51
	v_mov_b32_e32 v68, v192
	v_mov_b32_e32 v69, v196
	global_load_dwordx4 v[54:57], v[120:121], off offset:2048
	global_load_dwordx4 v[62:65], v[120:121], off offset:3072
	v_lshl_add_u64 v[50:51], v[124:125], 2, v[66:67]
	v_mul_f32_e64 v70, v58, v58
	v_mul_f32_e64 v71, v59, v59
	global_load_dwordx4 v[50:53], v[50:51], off
	v_fma_f32 v68, v68, v68, v70
	v_fma_f32 v69, v69, v69, v71
	v_mov_b32_e32 v70, v190
	v_mov_b32_e32 v71, v194
	v_lshl_add_u64 v[58:59], v[126:127], 2, v[66:67]
	v_fma_f32 v68, v70, v70, v68
	v_fma_f32 v69, v71, v71, v69
	v_mov_b32_e32 v70, v191
	v_mov_b32_e32 v71, v195
	global_load_dwordx4 v[58:61], v[58:59], off
	v_fma_f32 v68, v70, v70, v68
	v_fma_f32 v69, v71, v71, v69
	global_load_dwordx4 v[78:81], v[130:131], off
	global_load_dwordx4 v[232:235], v[134:135], off
	v_lshl_add_u64 v[72:73], v[128:129], 2, v[66:67]
	v_add_f32_e32 v69, v69, v83
	global_load_dwordx4 v[74:77], v[72:73], off
	v_add_f32_e32 v83, v68, v69
	v_lshl_add_u64 v[68:69], v[136:137], 2, v[66:67]
	global_load_dwordx4 v[244:247], v[68:69], off
	v_lshl_add_u64 v[72:73], v[132:133], 2, v[66:67]
	global_load_dwordx4 v[236:239], v[72:73], off
	global_load_dwordx4 v[240:243], v[138:139], off
	v_lshl_add_u64 v[66:67], v[140:141], 2, v[66:67]
	global_load_dwordx4 v[66:69], v[66:67], off
	v_mov_b32_e32 v248, v185
	global_load_dwordx4 v[70:73], v[142:143], off
	v_mov_b32_e32 v249, v189
	v_mov_b32_e32 v218, v184
	v_mov_b32_e32 v219, v188
	v_mul_f32_e64 v248, v248, v248
	v_mul_f32_e64 v249, v249, v249
	s_mov_b64 s[54:55], -1
	v_fma_f32 v218, v218, v218, v248
	v_fma_f32 v219, v219, v219, v249
	v_mov_b32_e32 v248, v182
	v_mov_b32_e32 v249, v186
	v_fma_f32 v218, v248, v248, v218
	v_fma_f32 v219, v249, v249, v219
	v_mov_b32_e32 v248, v183
	v_mov_b32_e32 v249, v187
	v_fma_f32 v218, v248, v248, v218
	v_fma_f32 v219, v249, v249, v219
	s_nop 0
	v_add_f32_e32 v83, v219, v83
	v_add_f32_e32 v83, v218, v83
	s_nop 1
	v_add_f32_dpp v83, v83, v83 quad_perm:[1,0,3,2] row_mask:0xf bank_mask:0xf bound_ctrl:1
	s_nop 1
	v_add_f32_dpp v83, v83, v83 quad_perm:[2,3,0,1] row_mask:0xf bank_mask:0xf bound_ctrl:1
	s_nop 1
	v_add_f32_dpp v83, v83, v83 row_half_mirror row_mask:0xf bank_mask:0xf bound_ctrl:1
	s_nop 1
	v_add_f32_dpp v83, v83, v83 row_mirror row_mask:0xf bank_mask:0xf bound_ctrl:1
	s_nop 0
	v_readlane_b32 s3, v83, 16
	v_readlane_b32 s17, v83, 48
	v_readlane_b32 s0, v83, 0
	v_readlane_b32 s1, v83, 32
	v_mov_b32_e32 v218, s3
	v_mov_b32_e32 v219, s17
	v_add_f32_e64 v218, s0, v218
	v_add_f32_e64 v219, s1, v219
	s_mov_b32 s0, 0x800000
	v_add_f32_e32 v83, v218, v219
	v_fmamk_f32 v83, v83, 0x3a000000, v227
	v_mul_f32_e32 v181, 0x4b800000, v83
	v_cmp_gt_f32_e32 vcc, s0, v83
	s_nop 1
	v_cndmask_b32_e32 v83, v83, v181, vcc
	v_rsq_f32_e32 v83, v83
	s_nop 0
	v_mul_f32_e32 v181, 0x45800000, v83
	v_cndmask_b32_e32 v218, v83, v181, vcc
	v_mul_f32_e64 v210, v218, v210
	v_mul_f32_e64 v211, v218, v211
	v_mul_f32_e64 v212, v218, v212
	v_mul_f32_e64 v213, v218, v213
	s_waitcnt vmcnt(15)
	v_mul_f32_e64 v38, v38, v212
	v_mul_f32_e64 v39, v39, v213
	v_mul_f32_e64 v40, v40, v210
	v_mul_f32_e64 v41, v41, v211
	s_waitcnt vmcnt(14)
	v_fma_f32 v34, v34, v38, v178
	v_fma_f32 v35, v35, v39, v179
	v_fma_f32 v36, v36, v40, v176
	v_fma_f32 v37, v37, v41, v177
	v_mul_f32_e64 v38, v218, v206
	v_mul_f32_e64 v39, v218, v207
	v_mul_f32_e64 v40, v218, v208
	v_mul_f32_e64 v41, v218, v209
	s_waitcnt vmcnt(13)
	v_mul_f32_e64 v46, v46, v40
	v_mul_f32_e64 v47, v47, v41
	v_mul_f32_e64 v38, v48, v38
	v_mul_f32_e64 v39, v49, v39
	v_mul_f32_e64 v48, v218, v200
	v_mul_f32_e64 v49, v218, v201
	s_waitcnt vmcnt(12)
	v_fma_f32 v40, v44, v38, v172
	v_fma_f32 v41, v45, v39, v173
	v_fma_f32 v38, v42, v46, v174
	v_fma_f32 v39, v43, v47, v175
	v_mul_f32_e64 v42, v218, v202
	v_mul_f32_e64 v43, v218, v203
	v_mul_f32_e64 v44, v218, v204
	v_mul_f32_e64 v45, v218, v205
	s_waitcnt vmcnt(11)
	v_mul_f32_e64 v46, v54, v44
	v_mul_f32_e64 v47, v55, v45
	v_mul_f32_e64 v42, v56, v42
	v_mul_f32_e64 v43, v57, v43
	s_waitcnt vmcnt(10)
; __device__ __forceinline__ const float* modp(const Params& p, int l, int v, int j) { return (const float*)(p.ws + OFF_MOD) + ((size_t)(l * 5 + v) * NMODC + (size_t)j * DM); }
; __device__ __forceinline__ void stx(_Float16* p, f32x4 v) { *(h16x4*)p = __builtin_convertvector(v, h16x4); }
; __device__ __forceinline__ void phase_postffn(const Params& p, const Ctx& c, int l, bool last) {
;     ...
;     for (int i = 0; i < 8; ++i) { const int col = (c.lane + 64 * i) * 4; x[i] += *(const f32x4*)(m5 + col) * (m[i] * r1 * *(const f32x4*)(gp + col)); }
;     if (last) { f32x4* o = (f32x4*)(p.out + ((size_t)b * SEQ + (t - CTXL)) * DM);
; #pragma unroll
;       for (int i = 0; i < 8; ++i) o[c.lane + 64 * i] = x[i]; }
;     else {
; #pragma unroll
;       for (int i = 0; i < 8; ++i) stx(xr + (c.lane + 64 * i) * 4, x[i]);
;       const float r2 = rsqrtf(sumsq8(x) * (1.f / DM) + 1e-6f);
;       prenorm_row(x, r2, p.g_mix_pre + (size_t)(l + 1) * DM, modp(p, l + 1, v, 1), modp(p, l + 1, v, 0), Hn + (size_t)row * DM, c.lane); } };
	v_mul_f32_e64 v48, v62, v48
	v_mul_f32_e64 v49, v63, v49
	s_waitcnt vmcnt(9)
	v_fma_f32 v44, v52, v42, v168
	v_fma_f32 v45, v53, v43, v169
	v_fma_f32 v42, v50, v46, v170
	v_fma_f32 v43, v51, v47, v171
	v_mul_f32_e64 v46, v218, v198
	v_mul_f32_e64 v47, v218, v199
	v_mul_f32_e64 v46, v64, v46
	v_mul_f32_e64 v47, v65, v47
	s_waitcnt vmcnt(8)
	v_fma_f32 v54, v58, v48, v166
	v_fma_f32 v55, v59, v49, v167
	v_fma_f32 v56, v60, v46, v164
	v_fma_f32 v57, v61, v47, v165
	v_mul_f32_e64 v46, v218, v194
	v_mul_f32_e64 v47, v218, v195
	v_mul_f32_e64 v48, v218, v196
	v_mul_f32_e64 v49, v218, v197
	s_waitcnt vmcnt(7)
	v_mul_f32_e64 v48, v78, v48
	v_mul_f32_e64 v49, v79, v49
	v_mul_f32_e64 v46, v80, v46
	v_mul_f32_e64 v47, v81, v47
	s_waitcnt vmcnt(5)
	v_fma_f32 v50, v74, v48, v162
	v_fma_f32 v51, v75, v49, v163
	v_fma_f32 v52, v76, v46, v160
	v_fma_f32 v53, v77, v47, v161
	v_mul_f32_e64 v46, v218, v190
	v_mul_f32_e64 v47, v218, v191
	v_mul_f32_e64 v48, v218, v192
	v_mul_f32_e64 v49, v218, v193
	v_mul_f32_e64 v58, v48, v232
	v_mul_f32_e64 v59, v49, v233
	v_mul_f32_e64 v46, v46, v234
	v_mul_f32_e64 v47, v47, v235
	v_mul_f32_e64 v60, v218, v188
	v_mul_f32_e64 v61, v218, v189
	s_waitcnt vmcnt(3)
	v_fma_f32 v48, v238, v46, v156
	v_fma_f32 v49, v239, v47, v157
	v_fma_f32 v46, v236, v58, v158
	v_fma_f32 v47, v237, v59, v159
	v_mul_f32_e64 v58, v218, v186
	v_mul_f32_e64 v59, v218, v187
	s_waitcnt vmcnt(2)
	v_mul_f32_e64 v62, v60, v240
	v_mul_f32_e64 v63, v61, v241
	v_mul_f32_e64 v58, v58, v242
	v_mul_f32_e64 v59, v59, v243
	v_mul_f32_e64 v64, v218, v184
	v_mul_f32_e64 v65, v218, v185
	v_fma_f32 v60, v246, v58, v152
	v_fma_f32 v61, v247, v59, v153
	v_fma_f32 v58, v244, v62, v154
	v_fma_f32 v59, v245, v63, v155
	v_mul_f32_e64 v62, v218, v182
	v_mul_f32_e64 v63, v218, v183
	s_waitcnt vmcnt(0)
	v_mul_f32_e64 v70, v64, v70
	v_mul_f32_e64 v71, v65, v71
	v_mul_f32_e64 v62, v62, v72
	v_mul_f32_e64 v63, v63, v73
	s_and_b64 vcc, exec, s[8:9]
	v_fma_f32 v64, v68, v62, v150
	v_fma_f32 v65, v69, v63, v151
	v_fma_f32 v62, v66, v70, v148
	v_fma_f32 v63, v67, v71, v149
	s_cbranch_vccnz .LBB0_1327
	v_ashrrev_i32_e32 v181, 31, v180
	v_lshlrev_b64 v[152:153], 12, v[180:181]
	v_lshl_add_u64 v[66:67], s[6:7], 0, v[152:153]
	v_lshlrev_b64 v[150:151], 1, v[86:87]
	v_lshl_add_u64 v[66:67], v[66:67], 0, v[150:151]
	v_cvt_pk_f16_f32 v69, v36, v37
	v_cvt_pk_f16_f32 v68, v34, v35
	global_store_dwordx2 v[66:67], v[68:69], off
	v_cvt_pk_f16_f32 v69, v40, v41
	v_cvt_pk_f16_f32 v68, v38, v39
	global_store_dwordx2 v[66:67], v[68:69], off offset:512
	v_cvt_pk_f16_f32 v69, v44, v45
	v_cvt_pk_f16_f32 v68, v42, v43
	global_store_dwordx2 v[66:67], v[68:69], off offset:1024
	v_cvt_pk_f16_f32 v69, v56, v57
	v_cvt_pk_f16_f32 v68, v54, v55
	global_store_dwordx2 v[66:67], v[68:69], off offset:1536
	v_cvt_pk_f16_f32 v69, v52, v53
	v_cvt_pk_f16_f32 v68, v50, v51
	global_store_dwordx2 v[66:67], v[68:69], off offset:2048
	v_cvt_pk_f16_f32 v69, v48, v49
	v_cvt_pk_f16_f32 v68, v46, v47
	global_store_dwordx2 v[66:67], v[68:69], off offset:2560
	v_cvt_pk_f16_f32 v69, v60, v61
	v_cvt_pk_f16_f32 v68, v58, v59
	global_store_dwordx2 v[66:67], v[68:69], off offset:3072
	v_cvt_pk_f16_f32 v69, v64, v65
	v_cvt_pk_f16_f32 v68, v62, v63
	global_store_dwordx2 v[66:67], v[68:69], off offset:3584
	s_load_dwordx2 s[0:1], s[84:85], 0x30
	v_add_u32_e32 v1, 5, v1
	v_mul_hi_i32_i24_e32 v67, 0xc000, v1
	v_mul_i32_i24_e32 v66, 0xc000, v1
	v_lshl_add_u64 v[78:79], s[12:13], 0, v[66:67]
	s_waitcnt lgkmcnt(0)
	s_add_u32 s54, s0, s2
	s_addc_u32 s55, s1, 0
	s_mov_b64 s[0:1], 0x2000
	v_lshl_add_u64 v[80:81], v[78:79], 0, s[0:1]
	v_lshlrev_b64 v[66:67], 2, v[86:87]
	v_lshl_add_u64 v[154:155], s[54:55], 0, v[66:67]
	v_lshl_add_u64 v[68:69], v[80:81], 0, v[66:67]
	global_load_dwordx4 v[74:77], v[154:155], off
	global_load_dwordx4 v[70:73], v[68:69], off
	v_lshl_add_u64 v[156:157], v[78:79], 0, v[66:67]
	global_load_dwordx4 v[66:69], v[156:157], off
	v_mul_f32_e32 v83, v35, v35
	v_mul_f32_e32 v1, v39, v39
	v_mov_b32_e32 v158, v55
	v_mov_b32_e32 v159, v43
	v_fmac_f32_e32 v83, v34, v34
	v_fmac_f32_e32 v1, v38, v38
	v_mov_b32_e32 v148, v54
	v_mov_b32_e32 v149, v42
	v_mul_f32_e64 v158, v158, v158
	v_mul_f32_e64 v159, v159, v159
	v_fmac_f32_e32 v83, v36, v36
	v_fmac_f32_e32 v1, v40, v40
	v_fma_f32 v148, v148, v148, v158
	v_fma_f32 v149, v149, v149, v159
	v_mov_b32_e32 v158, v56
	v_mov_b32_e32 v159, v44
	v_fmac_f32_e32 v83, v37, v37
	v_fmac_f32_e32 v1, v41, v41
	v_fma_f32 v148, v158, v158, v148
	v_fma_f32 v149, v159, v159, v149
	v_mov_b32_e32 v158, v57
	v_mov_b32_e32 v159, v45
	v_add_f32_e32 v1, v83, v1
	v_fma_f32 v148, v158, v158, v148
	v_fma_f32 v149, v159, v159, v149
	v_mov_b32_e32 v158, v47
	v_add_f32_e32 v1, v149, v1
	v_mov_b32_e32 v159, v51
	v_add_f32_e32 v1, v148, v1
	v_mov_b32_e32 v148, v46
	v_mov_b32_e32 v149, v50
	v_mul_f32_e64 v158, v158, v158
	v_mul_f32_e64 v159, v159, v159
	v_lshl_add_u64 v[152:153], s[10:11], 0, v[152:153]
	v_fma_f32 v148, v148, v148, v158
	v_fma_f32 v149, v149, v149, v159
	v_mov_b32_e32 v158, v48
	v_mov_b32_e32 v159, v52
	v_fma_f32 v148, v158, v158, v148
	v_fma_f32 v149, v159, v159, v149
	v_mov_b32_e32 v158, v49
	v_mov_b32_e32 v159, v53
	v_fma_f32 v148, v158, v158, v148
	v_fma_f32 v149, v159, v159, v149
	v_mov_b32_e32 v158, v63
	v_add_f32_e32 v1, v149, v1
	v_mov_b32_e32 v159, v59
	v_add_f32_e32 v1, v148, v1
	v_mov_b32_e32 v148, v62
	v_mov_b32_e32 v149, v58
	v_mul_f32_e64 v158, v158, v158
	v_mul_f32_e64 v159, v159, v159
	s_waitcnt vmcnt(1)
; __device__ __forceinline__ unsigned cvtpk(float lo, float hi) { unsigned r; asm volatile("v_cvt_pk_bf16_f32 %0, %1, %2" : "=v"(r) : "v"(lo), "v"(hi)); return r; }
; __device__ __forceinline__ const float* modp(const Params& p, int l, int v, int j) { return (const float*)(p.ws + OFF_MOD) + ((size_t)(l * 5 + v) * NMODC + (size_t)j * DM); }
; __device__ __forceinline__ void prenorm_row(const f32x4 (&x)[8], float rinv, const float* g, const float* sc, const float* sh, bf16_t* dst, int lane) {
; #pragma unroll
;   for (int i = 0; i < 8; ++i) { const int col = (lane + 64 * i) * 4; const f32x4 gg = *(const f32x4*)(g + col), s1 = *(const f32x4*)(sc + col), s0 = *(const f32x4*)(sh + col);
;     const f32x4 y = (x[i] * rinv * gg) * (s1 + 1.f) + s0; u32x2 o = {cvtpk(y[0], y[1]), cvtpk(y[2], y[3])}; *(u32x2*)(dst + col) = o; }
; }
; __device__ __forceinline__ void phase_postffn(const Params& p, const Ctx& c, int l, bool last) {
;     ...
;       const float r2 = rsqrtf(sumsq8(x) * (1.f / DM) + 1e-6f);
;       prenorm_row(x, r2, p.g_mix_pre + (size_t)(l + 1) * DM, modp(p, l + 1, v, 1), modp(p, l + 1, v, 0), Hn + (size_t)row * DM, c.lane); } };
	v_add_f32_e64 v70, v70, 1.0
	v_add_f32_e64 v71, v71, 1.0
	v_fma_f32 v148, v148, v148, v158
	v_fma_f32 v149, v149, v149, v159
	v_mov_b32_e32 v158, v64
	v_mov_b32_e32 v159, v60
	v_fma_f32 v148, v158, v158, v148
	v_fma_f32 v149, v159, v159, v149
	v_mov_b32_e32 v158, v65
	v_mov_b32_e32 v159, v61
	v_fma_f32 v148, v158, v158, v148
	v_fma_f32 v149, v159, v159, v149
	v_add_f32_e64 v72, v72, 1.0
	v_add_f32_e64 v73, v73, 1.0
	v_add_f32_e32 v1, v149, v1
	v_add_f32_e32 v1, v148, v1
	s_nop 1
	v_add_f32_dpp v1, v1, v1 quad_perm:[1,0,3,2] row_mask:0xf bank_mask:0xf bound_ctrl:1
	s_nop 1
	v_add_f32_dpp v1, v1, v1 quad_perm:[2,3,0,1] row_mask:0xf bank_mask:0xf bound_ctrl:1
	s_nop 1
	v_add_f32_dpp v1, v1, v1 row_half_mirror row_mask:0xf bank_mask:0xf bound_ctrl:1
	s_nop 1
	v_add_f32_dpp v1, v1, v1 row_mirror row_mask:0xf bank_mask:0xf bound_ctrl:1
	s_nop 0
	v_readlane_b32 s3, v1, 16
	v_readlane_b32 s17, v1, 48
	v_readlane_b32 s0, v1, 0
	v_readlane_b32 s1, v1, 32
	v_mov_b32_e32 v148, s3
	v_mov_b32_e32 v149, s17
	v_add_f32_e64 v148, s0, v148
	v_add_f32_e64 v149, s1, v149
	s_mov_b32 s0, 0x800000
	v_add_f32_e32 v1, v148, v149
	v_fmamk_f32 v1, v1, 0x3a000000, v227
	v_mul_f32_e32 v83, 0x4b800000, v1
	v_cmp_gt_f32_e32 vcc, s0, v1
	s_nop 1
	v_cndmask_b32_e32 v1, v1, v83, vcc
	v_rsq_f32_e32 v1, v1
	s_nop 0
	v_mul_f32_e32 v83, 0x45800000, v1
	v_cndmask_b32_e32 v148, v1, v83, vcc
	v_mul_f32_e64 v160, v34, v148
	v_mul_f32_e64 v161, v35, v148
	v_mul_f32_e64 v158, v36, v148
	v_mul_f32_e64 v159, v37, v148
	v_mul_f32_e64 v74, v74, v160
	v_mul_f32_e64 v75, v75, v161
	v_mul_f32_e64 v76, v76, v158
	v_mul_f32_e64 v77, v77, v159
	s_waitcnt vmcnt(0)
	v_fma_f32 v66, v70, v74, v66
	v_fma_f32 v67, v71, v75, v67
	v_fma_f32 v68, v72, v76, v68
	v_fma_f32 v69, v73, v77, v69
	v_cvt_pk_bf16_f32 v70, v66, v67
	v_lshl_add_u64 v[66:67], v[152:153], 0, v[150:151]
	v_cvt_pk_bf16_f32 v71, v68, v69
	global_store_dwordx2 v[66:67], v[70:71], off
	global_load_dwordx4 v[68:71], v[154:155], off offset:1024
	v_lshl_add_u64 v[72:73], v[122:123], 2, v[80:81]
	global_load_dwordx4 v[72:75], v[72:73], off
	s_nop 0
	global_load_dwordx4 v[150:153], v[156:157], off offset:1024
	v_mul_f32_e64 v158, v38, v148
	v_mul_f32_e64 v159, v39, v148
	v_mul_f32_e64 v76, v40, v148
	v_mul_f32_e64 v77, v41, v148
	s_waitcnt vmcnt(2)
	v_mul_f32_e64 v68, v68, v158
	v_mul_f32_e64 v69, v69, v159
	s_waitcnt vmcnt(1)
	v_add_f32_e64 v72, v72, 1.0
	v_add_f32_e64 v73, v73, 1.0
	v_mul_f32_e64 v70, v70, v76
	v_mul_f32_e64 v71, v71, v77
	v_add_f32_e64 v74, v74, 1.0
	v_add_f32_e64 v75, v75, 1.0
	s_waitcnt vmcnt(0)
	v_fma_f32 v68, v72, v68, v150
	v_fma_f32 v69, v73, v69, v151
	v_fma_f32 v70, v74, v70, v152
	v_fma_f32 v71, v75, v71, v153
	v_cvt_pk_bf16_f32 v68, v68, v69
	v_lshl_add_u64 v[72:73], v[124:125], 2, v[80:81]
	v_cvt_pk_bf16_f32 v69, v70, v71
	global_store_dwordx2 v[66:67], v[68:69], off offset:512
	global_load_dwordx4 v[68:71], v[154:155], off offset:2048
	s_nop 0
	global_load_dwordx4 v[72:75], v[72:73], off
	s_nop 0
	global_load_dwordx4 v[150:153], v[156:157], off offset:2048
	v_mul_f32_e64 v158, v42, v148
	v_mul_f32_e64 v159, v43, v148
	v_mul_f32_e64 v76, v44, v148
	v_mul_f32_e64 v77, v45, v148
	s_waitcnt vmcnt(2)
	v_mul_f32_e64 v68, v158, v68
	v_mul_f32_e64 v69, v159, v69
	s_waitcnt vmcnt(1)
	v_add_f32_e64 v72, v72, 1.0
	v_add_f32_e64 v73, v73, 1.0
	v_mul_f32_e64 v70, v76, v70
	v_mul_f32_e64 v71, v77, v71
	v_add_f32_e64 v74, v74, 1.0
	v_add_f32_e64 v75, v75, 1.0
	s_waitcnt vmcnt(0)
	v_fma_f32 v68, v68, v72, v150
	v_fma_f32 v69, v69, v73, v151
	v_fma_f32 v70, v70, v74, v152
	v_fma_f32 v71, v71, v75, v153
	v_cvt_pk_bf16_f32 v68, v68, v69
	v_lshl_add_u64 v[72:73], v[126:127], 2, v[80:81]
	v_cvt_pk_bf16_f32 v69, v70, v71
	global_store_dwordx2 v[66:67], v[68:69], off offset:1024
	global_load_dwordx4 v[68:71], v[154:155], off offset:3072
	s_nop 0
	global_load_dwordx4 v[72:75], v[72:73], off
	s_nop 0
	global_load_dwordx4 v[150:153], v[156:157], off offset:3072
	v_mul_f32_e64 v158, v54, v148
	v_mul_f32_e64 v159, v55, v148
	v_mul_f32_e64 v156, v56, v148
	v_mul_f32_e64 v157, v57, v148
	v_lshlrev_b64 v[76:77], 2, v[128:129]
	v_lshl_add_u64 v[154:155], s[54:55], 0, v[76:77]
	s_waitcnt vmcnt(2)
	v_mul_f32_e64 v68, v158, v68
	v_mul_f32_e64 v69, v159, v69
	s_waitcnt vmcnt(1)
; __device__ __forceinline__ unsigned cvtpk(float lo, float hi) { unsigned r; asm volatile("v_cvt_pk_bf16_f32 %0, %1, %2" : "=v"(r) : "v"(lo), "v"(hi)); return r; }
; __device__ __forceinline__ void prenorm_row(const f32x4 (&x)[8], float rinv, const float* g, const float* sc, const float* sh, bf16_t* dst, int lane) {
; #pragma unroll
;   for (int i = 0; i < 8; ++i) { const int col = (lane + 64 * i) * 4; const f32x4 gg = *(const f32x4*)(g + col), s1 = *(const f32x4*)(sc + col), s0 = *(const f32x4*)(sh + col);
;     const f32x4 y = (x[i] * rinv * gg) * (s1 + 1.f) + s0; u32x2 o = {cvtpk(y[0], y[1]), cvtpk(y[2], y[3])}; *(u32x2*)(dst + col) = o; }
; }
	v_add_f32_e64 v72, v72, 1.0
	v_add_f32_e64 v73, v73, 1.0
	v_mul_f32_e64 v70, v156, v70
	v_mul_f32_e64 v71, v157, v71
	v_add_f32_e64 v74, v74, 1.0
	v_add_f32_e64 v75, v75, 1.0
	s_waitcnt vmcnt(0)
	v_fma_f32 v68, v68, v72, v150
	v_fma_f32 v69, v69, v73, v151
	v_fma_f32 v70, v70, v74, v152
	v_fma_f32 v71, v71, v75, v153
	v_cvt_pk_bf16_f32 v68, v68, v69
	v_lshl_add_u64 v[72:73], v[80:81], 0, v[76:77]
	v_cvt_pk_bf16_f32 v69, v70, v71
	global_store_dwordx2 v[66:67], v[68:69], off offset:1536
	global_load_dwordx4 v[68:71], v[154:155], off
	v_lshl_add_u64 v[76:77], v[78:79], 0, v[76:77]
	global_load_dwordx4 v[72:75], v[72:73], off
	v_mul_f32_e64 v158, v50, v148
	v_mul_f32_e64 v159, v51, v148
	global_load_dwordx4 v[150:153], v[76:77], off
	v_mul_f32_e64 v156, v52, v148
	v_mul_f32_e64 v157, v53, v148
	v_lshlrev_b64 v[76:77], 2, v[132:133]
	v_lshl_add_u64 v[154:155], s[54:55], 0, v[76:77]
	s_waitcnt vmcnt(2)
	v_mul_f32_e64 v68, v158, v68
	v_mul_f32_e64 v69, v159, v69
	v_mul_f32_e64 v70, v156, v70
	v_mul_f32_e64 v71, v157, v71
	s_waitcnt vmcnt(1)
	v_add_f32_e64 v72, v72, 1.0
	v_add_f32_e64 v73, v73, 1.0
	v_add_f32_e64 v74, v74, 1.0
	v_add_f32_e64 v75, v75, 1.0
	s_waitcnt vmcnt(0)
	v_fma_f32 v68, v68, v72, v150
	v_fma_f32 v69, v69, v73, v151
	v_fma_f32 v70, v70, v74, v152
	v_fma_f32 v71, v71, v75, v153
	v_cvt_pk_bf16_f32 v68, v68, v69
	v_lshl_add_u64 v[72:73], v[80:81], 0, v[76:77]
	v_cvt_pk_bf16_f32 v69, v70, v71
	global_store_dwordx2 v[66:67], v[68:69], off offset:2048
	global_load_dwordx4 v[68:71], v[154:155], off
	v_lshl_add_u64 v[76:77], v[78:79], 0, v[76:77]
	global_load_dwordx4 v[72:75], v[72:73], off
	v_mul_f32_e64 v158, v46, v148
	v_mul_f32_e64 v159, v47, v148
	global_load_dwordx4 v[150:153], v[76:77], off
	v_mul_f32_e64 v156, v48, v148
	v_mul_f32_e64 v157, v49, v148
	v_lshlrev_b64 v[76:77], 2, v[136:137]
	v_lshl_add_u64 v[154:155], s[54:55], 0, v[76:77]
	s_waitcnt vmcnt(2)
	v_mul_f32_e64 v68, v158, v68
	v_mul_f32_e64 v69, v159, v69
	v_mul_f32_e64 v70, v156, v70
	v_mul_f32_e64 v71, v157, v71
	s_waitcnt vmcnt(1)
	v_add_f32_e64 v72, v72, 1.0
	v_add_f32_e64 v73, v73, 1.0
	v_add_f32_e64 v74, v74, 1.0
	v_add_f32_e64 v75, v75, 1.0
	s_waitcnt vmcnt(0)
	v_fma_f32 v68, v68, v72, v150
	v_fma_f32 v69, v69, v73, v151
	v_fma_f32 v70, v70, v74, v152
	v_fma_f32 v71, v71, v75, v153
	v_cvt_pk_bf16_f32 v68, v68, v69
	v_lshl_add_u64 v[72:73], v[80:81], 0, v[76:77]
	v_cvt_pk_bf16_f32 v69, v70, v71
	global_store_dwordx2 v[66:67], v[68:69], off offset:2560
	global_load_dwordx4 v[68:71], v[154:155], off
	v_lshl_add_u64 v[76:77], v[78:79], 0, v[76:77]
	global_load_dwordx4 v[72:75], v[72:73], off
	v_mul_f32_e64 v158, v58, v148
	v_mul_f32_e64 v159, v59, v148
	global_load_dwordx4 v[150:153], v[76:77], off
	v_mul_f32_e64 v156, v60, v148
	v_mul_f32_e64 v157, v61, v148
	v_lshlrev_b64 v[76:77], 2, v[140:141]
	v_lshl_add_u64 v[154:155], s[54:55], 0, v[76:77]
	s_waitcnt vmcnt(2)
	v_mul_f32_e64 v68, v158, v68
	v_mul_f32_e64 v69, v159, v69
	v_mul_f32_e64 v70, v156, v70
	v_mul_f32_e64 v71, v157, v71
	s_waitcnt vmcnt(1)
	v_add_f32_e64 v72, v72, 1.0
	v_add_f32_e64 v73, v73, 1.0
	v_add_f32_e64 v74, v74, 1.0
	v_add_f32_e64 v75, v75, 1.0
	s_waitcnt vmcnt(0)
	v_fma_f32 v68, v68, v72, v150
	v_fma_f32 v69, v69, v73, v151
	v_fma_f32 v70, v70, v74, v152
	v_fma_f32 v71, v71, v75, v153
	v_cvt_pk_bf16_f32 v68, v68, v69
	v_lshl_add_u64 v[72:73], v[80:81], 0, v[76:77]
	v_cvt_pk_bf16_f32 v69, v70, v71
	global_store_dwordx2 v[66:67], v[68:69], off offset:3072
	global_load_dwordx4 v[68:71], v[154:155], off
	v_lshl_add_u64 v[76:77], v[78:79], 0, v[76:77]
	global_load_dwordx4 v[72:75], v[72:73], off
	v_mul_f32_e64 v80, v64, v148
	v_mul_f32_e64 v81, v65, v148
	global_load_dwordx4 v[76:79], v[76:77], off
	v_mul_f32_e64 v149, v63, v148
	v_mul_f32_e64 v148, v62, v148
	s_waitcnt vmcnt(2)
	v_mul_f32_e64 v70, v80, v70
	v_mul_f32_e64 v71, v81, v71
	v_mul_f32_e64 v68, v148, v68
	v_mul_f32_e64 v69, v149, v69
	s_waitcnt vmcnt(1)
	v_add_f32_e64 v72, v72, 1.0
	v_add_f32_e64 v73, v73, 1.0
	v_add_f32_e64 v74, v74, 1.0
	v_add_f32_e64 v75, v75, 1.0
	s_waitcnt vmcnt(0)
	v_fma_f32 v68, v68, v72, v76
	v_fma_f32 v69, v69, v73, v77
	v_fma_f32 v70, v70, v74, v78
	v_fma_f32 v71, v71, v75, v79
	v_cvt_pk_bf16_f32 v68, v68, v69
	s_nop 0
	v_cvt_pk_bf16_f32 v69, v70, v71
	global_store_dwordx2 v[66:67], v[68:69], off offset:3584
	s_cbranch_execnz .LBB0_1329
	s_branch .LBB0_1328

; __device__ __forceinline__ unsigned cvtpk(float lo, float hi) { unsigned r; asm volatile("v_cvt_pk_bf16_f32 %0, %1, %2" : "=v"(r) : "v"(lo), "v"(hi)); return r; }
; __device__ __forceinline__ void fold_four(const Params& p, const Ctx& c, int l, float* lds) {
;     ...
;     const int kq = c.tid & 15, dq = c.tid >> 4;
;     f32x4 acc[4] = {};
;     for (int cc = 0; cc < 128; ++cc) {
;       const f32x4 a = *(const f32x4*)(WlT + cc * 68 + kq * 4), w = *(const f32x4*)(Wc + cc * 128 + dq * 4);
; #pragma unroll
;       for (int di = 0; di < 4; ++di) acc[di] += a * w[di];
;     }
; #pragma unroll
;     for (int di = 0; di < 4; ++di) { u32x2 o = {cvtpk(acc[di][0], acc[di][1]), cvtpk(acc[di][2], acc[di][3])};
;       *(u32x2*)(dstb + (size_t)(3584 + cs * 512 + g * 128 + dq * 4 + di) * DM + k0 + kq * 4) = o; }
;     __syncthreads();
.LBB0_1393:
	v_add_u32_e32 v94, s14, v1
	ds_read_b128 v[2:5], v53
	ds_read_b128 v[6:9], v53 offset:512
	ds_read_b128 v[10:13], v53 offset:1024
	ds_read_b128 v[14:17], v53 offset:1536
	ds_read_b128 v[18:21], v53 offset:2048
	ds_read_b128 v[54:57], v53 offset:2560
	ds_read_b128 v[58:61], v53 offset:3072
	ds_read_b128 v[62:65], v53 offset:3584
	s_waitcnt lgkmcnt(7)
	v_mov_b32_e32 v98, v5
	ds_read_b128 v[66:69], v94
	ds_read_b128 v[70:73], v94 offset:272
	ds_read_b128 v[74:77], v94 offset:544
	ds_read_b128 v[78:81], v94 offset:816
	ds_read_b128 v[82:85], v94 offset:1088
	ds_read_b128 v[86:89], v94 offset:1360
	ds_read_b128 v[90:93], v94 offset:1632
	ds_read_b128 v[94:97], v94 offset:1904
	s_waitcnt lgkmcnt(14)
	v_mov_b32_e32 v100, v9
	s_waitcnt lgkmcnt(7)
	v_fma_f32 v42, v66, v2, v42
	v_fma_f32 v43, v67, v2, v43
	v_fma_f32 v40, v68, v2, v40
	v_fma_f32 v41, v69, v2, v41
	v_fma_f32 v38, v66, v3, v38
	v_fma_f32 v39, v67, v3, v39
	v_fma_f32 v2, v68, v3, v36
	v_fma_f32 v3, v69, v3, v37
	v_fma_f32 v34, v66, v4, v34
	v_fma_f32 v35, v67, v4, v35
	v_fma_f32 v5, v69, v4, v33
	v_fma_f32 v4, v68, v4, v32
	v_fma_f32 v28, v66, v98, v28
	v_fma_f32 v29, v67, v98, v29
	v_fma_f32 v30, v68, v98, v30
	v_fma_f32 v31, v69, v98, v31
	v_mov_b32_e32 v102, v13
	s_waitcnt lgkmcnt(6)
	v_fma_f32 v32, v72, v6, v40
	v_fma_f32 v33, v73, v6, v41
	v_fma_f32 v36, v70, v6, v42
	v_fma_f32 v37, v71, v6, v43
	v_fma_f32 v2, v72, v7, v2
	v_fma_f32 v3, v73, v7, v3
	v_fma_f32 v6, v70, v7, v38
	v_fma_f32 v7, v71, v7, v39
	v_fma_f32 v4, v72, v8, v4
	v_fma_f32 v5, v73, v8, v5
	v_fma_f32 v9, v71, v8, v35
	v_fma_f32 v8, v70, v8, v34
	v_fma_f32 v30, v72, v100, v30
	v_fma_f32 v31, v73, v100, v31
	v_fma_f32 v28, v70, v100, v28
	v_fma_f32 v29, v71, v100, v29
	v_mov_b32_e32 v104, v17
	s_waitcnt lgkmcnt(5)
	v_fma_f32 v32, v76, v10, v32
	v_fma_f32 v33, v77, v10, v33
	v_fma_f32 v34, v74, v10, v36
	v_fma_f32 v35, v75, v10, v37
	v_fma_f32 v2, v76, v11, v2
	v_fma_f32 v3, v77, v11, v3
	v_fma_f32 v6, v74, v11, v6
	v_fma_f32 v7, v75, v11, v7
	v_fma_f32 v8, v74, v12, v8
	v_fma_f32 v9, v75, v12, v9
	v_fma_f32 v4, v76, v12, v4
	v_fma_f32 v5, v77, v12, v5
	v_fma_f32 v10, v74, v102, v28
	v_fma_f32 v11, v75, v102, v29
	v_fma_f32 v12, v76, v102, v30
	v_fma_f32 v13, v77, v102, v31
	v_mov_b32_e32 v106, v21
	s_waitcnt lgkmcnt(4)
	v_fma_f32 v28, v80, v14, v32
	v_fma_f32 v29, v81, v14, v33
	v_fma_f32 v30, v78, v14, v34
	v_fma_f32 v31, v79, v14, v35
	v_fma_f32 v2, v80, v15, v2
	v_fma_f32 v3, v81, v15, v3
	v_fma_f32 v6, v78, v15, v6
	v_fma_f32 v7, v79, v15, v7
	v_fma_f32 v4, v80, v16, v4
	v_fma_f32 v5, v81, v16, v5
	v_fma_f32 v8, v78, v16, v8
	v_fma_f32 v9, v79, v16, v9
	v_fma_f32 v12, v80, v104, v12
	v_fma_f32 v13, v81, v104, v13
	v_fma_f32 v10, v78, v104, v10
	v_fma_f32 v11, v79, v104, v11
	v_mov_b32_e32 v108, v57
	s_waitcnt lgkmcnt(3)
	v_fma_f32 v14, v84, v18, v28
	v_fma_f32 v15, v85, v18, v29
	v_fma_f32 v16, v82, v18, v30
	v_fma_f32 v17, v83, v18, v31
	v_fma_f32 v2, v84, v19, v2
	v_fma_f32 v3, v85, v19, v3
	v_fma_f32 v6, v82, v19, v6
	v_fma_f32 v7, v83, v19, v7
	v_fma_f32 v8, v82, v20, v8
	v_fma_f32 v9, v83, v20, v9
	v_fma_f32 v4, v84, v20, v4
	v_fma_f32 v5, v85, v20, v5
	v_fma_f32 v10, v82, v106, v10
	v_fma_f32 v11, v83, v106, v11
	v_fma_f32 v12, v84, v106, v12
	v_fma_f32 v13, v85, v106, v13
	v_mov_b32_e32 v110, v61
	s_waitcnt lgkmcnt(2)
	v_fma_f32 v14, v88, v54, v14
	v_fma_f32 v15, v89, v54, v15
	v_fma_f32 v16, v86, v54, v16
	v_fma_f32 v17, v87, v54, v17
	v_fma_f32 v2, v88, v55, v2
	v_fma_f32 v3, v89, v55, v3
	v_fma_f32 v6, v86, v55, v6
	v_fma_f32 v7, v87, v55, v7
	v_fma_f32 v4, v88, v56, v4
	v_fma_f32 v5, v89, v56, v5
	v_fma_f32 v8, v86, v56, v8
	v_fma_f32 v9, v87, v56, v9
	v_fma_f32 v12, v88, v108, v12
	v_fma_f32 v13, v89, v108, v13
	v_fma_f32 v10, v86, v108, v10
	v_fma_f32 v11, v87, v108, v11
	s_addk_i32 s14, 0x880
	v_mov_b32_e32 v112, v65
	s_waitcnt lgkmcnt(1)
	v_fma_f32 v14, v92, v58, v14
	v_fma_f32 v15, v93, v58, v15
	v_fma_f32 v16, v90, v58, v16
	v_fma_f32 v17, v91, v58, v17
	v_fma_f32 v2, v92, v59, v2
	v_fma_f32 v3, v93, v59, v3
	v_fma_f32 v6, v90, v59, v6
	v_fma_f32 v7, v91, v59, v7
	v_fma_f32 v8, v90, v60, v8
	v_fma_f32 v9, v91, v60, v9
	v_fma_f32 v4, v92, v60, v4
	v_fma_f32 v5, v93, v60, v5
	v_fma_f32 v10, v90, v110, v10
	v_fma_f32 v11, v91, v110, v11
	v_fma_f32 v12, v92, v110, v12
	v_fma_f32 v13, v93, v110, v13
	v_add_u32_e32 v53, 0x1000, v53
	s_cmpk_eq_u32 s14, 0x8800
	s_waitcnt lgkmcnt(0)
	v_fma_f32 v40, v96, v62, v14
	v_fma_f32 v41, v97, v62, v15
	v_fma_f32 v42, v94, v62, v16
	v_fma_f32 v43, v95, v62, v17
	v_fma_f32 v36, v96, v63, v2
	v_fma_f32 v37, v97, v63, v3
	v_fma_f32 v38, v94, v63, v6
	v_fma_f32 v39, v95, v63, v7
	v_fma_f32 v32, v96, v64, v4
	v_fma_f32 v33, v97, v64, v5
	v_fma_f32 v34, v94, v64, v8
	v_fma_f32 v35, v95, v64, v9
	v_fma_f32 v30, v96, v112, v12
	v_fma_f32 v31, v97, v112, v13
	v_fma_f32 v28, v94, v112, v10
	v_fma_f32 v29, v95, v112, v11
	s_cbranch_scc0 .LBB0_1393
	s_lshl_b32 s14, s17, 9
	s_add_i32 s14, s14, s50
	v_add_u32_e32 v2, s14, v44
	s_lshl_b32 s30, s3, 1
	v_ashrrev_i32_e32 v3, 31, v2
	v_lshl_add_u64 v[4:5], v[24:25], 0, s[30:31]
	v_lshlrev_b64 v[8:9], 12, v[2:3]
	v_lshl_add_u64 v[8:9], v[4:5], 0, v[8:9]
	v_cvt_pk_bf16_f32 v6, v42, v43
	v_cvt_pk_bf16_f32 v7, v40, v41
	global_store_dwordx2 v[8:9], v[6:7], off
	v_or_b32_e32 v8, 1, v2
	v_ashrrev_i32_e32 v9, 31, v8
	v_lshlrev_b64 v[8:9], 12, v[8:9]
	v_lshl_add_u64 v[8:9], v[4:5], 0, v[8:9]
	v_cvt_pk_bf16_f32 v6, v38, v39
	v_cvt_pk_bf16_f32 v7, v36, v37
	global_store_dwordx2 v[8:9], v[6:7], off
	v_or_b32_e32 v8, 2, v2
	v_or_b32_e32 v2, 3, v2
	v_ashrrev_i32_e32 v9, 31, v8
	v_ashrrev_i32_e32 v3, 31, v2
	v_lshlrev_b64 v[8:9], 12, v[8:9]
	v_lshlrev_b64 v[2:3], 12, v[2:3]
	s_add_i32 s0, s0, s26
	v_cvt_pk_bf16_f32 v6, v34, v35
	v_cvt_pk_bf16_f32 v7, v32, v33
	v_lshl_add_u64 v[8:9], v[4:5], 0, v[8:9]
	v_lshl_add_u64 v[2:3], v[4:5], 0, v[2:3]
	s_cmpk_gt_i32 s0, 0xff
	global_store_dwordx2 v[8:9], v[6:7], off
	v_cvt_pk_bf16_f32 v6, v28, v29
	v_cvt_pk_bf16_f32 v7, v30, v31
	global_store_dwordx2 v[2:3], v[6:7], off
	s_barrier
	s_cbranch_scc0 .LBB0_1374
